# GEMM K-loops (10 of 15): phase-1 load-segment scalar address/select block computed at the end of the previous iteration's last MFMA block (plus a copy at tile start)
# speedup vs baseline: 1.0011x; 1.0011x over previous
;     DI const char* a(const Unit& u) const { return (const char*)(A + (size_t)u.pm * BM * lda); }
;     DI const char* a(const Unit& u) const { return (const char*)(A + (size_t)u.pm * BM * 2048 + (u.pn >> 1) * 512); }
;     DI const char* a(const Unit& u) const { return (const char*)((u.pn < 12 ? A1 : A2) + (size_t)u.pm * BM * 512); }
; #define PG8_STAGE(bufoff, gbase, voff) do { _Pragma("unroll") for (int _i = 0; _i < 2; ++_i) \
;         __builtin_amdgcn_global_load_lds((const unsigned*)((const char*)(gbase) + (voff)[_i]), (LAS unsigned*)(lds + (bufoff) + ldsw + _i * 8192), 16, 0, 0); } while (0)
; #define PG8_LDA(dst, b, h) do { _Pragma("unroll") for (int m = 0; m < 4; ++m) _Pragma("unroll") for (int k = 0; k < 2; ++k) dst[m][k] = *(const LAS bf16x8*)(lds + PG8_SA(b, h) + aoff + m * 2048 + k * 1024); } while (0)
; #define PG8_LDB(dst, b, h) do { _Pragma("unroll") for (int n = 0; n < 2; ++n) _Pragma("unroll") for (int k = 0; k < 2; ++k) dst[n][k] = *(const LAS bf16x8*)(lds + PG8_SB(b, h) + boff + n * 2048 + k * 1024); } while (0)
; #define PG8_SCHED __builtin_amdgcn_sched_barrier(0)
; template <class Map, class Epi>
; DI void gemm_phase(LAS unsigned char* lds, const Map& MP, const Epi& E, const int nM, const int nN, const int K, const int lda, const int ldb) {
;     ...
;         const bool has_next = sched_next(ui + 1, nM, nN, G, cblk, nxt);
;         const char* nA = has_next ? MP.a(nxt) : cA; const char* nB = has_next ? MP.b(nxt) : cB;
;         for (int t = 0; t < nt; t += 2) {
;             const bool last = (t == nt - 2);
;             const char* a1 = cA + (size_t)(t + 1) * kstep;
;             const char* a2 = last ? nA : cA + (size_t)(t + 2) * kstep; const char* b2 = last ? nB : cB + (size_t)(t + 2) * kstep;
;             const char* a3 = a2 + kstep; const char* b3 = b2 + kstep;
;             PG8_LDB(B0, 0, 0); PG8_SCHED; PG8_LDA(At, 0, 0); PG8_STAGE(PG8_SA(1, 1), a1 + hstepA, voffA);
;     ...
; #pragma unroll
;         for (int a = 0; a < 2; ++a)
; #pragma unroll
;             for (int b = 0; b < 2; ++b)
; #pragma unroll
;                 for (int m = 0; m < 4; ++m)
; #pragma unroll
;                     for (int n = 0; n < 2; ++n) acc[a][b][m][n] = (f32x4){0.f, 0.f, 0.f, 0.f};
;         cur = nxt; cA = nA; cB = nB; ++ui;
.LBB1_228:
	s_ashr_i32 s17, s16, 31
	v_cmp_lt_i64_e32 vcc, s[18:19], v[156:157]
	s_lshl_b64 s[18:19], s[16:17], 20
	s_add_u32 s17, s31, s18
	s_addc_u32 s20, s33, s19
	s_lshl_b32 s18, s52, 8
	s_and_b32 s18, s18, 0xfffffe00
	s_ashr_i32 s19, s18, 31
	s_lshl_b64 s[18:19], s[18:19], 1
	s_add_u32 s18, s17, s18
	s_addc_u32 s19, s20, s19
	s_and_b64 s[20:21], vcc, exec
	s_cselect_b32 s17, s19, s27
	s_cselect_b32 s43, s18, s26
	s_ashr_i32 s20, s52, 1
	s_ashr_i32 s21, s20, 31
	s_lshl_b64 s[20:21], s[20:21], 19
	s_add_u32 s20, s6, s20
	s_addc_u32 s21, s7, s21
	s_lshl_b32 s28, s52, 18
	s_and_b32 s28, s28, 0x40000
	s_add_u32 s20, s20, s28
	s_addc_u32 s21, s21, 0
	s_and_b64 s[28:29], vcc, exec
	s_cselect_b32 s53, s21, s25
	s_cselect_b32 s54, s20, s24
	s_add_u32 s55, s24, 0x100
	s_addc_u32 s56, s25, 0
	s_add_u32 s24, s26, 0x80080
	v_mov_b32_e32 v0, 0
	s_addc_u32 s25, s27, 0
	s_mov_b32 s57, -2
	v_mov_b32_e32 v1, 0
	v_mov_b64_e32 v[2:3], 0
	v_mov_b64_e32 v[4:5], 0
	v_mov_b64_e32 v[6:7], 0
	v_mov_b64_e32 v[8:9], 0
	v_mov_b64_e32 v[10:11], 0
	v_mov_b64_e32 v[12:13], 0
	v_mov_b64_e32 v[14:15], 0
	v_mov_b64_e32 v[16:17], 0
	v_mov_b64_e32 v[18:19], 0
	v_mov_b64_e32 v[20:21], 0
	v_mov_b64_e32 v[22:23], 0
	v_mov_b64_e32 v[24:25], 0
	v_mov_b64_e32 v[26:27], 0
	v_mov_b64_e32 v[28:29], 0
	v_mov_b64_e32 v[30:31], 0
	v_mov_b64_e32 v[32:33], 0
	v_mov_b64_e32 v[34:35], 0
	v_mov_b64_e32 v[36:37], 0
	v_mov_b64_e32 v[38:39], 0
	v_mov_b64_e32 v[40:41], 0
	v_mov_b64_e32 v[42:43], 0
	v_mov_b64_e32 v[44:45], 0
	v_mov_b64_e32 v[46:47], 0
	v_mov_b64_e32 v[48:49], 0
	v_mov_b64_e32 v[50:51], 0
	v_mov_b64_e32 v[52:53], 0
	v_mov_b64_e32 v[54:55], 0
	v_mov_b64_e32 v[56:57], 0
	v_mov_b64_e32 v[58:59], 0
	v_mov_b64_e32 v[60:61], 0
	v_mov_b64_e32 v[62:63], 0
	v_mov_b64_e32 v[64:65], 0
	v_mov_b64_e32 v[66:67], 0
	v_mov_b64_e32 v[68:69], 0
	v_mov_b64_e32 v[70:71], 0
	v_mov_b64_e32 v[88:89], 0
	v_mov_b64_e32 v[90:91], 0
	v_mov_b64_e32 v[92:93], 0
	v_mov_b64_e32 v[94:95], 0
	v_mov_b64_e32 v[96:97], 0
	v_mov_b64_e32 v[98:99], 0
	v_mov_b64_e32 v[100:101], 0
	v_mov_b64_e32 v[102:103], 0
	v_mov_b64_e32 v[104:105], 0
	v_mov_b64_e32 v[106:107], 0
	v_mov_b64_e32 v[108:109], 0
	v_mov_b64_e32 v[110:111], 0
	v_mov_b64_e32 v[112:113], 0
	v_mov_b64_e32 v[114:115], 0
	v_mov_b64_e32 v[116:117], 0
	v_mov_b64_e32 v[118:119], 0
	v_mov_b64_e32 v[120:121], 0
	v_mov_b64_e32 v[122:123], 0
	v_mov_b64_e32 v[124:125], 0
	v_mov_b64_e32 v[126:127], 0
	v_mov_b64_e32 v[128:129], 0
	v_mov_b64_e32 v[130:131], 0
	v_mov_b64_e32 v[132:133], 0
	v_mov_b64_e32 v[134:135], 0
	v_mov_b64_e32 v[136:137], 0
	v_mov_b64_e32 v[138:139], 0
	v_mov_b64_e32 v[140:141], 0
	v_mov_b64_e32 v[142:143], 0
	ds_read_b128 v[72:75], v167
	ds_read_b128 v[76:79], v167 offset:1024
	ds_read_b128 v[80:83], v167 offset:2048
	ds_read_b128 v[84:87], v167 offset:3072
	s_add_u32 s26, s24, 0xfff80080
	s_addc_u32 s27, s25, -1
	s_cmp_eq_u32 s57, 4
	s_cselect_b32 s29, s17, s27
	s_cselect_b32 s28, s43, s26
	s_cselect_b32 s27, s53, s56
	s_cselect_b32 s26, s54, s55
.LBB1_229:
	s_add_i32 m0, s2, 0xc000
	ds_read_b128 v[160:163], v168
	ds_read_b128 v[170:173], v168 offset:1024
	ds_read_b128 v[174:177], v168 offset:2048
	ds_read_b128 v[178:181], v168 offset:3072
	ds_read_b128 v[182:185], v168 offset:4096
	ds_read_b128 v[186:189], v168 offset:5120
	ds_read_b128 v[190:193], v168 offset:6144
	ds_read_b128 v[198:201], v168 offset:7168
	global_load_lds_dwordx4 v154, s[24:25]
	s_add_i32 m0, s2, 0xe000
	s_nop 0
	global_load_lds_dwordx4 v152, s[24:25]
	s_waitcnt lgkmcnt(8)
	s_setprio 1
	s_barrier
	s_waitcnt lgkmcnt(7)
	v_mfma_f32_16x16x32_bf16 v[140:143], v[72:75], v[160:163], v[140:143]
	v_mfma_f32_16x16x32_bf16 v[136:139], v[80:83], v[160:163], v[136:139]
	s_waitcnt lgkmcnt(5)
	v_mfma_f32_16x16x32_bf16 v[124:127], v[72:75], v[174:177], v[124:127]
	v_mfma_f32_16x16x32_bf16 v[120:123], v[80:83], v[174:177], v[120:123]
	s_waitcnt lgkmcnt(3)
	v_mfma_f32_16x16x32_bf16 v[108:111], v[72:75], v[182:185], v[108:111]
	v_mfma_f32_16x16x32_bf16 v[104:107], v[80:83], v[182:185], v[104:107]
	s_waitcnt lgkmcnt(1)
	v_mfma_f32_16x16x32_bf16 v[92:95], v[72:75], v[190:193], v[92:95]
	v_mfma_f32_16x16x32_bf16 v[88:91], v[80:83], v[190:193], v[88:91]
	v_mfma_f32_16x16x32_bf16 v[140:143], v[76:79], v[170:173], v[140:143]
	s_add_i32 s58, s48, s34
	v_mfma_f32_16x16x32_bf16 v[136:139], v[84:87], v[170:173], v[136:139]
	v_lshl_add_u64 v[194:195], s[26:27], 0, v[148:149]
	v_mfma_f32_16x16x32_bf16 v[124:127], v[76:79], v[178:181], v[124:127]
	v_lshl_add_u64 v[218:219], s[26:27], 0, v[144:145]
	v_mfma_f32_16x16x32_bf16 v[120:123], v[84:87], v[178:181], v[120:123]
	v_mfma_f32_16x16x32_bf16 v[108:111], v[76:79], v[186:189], v[108:111]
	v_mfma_f32_16x16x32_bf16 v[104:107], v[84:87], v[186:189], v[104:107]
	s_waitcnt lgkmcnt(0)
	v_mfma_f32_16x16x32_bf16 v[92:95], v[76:79], v[198:201], v[92:95]
	v_mfma_f32_16x16x32_bf16 v[88:91], v[84:87], v[198:201], v[88:91]
	s_barrier
	s_setprio 0
	s_mov_b32 m0, s58
	ds_read_b128 v[202:205], v169
	ds_read_b128 v[206:209], v169 offset:1024
	ds_read_b128 v[210:213], v169 offset:2048
	ds_read_b128 v[214:217], v169 offset:3072
	global_load_lds_dwordx4 v[194:195], off
	s_add_i32 m0, s58, 0x2000
	s_nop 0
	global_load_lds_dwordx4 v[218:219], off
	s_setprio 1
	s_barrier
; #define PG8_STAGE(bufoff, gbase, voff) do { _Pragma("unroll") for (int _i = 0; _i < 2; ++_i) \
;         __builtin_amdgcn_global_load_lds((const unsigned*)((const char*)(gbase) + (voff)[_i]), (LAS unsigned*)(lds + (bufoff) + ldsw + _i * 8192), 16, 0, 0); } while (0)
; #define PG8_LDA(dst, b, h) do { _Pragma("unroll") for (int m = 0; m < 4; ++m) _Pragma("unroll") for (int k = 0; k < 2; ++k) dst[m][k] = *(const LAS bf16x8*)(lds + PG8_SA(b, h) + aoff + m * 2048 + k * 1024); } while (0)
; #define PG8_LDB(dst, b, h) do { _Pragma("unroll") for (int n = 0; n < 2; ++n) _Pragma("unroll") for (int k = 0; k < 2; ++k) dst[n][k] = *(const LAS bf16x8*)(lds + PG8_SB(b, h) + boff + n * 2048 + k * 1024); } while (0)
; #define PG8_MMA(ai, bj, At, Bt) do { __builtin_amdgcn_s_setprio(1); _Pragma("unroll") for (int m = 0; m < 4; ++m) _Pragma("unroll") for (int n = 0; n < 2; ++n) _Pragma("unroll") for (int k = 0; k < 2; ++k) \
;         acc[ai][bj][m][n] = __builtin_amdgcn_mfma_f32_16x16x32_bf16(Bt[n][k], At[m][k], acc[ai][bj][m][n], 0, 0, 0); __builtin_amdgcn_s_setprio(0); } while (0)
; #define PG8_WAIT_V(n) asm volatile("s_waitcnt vmcnt(" #n ")" ::: "memory")
; #define PG8_WAIT_L(n) asm volatile("s_waitcnt lgkmcnt(" #n ")" ::: "memory")
; #define PG8_BAR __builtin_amdgcn_s_barrier()
; #define PG8_SCHED __builtin_amdgcn_sched_barrier(0)
; template <class Map, class Epi>
; DI void gemm_phase(LAS unsigned char* lds, const Map& MP, const Epi& E, const int nM, const int nN, const int K, const int lda, const int ldb) {
;     ...
;             PG8_LDB(B1, 0, 1); PG8_STAGE(PG8_SB(0, 0), b2, voffB);
;             PG8_BAR; PG8_WAIT_L(0); PG8_MMA(0, 1, At, B1); PG8_BAR;
;             PG8_LDA(At, 0, 1); PG8_STAGE(PG8_SA(0, 0), a2, voffA);
;             PG8_BAR; PG8_WAIT_L(0); PG8_MMA(1, 0, At, B0); PG8_BAR; PG8_SCHED;
;             PG8_STAGE(PG8_SB(0, 1), b2 + hstepB, voffB);
;             PG8_WAIT_V(6); PG8_BAR; PG8_MMA(1, 1, At, B1); PG8_BAR;
;             PG8_LDB(B0, 1, 0); PG8_SCHED; PG8_LDA(At, 1, 0); PG8_STAGE(PG8_SA(0, 1), a2 + hstepA, voffA);
;             PG8_WAIT_L(8); PG8_BAR; PG8_WAIT_L(0); PG8_MMA(0, 0, At, B0); PG8_BAR; PG8_SCHED;
;             PG8_LDB(B1, 1, 1); PG8_STAGE(PG8_SB(1, 0), b3, voffB);
;             PG8_BAR; PG8_WAIT_L(0); PG8_MMA(0, 1, At, B1); PG8_BAR;
;             PG8_LDA(At, 1, 1); PG8_STAGE(PG8_SA(1, 0), a3, voffA);
	s_waitcnt lgkmcnt(3)
	v_mfma_f32_16x16x32_bf16 v[132:135], v[202:205], v[160:163], v[132:135]
	s_waitcnt lgkmcnt(1)
	v_mfma_f32_16x16x32_bf16 v[128:131], v[210:213], v[160:163], v[128:131]
	v_mfma_f32_16x16x32_bf16 v[116:119], v[202:205], v[174:177], v[116:119]
	v_mfma_f32_16x16x32_bf16 v[112:115], v[210:213], v[174:177], v[112:115]
	v_mfma_f32_16x16x32_bf16 v[100:103], v[202:205], v[182:185], v[100:103]
	v_mfma_f32_16x16x32_bf16 v[96:99], v[210:213], v[182:185], v[96:99]
	v_mfma_f32_16x16x32_bf16 v[68:71], v[202:205], v[190:193], v[68:71]
	v_mfma_f32_16x16x32_bf16 v[64:67], v[210:213], v[190:193], v[64:67]
	v_mfma_f32_16x16x32_bf16 v[132:135], v[206:209], v[170:173], v[132:135]
	v_lshl_add_u64 v[222:223], s[28:29], 0, v[146:147]
	s_mov_b32 m0, s2
	s_waitcnt lgkmcnt(0)
	v_mfma_f32_16x16x32_bf16 v[128:131], v[214:217], v[170:173], v[128:131]
	v_lshl_add_u64 v[220:221], s[28:29], 0, v[150:151]
	v_mfma_f32_16x16x32_bf16 v[116:119], v[206:209], v[178:181], v[116:119]
	v_mfma_f32_16x16x32_bf16 v[112:115], v[214:217], v[178:181], v[112:115]
	v_mfma_f32_16x16x32_bf16 v[100:103], v[206:209], v[186:189], v[100:103]
	v_mfma_f32_16x16x32_bf16 v[96:99], v[214:217], v[186:189], v[96:99]
	v_mfma_f32_16x16x32_bf16 v[68:71], v[206:209], v[198:201], v[68:71]
	v_mfma_f32_16x16x32_bf16 v[64:67], v[214:217], v[198:201], v[64:67]
	s_barrier
	s_setprio 0
	ds_read_b128 v[160:163], v168 offset:16384
	ds_read_b128 v[170:173], v168 offset:17408
	ds_read_b128 v[174:177], v168 offset:18432
	ds_read_b128 v[178:181], v168 offset:19456
	ds_read_b128 v[182:185], v168 offset:20480
	ds_read_b128 v[186:189], v168 offset:21504
	ds_read_b128 v[190:193], v168 offset:22528
	ds_read_b128 v[198:201], v168 offset:23552
	global_load_lds_dwordx4 v[220:221], off
	s_mov_b32 m0, s4
	s_nop 0
	global_load_lds_dwordx4 v[222:223], off
	s_waitcnt vmcnt(10)
	s_setprio 1
	s_barrier
	s_waitcnt lgkmcnt(7)
	v_mfma_f32_16x16x32_bf16 v[60:63], v[72:75], v[160:163], v[60:63]
	v_mfma_f32_16x16x32_bf16 v[56:59], v[80:83], v[160:163], v[56:59]
	s_waitcnt lgkmcnt(5)
	v_mfma_f32_16x16x32_bf16 v[44:47], v[72:75], v[174:177], v[44:47]
	v_mfma_f32_16x16x32_bf16 v[40:43], v[80:83], v[174:177], v[40:43]
	s_waitcnt lgkmcnt(3)
	v_mfma_f32_16x16x32_bf16 v[28:31], v[72:75], v[182:185], v[28:31]
	v_mfma_f32_16x16x32_bf16 v[24:27], v[80:83], v[182:185], v[24:27]
	s_waitcnt lgkmcnt(1)
	v_mfma_f32_16x16x32_bf16 v[12:15], v[72:75], v[190:193], v[12:15]
	v_mfma_f32_16x16x32_bf16 v[8:11], v[80:83], v[190:193], v[8:11]
	v_mfma_f32_16x16x32_bf16 v[60:63], v[76:79], v[170:173], v[60:63]
	s_add_u32 s58, s26, 0x20000
	s_addc_u32 s59, s27, 0
	v_mfma_f32_16x16x32_bf16 v[56:59], v[84:87], v[170:173], v[56:59]
	s_add_i32 s60, s49, s34
	v_mfma_f32_16x16x32_bf16 v[44:47], v[76:79], v[178:181], v[44:47]
	v_mfma_f32_16x16x32_bf16 v[40:43], v[84:87], v[178:181], v[40:43]
	v_mfma_f32_16x16x32_bf16 v[28:31], v[76:79], v[186:189], v[28:31]
	v_mfma_f32_16x16x32_bf16 v[24:27], v[84:87], v[186:189], v[24:27]
	s_waitcnt lgkmcnt(0)
	v_mfma_f32_16x16x32_bf16 v[12:15], v[76:79], v[198:201], v[12:15]
	v_mfma_f32_16x16x32_bf16 v[8:11], v[84:87], v[198:201], v[8:11]
	s_barrier
	s_setprio 0
	s_mov_b32 m0, s60
	s_nop 0
	global_load_lds_dwordx4 v148, s[58:59]
	s_add_i32 m0, s60, 0x2000
	s_nop 0
	global_load_lds_dwordx4 v144, s[58:59]
	s_waitcnt vmcnt(6)
	s_setprio 1
	s_barrier
	v_mfma_f32_16x16x32_bf16 v[52:55], v[202:205], v[160:163], v[52:55]
	v_mfma_f32_16x16x32_bf16 v[48:51], v[210:213], v[160:163], v[48:51]
	s_add_i32 s58, 0, 0x18000
	v_add_u32_e32 v84, s58, v166
	ds_read_b128 v[72:75], v84
	v_mfma_f32_16x16x32_bf16 v[36:39], v[202:205], v[174:177], v[36:39]
	v_mfma_f32_16x16x32_bf16 v[32:35], v[210:213], v[174:177], v[32:35]
	ds_read_b128 v[76:79], v84 offset:1024
	v_mfma_f32_16x16x32_bf16 v[20:23], v[202:205], v[182:185], v[20:23]
	v_mfma_f32_16x16x32_bf16 v[16:19], v[210:213], v[182:185], v[16:19]
	ds_read_b128 v[80:83], v84 offset:2048
	v_mfma_f32_16x16x32_bf16 v[4:7], v[202:205], v[190:193], v[4:7]
	v_mfma_f32_16x16x32_bf16 v[0:3], v[210:213], v[190:193], v[0:3]
	ds_read_b128 v[84:87], v84 offset:3072
	v_mfma_f32_16x16x32_bf16 v[52:55], v[206:209], v[170:173], v[52:55]
	s_add_u32 s28, s28, 0x80000
	s_addc_u32 s29, s29, 0
	v_mfma_f32_16x16x32_bf16 v[48:51], v[214:217], v[170:173], v[48:51]
	v_mfma_f32_16x16x32_bf16 v[36:39], v[206:209], v[178:181], v[36:39]
	v_mfma_f32_16x16x32_bf16 v[32:35], v[214:217], v[178:181], v[32:35]
	v_mfma_f32_16x16x32_bf16 v[20:23], v[206:209], v[186:189], v[20:23]
	v_mfma_f32_16x16x32_bf16 v[16:19], v[214:217], v[186:189], v[16:19]
	v_mfma_f32_16x16x32_bf16 v[4:7], v[206:209], v[198:201], v[4:7]
	v_mfma_f32_16x16x32_bf16 v[0:3], v[214:217], v[198:201], v[0:3]
	s_barrier
	s_setprio 0
	s_mov_b32 m0, s5
	ds_read_b128 v[160:163], v168 offset:32768
	ds_read_b128 v[170:173], v168 offset:33792
	ds_read_b128 v[174:177], v168 offset:34816
	ds_read_b128 v[178:181], v168 offset:35840
	ds_read_b128 v[182:185], v168 offset:36864
	ds_read_b128 v[186:189], v168 offset:37888
	ds_read_b128 v[190:193], v168 offset:38912
	ds_read_b128 v[198:201], v168 offset:39936
	global_load_lds_dwordx4 v150, s[28:29]
	s_mov_b32 m0, s23
	s_nop 0
	global_load_lds_dwordx4 v146, s[28:29]
	s_waitcnt lgkmcnt(8)
	s_setprio 1
	s_barrier
; #define PG8_STAGE(bufoff, gbase, voff) do { _Pragma("unroll") for (int _i = 0; _i < 2; ++_i) \
;         __builtin_amdgcn_global_load_lds((const unsigned*)((const char*)(gbase) + (voff)[_i]), (LAS unsigned*)(lds + (bufoff) + ldsw + _i * 8192), 16, 0, 0); } while (0)
; #define PG8_LDA(dst, b, h) do { _Pragma("unroll") for (int m = 0; m < 4; ++m) _Pragma("unroll") for (int k = 0; k < 2; ++k) dst[m][k] = *(const LAS bf16x8*)(lds + PG8_SA(b, h) + aoff + m * 2048 + k * 1024); } while (0)
; #define PG8_LDB(dst, b, h) do { _Pragma("unroll") for (int n = 0; n < 2; ++n) _Pragma("unroll") for (int k = 0; k < 2; ++k) dst[n][k] = *(const LAS bf16x8*)(lds + PG8_SB(b, h) + boff + n * 2048 + k * 1024); } while (0)
; #define PG8_MMA(ai, bj, At, Bt) do { __builtin_amdgcn_s_setprio(1); _Pragma("unroll") for (int m = 0; m < 4; ++m) _Pragma("unroll") for (int n = 0; n < 2; ++n) _Pragma("unroll") for (int k = 0; k < 2; ++k) \
;         acc[ai][bj][m][n] = __builtin_amdgcn_mfma_f32_16x16x32_bf16(Bt[n][k], At[m][k], acc[ai][bj][m][n], 0, 0, 0); __builtin_amdgcn_s_setprio(0); } while (0)
; #define PG8_WAIT_L(n) asm volatile("s_waitcnt lgkmcnt(" #n ")" ::: "memory")
; #define PG8_BAR __builtin_amdgcn_s_barrier()
; #define PG8_SCHED __builtin_amdgcn_sched_barrier(0)
; template <class Map, class Epi>
; DI void gemm_phase(LAS unsigned char* lds, const Map& MP, const Epi& E, const int nM, const int nN, const int K, const int lda, const int ldb) {
;     ...
;             PG8_LDB(B0, 1, 0); PG8_SCHED; PG8_LDA(At, 1, 0); PG8_STAGE(PG8_SA(0, 1), a2 + hstepA, voffA);
;             PG8_WAIT_L(8); PG8_BAR; PG8_WAIT_L(0); PG8_MMA(0, 0, At, B0); PG8_BAR; PG8_SCHED;
;             PG8_LDB(B1, 1, 1); PG8_STAGE(PG8_SB(1, 0), b3, voffB);
;             PG8_BAR; PG8_WAIT_L(0); PG8_MMA(0, 1, At, B1); PG8_BAR;
;             PG8_LDA(At, 1, 1); PG8_STAGE(PG8_SA(1, 0), a3, voffA);
;             PG8_BAR; PG8_WAIT_L(0); PG8_MMA(1, 0, At, B0); PG8_BAR; PG8_SCHED;
;             PG8_STAGE(PG8_SB(1, 1), b3 + hstepB, voffB);
	s_waitcnt lgkmcnt(7)
	v_mfma_f32_16x16x32_bf16 v[140:143], v[72:75], v[160:163], v[140:143]
	v_mfma_f32_16x16x32_bf16 v[136:139], v[80:83], v[160:163], v[136:139]
	s_waitcnt lgkmcnt(5)
	v_mfma_f32_16x16x32_bf16 v[124:127], v[72:75], v[174:177], v[124:127]
	v_mfma_f32_16x16x32_bf16 v[120:123], v[80:83], v[174:177], v[120:123]
	s_waitcnt lgkmcnt(3)
	v_mfma_f32_16x16x32_bf16 v[108:111], v[72:75], v[182:185], v[108:111]
	v_mfma_f32_16x16x32_bf16 v[104:107], v[80:83], v[182:185], v[104:107]
	s_waitcnt lgkmcnt(1)
	v_mfma_f32_16x16x32_bf16 v[92:95], v[72:75], v[190:193], v[92:95]
	v_mfma_f32_16x16x32_bf16 v[88:91], v[80:83], v[190:193], v[88:91]
	v_mfma_f32_16x16x32_bf16 v[140:143], v[76:79], v[170:173], v[140:143]
	s_add_i32 s28, 0, 0x1c000
	v_mfma_f32_16x16x32_bf16 v[136:139], v[84:87], v[170:173], v[136:139]
	s_add_i32 s29, s58, s34
	v_mfma_f32_16x16x32_bf16 v[124:127], v[76:79], v[178:181], v[124:127]
	v_add_u32_e32 v196, s28, v166
	v_mfma_f32_16x16x32_bf16 v[120:123], v[84:87], v[178:181], v[120:123]
	v_lshl_add_u64 v[194:195], v[194:195], 0, s[12:13]
	v_mfma_f32_16x16x32_bf16 v[108:111], v[76:79], v[186:189], v[108:111]
	v_mfma_f32_16x16x32_bf16 v[104:107], v[84:87], v[186:189], v[104:107]
	s_waitcnt lgkmcnt(0)
	v_mfma_f32_16x16x32_bf16 v[92:95], v[76:79], v[198:201], v[92:95]
	v_mfma_f32_16x16x32_bf16 v[88:91], v[84:87], v[198:201], v[88:91]
	s_barrier
	s_setprio 0
	s_mov_b32 m0, s29
	ds_read_b128 v[202:205], v196
	ds_read_b128 v[206:209], v196 offset:1024
	ds_read_b128 v[210:213], v196 offset:2048
	ds_read_b128 v[214:217], v196 offset:3072
	global_load_lds_dwordx4 v[194:195], off
	v_lshl_add_u64 v[194:195], v[218:219], 0, s[12:13]
	s_add_i32 m0, s29, 0x2000
	s_nop 0
	global_load_lds_dwordx4 v[194:195], off
	s_setprio 1
	s_barrier
	s_waitcnt lgkmcnt(3)
	v_mfma_f32_16x16x32_bf16 v[132:135], v[202:205], v[160:163], v[132:135]
	s_waitcnt lgkmcnt(1)
	v_mfma_f32_16x16x32_bf16 v[128:131], v[210:213], v[160:163], v[128:131]
	v_mfma_f32_16x16x32_bf16 v[116:119], v[202:205], v[174:177], v[116:119]
	v_mfma_f32_16x16x32_bf16 v[112:115], v[210:213], v[174:177], v[112:115]
	v_mfma_f32_16x16x32_bf16 v[100:103], v[202:205], v[182:185], v[100:103]
	v_mfma_f32_16x16x32_bf16 v[96:99], v[210:213], v[182:185], v[96:99]
	v_mfma_f32_16x16x32_bf16 v[68:71], v[202:205], v[190:193], v[68:71]
	v_mfma_f32_16x16x32_bf16 v[64:67], v[210:213], v[190:193], v[64:67]
	v_mfma_f32_16x16x32_bf16 v[132:135], v[206:209], v[170:173], v[132:135]
	s_mov_b32 m0, s39
	s_waitcnt lgkmcnt(0)
	v_mfma_f32_16x16x32_bf16 v[128:131], v[214:217], v[170:173], v[128:131]
	v_lshl_add_u64 v[194:195], v[220:221], 0, s[12:13]
	v_mfma_f32_16x16x32_bf16 v[116:119], v[206:209], v[178:181], v[116:119]
	v_mfma_f32_16x16x32_bf16 v[112:115], v[214:217], v[178:181], v[112:115]
	v_mfma_f32_16x16x32_bf16 v[100:103], v[206:209], v[186:189], v[100:103]
	v_mfma_f32_16x16x32_bf16 v[96:99], v[214:217], v[186:189], v[96:99]
	v_mfma_f32_16x16x32_bf16 v[68:71], v[206:209], v[198:201], v[68:71]
	v_mfma_f32_16x16x32_bf16 v[64:67], v[214:217], v[198:201], v[64:67]
	s_barrier
	s_setprio 0
	ds_read_b128 v[160:163], v168 offset:49152
	ds_read_b128 v[170:173], v168 offset:50176
	ds_read_b128 v[174:177], v168 offset:51200
	ds_read_b128 v[178:181], v168 offset:52224
	ds_read_b128 v[182:185], v168 offset:53248
	ds_read_b128 v[186:189], v168 offset:54272
	ds_read_b128 v[190:193], v168 offset:55296
	ds_read_b128 v[198:201], v168 offset:56320
	global_load_lds_dwordx4 v[194:195], off
	v_lshl_add_u64 v[194:195], v[222:223], 0, s[12:13]
	s_mov_b32 m0, s46
	s_nop 0
	global_load_lds_dwordx4 v[194:195], off
	s_waitcnt vmcnt(10)
	s_setprio 1
	s_barrier
; #define PG8_STAGE(bufoff, gbase, voff) do { _Pragma("unroll") for (int _i = 0; _i < 2; ++_i) \
;         __builtin_amdgcn_global_load_lds((const unsigned*)((const char*)(gbase) + (voff)[_i]), (LAS unsigned*)(lds + (bufoff) + ldsw + _i * 8192), 16, 0, 0); } while (0)
; #define PG8_LDA(dst, b, h) do { _Pragma("unroll") for (int m = 0; m < 4; ++m) _Pragma("unroll") for (int k = 0; k < 2; ++k) dst[m][k] = *(const LAS bf16x8*)(lds + PG8_SA(b, h) + aoff + m * 2048 + k * 1024); } while (0)
; #define PG8_WAIT_V(n) asm volatile("s_waitcnt vmcnt(" #n ")" ::: "memory")
; #define PG8_WAIT_L(n) asm volatile("s_waitcnt lgkmcnt(" #n ")" ::: "memory")
; template <class Map, class Epi>
; DI void gemm_phase(LAS unsigned char* lds, const Map& MP, const Epi& E, const int nM, const int nN, const int K, const int lda, const int ldb) {
;     ...
;             const bool last = (t == nt - 2);
;             const char* a1 = cA + (size_t)(t + 1) * kstep;
;             const char* a2 = last ? nA : cA + (size_t)(t + 2) * kstep; const char* b2 = last ? nB : cB + (size_t)(t + 2) * kstep;
;             const char* a3 = a2 + kstep; const char* b3 = b2 + kstep;
;             PG8_LDB(B0, 0, 0); PG8_SCHED; PG8_LDA(At, 0, 0); PG8_STAGE(PG8_SA(1, 1), a1 + hstepA, voffA);
;             PG8_WAIT_L(8); PG8_BAR; PG8_WAIT_L(0); PG8_MMA(0, 0, At, B0); PG8_BAR; PG8_SCHED;
;             PG8_LDB(B1, 0, 1); PG8_STAGE(PG8_SB(0, 0), b2, voffB);
;             PG8_BAR; PG8_WAIT_L(0); PG8_MMA(0, 1, At, B1); PG8_BAR;
;             PG8_LDA(At, 0, 1); PG8_STAGE(PG8_SA(0, 0), a2, voffA);
;             PG8_BAR; PG8_WAIT_L(0); PG8_MMA(1, 0, At, B0); PG8_BAR; PG8_SCHED;
;             PG8_STAGE(PG8_SB(0, 1), b2 + hstepB, voffB);
;             PG8_WAIT_V(6); PG8_BAR; PG8_MMA(1, 1, At, B1); PG8_BAR;
;             PG8_LDB(B0, 1, 0); PG8_SCHED; PG8_LDA(At, 1, 0); PG8_STAGE(PG8_SA(0, 1), a2 + hstepA, voffA);
;             PG8_WAIT_L(8); PG8_BAR; PG8_WAIT_L(0); PG8_MMA(0, 0, At, B0); PG8_BAR; PG8_SCHED;
;             PG8_LDB(B1, 1, 1); PG8_STAGE(PG8_SB(1, 0), b3, voffB);
;             PG8_BAR; PG8_WAIT_L(0); PG8_MMA(0, 1, At, B1); PG8_BAR;
;             PG8_LDA(At, 1, 1); PG8_STAGE(PG8_SA(1, 0), a3, voffA);
;             PG8_BAR; PG8_WAIT_L(0); PG8_MMA(1, 0, At, B0); PG8_BAR; PG8_SCHED;
;             PG8_STAGE(PG8_SB(1, 1), b3 + hstepB, voffB);
;             PG8_WAIT_V(6); PG8_BAR; PG8_MMA(1, 1, At, B1); PG8_BAR;
	s_waitcnt lgkmcnt(7)
	v_mfma_f32_16x16x32_bf16 v[60:63], v[72:75], v[160:163], v[60:63]
	v_mfma_f32_16x16x32_bf16 v[56:59], v[80:83], v[160:163], v[56:59]
	s_waitcnt lgkmcnt(5)
	v_mfma_f32_16x16x32_bf16 v[44:47], v[72:75], v[174:177], v[44:47]
	v_mfma_f32_16x16x32_bf16 v[40:43], v[80:83], v[174:177], v[40:43]
	s_waitcnt lgkmcnt(3)
	v_mfma_f32_16x16x32_bf16 v[28:31], v[72:75], v[182:185], v[28:31]
	v_mfma_f32_16x16x32_bf16 v[24:27], v[80:83], v[182:185], v[24:27]
	s_waitcnt lgkmcnt(1)
	v_mfma_f32_16x16x32_bf16 v[12:15], v[72:75], v[190:193], v[12:15]
	v_mfma_f32_16x16x32_bf16 v[8:11], v[80:83], v[190:193], v[8:11]
	v_mfma_f32_16x16x32_bf16 v[60:63], v[76:79], v[170:173], v[60:63]
	s_add_u32 s26, s26, 0x20080
	s_addc_u32 s27, s27, 0
	v_mfma_f32_16x16x32_bf16 v[56:59], v[84:87], v[170:173], v[56:59]
	s_add_i32 s28, s28, s34
	v_mfma_f32_16x16x32_bf16 v[44:47], v[76:79], v[178:181], v[44:47]
	v_mfma_f32_16x16x32_bf16 v[40:43], v[84:87], v[178:181], v[40:43]
	v_mfma_f32_16x16x32_bf16 v[28:31], v[76:79], v[186:189], v[28:31]
	v_mfma_f32_16x16x32_bf16 v[24:27], v[84:87], v[186:189], v[24:27]
	s_waitcnt lgkmcnt(0)
	v_mfma_f32_16x16x32_bf16 v[12:15], v[76:79], v[198:201], v[12:15]
	v_mfma_f32_16x16x32_bf16 v[8:11], v[84:87], v[198:201], v[8:11]
	s_barrier
	s_setprio 0
	s_mov_b32 m0, s28
	s_nop 0
	global_load_lds_dwordx4 v148, s[26:27]
	s_add_i32 m0, s28, 0x2000
	s_nop 0
	global_load_lds_dwordx4 v144, s[26:27]
	s_waitcnt vmcnt(6)
	s_setprio 1
	s_barrier
	v_mfma_f32_16x16x32_bf16 v[52:55], v[202:205], v[160:163], v[52:55]
	v_mfma_f32_16x16x32_bf16 v[48:51], v[210:213], v[160:163], v[48:51]
	ds_read_b128 v[72:75], v167
	v_mfma_f32_16x16x32_bf16 v[36:39], v[202:205], v[174:177], v[36:39]
	v_mfma_f32_16x16x32_bf16 v[32:35], v[210:213], v[174:177], v[32:35]
	ds_read_b128 v[76:79], v167 offset:1024
	v_mfma_f32_16x16x32_bf16 v[20:23], v[202:205], v[182:185], v[20:23]
	v_mfma_f32_16x16x32_bf16 v[16:19], v[210:213], v[182:185], v[16:19]
	ds_read_b128 v[80:83], v167 offset:2048
	v_mfma_f32_16x16x32_bf16 v[4:7], v[202:205], v[190:193], v[4:7]
	v_mfma_f32_16x16x32_bf16 v[0:3], v[210:213], v[190:193], v[0:3]
	ds_read_b128 v[84:87], v167 offset:3072
	v_mfma_f32_16x16x32_bf16 v[52:55], v[206:209], v[170:173], v[52:55]
	s_add_i32 s57, s57, 2
	v_mfma_f32_16x16x32_bf16 v[48:51], v[214:217], v[170:173], v[48:51]
	s_add_u32 s55, s55, 0x100
	s_addc_u32 s56, s56, 0
	v_mfma_f32_16x16x32_bf16 v[36:39], v[206:209], v[178:181], v[36:39]
	s_add_u32 s24, s24, 0x100
	s_addc_u32 s25, s25, 0
	v_mfma_f32_16x16x32_bf16 v[32:35], v[214:217], v[178:181], v[32:35]
	s_add_u32 s26, s24, 0xfff80080
	s_addc_u32 s27, s25, -1
	s_cmp_eq_u32 s57, 4
	s_cselect_b32 s29, s17, s27
	s_cselect_b32 s28, s43, s26
	s_cselect_b32 s27, s53, s56
	s_cselect_b32 s26, s54, s55
	s_cmp_gt_u32 s57, 5
	v_mfma_f32_16x16x32_bf16 v[20:23], v[206:209], v[186:189], v[20:23]
	v_mfma_f32_16x16x32_bf16 v[16:19], v[214:217], v[186:189], v[16:19]
	v_mfma_f32_16x16x32_bf16 v[4:7], v[206:209], v[198:201], v[4:7]
	v_mfma_f32_16x16x32_bf16 v[0:3], v[214:217], v[198:201], v[0:3]
	s_barrier
	s_setprio 0
	s_cbranch_scc0 .LBB1_229
	s_waitcnt lgkmcnt(0)
	s_lshl_b32 s17, s42, 8
	v_mov_b32_e32 v170, v164
	v_mov_b32_e32 v72, v165
	s_or_b32 s17, s17, s38
	v_mov_b32_e32 v80, 1.0
	v_lshl_add_u32 v160, v72, 3, s17
	v_ashrrev_i32_e32 v161, 31, v160
	v_cndmask_b32_e64 v72, 0, 1, s[14:15]
	v_lshl_add_u64 v[162:163], v[160:161], 2, s[8:9]
	v_cmp_ne_u32_e64 s[42:43], 1, v72
	s_andn2_b64 vcc, exec, s[14:15]
	v_mov_b32_e32 v84, 1.0
	v_mov_b32_e32 v85, 1.0
	v_mov_b32_e32 v86, 1.0
	v_mov_b32_e32 v87, 1.0
	s_cbranch_vccnz .LBB1_232
	global_load_dwordx4 v[84:87], v[162:163], off

;     DI const char* a(const Unit& u) const { return (const char*)(A + (size_t)u.pm * BM * lda); }
;     DI const char* a(const Unit& u) const { return (const char*)(A + (size_t)u.pm * BM * 2048 + (u.pn >> 1) * 512); }
;     DI const char* a(const Unit& u) const { return (const char*)((u.pn < 12 ? A1 : A2) + (size_t)u.pm * BM * 512); }
; #define PG8_STAGE(bufoff, gbase, voff) do { _Pragma("unroll") for (int _i = 0; _i < 2; ++_i) \
;         __builtin_amdgcn_global_load_lds((const unsigned*)((const char*)(gbase) + (voff)[_i]), (LAS unsigned*)(lds + (bufoff) + ldsw + _i * 8192), 16, 0, 0); } while (0)
; #define PG8_WAIT_V(n) asm volatile("s_waitcnt vmcnt(" #n ")" ::: "memory")
; #define PG8_BAR __builtin_amdgcn_s_barrier()
; template <class Map, class Epi>
; DI void gemm_phase(LAS unsigned char* lds, const Map& MP, const Epi& E, const int nM, const int nN, const int K, const int lda, const int ldb) {
;     ...
;         const bool has_next = sched_next(ui + 1, nM, nN, G, cblk, nxt);
;         const char* nA = has_next ? MP.a(nxt) : cA; const char* nB = has_next ? MP.b(nxt) : cB;
;         for (int t = 0; t < nt; t += 2) {
;             const bool last = (t == nt - 2);
;             const char* a1 = cA + (size_t)(t + 1) * kstep;
;             const char* a2 = last ? nA : cA + (size_t)(t + 2) * kstep; const char* b2 = last ? nB : cB + (size_t)(t + 2) * kstep;
;             const char* a3 = a2 + kstep; const char* b3 = b2 + kstep;
;             PG8_LDB(B0, 0, 0); PG8_SCHED; PG8_LDA(At, 0, 0); PG8_STAGE(PG8_SA(1, 1), a1 + hstepA, voffA);
;             PG8_WAIT_L(8); PG8_BAR; PG8_WAIT_L(0); PG8_MMA(0, 0, At, B0); PG8_BAR; PG8_SCHED;
;             PG8_LDB(B1, 0, 1); PG8_STAGE(PG8_SB(0, 0), b2, voffB);
;             PG8_BAR; PG8_WAIT_L(0); PG8_MMA(0, 1, At, B1); PG8_BAR;
;             PG8_LDA(At, 0, 1); PG8_STAGE(PG8_SA(0, 0), a2, voffA);
;             PG8_BAR; PG8_WAIT_L(0); PG8_MMA(1, 0, At, B0); PG8_BAR; PG8_SCHED;
;             PG8_STAGE(PG8_SB(0, 1), b2 + hstepB, voffB);
;             PG8_WAIT_V(6); PG8_BAR; PG8_MMA(1, 1, At, B1); PG8_BAR;
;     ...
; #pragma unroll
;         for (int a = 0; a < 2; ++a)
; #pragma unroll
;             for (int b = 0; b < 2; ++b)
; #pragma unroll
;                 for (int m = 0; m < 4; ++m)
; #pragma unroll
;                     for (int n = 0; n < 2; ++n) acc[a][b][m][n] = (f32x4){0.f, 0.f, 0.f, 0.f};
;         cur = nxt; cA = nA; cB = nB; ++ui;
.LBB1_692:
	s_ashr_i32 s15, s14, 31
	v_cmp_lt_i64_e32 vcc, s[16:17], v[140:141]
	s_lshl_b64 s[16:17], s[14:15], 20
	s_add_u32 s16, s5, s16
	s_addc_u32 s17, s26, s17
	s_and_b64 s[18:19], vcc, exec
	s_cselect_b32 s15, s17, s23
	s_cselect_b32 s48, s16, s22
	s_ashr_i32 s13, s12, 31
	s_lshl_b64 s[18:19], s[12:13], 20
	s_add_u32 s18, s27, s18
	s_addc_u32 s19, s28, s19
	s_and_b64 s[24:25], vcc, exec
	s_cselect_b32 s13, s19, s21
	s_cselect_b32 s49, s18, s20
	s_add_u32 s52, s20, 0x100
	s_addc_u32 s53, s21, 0
	s_add_u32 s20, s22, 0x80080
	v_mov_b32_e32 v0, 0
	s_addc_u32 s21, s23, 0
	s_mov_b32 s54, -2
	v_mov_b32_e32 v1, 0
	v_mov_b64_e32 v[2:3], 0
	v_mov_b64_e32 v[4:5], 0
	v_mov_b64_e32 v[6:7], 0
	v_mov_b64_e32 v[8:9], 0
	v_mov_b64_e32 v[10:11], 0
	v_mov_b64_e32 v[12:13], 0
	v_mov_b64_e32 v[14:15], 0
	v_mov_b64_e32 v[16:17], 0
	v_mov_b64_e32 v[18:19], 0
	v_mov_b64_e32 v[20:21], 0
	v_mov_b64_e32 v[22:23], 0
	v_mov_b64_e32 v[24:25], 0
	v_mov_b64_e32 v[26:27], 0
	v_mov_b64_e32 v[28:29], 0
	v_mov_b64_e32 v[30:31], 0
	v_mov_b64_e32 v[32:33], 0
	v_mov_b64_e32 v[34:35], 0
	v_mov_b64_e32 v[36:37], 0
	v_mov_b64_e32 v[38:39], 0
	v_mov_b64_e32 v[40:41], 0
	v_mov_b64_e32 v[42:43], 0
	v_mov_b64_e32 v[44:45], 0
	v_mov_b64_e32 v[46:47], 0
	v_mov_b64_e32 v[48:49], 0
	v_mov_b64_e32 v[50:51], 0
	v_mov_b64_e32 v[52:53], 0
	v_mov_b64_e32 v[54:55], 0
	v_mov_b64_e32 v[56:57], 0
	v_mov_b64_e32 v[58:59], 0
	v_mov_b64_e32 v[60:61], 0
	v_mov_b64_e32 v[62:63], 0
	v_mov_b64_e32 v[64:65], 0
	v_mov_b64_e32 v[66:67], 0
	v_mov_b64_e32 v[68:69], 0
	v_mov_b64_e32 v[70:71], 0
	v_mov_b64_e32 v[72:73], 0
	v_mov_b64_e32 v[74:75], 0
	v_mov_b64_e32 v[76:77], 0
	v_mov_b64_e32 v[78:79], 0
	v_mov_b64_e32 v[80:81], 0
	v_mov_b64_e32 v[82:83], 0
	v_mov_b64_e32 v[84:85], 0
	v_mov_b64_e32 v[86:87], 0
	v_mov_b64_e32 v[88:89], 0
	v_mov_b64_e32 v[90:91], 0
	v_mov_b64_e32 v[92:93], 0
	v_mov_b64_e32 v[94:95], 0
	v_mov_b64_e32 v[96:97], 0
	v_mov_b64_e32 v[98:99], 0
	v_mov_b64_e32 v[100:101], 0
	v_mov_b64_e32 v[102:103], 0
	v_mov_b64_e32 v[104:105], 0
	v_mov_b64_e32 v[106:107], 0
	v_mov_b64_e32 v[108:109], 0
	v_mov_b64_e32 v[110:111], 0
	v_mov_b64_e32 v[112:113], 0
	v_mov_b64_e32 v[114:115], 0
	v_mov_b64_e32 v[116:117], 0
	v_mov_b64_e32 v[118:119], 0
	v_mov_b64_e32 v[120:121], 0
	v_mov_b64_e32 v[122:123], 0
	v_mov_b64_e32 v[124:125], 0
	v_mov_b64_e32 v[126:127], 0
	ds_read_b128 v[150:153], v147
	ds_read_b128 v[154:157], v147 offset:1024
	ds_read_b128 v[158:161], v147 offset:2048
	ds_read_b128 v[162:165], v147 offset:3072
	s_add_u32 s3, s20, 0xfff80080
	s_addc_u32 s22, s21, -1
	s_cmp_eq_u32 s54, 28
	s_cselect_b32 s25, s15, s22
	s_cselect_b32 s24, s48, s3
	s_cselect_b32 s23, s13, s53
	s_cselect_b32 s22, s49, s52
.LBB1_693:
	s_add_i32 m0, s31, 0xc000
	ds_read_b128 v[166:169], v148
	ds_read_b128 v[170:173], v148 offset:1024
	ds_read_b128 v[174:177], v148 offset:2048
	ds_read_b128 v[178:181], v148 offset:3072
	ds_read_b128 v[182:185], v148 offset:4096
	ds_read_b128 v[186:189], v148 offset:5120
	ds_read_b128 v[190:193], v148 offset:6144
	ds_read_b128 v[198:201], v148 offset:7168
	global_load_lds_dwordx4 v138, s[20:21]
	s_add_i32 m0, s31, 0xe000
	s_nop 0
	global_load_lds_dwordx4 v136, s[20:21]
	s_waitcnt lgkmcnt(8)
	s_setprio 1
	s_barrier
	s_waitcnt lgkmcnt(7)
	v_mfma_f32_16x16x32_bf16 v[124:127], v[150:153], v[166:169], v[124:127]
	v_mfma_f32_16x16x32_bf16 v[120:123], v[158:161], v[166:169], v[120:123]
	s_waitcnt lgkmcnt(5)
	v_mfma_f32_16x16x32_bf16 v[116:119], v[150:153], v[174:177], v[116:119]
	v_mfma_f32_16x16x32_bf16 v[112:115], v[158:161], v[174:177], v[112:115]
	s_waitcnt lgkmcnt(3)
	v_mfma_f32_16x16x32_bf16 v[100:103], v[150:153], v[182:185], v[100:103]
	v_mfma_f32_16x16x32_bf16 v[96:99], v[158:161], v[182:185], v[96:99]
	s_waitcnt lgkmcnt(1)
	v_mfma_f32_16x16x32_bf16 v[84:87], v[150:153], v[190:193], v[84:87]
	v_mfma_f32_16x16x32_bf16 v[80:83], v[158:161], v[190:193], v[80:83]
	v_mfma_f32_16x16x32_bf16 v[124:127], v[154:157], v[170:173], v[124:127]
	s_add_i32 s3, s44, s29
	v_mfma_f32_16x16x32_bf16 v[120:123], v[162:165], v[170:173], v[120:123]
	v_lshl_add_u64 v[194:195], s[22:23], 0, v[132:133]
	v_mfma_f32_16x16x32_bf16 v[116:119], v[154:157], v[178:181], v[116:119]
	v_lshl_add_u64 v[218:219], s[22:23], 0, v[128:129]
	v_mfma_f32_16x16x32_bf16 v[112:115], v[162:165], v[178:181], v[112:115]
	v_mfma_f32_16x16x32_bf16 v[100:103], v[154:157], v[186:189], v[100:103]
	v_mfma_f32_16x16x32_bf16 v[96:99], v[162:165], v[186:189], v[96:99]
	s_waitcnt lgkmcnt(0)
	v_mfma_f32_16x16x32_bf16 v[84:87], v[154:157], v[198:201], v[84:87]
	v_mfma_f32_16x16x32_bf16 v[80:83], v[162:165], v[198:201], v[80:83]
	s_barrier
	s_setprio 0
	s_mov_b32 m0, s3
	ds_read_b128 v[202:205], v149
	ds_read_b128 v[206:209], v149 offset:1024
	ds_read_b128 v[210:213], v149 offset:2048
	ds_read_b128 v[214:217], v149 offset:3072
	global_load_lds_dwordx4 v[194:195], off
	s_add_i32 m0, s3, 0x2000
	s_nop 0
	global_load_lds_dwordx4 v[218:219], off
	s_setprio 1
	s_barrier
	s_waitcnt lgkmcnt(3)
	v_mfma_f32_16x16x32_bf16 v[108:111], v[202:205], v[166:169], v[108:111]
	s_waitcnt lgkmcnt(1)
	v_mfma_f32_16x16x32_bf16 v[104:107], v[210:213], v[166:169], v[104:107]
	v_mfma_f32_16x16x32_bf16 v[92:95], v[202:205], v[174:177], v[92:95]
	v_mfma_f32_16x16x32_bf16 v[88:91], v[210:213], v[174:177], v[88:91]
	v_mfma_f32_16x16x32_bf16 v[76:79], v[202:205], v[182:185], v[76:79]
	v_mfma_f32_16x16x32_bf16 v[72:75], v[210:213], v[182:185], v[72:75]
	v_mfma_f32_16x16x32_bf16 v[68:71], v[202:205], v[190:193], v[68:71]
	v_mfma_f32_16x16x32_bf16 v[64:67], v[210:213], v[190:193], v[64:67]
	v_mfma_f32_16x16x32_bf16 v[108:111], v[206:209], v[170:173], v[108:111]
	v_lshl_add_u64 v[222:223], s[24:25], 0, v[130:131]
	s_mov_b32 m0, s31
	s_waitcnt lgkmcnt(0)
	v_mfma_f32_16x16x32_bf16 v[104:107], v[214:217], v[170:173], v[104:107]
	v_lshl_add_u64 v[220:221], s[24:25], 0, v[134:135]
	v_mfma_f32_16x16x32_bf16 v[92:95], v[206:209], v[178:181], v[92:95]
	v_mfma_f32_16x16x32_bf16 v[88:91], v[214:217], v[178:181], v[88:91]
	v_mfma_f32_16x16x32_bf16 v[76:79], v[206:209], v[186:189], v[76:79]
	v_mfma_f32_16x16x32_bf16 v[72:75], v[214:217], v[186:189], v[72:75]
	v_mfma_f32_16x16x32_bf16 v[68:71], v[206:209], v[198:201], v[68:71]
	v_mfma_f32_16x16x32_bf16 v[64:67], v[214:217], v[198:201], v[64:67]
	s_barrier
; #define PG8_STAGE(bufoff, gbase, voff) do { _Pragma("unroll") for (int _i = 0; _i < 2; ++_i) \
;         __builtin_amdgcn_global_load_lds((const unsigned*)((const char*)(gbase) + (voff)[_i]), (LAS unsigned*)(lds + (bufoff) + ldsw + _i * 8192), 16, 0, 0); } while (0)
; #define PG8_LDA(dst, b, h) do { _Pragma("unroll") for (int m = 0; m < 4; ++m) _Pragma("unroll") for (int k = 0; k < 2; ++k) dst[m][k] = *(const LAS bf16x8*)(lds + PG8_SA(b, h) + aoff + m * 2048 + k * 1024); } while (0)
; #define PG8_LDB(dst, b, h) do { _Pragma("unroll") for (int n = 0; n < 2; ++n) _Pragma("unroll") for (int k = 0; k < 2; ++k) dst[n][k] = *(const LAS bf16x8*)(lds + PG8_SB(b, h) + boff + n * 2048 + k * 1024); } while (0)
; #define PG8_MMA(ai, bj, At, Bt) do { __builtin_amdgcn_s_setprio(1); _Pragma("unroll") for (int m = 0; m < 4; ++m) _Pragma("unroll") for (int n = 0; n < 2; ++n) _Pragma("unroll") for (int k = 0; k < 2; ++k) \
;         acc[ai][bj][m][n] = __builtin_amdgcn_mfma_f32_16x16x32_bf16(Bt[n][k], At[m][k], acc[ai][bj][m][n], 0, 0, 0); __builtin_amdgcn_s_setprio(0); } while (0)
; #define PG8_WAIT_V(n) asm volatile("s_waitcnt vmcnt(" #n ")" ::: "memory")
; #define PG8_WAIT_L(n) asm volatile("s_waitcnt lgkmcnt(" #n ")" ::: "memory")
; #define PG8_BAR __builtin_amdgcn_s_barrier()
; #define PG8_SCHED __builtin_amdgcn_sched_barrier(0)
; template <class Map, class Epi>
; DI void gemm_phase(LAS unsigned char* lds, const Map& MP, const Epi& E, const int nM, const int nN, const int K, const int lda, const int ldb) {
;     ...
;             PG8_LDB(B1, 0, 1); PG8_STAGE(PG8_SB(0, 0), b2, voffB);
;             PG8_BAR; PG8_WAIT_L(0); PG8_MMA(0, 1, At, B1); PG8_BAR;
;             PG8_LDA(At, 0, 1); PG8_STAGE(PG8_SA(0, 0), a2, voffA);
;             PG8_BAR; PG8_WAIT_L(0); PG8_MMA(1, 0, At, B0); PG8_BAR; PG8_SCHED;
;             PG8_STAGE(PG8_SB(0, 1), b2 + hstepB, voffB);
;             PG8_WAIT_V(6); PG8_BAR; PG8_MMA(1, 1, At, B1); PG8_BAR;
;             PG8_LDB(B0, 1, 0); PG8_SCHED; PG8_LDA(At, 1, 0); PG8_STAGE(PG8_SA(0, 1), a2 + hstepA, voffA);
;             PG8_WAIT_L(8); PG8_BAR; PG8_WAIT_L(0); PG8_MMA(0, 0, At, B0); PG8_BAR; PG8_SCHED;
;             PG8_LDB(B1, 1, 1); PG8_STAGE(PG8_SB(1, 0), b3, voffB);
;             PG8_BAR; PG8_WAIT_L(0); PG8_MMA(0, 1, At, B1); PG8_BAR;
;             PG8_LDA(At, 1, 1); PG8_STAGE(PG8_SA(1, 0), a3, voffA);
	s_setprio 0
	ds_read_b128 v[166:169], v148 offset:16384
	ds_read_b128 v[170:173], v148 offset:17408
	ds_read_b128 v[174:177], v148 offset:18432
	ds_read_b128 v[178:181], v148 offset:19456
	ds_read_b128 v[182:185], v148 offset:20480
	ds_read_b128 v[186:189], v148 offset:21504
	ds_read_b128 v[190:193], v148 offset:22528
	ds_read_b128 v[198:201], v148 offset:23552
	global_load_lds_dwordx4 v[220:221], off
	s_mov_b32 m0, s11
	s_nop 0
	global_load_lds_dwordx4 v[222:223], off
	s_waitcnt vmcnt(10)
	s_setprio 1
	s_barrier
	s_waitcnt lgkmcnt(7)
	v_mfma_f32_16x16x32_bf16 v[60:63], v[150:153], v[166:169], v[60:63]
	v_mfma_f32_16x16x32_bf16 v[56:59], v[158:161], v[166:169], v[56:59]
	s_waitcnt lgkmcnt(5)
	v_mfma_f32_16x16x32_bf16 v[52:55], v[150:153], v[174:177], v[52:55]
	v_mfma_f32_16x16x32_bf16 v[48:51], v[158:161], v[174:177], v[48:51]
	s_waitcnt lgkmcnt(3)
	v_mfma_f32_16x16x32_bf16 v[36:39], v[150:153], v[182:185], v[36:39]
	v_mfma_f32_16x16x32_bf16 v[32:35], v[158:161], v[182:185], v[32:35]
	s_waitcnt lgkmcnt(1)
	v_mfma_f32_16x16x32_bf16 v[20:23], v[150:153], v[190:193], v[20:23]
	v_mfma_f32_16x16x32_bf16 v[16:19], v[158:161], v[190:193], v[16:19]
	v_mfma_f32_16x16x32_bf16 v[60:63], v[154:157], v[170:173], v[60:63]
	s_add_u32 s56, s22, 0x80000
	s_addc_u32 s57, s23, 0
	v_mfma_f32_16x16x32_bf16 v[56:59], v[162:165], v[170:173], v[56:59]
	s_add_i32 s3, s45, s29
	v_mfma_f32_16x16x32_bf16 v[52:55], v[154:157], v[178:181], v[52:55]
	v_mfma_f32_16x16x32_bf16 v[48:51], v[162:165], v[178:181], v[48:51]
	v_mfma_f32_16x16x32_bf16 v[36:39], v[154:157], v[186:189], v[36:39]
	v_mfma_f32_16x16x32_bf16 v[32:35], v[162:165], v[186:189], v[32:35]
	s_waitcnt lgkmcnt(0)
	v_mfma_f32_16x16x32_bf16 v[20:23], v[154:157], v[198:201], v[20:23]
	v_mfma_f32_16x16x32_bf16 v[16:19], v[162:165], v[198:201], v[16:19]
	s_barrier
	s_setprio 0
	s_mov_b32 m0, s3
	s_nop 0
	global_load_lds_dwordx4 v132, s[56:57]
	s_add_i32 m0, s3, 0x2000
	s_nop 0
	global_load_lds_dwordx4 v128, s[56:57]
	s_waitcnt vmcnt(6)
	s_setprio 1
	s_barrier
	v_mfma_f32_16x16x32_bf16 v[44:47], v[202:205], v[166:169], v[44:47]
	v_mfma_f32_16x16x32_bf16 v[40:43], v[210:213], v[166:169], v[40:43]
	s_add_i32 s3, 0, 0x18000
	v_add_u32_e32 v162, s3, v146
	ds_read_b128 v[150:153], v162
	v_mfma_f32_16x16x32_bf16 v[28:31], v[202:205], v[174:177], v[28:31]
	v_mfma_f32_16x16x32_bf16 v[24:27], v[210:213], v[174:177], v[24:27]
	ds_read_b128 v[154:157], v162 offset:1024
	v_mfma_f32_16x16x32_bf16 v[12:15], v[202:205], v[182:185], v[12:15]
	v_mfma_f32_16x16x32_bf16 v[8:11], v[210:213], v[182:185], v[8:11]
	ds_read_b128 v[158:161], v162 offset:2048
	v_mfma_f32_16x16x32_bf16 v[4:7], v[202:205], v[190:193], v[4:7]
	v_mfma_f32_16x16x32_bf16 v[0:3], v[210:213], v[190:193], v[0:3]
	ds_read_b128 v[162:165], v162 offset:3072
	v_mfma_f32_16x16x32_bf16 v[44:47], v[206:209], v[170:173], v[44:47]
	s_add_u32 s24, s24, 0x80000
	s_addc_u32 s25, s25, 0
	v_mfma_f32_16x16x32_bf16 v[40:43], v[214:217], v[170:173], v[40:43]
	v_mfma_f32_16x16x32_bf16 v[28:31], v[206:209], v[178:181], v[28:31]
	v_mfma_f32_16x16x32_bf16 v[24:27], v[214:217], v[178:181], v[24:27]
	v_mfma_f32_16x16x32_bf16 v[12:15], v[206:209], v[186:189], v[12:15]
	v_mfma_f32_16x16x32_bf16 v[8:11], v[214:217], v[186:189], v[8:11]
	v_mfma_f32_16x16x32_bf16 v[4:7], v[206:209], v[198:201], v[4:7]
	v_mfma_f32_16x16x32_bf16 v[0:3], v[214:217], v[198:201], v[0:3]
	s_barrier
	s_setprio 0
	s_mov_b32 m0, s34
	ds_read_b128 v[166:169], v148 offset:32768
	ds_read_b128 v[170:173], v148 offset:33792
	ds_read_b128 v[174:177], v148 offset:34816
	ds_read_b128 v[178:181], v148 offset:35840
	ds_read_b128 v[182:185], v148 offset:36864
	ds_read_b128 v[186:189], v148 offset:37888
	ds_read_b128 v[190:193], v148 offset:38912
	ds_read_b128 v[198:201], v148 offset:39936
	global_load_lds_dwordx4 v134, s[24:25]
	s_mov_b32 m0, s35
	s_nop 0
	global_load_lds_dwordx4 v130, s[24:25]
	s_waitcnt lgkmcnt(8)
	s_setprio 1
	s_barrier
	s_waitcnt lgkmcnt(7)
	v_mfma_f32_16x16x32_bf16 v[124:127], v[150:153], v[166:169], v[124:127]
	v_mfma_f32_16x16x32_bf16 v[120:123], v[158:161], v[166:169], v[120:123]
	s_waitcnt lgkmcnt(5)
	v_mfma_f32_16x16x32_bf16 v[116:119], v[150:153], v[174:177], v[116:119]
	v_mfma_f32_16x16x32_bf16 v[112:115], v[158:161], v[174:177], v[112:115]
	s_waitcnt lgkmcnt(3)
	v_mfma_f32_16x16x32_bf16 v[100:103], v[150:153], v[182:185], v[100:103]
	v_mfma_f32_16x16x32_bf16 v[96:99], v[158:161], v[182:185], v[96:99]
	s_waitcnt lgkmcnt(1)
	v_mfma_f32_16x16x32_bf16 v[84:87], v[150:153], v[190:193], v[84:87]
	v_mfma_f32_16x16x32_bf16 v[80:83], v[158:161], v[190:193], v[80:83]
	v_mfma_f32_16x16x32_bf16 v[124:127], v[154:157], v[170:173], v[124:127]
	s_add_i32 s24, 0, 0x1c000
	v_mfma_f32_16x16x32_bf16 v[120:123], v[162:165], v[170:173], v[120:123]
	s_add_i32 s3, s3, s29
	v_mfma_f32_16x16x32_bf16 v[116:119], v[154:157], v[178:181], v[116:119]
	v_add_u32_e32 v196, s24, v146
	v_mfma_f32_16x16x32_bf16 v[112:115], v[162:165], v[178:181], v[112:115]
	v_lshl_add_u64 v[194:195], v[194:195], 0, s[8:9]
	v_mfma_f32_16x16x32_bf16 v[100:103], v[154:157], v[186:189], v[100:103]
	v_mfma_f32_16x16x32_bf16 v[96:99], v[162:165], v[186:189], v[96:99]
	s_waitcnt lgkmcnt(0)
	v_mfma_f32_16x16x32_bf16 v[84:87], v[154:157], v[198:201], v[84:87]
	v_mfma_f32_16x16x32_bf16 v[80:83], v[162:165], v[198:201], v[80:83]
	s_barrier
	s_setprio 0
	s_mov_b32 m0, s3
	ds_read_b128 v[202:205], v196
	ds_read_b128 v[206:209], v196 offset:1024
	ds_read_b128 v[210:213], v196 offset:2048
	ds_read_b128 v[214:217], v196 offset:3072
	global_load_lds_dwordx4 v[194:195], off
	v_lshl_add_u64 v[194:195], v[218:219], 0, s[8:9]
	s_add_i32 m0, s3, 0x2000
	s_nop 0
	global_load_lds_dwordx4 v[194:195], off
	s_setprio 1
	s_barrier
; #define PG8_STAGE(bufoff, gbase, voff) do { _Pragma("unroll") for (int _i = 0; _i < 2; ++_i) \
;         __builtin_amdgcn_global_load_lds((const unsigned*)((const char*)(gbase) + (voff)[_i]), (LAS unsigned*)(lds + (bufoff) + ldsw + _i * 8192), 16, 0, 0); } while (0)
; #define PG8_LDA(dst, b, h) do { _Pragma("unroll") for (int m = 0; m < 4; ++m) _Pragma("unroll") for (int k = 0; k < 2; ++k) dst[m][k] = *(const LAS bf16x8*)(lds + PG8_SA(b, h) + aoff + m * 2048 + k * 1024); } while (0)
; #define PG8_LDB(dst, b, h) do { _Pragma("unroll") for (int n = 0; n < 2; ++n) _Pragma("unroll") for (int k = 0; k < 2; ++k) dst[n][k] = *(const LAS bf16x8*)(lds + PG8_SB(b, h) + boff + n * 2048 + k * 1024); } while (0)
; #define PG8_MMA(ai, bj, At, Bt) do { __builtin_amdgcn_s_setprio(1); _Pragma("unroll") for (int m = 0; m < 4; ++m) _Pragma("unroll") for (int n = 0; n < 2; ++n) _Pragma("unroll") for (int k = 0; k < 2; ++k) \
;         acc[ai][bj][m][n] = __builtin_amdgcn_mfma_f32_16x16x32_bf16(Bt[n][k], At[m][k], acc[ai][bj][m][n], 0, 0, 0); __builtin_amdgcn_s_setprio(0); } while (0)
; #define PG8_WAIT_V(n) asm volatile("s_waitcnt vmcnt(" #n ")" ::: "memory")
; #define PG8_WAIT_L(n) asm volatile("s_waitcnt lgkmcnt(" #n ")" ::: "memory")
; #define PG8_BAR __builtin_amdgcn_s_barrier()
; #define PG8_SCHED __builtin_amdgcn_sched_barrier(0)
; template <class Map, class Epi>
; DI void gemm_phase(LAS unsigned char* lds, const Map& MP, const Epi& E, const int nM, const int nN, const int K, const int lda, const int ldb) {
;     ...
;             const bool last = (t == nt - 2);
;             const char* a1 = cA + (size_t)(t + 1) * kstep;
;             const char* a2 = last ? nA : cA + (size_t)(t + 2) * kstep; const char* b2 = last ? nB : cB + (size_t)(t + 2) * kstep;
;     ...
;             PG8_LDB(B0, 1, 0); PG8_SCHED; PG8_LDA(At, 1, 0); PG8_STAGE(PG8_SA(0, 1), a2 + hstepA, voffA);
;             PG8_WAIT_L(8); PG8_BAR; PG8_WAIT_L(0); PG8_MMA(0, 0, At, B0); PG8_BAR; PG8_SCHED;
;             PG8_LDB(B1, 1, 1); PG8_STAGE(PG8_SB(1, 0), b3, voffB);
;             PG8_BAR; PG8_WAIT_L(0); PG8_MMA(0, 1, At, B1); PG8_BAR;
;             PG8_LDA(At, 1, 1); PG8_STAGE(PG8_SA(1, 0), a3, voffA);
;             PG8_BAR; PG8_WAIT_L(0); PG8_MMA(1, 0, At, B0); PG8_BAR; PG8_SCHED;
;             PG8_STAGE(PG8_SB(1, 1), b3 + hstepB, voffB);
;             PG8_WAIT_V(6); PG8_BAR; PG8_MMA(1, 1, At, B1); PG8_BAR;
	s_waitcnt lgkmcnt(3)
	v_mfma_f32_16x16x32_bf16 v[108:111], v[202:205], v[166:169], v[108:111]
	s_waitcnt lgkmcnt(1)
	v_mfma_f32_16x16x32_bf16 v[104:107], v[210:213], v[166:169], v[104:107]
	v_mfma_f32_16x16x32_bf16 v[92:95], v[202:205], v[174:177], v[92:95]
	v_mfma_f32_16x16x32_bf16 v[88:91], v[210:213], v[174:177], v[88:91]
	v_mfma_f32_16x16x32_bf16 v[76:79], v[202:205], v[182:185], v[76:79]
	v_mfma_f32_16x16x32_bf16 v[72:75], v[210:213], v[182:185], v[72:75]
	v_mfma_f32_16x16x32_bf16 v[68:71], v[202:205], v[190:193], v[68:71]
	v_mfma_f32_16x16x32_bf16 v[64:67], v[210:213], v[190:193], v[64:67]
	v_mfma_f32_16x16x32_bf16 v[108:111], v[206:209], v[170:173], v[108:111]
	s_mov_b32 m0, s39
	s_waitcnt lgkmcnt(0)
	v_mfma_f32_16x16x32_bf16 v[104:107], v[214:217], v[170:173], v[104:107]
	v_lshl_add_u64 v[194:195], v[220:221], 0, s[8:9]
	v_mfma_f32_16x16x32_bf16 v[92:95], v[206:209], v[178:181], v[92:95]
	v_mfma_f32_16x16x32_bf16 v[88:91], v[214:217], v[178:181], v[88:91]
	v_mfma_f32_16x16x32_bf16 v[76:79], v[206:209], v[186:189], v[76:79]
	v_mfma_f32_16x16x32_bf16 v[72:75], v[214:217], v[186:189], v[72:75]
	v_mfma_f32_16x16x32_bf16 v[68:71], v[206:209], v[198:201], v[68:71]
	v_mfma_f32_16x16x32_bf16 v[64:67], v[214:217], v[198:201], v[64:67]
	s_barrier
	s_setprio 0
	ds_read_b128 v[166:169], v148 offset:49152
	ds_read_b128 v[170:173], v148 offset:50176
	ds_read_b128 v[174:177], v148 offset:51200
	ds_read_b128 v[178:181], v148 offset:52224
	ds_read_b128 v[182:185], v148 offset:53248
	ds_read_b128 v[186:189], v148 offset:54272
	ds_read_b128 v[190:193], v148 offset:55296
	ds_read_b128 v[198:201], v148 offset:56320
	global_load_lds_dwordx4 v[194:195], off
	v_lshl_add_u64 v[194:195], v[222:223], 0, s[8:9]
	s_mov_b32 m0, s42
	s_nop 0
	global_load_lds_dwordx4 v[194:195], off
	s_waitcnt vmcnt(10)
	s_setprio 1
	s_barrier
	s_waitcnt lgkmcnt(7)
	v_mfma_f32_16x16x32_bf16 v[60:63], v[150:153], v[166:169], v[60:63]
	v_mfma_f32_16x16x32_bf16 v[56:59], v[158:161], v[166:169], v[56:59]
	s_waitcnt lgkmcnt(5)
	v_mfma_f32_16x16x32_bf16 v[52:55], v[150:153], v[174:177], v[52:55]
	v_mfma_f32_16x16x32_bf16 v[48:51], v[158:161], v[174:177], v[48:51]
	s_waitcnt lgkmcnt(3)
	v_mfma_f32_16x16x32_bf16 v[36:39], v[150:153], v[182:185], v[36:39]
	v_mfma_f32_16x16x32_bf16 v[32:35], v[158:161], v[182:185], v[32:35]
	s_waitcnt lgkmcnt(1)
	v_mfma_f32_16x16x32_bf16 v[20:23], v[150:153], v[190:193], v[20:23]
	v_mfma_f32_16x16x32_bf16 v[16:19], v[158:161], v[190:193], v[16:19]
	v_mfma_f32_16x16x32_bf16 v[60:63], v[154:157], v[170:173], v[60:63]
	s_add_u32 s22, s22, 0x80080
	s_addc_u32 s23, s23, 0
	v_mfma_f32_16x16x32_bf16 v[56:59], v[162:165], v[170:173], v[56:59]
	s_add_i32 s3, s24, s29
	v_mfma_f32_16x16x32_bf16 v[52:55], v[154:157], v[178:181], v[52:55]
	v_mfma_f32_16x16x32_bf16 v[48:51], v[162:165], v[178:181], v[48:51]
	v_mfma_f32_16x16x32_bf16 v[36:39], v[154:157], v[186:189], v[36:39]
	v_mfma_f32_16x16x32_bf16 v[32:35], v[162:165], v[186:189], v[32:35]
	s_waitcnt lgkmcnt(0)
	v_mfma_f32_16x16x32_bf16 v[20:23], v[154:157], v[198:201], v[20:23]
	v_mfma_f32_16x16x32_bf16 v[16:19], v[162:165], v[198:201], v[16:19]
	s_barrier
	s_setprio 0
	s_mov_b32 m0, s3
	s_nop 0
	global_load_lds_dwordx4 v132, s[22:23]
	s_add_i32 m0, s3, 0x2000
	s_nop 0
	global_load_lds_dwordx4 v128, s[22:23]
	s_waitcnt vmcnt(6)
	s_setprio 1
	s_barrier
	v_mfma_f32_16x16x32_bf16 v[44:47], v[202:205], v[166:169], v[44:47]
	v_mfma_f32_16x16x32_bf16 v[40:43], v[210:213], v[166:169], v[40:43]
	ds_read_b128 v[150:153], v147
	v_mfma_f32_16x16x32_bf16 v[28:31], v[202:205], v[174:177], v[28:31]
	v_mfma_f32_16x16x32_bf16 v[24:27], v[210:213], v[174:177], v[24:27]
	ds_read_b128 v[154:157], v147 offset:1024
	v_mfma_f32_16x16x32_bf16 v[12:15], v[202:205], v[182:185], v[12:15]
	v_mfma_f32_16x16x32_bf16 v[8:11], v[210:213], v[182:185], v[8:11]
	ds_read_b128 v[158:161], v147 offset:2048
	v_mfma_f32_16x16x32_bf16 v[4:7], v[202:205], v[190:193], v[4:7]
	v_mfma_f32_16x16x32_bf16 v[0:3], v[210:213], v[190:193], v[0:3]
	ds_read_b128 v[162:165], v147 offset:3072
	v_mfma_f32_16x16x32_bf16 v[44:47], v[206:209], v[170:173], v[44:47]
	s_add_i32 s54, s54, 2
	v_mfma_f32_16x16x32_bf16 v[40:43], v[214:217], v[170:173], v[40:43]
	s_add_u32 s52, s52, 0x100
	s_addc_u32 s53, s53, 0
	v_mfma_f32_16x16x32_bf16 v[28:31], v[206:209], v[178:181], v[28:31]
	s_add_u32 s20, s20, 0x100
	s_addc_u32 s21, s21, 0
	v_mfma_f32_16x16x32_bf16 v[24:27], v[214:217], v[178:181], v[24:27]
	s_add_u32 s3, s20, 0xfff80080
	s_addc_u32 s22, s21, -1
	s_cmp_eq_u32 s54, 28
	s_cselect_b32 s25, s15, s22
	s_cselect_b32 s24, s48, s3
	s_cselect_b32 s23, s13, s53
	s_cselect_b32 s22, s49, s52
	s_cmp_gt_u32 s54, 29
	v_mfma_f32_16x16x32_bf16 v[12:15], v[206:209], v[186:189], v[12:15]
	v_mfma_f32_16x16x32_bf16 v[8:11], v[214:217], v[186:189], v[8:11]
	v_mfma_f32_16x16x32_bf16 v[4:7], v[206:209], v[198:201], v[4:7]
	v_mfma_f32_16x16x32_bf16 v[0:3], v[214:217], v[198:201], v[0:3]
	s_barrier
; DI unsigned pack2(float a, float b) { f32x2 v = {a, b}; hwbf16x2 r = __builtin_convertvector(v, hwbf16x2); return __builtin_bit_cast(unsigned, r); }
;     DI const char* a(const Unit& u) const { return (const char*)(A + (size_t)u.pm * BM * lda); }
;     DI const char* a(const Unit& u) const { return (const char*)(A + (size_t)u.pm * BM * 2048 + (u.pn >> 1) * 512); }
;     DI const char* a(const Unit& u) const { return (const char*)((u.pn < 12 ? A1 : A2) + (size_t)u.pm * BM * 512); }
; #define PG8_WAIT_V(n) asm volatile("s_waitcnt vmcnt(" #n ")" ::: "memory")
; #define PG8_BAR __builtin_amdgcn_s_barrier()
;     DI void operator()(const f32x4 (&acc)[2][2][4][2], const Unit& u, int wr, int wc, int fr, int fq) const {
;         bf16_t* O = O1; int ldc = ldc1, pn = u.pn; if (pn >= split) { O = O2; ldc = ldc2; pn -= split; }
;         const int row0 = u.pm * BM + wr * 64 + fr, col0 = pn * BM + wc * 32 + 8 * fq;
; #pragma unroll
;         for (int ai = 0; ai < 2; ++ai)
; #pragma unroll
;             for (int m = 0; m < 4; ++m) { bf16_t* rowp = O + (size_t)(row0 + ai * HALF + m * 16) * ldc + col0;
; #pragma unroll
;                 for (int bj = 0; bj < 2; ++bj) { const f32x4 v0 = acc[ai][bj][m][0], v1 = acc[ai][bj][m][1];
;                     u32x4 o; o[0] = pack2(v0[0], v0[1]); o[1] = pack2(v0[2], v0[3]); o[2] = pack2(v1[0], v1[1]); o[3] = pack2(v1[2], v1[3]);
;                     *(u32x4*)(rowp + bj * HALF) = o; } }
; template <class Map, class Epi>
; DI void gemm_phase(LAS unsigned char* lds, const Map& MP, const Epi& E, const int nM, const int nN, const int K, const int lda, const int ldb) {
;     ...
;         { int frr = fr, fqq = fq; asm volatile("" : "+v"(frr), "+v"(fqq)); E(acc, cur, wr, wc, frr, fqq); }
;         if (!has_next) break;
; #pragma unroll
;         for (int a = 0; a < 2; ++a)
; #pragma unroll
;             for (int b = 0; b < 2; ++b)
; #pragma unroll
;                 for (int m = 0; m < 4; ++m)
; #pragma unroll
;                     for (int n = 0; n < 2; ++n) acc[a][b][m][n] = (f32x4){0.f, 0.f, 0.f, 0.f};
;         cur = nxt; cA = nA; cB = nB; ++ui;
;     }
;     PG8_WAIT_V(0);
;     if (wr == 0) PG8_BAR;
;     PG8_BAR;
	s_setprio 0
	s_cbranch_scc0 .LBB1_693
	s_waitcnt lgkmcnt(0)
	s_lshl_b32 s3, s10, 8
	v_mov_b32_e32 v150, v144
	v_mov_b32_e32 v151, v145
	s_add_i32 s3, s3, s37
	v_cvt_pk_bf16_f32 v68, v68, v69
	v_add_u32_e32 v154, s3, v150
	s_lshl_b32 s3, s47, 8
	s_or_b32 s3, s3, s38
	v_lshl_add_u32 v150, v151, 3, s3
	v_ashrrev_i32_e32 v151, 31, v150
	v_lshl_add_u64 v[150:151], v[150:151], 1, s[6:7]
	v_cvt_pk_bf16_f32 v69, v70, v71
	v_cvt_pk_bf16_f32 v70, v64, v65
	v_add_u32_e32 v64, 0x80, v154
	v_mad_i64_i32 v[152:153], s[20:21], v154, s46, v[150:151]
	v_cvt_pk_bf16_f32 v108, v108, v109
	v_cvt_pk_bf16_f32 v109, v110, v111
	v_cvt_pk_bf16_f32 v110, v104, v105
	v_cvt_pk_bf16_f32 v111, v106, v107
	v_add_u32_e32 v104, 16, v154
	v_mad_i64_i32 v[64:65], s[20:21], v64, s46, v[150:151]
	v_cvt_pk_bf16_f32 v44, v44, v45
	v_cvt_pk_bf16_f32 v45, v46, v47
	v_cvt_pk_bf16_f32 v46, v40, v41
	v_cvt_pk_bf16_f32 v47, v42, v43
	v_add_u32_e32 v40, 0x90, v154
	global_store_dwordx4 v[152:153], v[108:111], off offset:256
	v_cvt_pk_bf16_f32 v92, v92, v93
	v_cvt_pk_bf16_f32 v93, v94, v95
	v_mad_i64_i32 v[108:109], s[20:21], v104, s46, v[150:151]
	v_cvt_pk_bf16_f32 v94, v88, v89
	v_cvt_pk_bf16_f32 v95, v90, v91
	v_add_u32_e32 v88, 32, v154
	global_store_dwordx4 v[64:65], v[44:47], off offset:256
	v_cvt_pk_bf16_f32 v28, v28, v29
	v_cvt_pk_bf16_f32 v29, v30, v31
	v_mad_i64_i32 v[44:45], s[20:21], v40, s46, v[150:151]
	v_cvt_pk_bf16_f32 v30, v24, v25
	v_cvt_pk_bf16_f32 v31, v26, v27
	v_add_u32_e32 v24, 0xa0, v154
	global_store_dwordx4 v[108:109], v[92:95], off offset:256
	v_cvt_pk_bf16_f32 v76, v76, v77
	v_cvt_pk_bf16_f32 v77, v78, v79
	v_mad_i64_i32 v[92:93], s[20:21], v88, s46, v[150:151]
	v_cvt_pk_bf16_f32 v78, v72, v73
	v_cvt_pk_bf16_f32 v79, v74, v75
	v_add_u32_e32 v72, 48, v154
	global_store_dwordx4 v[44:45], v[28:31], off offset:256
	v_cvt_pk_bf16_f32 v12, v12, v13
	v_cvt_pk_bf16_f32 v13, v14, v15
	v_mad_i64_i32 v[28:29], s[20:21], v24, s46, v[150:151]
	v_cvt_pk_bf16_f32 v14, v8, v9
	v_cvt_pk_bf16_f32 v15, v10, v11
	v_add_u32_e32 v8, 0xb0, v154
	global_store_dwordx4 v[92:93], v[76:79], off offset:256
	global_store_dwordx4 v[28:29], v[12:15], off offset:256
	v_cvt_pk_bf16_f32 v124, v124, v125
	v_mad_i64_i32 v[76:77], s[20:21], v72, s46, v[150:151]
	v_mad_i64_i32 v[12:13], s[20:21], v8, s46, v[150:151]
	v_cvt_pk_bf16_f32 v125, v126, v127
	v_cvt_pk_bf16_f32 v126, v120, v121
	v_cvt_pk_bf16_f32 v127, v122, v123
	v_cvt_pk_bf16_f32 v104, v116, v117
	v_cvt_pk_bf16_f32 v105, v118, v119
	v_cvt_pk_bf16_f32 v106, v112, v113
	v_cvt_pk_bf16_f32 v107, v114, v115
	v_cvt_pk_bf16_f32 v88, v100, v101
	v_cvt_pk_bf16_f32 v89, v102, v103
	v_cvt_pk_bf16_f32 v90, v96, v97
	v_cvt_pk_bf16_f32 v91, v98, v99
	v_cvt_pk_bf16_f32 v72, v84, v85
	v_cvt_pk_bf16_f32 v73, v86, v87
	v_cvt_pk_bf16_f32 v74, v80, v81
	v_cvt_pk_bf16_f32 v75, v82, v83
	v_cvt_pk_bf16_f32 v71, v66, v67
	v_cvt_pk_bf16_f32 v60, v60, v61
	v_cvt_pk_bf16_f32 v61, v62, v63
	v_cvt_pk_bf16_f32 v62, v56, v57
	v_cvt_pk_bf16_f32 v63, v58, v59
	v_cvt_pk_bf16_f32 v40, v52, v53
	v_cvt_pk_bf16_f32 v41, v54, v55
	v_cvt_pk_bf16_f32 v42, v48, v49
	v_cvt_pk_bf16_f32 v43, v50, v51
	v_cvt_pk_bf16_f32 v24, v36, v37
	v_cvt_pk_bf16_f32 v25, v38, v39
	v_cvt_pk_bf16_f32 v26, v32, v33
	v_cvt_pk_bf16_f32 v27, v34, v35
	v_cvt_pk_bf16_f32 v8, v20, v21
	v_cvt_pk_bf16_f32 v9, v22, v23
	v_cvt_pk_bf16_f32 v10, v16, v17
	v_cvt_pk_bf16_f32 v11, v18, v19
	v_cvt_pk_bf16_f32 v4, v4, v5
	v_cvt_pk_bf16_f32 v5, v6, v7
	v_cvt_pk_bf16_f32 v6, v0, v1
	v_cvt_pk_bf16_f32 v7, v2, v3
	s_and_b64 vcc, exec, s[40:41]
	s_mov_b32 s47, s12
	s_mov_b32 s10, s14
	s_mov_b64 s[20:21], s[18:19]
	s_mov_b64 s[22:23], s[16:17]
	global_store_dwordx4 v[152:153], v[124:127], off
	global_store_dwordx4 v[108:109], v[104:107], off
	global_store_dwordx4 v[92:93], v[88:91], off
	global_store_dwordx4 v[76:77], v[72:75], off
	global_store_dwordx4 v[76:77], v[68:71], off offset:256
	global_store_dwordx4 v[64:65], v[60:63], off
	global_store_dwordx4 v[44:45], v[40:43], off
	global_store_dwordx4 v[28:29], v[24:27], off
	global_store_dwordx4 v[12:13], v[8:11], off
	global_store_dwordx4 v[12:13], v[4:7], off offset:256
	s_cbranch_vccz .LBB1_690
	s_waitcnt vmcnt(0)
	s_cmpk_gt_u32 s4, 0xff
	s_cbranch_scc1 .LBB1_697
	s_barrier

;     DI const char* a(const Unit& u) const { return (const char*)(A + (size_t)u.pm * BM * lda); }
;     DI const char* a(const Unit& u) const { return (const char*)(A + (size_t)u.pm * BM * 2048 + (u.pn >> 1) * 512); }
;     DI const char* a(const Unit& u) const { return (const char*)((u.pn < 12 ? A1 : A2) + (size_t)u.pm * BM * 512); }
; #define PG8_STAGE(bufoff, gbase, voff) do { _Pragma("unroll") for (int _i = 0; _i < 2; ++_i) \
;         __builtin_amdgcn_global_load_lds((const unsigned*)((const char*)(gbase) + (voff)[_i]), (LAS unsigned*)(lds + (bufoff) + ldsw + _i * 8192), 16, 0, 0); } while (0)
; #define PG8_LDA(dst, b, h) do { _Pragma("unroll") for (int m = 0; m < 4; ++m) _Pragma("unroll") for (int k = 0; k < 2; ++k) dst[m][k] = *(const LAS bf16x8*)(lds + PG8_SA(b, h) + aoff + m * 2048 + k * 1024); } while (0)
; template <class Map, class Epi>
; DI void gemm_phase(LAS unsigned char* lds, const Map& MP, const Epi& E, const int nM, const int nN, const int K, const int lda, const int ldb) {
;     ...
;         const bool has_next = sched_next(ui + 1, nM, nN, G, cblk, nxt);
;         const char* nA = has_next ? MP.a(nxt) : cA; const char* nB = has_next ? MP.b(nxt) : cB;
;         for (int t = 0; t < nt; t += 2) {
;             const bool last = (t == nt - 2);
;             const char* a1 = cA + (size_t)(t + 1) * kstep;
;             const char* a2 = last ? nA : cA + (size_t)(t + 2) * kstep; const char* b2 = last ? nB : cB + (size_t)(t + 2) * kstep;
;             const char* a3 = a2 + kstep; const char* b3 = b2 + kstep;
;             PG8_LDB(B0, 0, 0); PG8_SCHED; PG8_LDA(At, 0, 0); PG8_STAGE(PG8_SA(1, 1), a1 + hstepA, voffA);
;             PG8_WAIT_L(8); PG8_BAR; PG8_WAIT_L(0); PG8_MMA(0, 0, At, B0); PG8_BAR; PG8_SCHED;
;             PG8_LDB(B1, 0, 1); PG8_STAGE(PG8_SB(0, 0), b2, voffB);
;             PG8_BAR; PG8_WAIT_L(0); PG8_MMA(0, 1, At, B1); PG8_BAR;
;             PG8_LDA(At, 0, 1); PG8_STAGE(PG8_SA(0, 0), a2, voffA);
;             PG8_BAR; PG8_WAIT_L(0); PG8_MMA(1, 0, At, B0); PG8_BAR; PG8_SCHED;
;     ...
; #pragma unroll
;         for (int a = 0; a < 2; ++a)
; #pragma unroll
;             for (int b = 0; b < 2; ++b)
; #pragma unroll
;                 for (int m = 0; m < 4; ++m)
; #pragma unroll
;                     for (int n = 0; n < 2; ++n) acc[a][b][m][n] = (f32x4){0.f, 0.f, 0.f, 0.f};
;         cur = nxt; cA = nA; cB = nB; ++ui;
.LBB1_924:
	s_ashr_i32 s53, s52, 31
	s_lshl_b64 s[4:5], s[52:53], 20
	s_add_u32 s54, s18, s4
	v_cmp_lt_i64_e32 vcc, s[6:7], v[140:141]
	s_addc_u32 s55, s19, s5
	s_and_b64 s[4:5], vcc, exec
	s_cselect_b32 s4, s55, s13
	s_cselect_b32 s5, s54, s12
	s_ashr_i32 s47, s46, 31
	s_lshl_b64 s[6:7], s[46:47], 20
	s_add_u32 s6, s20, s6
	s_addc_u32 s7, s21, s7
	s_and_b64 s[14:15], vcc, exec
	s_cselect_b32 s37, s7, s11
	s_cselect_b32 s38, s6, s10
	s_add_u32 s39, s10, 0x100
	s_addc_u32 s47, s11, 0
	s_add_u32 s10, s12, 0x80080
	v_mov_b32_e32 v0, 0
	s_addc_u32 s11, s13, 0
	s_mov_b32 s48, -2
	v_mov_b32_e32 v1, 0
	v_mov_b64_e32 v[2:3], 0
	v_mov_b64_e32 v[4:5], 0
	v_mov_b64_e32 v[6:7], 0
	v_mov_b64_e32 v[8:9], 0
	v_mov_b64_e32 v[10:11], 0
	v_mov_b64_e32 v[12:13], 0
	v_mov_b64_e32 v[14:15], 0
	v_mov_b64_e32 v[16:17], 0
	v_mov_b64_e32 v[18:19], 0
	v_mov_b64_e32 v[20:21], 0
	v_mov_b64_e32 v[22:23], 0
	v_mov_b64_e32 v[24:25], 0
	v_mov_b64_e32 v[26:27], 0
	v_mov_b64_e32 v[28:29], 0
	v_mov_b64_e32 v[30:31], 0
	v_mov_b64_e32 v[32:33], 0
	v_mov_b64_e32 v[34:35], 0
	v_mov_b64_e32 v[36:37], 0
	v_mov_b64_e32 v[38:39], 0
	v_mov_b64_e32 v[40:41], 0
	v_mov_b64_e32 v[42:43], 0
	v_mov_b64_e32 v[44:45], 0
	v_mov_b64_e32 v[46:47], 0
	v_mov_b64_e32 v[48:49], 0
	v_mov_b64_e32 v[50:51], 0
	v_mov_b64_e32 v[52:53], 0
	v_mov_b64_e32 v[54:55], 0
	v_mov_b64_e32 v[56:57], 0
	v_mov_b64_e32 v[58:59], 0
	v_mov_b64_e32 v[60:61], 0
	v_mov_b64_e32 v[62:63], 0
	v_mov_b64_e32 v[64:65], 0
	v_mov_b64_e32 v[66:67], 0
	v_mov_b64_e32 v[68:69], 0
	v_mov_b64_e32 v[70:71], 0
	v_mov_b64_e32 v[72:73], 0
	v_mov_b64_e32 v[74:75], 0
	v_mov_b64_e32 v[76:77], 0
	v_mov_b64_e32 v[78:79], 0
	v_mov_b64_e32 v[80:81], 0
	v_mov_b64_e32 v[82:83], 0
	v_mov_b64_e32 v[84:85], 0
	v_mov_b64_e32 v[86:87], 0
	v_mov_b64_e32 v[88:89], 0
	v_mov_b64_e32 v[90:91], 0
	v_mov_b64_e32 v[92:93], 0
	v_mov_b64_e32 v[94:95], 0
	v_mov_b64_e32 v[96:97], 0
	v_mov_b64_e32 v[98:99], 0
	v_mov_b64_e32 v[100:101], 0
	v_mov_b64_e32 v[102:103], 0
	v_mov_b64_e32 v[104:105], 0
	v_mov_b64_e32 v[106:107], 0
	v_mov_b64_e32 v[108:109], 0
	v_mov_b64_e32 v[110:111], 0
	v_mov_b64_e32 v[112:113], 0
	v_mov_b64_e32 v[114:115], 0
	v_mov_b64_e32 v[116:117], 0
	v_mov_b64_e32 v[118:119], 0
	v_mov_b64_e32 v[120:121], 0
	v_mov_b64_e32 v[122:123], 0
	v_mov_b64_e32 v[124:125], 0
	v_mov_b64_e32 v[126:127], 0
	ds_read_b128 v[152:155], v149
	ds_read_b128 v[156:159], v149 offset:1024
	ds_read_b128 v[160:163], v149 offset:2048
	ds_read_b128 v[164:167], v149 offset:3072
	s_add_u32 s3, s10, 0xfff80080
	s_addc_u32 s12, s11, -1
	s_cmp_eq_u32 s48, 28
	s_cselect_b32 s15, s4, s12
	s_cselect_b32 s14, s5, s3
	s_cselect_b32 s13, s37, s47
	s_cselect_b32 s12, s38, s39
.LBB1_925:
	s_add_i32 m0, s24, 0xc000
	ds_read_b128 v[168:171], v150
	ds_read_b128 v[172:175], v150 offset:1024
	ds_read_b128 v[176:179], v150 offset:2048
	ds_read_b128 v[180:183], v150 offset:3072
	ds_read_b128 v[184:187], v150 offset:4096
	ds_read_b128 v[188:191], v150 offset:5120
	ds_read_b128 v[192:195], v150 offset:6144
	ds_read_b128 v[198:201], v150 offset:7168
	global_load_lds_dwordx4 v138, s[10:11]
	s_add_i32 m0, s24, 0xe000
	s_nop 0
	global_load_lds_dwordx4 v136, s[10:11]
	s_waitcnt lgkmcnt(8)
	s_setprio 1
	s_barrier
	s_waitcnt lgkmcnt(7)
	v_mfma_f32_16x16x32_bf16 v[124:127], v[152:155], v[168:171], v[124:127]
	v_mfma_f32_16x16x32_bf16 v[120:123], v[160:163], v[168:171], v[120:123]
	s_waitcnt lgkmcnt(5)
	v_mfma_f32_16x16x32_bf16 v[108:111], v[152:155], v[176:179], v[108:111]
	v_mfma_f32_16x16x32_bf16 v[104:107], v[160:163], v[176:179], v[104:107]
	s_waitcnt lgkmcnt(3)
	v_mfma_f32_16x16x32_bf16 v[92:95], v[152:155], v[184:187], v[92:95]
	v_mfma_f32_16x16x32_bf16 v[88:91], v[160:163], v[184:187], v[88:91]
	s_waitcnt lgkmcnt(1)
	v_mfma_f32_16x16x32_bf16 v[76:79], v[152:155], v[192:195], v[76:79]
	v_mfma_f32_16x16x32_bf16 v[72:75], v[160:163], v[192:195], v[72:75]
	v_mfma_f32_16x16x32_bf16 v[124:127], v[156:159], v[172:175], v[124:127]
	s_add_i32 s3, s35, s22
	v_mfma_f32_16x16x32_bf16 v[120:123], v[164:167], v[172:175], v[120:123]
	v_lshl_add_u64 v[144:145], s[12:13], 0, v[132:133]
	v_mfma_f32_16x16x32_bf16 v[108:111], v[156:159], v[180:183], v[108:111]
	v_lshl_add_u64 v[218:219], s[12:13], 0, v[128:129]
	v_mfma_f32_16x16x32_bf16 v[104:107], v[164:167], v[180:183], v[104:107]
	v_mfma_f32_16x16x32_bf16 v[92:95], v[156:159], v[188:191], v[92:95]
	v_mfma_f32_16x16x32_bf16 v[88:91], v[164:167], v[188:191], v[88:91]
	s_waitcnt lgkmcnt(0)
	v_mfma_f32_16x16x32_bf16 v[76:79], v[156:159], v[198:201], v[76:79]
	v_mfma_f32_16x16x32_bf16 v[72:75], v[164:167], v[198:201], v[72:75]
	s_barrier
	s_setprio 0
	s_mov_b32 m0, s3
	ds_read_b128 v[202:205], v151
	ds_read_b128 v[206:209], v151 offset:1024
	ds_read_b128 v[210:213], v151 offset:2048
	ds_read_b128 v[214:217], v151 offset:3072
	global_load_lds_dwordx4 v[144:145], off
	s_add_i32 m0, s3, 0x2000
	s_nop 0
	global_load_lds_dwordx4 v[218:219], off
	s_setprio 1
	s_barrier
	s_waitcnt lgkmcnt(3)
	v_mfma_f32_16x16x32_bf16 v[116:119], v[202:205], v[168:171], v[116:119]
	s_waitcnt lgkmcnt(1)
	v_mfma_f32_16x16x32_bf16 v[112:115], v[210:213], v[168:171], v[112:115]
	v_mfma_f32_16x16x32_bf16 v[100:103], v[202:205], v[176:179], v[100:103]
	v_mfma_f32_16x16x32_bf16 v[96:99], v[210:213], v[176:179], v[96:99]
	v_mfma_f32_16x16x32_bf16 v[84:87], v[202:205], v[184:187], v[84:87]
	v_mfma_f32_16x16x32_bf16 v[80:83], v[210:213], v[184:187], v[80:83]
	v_mfma_f32_16x16x32_bf16 v[68:71], v[202:205], v[192:195], v[68:71]
	v_mfma_f32_16x16x32_bf16 v[64:67], v[210:213], v[192:195], v[64:67]
	v_mfma_f32_16x16x32_bf16 v[116:119], v[206:209], v[172:175], v[116:119]
	v_lshl_add_u64 v[222:223], s[14:15], 0, v[130:131]
	s_mov_b32 m0, s24
	s_waitcnt lgkmcnt(0)
	v_mfma_f32_16x16x32_bf16 v[112:115], v[214:217], v[172:175], v[112:115]
	v_lshl_add_u64 v[220:221], s[14:15], 0, v[134:135]
	v_mfma_f32_16x16x32_bf16 v[100:103], v[206:209], v[180:183], v[100:103]
	v_mfma_f32_16x16x32_bf16 v[96:99], v[214:217], v[180:183], v[96:99]
	v_mfma_f32_16x16x32_bf16 v[84:87], v[206:209], v[188:191], v[84:87]
	v_mfma_f32_16x16x32_bf16 v[80:83], v[214:217], v[188:191], v[80:83]
	v_mfma_f32_16x16x32_bf16 v[68:71], v[206:209], v[198:201], v[68:71]
	v_mfma_f32_16x16x32_bf16 v[64:67], v[214:217], v[198:201], v[64:67]
	s_barrier
; #define PG8_STAGE(bufoff, gbase, voff) do { _Pragma("unroll") for (int _i = 0; _i < 2; ++_i) \
;         __builtin_amdgcn_global_load_lds((const unsigned*)((const char*)(gbase) + (voff)[_i]), (LAS unsigned*)(lds + (bufoff) + ldsw + _i * 8192), 16, 0, 0); } while (0)
; #define PG8_LDA(dst, b, h) do { _Pragma("unroll") for (int m = 0; m < 4; ++m) _Pragma("unroll") for (int k = 0; k < 2; ++k) dst[m][k] = *(const LAS bf16x8*)(lds + PG8_SA(b, h) + aoff + m * 2048 + k * 1024); } while (0)
; #define PG8_LDB(dst, b, h) do { _Pragma("unroll") for (int n = 0; n < 2; ++n) _Pragma("unroll") for (int k = 0; k < 2; ++k) dst[n][k] = *(const LAS bf16x8*)(lds + PG8_SB(b, h) + boff + n * 2048 + k * 1024); } while (0)
; #define PG8_MMA(ai, bj, At, Bt) do { __builtin_amdgcn_s_setprio(1); _Pragma("unroll") for (int m = 0; m < 4; ++m) _Pragma("unroll") for (int n = 0; n < 2; ++n) _Pragma("unroll") for (int k = 0; k < 2; ++k) \
;         acc[ai][bj][m][n] = __builtin_amdgcn_mfma_f32_16x16x32_bf16(Bt[n][k], At[m][k], acc[ai][bj][m][n], 0, 0, 0); __builtin_amdgcn_s_setprio(0); } while (0)
; #define PG8_WAIT_V(n) asm volatile("s_waitcnt vmcnt(" #n ")" ::: "memory")
; #define PG8_WAIT_L(n) asm volatile("s_waitcnt lgkmcnt(" #n ")" ::: "memory")
; #define PG8_BAR __builtin_amdgcn_s_barrier()
; #define PG8_SCHED __builtin_amdgcn_sched_barrier(0)
; template <class Map, class Epi>
; DI void gemm_phase(LAS unsigned char* lds, const Map& MP, const Epi& E, const int nM, const int nN, const int K, const int lda, const int ldb) {
;     ...
;             PG8_BAR; PG8_WAIT_L(0); PG8_MMA(1, 0, At, B0); PG8_BAR; PG8_SCHED;
;             PG8_STAGE(PG8_SB(0, 1), b2 + hstepB, voffB);
;             PG8_WAIT_V(6); PG8_BAR; PG8_MMA(1, 1, At, B1); PG8_BAR;
;             PG8_LDB(B0, 1, 0); PG8_SCHED; PG8_LDA(At, 1, 0); PG8_STAGE(PG8_SA(0, 1), a2 + hstepA, voffA);
;             PG8_WAIT_L(8); PG8_BAR; PG8_WAIT_L(0); PG8_MMA(0, 0, At, B0); PG8_BAR; PG8_SCHED;
;             PG8_LDB(B1, 1, 1); PG8_STAGE(PG8_SB(1, 0), b3, voffB);
;             PG8_BAR; PG8_WAIT_L(0); PG8_MMA(0, 1, At, B1); PG8_BAR;
;             PG8_LDA(At, 1, 1); PG8_STAGE(PG8_SA(1, 0), a3, voffA);
;             PG8_BAR; PG8_WAIT_L(0); PG8_MMA(1, 0, At, B0); PG8_BAR; PG8_SCHED;
	s_setprio 0
	ds_read_b128 v[168:171], v150 offset:16384
	ds_read_b128 v[172:175], v150 offset:17408
	ds_read_b128 v[176:179], v150 offset:18432
	ds_read_b128 v[180:183], v150 offset:19456
	ds_read_b128 v[184:187], v150 offset:20480
	ds_read_b128 v[188:191], v150 offset:21504
	ds_read_b128 v[192:195], v150 offset:22528
	ds_read_b128 v[198:201], v150 offset:23552
	global_load_lds_dwordx4 v[220:221], off
	s_mov_b32 m0, s9
	s_nop 0
	global_load_lds_dwordx4 v[222:223], off
	s_waitcnt vmcnt(10)
	s_setprio 1
	s_barrier
	s_waitcnt lgkmcnt(7)
	v_mfma_f32_16x16x32_bf16 v[60:63], v[152:155], v[168:171], v[60:63]
	v_mfma_f32_16x16x32_bf16 v[56:59], v[160:163], v[168:171], v[56:59]
	s_waitcnt lgkmcnt(5)
	v_mfma_f32_16x16x32_bf16 v[44:47], v[152:155], v[176:179], v[44:47]
	v_mfma_f32_16x16x32_bf16 v[40:43], v[160:163], v[176:179], v[40:43]
	s_waitcnt lgkmcnt(3)
	v_mfma_f32_16x16x32_bf16 v[28:31], v[152:155], v[184:187], v[28:31]
	v_mfma_f32_16x16x32_bf16 v[24:27], v[160:163], v[184:187], v[24:27]
	s_waitcnt lgkmcnt(1)
	v_mfma_f32_16x16x32_bf16 v[12:15], v[152:155], v[192:195], v[12:15]
	v_mfma_f32_16x16x32_bf16 v[8:11], v[160:163], v[192:195], v[8:11]
	v_mfma_f32_16x16x32_bf16 v[60:63], v[156:159], v[172:175], v[60:63]
	s_add_u32 s56, s12, 0x80000
	s_addc_u32 s57, s13, 0
	v_mfma_f32_16x16x32_bf16 v[56:59], v[164:167], v[172:175], v[56:59]
	s_add_i32 s3, s36, s22
	v_mfma_f32_16x16x32_bf16 v[44:47], v[156:159], v[180:183], v[44:47]
	v_mfma_f32_16x16x32_bf16 v[40:43], v[164:167], v[180:183], v[40:43]
	v_mfma_f32_16x16x32_bf16 v[28:31], v[156:159], v[188:191], v[28:31]
	v_mfma_f32_16x16x32_bf16 v[24:27], v[164:167], v[188:191], v[24:27]
	s_waitcnt lgkmcnt(0)
	v_mfma_f32_16x16x32_bf16 v[12:15], v[156:159], v[198:201], v[12:15]
	v_mfma_f32_16x16x32_bf16 v[8:11], v[164:167], v[198:201], v[8:11]
	s_barrier
	s_setprio 0
	s_mov_b32 m0, s3
	s_nop 0
	global_load_lds_dwordx4 v132, s[56:57]
	s_add_i32 m0, s3, 0x2000
	s_nop 0
	global_load_lds_dwordx4 v128, s[56:57]
	s_waitcnt vmcnt(6)
	s_setprio 1
	s_barrier
	v_mfma_f32_16x16x32_bf16 v[52:55], v[202:205], v[168:171], v[52:55]
	v_mfma_f32_16x16x32_bf16 v[48:51], v[210:213], v[168:171], v[48:51]
	s_add_i32 s3, 0, 0x18000
	v_add_u32_e32 v164, s3, v148
	ds_read_b128 v[152:155], v164
	v_mfma_f32_16x16x32_bf16 v[36:39], v[202:205], v[176:179], v[36:39]
	v_mfma_f32_16x16x32_bf16 v[32:35], v[210:213], v[176:179], v[32:35]
	ds_read_b128 v[156:159], v164 offset:1024
	v_mfma_f32_16x16x32_bf16 v[20:23], v[202:205], v[184:187], v[20:23]
	v_mfma_f32_16x16x32_bf16 v[16:19], v[210:213], v[184:187], v[16:19]
	ds_read_b128 v[160:163], v164 offset:2048
	v_mfma_f32_16x16x32_bf16 v[4:7], v[202:205], v[192:195], v[4:7]
	v_mfma_f32_16x16x32_bf16 v[0:3], v[210:213], v[192:195], v[0:3]
	ds_read_b128 v[164:167], v164 offset:3072
	v_mfma_f32_16x16x32_bf16 v[52:55], v[206:209], v[172:175], v[52:55]
	s_add_u32 s14, s14, 0x80000
	s_addc_u32 s15, s15, 0
	v_mfma_f32_16x16x32_bf16 v[48:51], v[214:217], v[172:175], v[48:51]
	v_mfma_f32_16x16x32_bf16 v[36:39], v[206:209], v[180:183], v[36:39]
	v_mfma_f32_16x16x32_bf16 v[32:35], v[214:217], v[180:183], v[32:35]
	v_mfma_f32_16x16x32_bf16 v[20:23], v[206:209], v[188:191], v[20:23]
	v_mfma_f32_16x16x32_bf16 v[16:19], v[214:217], v[188:191], v[16:19]
	v_mfma_f32_16x16x32_bf16 v[4:7], v[206:209], v[198:201], v[4:7]
	v_mfma_f32_16x16x32_bf16 v[0:3], v[214:217], v[198:201], v[0:3]
	s_barrier
	s_setprio 0
	s_mov_b32 m0, s25
	ds_read_b128 v[168:171], v150 offset:32768
	ds_read_b128 v[172:175], v150 offset:33792
	ds_read_b128 v[176:179], v150 offset:34816
	ds_read_b128 v[180:183], v150 offset:35840
	ds_read_b128 v[184:187], v150 offset:36864
	ds_read_b128 v[188:191], v150 offset:37888
	ds_read_b128 v[192:195], v150 offset:38912
	ds_read_b128 v[198:201], v150 offset:39936
	global_load_lds_dwordx4 v134, s[14:15]
	s_mov_b32 m0, s26
	s_nop 0
	global_load_lds_dwordx4 v130, s[14:15]
	s_waitcnt lgkmcnt(8)
	s_setprio 1
	s_barrier
	s_waitcnt lgkmcnt(7)
	v_mfma_f32_16x16x32_bf16 v[124:127], v[152:155], v[168:171], v[124:127]
	v_mfma_f32_16x16x32_bf16 v[120:123], v[160:163], v[168:171], v[120:123]
	s_waitcnt lgkmcnt(5)
	v_mfma_f32_16x16x32_bf16 v[108:111], v[152:155], v[176:179], v[108:111]
	v_mfma_f32_16x16x32_bf16 v[104:107], v[160:163], v[176:179], v[104:107]
	s_waitcnt lgkmcnt(3)
	v_mfma_f32_16x16x32_bf16 v[92:95], v[152:155], v[184:187], v[92:95]
	v_mfma_f32_16x16x32_bf16 v[88:91], v[160:163], v[184:187], v[88:91]
	s_waitcnt lgkmcnt(1)
	v_mfma_f32_16x16x32_bf16 v[76:79], v[152:155], v[192:195], v[76:79]
	v_mfma_f32_16x16x32_bf16 v[72:75], v[160:163], v[192:195], v[72:75]
	v_mfma_f32_16x16x32_bf16 v[124:127], v[156:159], v[172:175], v[124:127]
	s_add_i32 s14, 0, 0x1c000
	v_mfma_f32_16x16x32_bf16 v[120:123], v[164:167], v[172:175], v[120:123]
	s_add_i32 s3, s3, s22
	v_mfma_f32_16x16x32_bf16 v[108:111], v[156:159], v[180:183], v[108:111]
	v_add_u32_e32 v196, s14, v148
	v_mfma_f32_16x16x32_bf16 v[104:107], v[164:167], v[180:183], v[104:107]
	v_lshl_add_u64 v[144:145], v[144:145], 0, s[44:45]
	v_mfma_f32_16x16x32_bf16 v[92:95], v[156:159], v[188:191], v[92:95]
	v_mfma_f32_16x16x32_bf16 v[88:91], v[164:167], v[188:191], v[88:91]
	s_waitcnt lgkmcnt(0)
	v_mfma_f32_16x16x32_bf16 v[76:79], v[156:159], v[198:201], v[76:79]
	v_mfma_f32_16x16x32_bf16 v[72:75], v[164:167], v[198:201], v[72:75]
	s_barrier
	s_setprio 0
	s_mov_b32 m0, s3
	ds_read_b128 v[202:205], v196
	ds_read_b128 v[206:209], v196 offset:1024
	ds_read_b128 v[210:213], v196 offset:2048
	ds_read_b128 v[214:217], v196 offset:3072
	global_load_lds_dwordx4 v[144:145], off
	v_lshl_add_u64 v[144:145], v[218:219], 0, s[44:45]
	s_add_i32 m0, s3, 0x2000
	s_nop 0
	global_load_lds_dwordx4 v[144:145], off
	s_setprio 1
	s_barrier
; #define PG8_STAGE(bufoff, gbase, voff) do { _Pragma("unroll") for (int _i = 0; _i < 2; ++_i) \
;         __builtin_amdgcn_global_load_lds((const unsigned*)((const char*)(gbase) + (voff)[_i]), (LAS unsigned*)(lds + (bufoff) + ldsw + _i * 8192), 16, 0, 0); } while (0)
; #define PG8_LDA(dst, b, h) do { _Pragma("unroll") for (int m = 0; m < 4; ++m) _Pragma("unroll") for (int k = 0; k < 2; ++k) dst[m][k] = *(const LAS bf16x8*)(lds + PG8_SA(b, h) + aoff + m * 2048 + k * 1024); } while (0)
; #define PG8_MMA(ai, bj, At, Bt) do { __builtin_amdgcn_s_setprio(1); _Pragma("unroll") for (int m = 0; m < 4; ++m) _Pragma("unroll") for (int n = 0; n < 2; ++n) _Pragma("unroll") for (int k = 0; k < 2; ++k) \
;         acc[ai][bj][m][n] = __builtin_amdgcn_mfma_f32_16x16x32_bf16(Bt[n][k], At[m][k], acc[ai][bj][m][n], 0, 0, 0); __builtin_amdgcn_s_setprio(0); } while (0)
; #define PG8_WAIT_V(n) asm volatile("s_waitcnt vmcnt(" #n ")" ::: "memory")
; #define PG8_WAIT_L(n) asm volatile("s_waitcnt lgkmcnt(" #n ")" ::: "memory")
; #define PG8_BAR __builtin_amdgcn_s_barrier()
; #define PG8_SCHED __builtin_amdgcn_sched_barrier(0)
; template <class Map, class Epi>
; DI void gemm_phase(LAS unsigned char* lds, const Map& MP, const Epi& E, const int nM, const int nN, const int K, const int lda, const int ldb) {
;     ...
;             const bool last = (t == nt - 2);
;             const char* a1 = cA + (size_t)(t + 1) * kstep;
;             const char* a2 = last ? nA : cA + (size_t)(t + 2) * kstep; const char* b2 = last ? nB : cB + (size_t)(t + 2) * kstep;
;     ...
;             PG8_LDA(At, 1, 1); PG8_STAGE(PG8_SA(1, 0), a3, voffA);
;             PG8_BAR; PG8_WAIT_L(0); PG8_MMA(1, 0, At, B0); PG8_BAR; PG8_SCHED;
;             PG8_STAGE(PG8_SB(1, 1), b3 + hstepB, voffB);
;             PG8_WAIT_V(6); PG8_BAR; PG8_MMA(1, 1, At, B1); PG8_BAR;
	s_waitcnt lgkmcnt(3)
	v_mfma_f32_16x16x32_bf16 v[116:119], v[202:205], v[168:171], v[116:119]
	s_waitcnt lgkmcnt(1)
	v_mfma_f32_16x16x32_bf16 v[112:115], v[210:213], v[168:171], v[112:115]
	v_mfma_f32_16x16x32_bf16 v[100:103], v[202:205], v[176:179], v[100:103]
	v_mfma_f32_16x16x32_bf16 v[96:99], v[210:213], v[176:179], v[96:99]
	v_mfma_f32_16x16x32_bf16 v[84:87], v[202:205], v[184:187], v[84:87]
	v_mfma_f32_16x16x32_bf16 v[80:83], v[210:213], v[184:187], v[80:83]
	v_mfma_f32_16x16x32_bf16 v[68:71], v[202:205], v[192:195], v[68:71]
	v_mfma_f32_16x16x32_bf16 v[64:67], v[210:213], v[192:195], v[64:67]
	v_mfma_f32_16x16x32_bf16 v[116:119], v[206:209], v[172:175], v[116:119]
	s_mov_b32 m0, s30
	s_waitcnt lgkmcnt(0)
	v_mfma_f32_16x16x32_bf16 v[112:115], v[214:217], v[172:175], v[112:115]
	v_lshl_add_u64 v[144:145], v[220:221], 0, s[44:45]
	v_mfma_f32_16x16x32_bf16 v[100:103], v[206:209], v[180:183], v[100:103]
	v_mfma_f32_16x16x32_bf16 v[96:99], v[214:217], v[180:183], v[96:99]
	v_mfma_f32_16x16x32_bf16 v[84:87], v[206:209], v[188:191], v[84:87]
	v_mfma_f32_16x16x32_bf16 v[80:83], v[214:217], v[188:191], v[80:83]
	v_mfma_f32_16x16x32_bf16 v[68:71], v[206:209], v[198:201], v[68:71]
	v_mfma_f32_16x16x32_bf16 v[64:67], v[214:217], v[198:201], v[64:67]
	s_barrier
	s_setprio 0
	ds_read_b128 v[168:171], v150 offset:49152
	ds_read_b128 v[172:175], v150 offset:50176
	ds_read_b128 v[176:179], v150 offset:51200
	ds_read_b128 v[180:183], v150 offset:52224
	ds_read_b128 v[184:187], v150 offset:53248
	ds_read_b128 v[188:191], v150 offset:54272
	ds_read_b128 v[192:195], v150 offset:55296
	ds_read_b128 v[198:201], v150 offset:56320
	global_load_lds_dwordx4 v[144:145], off
	v_lshl_add_u64 v[144:145], v[222:223], 0, s[44:45]
	s_mov_b32 m0, s31
	s_nop 0
	global_load_lds_dwordx4 v[144:145], off
	s_waitcnt vmcnt(10)
	s_setprio 1
	s_barrier
	s_waitcnt lgkmcnt(7)
	v_mfma_f32_16x16x32_bf16 v[60:63], v[152:155], v[168:171], v[60:63]
	v_mfma_f32_16x16x32_bf16 v[56:59], v[160:163], v[168:171], v[56:59]
	s_waitcnt lgkmcnt(5)
	v_mfma_f32_16x16x32_bf16 v[44:47], v[152:155], v[176:179], v[44:47]
	v_mfma_f32_16x16x32_bf16 v[40:43], v[160:163], v[176:179], v[40:43]
	s_waitcnt lgkmcnt(3)
	v_mfma_f32_16x16x32_bf16 v[28:31], v[152:155], v[184:187], v[28:31]
	v_mfma_f32_16x16x32_bf16 v[24:27], v[160:163], v[184:187], v[24:27]
	s_waitcnt lgkmcnt(1)
	v_mfma_f32_16x16x32_bf16 v[12:15], v[152:155], v[192:195], v[12:15]
	v_mfma_f32_16x16x32_bf16 v[8:11], v[160:163], v[192:195], v[8:11]
	v_mfma_f32_16x16x32_bf16 v[60:63], v[156:159], v[172:175], v[60:63]
	s_add_u32 s12, s12, 0x80080
	s_addc_u32 s13, s13, 0
	v_mfma_f32_16x16x32_bf16 v[56:59], v[164:167], v[172:175], v[56:59]
	s_add_i32 s3, s14, s22
	v_mfma_f32_16x16x32_bf16 v[44:47], v[156:159], v[180:183], v[44:47]
	v_mfma_f32_16x16x32_bf16 v[40:43], v[164:167], v[180:183], v[40:43]
	v_mfma_f32_16x16x32_bf16 v[28:31], v[156:159], v[188:191], v[28:31]
	v_mfma_f32_16x16x32_bf16 v[24:27], v[164:167], v[188:191], v[24:27]
	s_waitcnt lgkmcnt(0)
	v_mfma_f32_16x16x32_bf16 v[12:15], v[156:159], v[198:201], v[12:15]
	v_mfma_f32_16x16x32_bf16 v[8:11], v[164:167], v[198:201], v[8:11]
	s_barrier
	s_setprio 0
	s_mov_b32 m0, s3
	s_nop 0
	global_load_lds_dwordx4 v132, s[12:13]
	s_add_i32 m0, s3, 0x2000
	s_nop 0
	global_load_lds_dwordx4 v128, s[12:13]
	s_waitcnt vmcnt(6)
	s_setprio 1
	s_barrier
	v_mfma_f32_16x16x32_bf16 v[52:55], v[202:205], v[168:171], v[52:55]
	v_mfma_f32_16x16x32_bf16 v[48:51], v[210:213], v[168:171], v[48:51]
	ds_read_b128 v[152:155], v149
	v_mfma_f32_16x16x32_bf16 v[36:39], v[202:205], v[176:179], v[36:39]
	v_mfma_f32_16x16x32_bf16 v[32:35], v[210:213], v[176:179], v[32:35]
	ds_read_b128 v[156:159], v149 offset:1024
	v_mfma_f32_16x16x32_bf16 v[20:23], v[202:205], v[184:187], v[20:23]
	v_mfma_f32_16x16x32_bf16 v[16:19], v[210:213], v[184:187], v[16:19]
	ds_read_b128 v[160:163], v149 offset:2048
	v_mfma_f32_16x16x32_bf16 v[4:7], v[202:205], v[192:195], v[4:7]
	v_mfma_f32_16x16x32_bf16 v[0:3], v[210:213], v[192:195], v[0:3]
	ds_read_b128 v[164:167], v149 offset:3072
	v_mfma_f32_16x16x32_bf16 v[52:55], v[206:209], v[172:175], v[52:55]
	s_add_i32 s48, s48, 2
	v_mfma_f32_16x16x32_bf16 v[48:51], v[214:217], v[172:175], v[48:51]
	s_add_u32 s39, s39, 0x100
	s_addc_u32 s47, s47, 0
	v_mfma_f32_16x16x32_bf16 v[36:39], v[206:209], v[180:183], v[36:39]
	s_add_u32 s10, s10, 0x100
	s_addc_u32 s11, s11, 0
	v_mfma_f32_16x16x32_bf16 v[32:35], v[214:217], v[180:183], v[32:35]
	s_add_u32 s3, s10, 0xfff80080
	s_addc_u32 s12, s11, -1
	s_cmp_eq_u32 s48, 28
	s_cselect_b32 s15, s4, s12
	s_cselect_b32 s14, s5, s3
	s_cselect_b32 s13, s37, s47
	s_cselect_b32 s12, s38, s39
	s_cmp_gt_u32 s48, 29
	v_mfma_f32_16x16x32_bf16 v[20:23], v[206:209], v[188:191], v[20:23]
	v_mfma_f32_16x16x32_bf16 v[16:19], v[214:217], v[188:191], v[16:19]
	v_mfma_f32_16x16x32_bf16 v[4:7], v[206:209], v[198:201], v[4:7]
	v_mfma_f32_16x16x32_bf16 v[0:3], v[214:217], v[198:201], v[0:3]
	s_barrier
	s_setprio 0
	s_cbranch_scc0 .LBB1_925
; DI unsigned pack2(float a, float b) { f32x2 v = {a, b}; hwbf16x2 r = __builtin_convertvector(v, hwbf16x2); return __builtin_bit_cast(unsigned, r); }
; DI float bflo(unsigned w) { return __uint_as_float(w << 16); }
; DI float bfhi(unsigned w) { return __uint_as_float(w & 0xffff0000u); }
;     DI void operator()(const f32x4 (&acc)[2][2][4][2], const Unit& u, int wr, int wc, int fr, int fq) const {
;     ...
;         for (int ai = 0; ai < 2; ++ai)
; #pragma unroll
;             for (int m = 0; m < 4; ++m) { const size_t ro = (size_t)(row0 + ai * HALF + m * 16) * D + col0;
; #pragma unroll
;                 for (int bj = 0; bj < 2; ++bj) {
;                     f32x4 x0, x1;
;                     if constexpr (IB) { const u32x4 w = *(const u32x4*)((const bf16_t*)Xin + ro + bj * HALF);
;                         x0 = (f32x4){bflo(w[0]), bfhi(w[0]), bflo(w[1]), bfhi(w[1])}; x1 = (f32x4){bflo(w[2]), bfhi(w[2]), bflo(w[3]), bfhi(w[3])}; }
;                     else { x0 = *(const f32x4*)((const float*)Xin + ro + bj * HALF); x1 = *(const f32x4*)((const float*)Xin + ro + bj * HALF + 4); }
;                     x0 += acc[ai][bj][m][0] * sc[bj][0]; x1 += acc[ai][bj][m][1] * sc[bj][1];
;                     if constexpr (OB) { u32x4 o; o[0] = pack2(x0[0], x0[1]); o[1] = pack2(x0[2], x0[3]); o[2] = pack2(x1[0], x1[1]); o[3] = pack2(x1[2], x1[3]);
;                         *(u32x4*)((bf16_t*)Xout + ro + bj * HALF) = o; }
;                     else { *(f32x4*)((float*)Xout + ro + bj * HALF) = x0; *(f32x4*)((float*)Xout + ro + bj * HALF + 4) = x1; } } }
	s_waitcnt lgkmcnt(0)
	v_mov_b32_e32 v152, v147
	v_mov_b32_e32 v144, v146
	s_lshl_b32 s2, s2, 8
	s_or_b32 s2, s2, s29
	v_lshl_add_u32 v144, v144, 3, s2
	s_lshl_b32 s2, s8, 8
	s_add_i32 s2, s2, s28
	v_add_u32_e32 v152, s2, v152
	v_ashrrev_i32_e32 v153, 31, v152
	v_lshlrev_b64 v[152:153], 12, v[152:153]
	v_ashrrev_i32_e32 v145, 31, v144
	v_lshl_add_u64 v[152:153], s[42:43], 0, v[152:153]
	v_lshl_add_u64 v[144:145], v[144:145], 1, v[152:153]
	global_load_dwordx4 v[160:163], v[144:145], off
	global_load_dwordx4 v[164:167], v[144:145], off offset:256
	s_mov_b64 s[98:99], 0x10000
	v_lshl_add_u64 v[154:155], v[144:145], 0, s[98:99]
	global_load_dwordx4 v[168:171], v[154:155], off
	global_load_dwordx4 v[172:175], v[154:155], off offset:256
	s_mov_b64 s[98:99], 0x20000
	v_lshl_add_u64 v[154:155], v[144:145], 0, s[98:99]
	global_load_dwordx4 v[176:179], v[154:155], off
	global_load_dwordx4 v[180:183], v[154:155], off offset:256
	s_mov_b64 s[98:99], 0x30000
	v_lshl_add_u64 v[154:155], v[144:145], 0, s[98:99]
	global_load_dwordx4 v[184:187], v[154:155], off
	global_load_dwordx4 v[188:191], v[154:155], off offset:256
	s_mov_b64 s[98:99], 0x80000
	v_lshl_add_u64 v[154:155], v[144:145], 0, s[98:99]
	global_load_dwordx4 v[192:195], v[154:155], off
	global_load_dwordx4 v[198:201], v[154:155], off offset:256
	s_mov_b64 s[98:99], 0x90000
	v_lshl_add_u64 v[154:155], v[144:145], 0, s[98:99]
	global_load_dwordx4 v[202:205], v[154:155], off
	global_load_dwordx4 v[206:209], v[154:155], off offset:256
	s_mov_b64 s[98:99], 0xa0000
	v_lshl_add_u64 v[154:155], v[144:145], 0, s[98:99]
	global_load_dwordx4 v[210:213], v[154:155], off
	global_load_dwordx4 v[214:217], v[154:155], off offset:256
	s_mov_b64 s[98:99], 0xb0000
	v_lshl_add_u64 v[154:155], v[144:145], 0, s[98:99]
	global_load_dwordx4 v[248:251], v[154:155], off
	global_load_dwordx4 v[252:255], v[154:155], off offset:256
	s_waitcnt vmcnt(15)
	s_nop 1
	v_mov_b32_e32 v152, v160
	v_mov_b32_e32 v153, v161
	v_mov_b32_e32 v154, v162
	v_mov_b32_e32 v155, v163
	s_mov_b64 s[2:3], 0x10000
	s_mov_b32 s8, s52
	s_mov_b64 s[10:11], s[6:7]
	s_mov_b64 s[12:13], s[54:55]
	s_waitcnt lgkmcnt(0)
	v_lshlrev_b32_e32 v156, 16, v152
	v_and_b32_e32 v157, 0xffff0000, v152
	v_lshlrev_b32_e32 v152, 16, v153
	v_and_b32_e32 v153, 0xffff0000, v153
	v_lshlrev_b32_e32 v158, 16, v154
	v_and_b32_e32 v159, 0xffff0000, v154
	v_lshlrev_b32_e32 v154, 16, v155
	v_and_b32_e32 v155, 0xffff0000, v155
	v_pk_add_f32 v[126:127], v[126:127], v[152:153]
	v_pk_add_f32 v[124:125], v[124:125], v[156:157]
	v_pk_add_f32 v[152:153], v[122:123], v[154:155]
	v_pk_add_f32 v[122:123], v[120:121], v[158:159]
	v_cvt_pk_bf16_f32 v120, v124, v125
	v_cvt_pk_bf16_f32 v121, v126, v127
	v_cvt_pk_bf16_f32 v122, v122, v123
	v_cvt_pk_bf16_f32 v123, v152, v153
	global_store_dwordx4 v[144:145], v[120:123], off
	s_waitcnt vmcnt(15)
	s_nop 1
	v_mov_b32_e32 v120, v164
	v_mov_b32_e32 v121, v165
	v_mov_b32_e32 v122, v166
	v_mov_b32_e32 v123, v167
	s_waitcnt lgkmcnt(0)
	v_lshlrev_b32_e32 v124, 16, v120
	v_and_b32_e32 v125, 0xffff0000, v120
	v_lshlrev_b32_e32 v120, 16, v121
	v_and_b32_e32 v121, 0xffff0000, v121
	v_lshlrev_b32_e32 v126, 16, v122
	v_and_b32_e32 v127, 0xffff0000, v122
	v_lshlrev_b32_e32 v122, 16, v123
	v_and_b32_e32 v123, 0xffff0000, v123
	v_pk_add_f32 v[116:117], v[116:117], v[124:125]
	v_pk_add_f32 v[118:119], v[118:119], v[120:121]
	v_pk_add_f32 v[120:121], v[114:115], v[122:123]
	v_pk_add_f32 v[114:115], v[112:113], v[126:127]
	v_cvt_pk_bf16_f32 v112, v116, v117
	v_lshl_add_u64 v[116:117], v[144:145], 0, s[2:3]
	s_mov_b32 s2, 0x10000
	v_cvt_pk_bf16_f32 v113, v118, v119
	v_add_co_u32_e32 v118, vcc, s2, v144
	v_cvt_pk_bf16_f32 v114, v114, v115
	v_cvt_pk_bf16_f32 v115, v120, v121
	v_addc_co_u32_e32 v119, vcc, 0, v145, vcc
	global_store_dwordx4 v[144:145], v[112:115], off offset:256
	s_waitcnt vmcnt(15)
	s_nop 1
	v_mov_b32_e32 v112, v168
	v_mov_b32_e32 v113, v169
	v_mov_b32_e32 v114, v170
	v_mov_b32_e32 v115, v171
	s_mov_b64 s[2:3], 0x20000
	s_waitcnt lgkmcnt(0)
	v_lshlrev_b32_e32 v120, 16, v112
	v_and_b32_e32 v121, 0xffff0000, v112
	v_lshlrev_b32_e32 v112, 16, v113
	v_and_b32_e32 v113, 0xffff0000, v113
	v_lshlrev_b32_e32 v122, 16, v114
	v_and_b32_e32 v123, 0xffff0000, v114
	v_lshlrev_b32_e32 v114, 16, v115
	v_and_b32_e32 v115, 0xffff0000, v115
	v_pk_add_f32 v[110:111], v[110:111], v[112:113]
	v_pk_add_f32 v[108:109], v[108:109], v[120:121]
	v_pk_add_f32 v[112:113], v[106:107], v[114:115]
	v_pk_add_f32 v[106:107], v[104:105], v[122:123]
	v_cvt_pk_bf16_f32 v104, v108, v109
	v_cvt_pk_bf16_f32 v105, v110, v111
	v_cvt_pk_bf16_f32 v106, v106, v107
	v_cvt_pk_bf16_f32 v107, v112, v113
	global_store_dwordx4 v[118:119], v[104:107], off
	s_waitcnt vmcnt(15)
	s_nop 1
	v_mov_b32_e32 v104, v172
	v_mov_b32_e32 v105, v173
	v_mov_b32_e32 v106, v174
	v_mov_b32_e32 v107, v175
	s_waitcnt lgkmcnt(0)
	v_lshlrev_b32_e32 v108, 16, v104
	v_and_b32_e32 v109, 0xffff0000, v104
	v_lshlrev_b32_e32 v104, 16, v105
	v_and_b32_e32 v105, 0xffff0000, v105
	v_lshlrev_b32_e32 v110, 16, v106
	v_and_b32_e32 v111, 0xffff0000, v106
	v_lshlrev_b32_e32 v106, 16, v107
	v_and_b32_e32 v107, 0xffff0000, v107
	v_pk_add_f32 v[100:101], v[100:101], v[108:109]
	v_pk_add_f32 v[102:103], v[102:103], v[104:105]
	v_pk_add_f32 v[104:105], v[98:99], v[106:107]
	v_pk_add_f32 v[98:99], v[96:97], v[110:111]
	v_cvt_pk_bf16_f32 v96, v100, v101
	v_lshl_add_u64 v[100:101], v[144:145], 0, s[2:3]
	s_mov_b32 s2, 0x20000
	v_cvt_pk_bf16_f32 v97, v102, v103
	v_add_co_u32_e32 v102, vcc, s2, v144
	v_cvt_pk_bf16_f32 v98, v98, v99
	v_cvt_pk_bf16_f32 v99, v104, v105
	v_addc_co_u32_e32 v103, vcc, 0, v145, vcc
	global_store_dwordx4 v[116:117], v[96:99], off offset:256
	s_waitcnt vmcnt(15)
; DI unsigned pack2(float a, float b) { f32x2 v = {a, b}; hwbf16x2 r = __builtin_convertvector(v, hwbf16x2); return __builtin_bit_cast(unsigned, r); }
; DI float bflo(unsigned w) { return __uint_as_float(w << 16); }
; DI float bfhi(unsigned w) { return __uint_as_float(w & 0xffff0000u); }
;     DI void operator()(const f32x4 (&acc)[2][2][4][2], const Unit& u, int wr, int wc, int fr, int fq) const {
;     ...
;         for (int ai = 0; ai < 2; ++ai)
; #pragma unroll
;             for (int m = 0; m < 4; ++m) { const size_t ro = (size_t)(row0 + ai * HALF + m * 16) * D + col0;
; #pragma unroll
;                 for (int bj = 0; bj < 2; ++bj) {
;                     f32x4 x0, x1;
;                     if constexpr (IB) { const u32x4 w = *(const u32x4*)((const bf16_t*)Xin + ro + bj * HALF);
;                         x0 = (f32x4){bflo(w[0]), bfhi(w[0]), bflo(w[1]), bfhi(w[1])}; x1 = (f32x4){bflo(w[2]), bfhi(w[2]), bflo(w[3]), bfhi(w[3])}; }
;                     else { x0 = *(const f32x4*)((const float*)Xin + ro + bj * HALF); x1 = *(const f32x4*)((const float*)Xin + ro + bj * HALF + 4); }
;                     x0 += acc[ai][bj][m][0] * sc[bj][0]; x1 += acc[ai][bj][m][1] * sc[bj][1];
;                     if constexpr (OB) { u32x4 o; o[0] = pack2(x0[0], x0[1]); o[1] = pack2(x0[2], x0[3]); o[2] = pack2(x1[0], x1[1]); o[3] = pack2(x1[2], x1[3]);
;                         *(u32x4*)((bf16_t*)Xout + ro + bj * HALF) = o; }
;                     else { *(f32x4*)((float*)Xout + ro + bj * HALF) = x0; *(f32x4*)((float*)Xout + ro + bj * HALF + 4) = x1; } } }
	s_nop 1
	v_mov_b32_e32 v96, v176
	v_mov_b32_e32 v97, v177
	v_mov_b32_e32 v98, v178
	v_mov_b32_e32 v99, v179
	s_mov_b64 s[2:3], 0x30000
	s_waitcnt lgkmcnt(0)
	v_lshlrev_b32_e32 v104, 16, v96
	v_and_b32_e32 v105, 0xffff0000, v96
	v_lshlrev_b32_e32 v96, 16, v97
	v_and_b32_e32 v97, 0xffff0000, v97
	v_lshlrev_b32_e32 v106, 16, v98
	v_and_b32_e32 v107, 0xffff0000, v98
	v_lshlrev_b32_e32 v98, 16, v99
	v_and_b32_e32 v99, 0xffff0000, v99
	v_pk_add_f32 v[94:95], v[94:95], v[96:97]
	v_pk_add_f32 v[92:93], v[92:93], v[104:105]
	v_pk_add_f32 v[96:97], v[90:91], v[98:99]
	v_pk_add_f32 v[90:91], v[88:89], v[106:107]
	v_cvt_pk_bf16_f32 v88, v92, v93
	v_cvt_pk_bf16_f32 v89, v94, v95
	v_cvt_pk_bf16_f32 v90, v90, v91
	v_cvt_pk_bf16_f32 v91, v96, v97
	global_store_dwordx4 v[102:103], v[88:91], off
	s_waitcnt vmcnt(15)
	s_nop 1
	v_mov_b32_e32 v88, v180
	v_mov_b32_e32 v89, v181
	v_mov_b32_e32 v90, v182
	v_mov_b32_e32 v91, v183
	s_waitcnt lgkmcnt(0)
	v_lshlrev_b32_e32 v92, 16, v88
	v_and_b32_e32 v93, 0xffff0000, v88
	v_lshlrev_b32_e32 v88, 16, v89
	v_and_b32_e32 v89, 0xffff0000, v89
	v_lshlrev_b32_e32 v94, 16, v90
	v_and_b32_e32 v95, 0xffff0000, v90
	v_lshlrev_b32_e32 v90, 16, v91
	v_and_b32_e32 v91, 0xffff0000, v91
	v_pk_add_f32 v[86:87], v[86:87], v[88:89]
	v_pk_add_f32 v[84:85], v[84:85], v[92:93]
	v_pk_add_f32 v[88:89], v[82:83], v[90:91]
	v_pk_add_f32 v[82:83], v[80:81], v[94:95]
	v_cvt_pk_bf16_f32 v80, v84, v85
	v_cvt_pk_bf16_f32 v81, v86, v87
	v_cvt_pk_bf16_f32 v82, v82, v83
	v_cvt_pk_bf16_f32 v83, v88, v89
	global_store_dwordx4 v[100:101], v[80:83], off offset:256
	s_nop 1
	v_lshl_add_u64 v[80:81], v[144:145], 0, s[2:3]
	s_mov_b32 s2, 0x30000
	v_add_co_u32_e32 v86, vcc, s2, v144
	s_mov_b64 s[2:3], 0x80000
	s_nop 0
	v_addc_co_u32_e32 v87, vcc, 0, v145, vcc
	s_waitcnt vmcnt(15)
	s_nop 1
	v_mov_b32_e32 v82, v184
	v_mov_b32_e32 v83, v185
	v_mov_b32_e32 v84, v186
	v_mov_b32_e32 v85, v187
	s_waitcnt lgkmcnt(0)
	v_lshlrev_b32_e32 v88, 16, v82
	v_and_b32_e32 v89, 0xffff0000, v82
	v_lshlrev_b32_e32 v82, 16, v83
	v_and_b32_e32 v83, 0xffff0000, v83
	v_lshlrev_b32_e32 v90, 16, v84
	v_and_b32_e32 v91, 0xffff0000, v84
	v_lshlrev_b32_e32 v84, 16, v85
	v_and_b32_e32 v85, 0xffff0000, v85
	v_pk_add_f32 v[78:79], v[78:79], v[82:83]
	v_pk_add_f32 v[76:77], v[76:77], v[88:89]
	v_pk_add_f32 v[82:83], v[74:75], v[84:85]
	v_pk_add_f32 v[74:75], v[72:73], v[90:91]
	v_cvt_pk_bf16_f32 v72, v76, v77
	v_cvt_pk_bf16_f32 v73, v78, v79
	v_cvt_pk_bf16_f32 v74, v74, v75
	v_cvt_pk_bf16_f32 v75, v82, v83
	global_store_dwordx4 v[86:87], v[72:75], off
	s_waitcnt vmcnt(15)
	s_nop 1
	v_mov_b32_e32 v72, v188
	v_mov_b32_e32 v73, v189
	v_mov_b32_e32 v74, v190
	v_mov_b32_e32 v75, v191
	s_waitcnt lgkmcnt(0)
	v_lshlrev_b32_e32 v76, 16, v72
	v_and_b32_e32 v77, 0xffff0000, v72
	v_lshlrev_b32_e32 v72, 16, v73
	v_and_b32_e32 v73, 0xffff0000, v73
	v_lshlrev_b32_e32 v78, 16, v74
	v_and_b32_e32 v79, 0xffff0000, v74
	v_lshlrev_b32_e32 v74, 16, v75
	v_and_b32_e32 v75, 0xffff0000, v75
	v_pk_add_f32 v[70:71], v[70:71], v[72:73]
	v_pk_add_f32 v[68:69], v[68:69], v[76:77]
	v_pk_add_f32 v[72:73], v[66:67], v[74:75]
	v_pk_add_f32 v[66:67], v[64:65], v[78:79]
	v_cvt_pk_bf16_f32 v64, v68, v69
	v_cvt_pk_bf16_f32 v65, v70, v71
	v_cvt_pk_bf16_f32 v66, v66, v67
	v_cvt_pk_bf16_f32 v67, v72, v73
	global_store_dwordx4 v[80:81], v[64:67], off offset:256
	s_nop 1
	v_lshl_add_u64 v[64:65], v[144:145], 0, s[2:3]
	s_mov_b32 s2, 0x80000
	v_add_co_u32_e32 v70, vcc, s2, v144
	s_mov_b64 s[2:3], 0x90000
	s_nop 0
	v_addc_co_u32_e32 v71, vcc, 0, v145, vcc
	s_waitcnt vmcnt(15)
	s_nop 1
	v_mov_b32_e32 v66, v192
	v_mov_b32_e32 v67, v193
	v_mov_b32_e32 v68, v194
	v_mov_b32_e32 v69, v195
	s_waitcnt lgkmcnt(0)
	v_lshlrev_b32_e32 v72, 16, v66
	v_and_b32_e32 v73, 0xffff0000, v66
	v_lshlrev_b32_e32 v66, 16, v67
	v_and_b32_e32 v67, 0xffff0000, v67
	v_lshlrev_b32_e32 v74, 16, v68
	v_and_b32_e32 v75, 0xffff0000, v68
	v_lshlrev_b32_e32 v68, 16, v69
	v_and_b32_e32 v69, 0xffff0000, v69
	v_pk_add_f32 v[62:63], v[62:63], v[66:67]
	v_pk_add_f32 v[60:61], v[60:61], v[72:73]
	v_pk_add_f32 v[66:67], v[58:59], v[68:69]
	v_pk_add_f32 v[58:59], v[56:57], v[74:75]
	v_cvt_pk_bf16_f32 v56, v60, v61
	v_cvt_pk_bf16_f32 v57, v62, v63
	v_cvt_pk_bf16_f32 v58, v58, v59
	v_cvt_pk_bf16_f32 v59, v66, v67
	global_store_dwordx4 v[70:71], v[56:59], off
	s_waitcnt vmcnt(15)
	s_nop 1
	v_mov_b32_e32 v56, v198
	v_mov_b32_e32 v57, v199
	v_mov_b32_e32 v58, v200
	v_mov_b32_e32 v59, v201
	s_waitcnt lgkmcnt(0)
	v_lshlrev_b32_e32 v60, 16, v56
	v_and_b32_e32 v61, 0xffff0000, v56
	v_lshlrev_b32_e32 v56, 16, v57
	v_and_b32_e32 v57, 0xffff0000, v57
	v_lshlrev_b32_e32 v62, 16, v58
	v_and_b32_e32 v63, 0xffff0000, v58
	v_lshlrev_b32_e32 v58, 16, v59
	v_and_b32_e32 v59, 0xffff0000, v59
	v_pk_add_f32 v[54:55], v[54:55], v[56:57]
	v_pk_add_f32 v[52:53], v[52:53], v[60:61]
	v_pk_add_f32 v[56:57], v[50:51], v[58:59]
	v_pk_add_f32 v[50:51], v[48:49], v[62:63]
	v_cvt_pk_bf16_f32 v48, v52, v53
	v_cvt_pk_bf16_f32 v49, v54, v55
	v_cvt_pk_bf16_f32 v50, v50, v51
	v_cvt_pk_bf16_f32 v51, v56, v57
	global_store_dwordx4 v[64:65], v[48:51], off offset:256
	s_nop 1
	v_lshl_add_u64 v[48:49], v[144:145], 0, s[2:3]
	s_mov_b32 s2, 0x90000
	v_add_co_u32_e32 v54, vcc, s2, v144
	s_mov_b64 s[2:3], 0xa0000
	s_nop 0
	v_addc_co_u32_e32 v55, vcc, 0, v145, vcc
	s_waitcnt vmcnt(15)
; DI unsigned pack2(float a, float b) { f32x2 v = {a, b}; hwbf16x2 r = __builtin_convertvector(v, hwbf16x2); return __builtin_bit_cast(unsigned, r); }
; DI float bflo(unsigned w) { return __uint_as_float(w << 16); }
; DI float bfhi(unsigned w) { return __uint_as_float(w & 0xffff0000u); }
; #define PG8_WAIT_V(n) asm volatile("s_waitcnt vmcnt(" #n ")" ::: "memory")
; #define PG8_BAR __builtin_amdgcn_s_barrier()
;     DI void operator()(const f32x4 (&acc)[2][2][4][2], const Unit& u, int wr, int wc, int fr, int fq) const {
;     ...
;         for (int ai = 0; ai < 2; ++ai)
; #pragma unroll
;             for (int m = 0; m < 4; ++m) { const size_t ro = (size_t)(row0 + ai * HALF + m * 16) * D + col0;
; #pragma unroll
;                 for (int bj = 0; bj < 2; ++bj) {
;                     f32x4 x0, x1;
;                     if constexpr (IB) { const u32x4 w = *(const u32x4*)((const bf16_t*)Xin + ro + bj * HALF);
;                         x0 = (f32x4){bflo(w[0]), bfhi(w[0]), bflo(w[1]), bfhi(w[1])}; x1 = (f32x4){bflo(w[2]), bfhi(w[2]), bflo(w[3]), bfhi(w[3])}; }
;                     else { x0 = *(const f32x4*)((const float*)Xin + ro + bj * HALF); x1 = *(const f32x4*)((const float*)Xin + ro + bj * HALF + 4); }
;                     x0 += acc[ai][bj][m][0] * sc[bj][0]; x1 += acc[ai][bj][m][1] * sc[bj][1];
;                     if constexpr (OB) { u32x4 o; o[0] = pack2(x0[0], x0[1]); o[1] = pack2(x0[2], x0[3]); o[2] = pack2(x1[0], x1[1]); o[3] = pack2(x1[2], x1[3]);
;                         *(u32x4*)((bf16_t*)Xout + ro + bj * HALF) = o; }
;                     else { *(f32x4*)((float*)Xout + ro + bj * HALF) = x0; *(f32x4*)((float*)Xout + ro + bj * HALF + 4) = x1; } } }
; template <class Map, class Epi>
; DI void gemm_phase(LAS unsigned char* lds, const Map& MP, const Epi& E, const int nM, const int nN, const int K, const int lda, const int ldb) {
;     ...
;         cur = nxt; cA = nA; cB = nB; ++ui;
;     }
;     PG8_WAIT_V(0);
;     if (wr == 0) PG8_BAR;
;     PG8_BAR;
	s_nop 1
	v_mov_b32_e32 v50, v202
	v_mov_b32_e32 v51, v203
	v_mov_b32_e32 v52, v204
	v_mov_b32_e32 v53, v205
	s_waitcnt lgkmcnt(0)
	v_lshlrev_b32_e32 v56, 16, v50
	v_and_b32_e32 v57, 0xffff0000, v50
	v_lshlrev_b32_e32 v50, 16, v51
	v_and_b32_e32 v51, 0xffff0000, v51
	v_lshlrev_b32_e32 v58, 16, v52
	v_and_b32_e32 v59, 0xffff0000, v52
	v_lshlrev_b32_e32 v52, 16, v53
	v_and_b32_e32 v53, 0xffff0000, v53
	v_pk_add_f32 v[46:47], v[46:47], v[50:51]
	v_pk_add_f32 v[44:45], v[44:45], v[56:57]
	v_pk_add_f32 v[50:51], v[42:43], v[52:53]
	v_pk_add_f32 v[42:43], v[40:41], v[58:59]
	v_cvt_pk_bf16_f32 v40, v44, v45
	v_cvt_pk_bf16_f32 v41, v46, v47
	v_cvt_pk_bf16_f32 v42, v42, v43
	v_cvt_pk_bf16_f32 v43, v50, v51
	global_store_dwordx4 v[54:55], v[40:43], off
	s_waitcnt vmcnt(15)
	s_nop 1
	v_mov_b32_e32 v40, v206
	v_mov_b32_e32 v41, v207
	v_mov_b32_e32 v42, v208
	v_mov_b32_e32 v43, v209
	s_waitcnt lgkmcnt(0)
	v_lshlrev_b32_e32 v44, 16, v40
	v_and_b32_e32 v45, 0xffff0000, v40
	v_lshlrev_b32_e32 v40, 16, v41
	v_and_b32_e32 v41, 0xffff0000, v41
	v_lshlrev_b32_e32 v46, 16, v42
	v_and_b32_e32 v47, 0xffff0000, v42
	v_lshlrev_b32_e32 v42, 16, v43
	v_and_b32_e32 v43, 0xffff0000, v43
	v_pk_add_f32 v[38:39], v[38:39], v[40:41]
	v_pk_add_f32 v[36:37], v[36:37], v[44:45]
	v_pk_add_f32 v[40:41], v[34:35], v[42:43]
	v_pk_add_f32 v[34:35], v[32:33], v[46:47]
	v_cvt_pk_bf16_f32 v32, v36, v37
	v_cvt_pk_bf16_f32 v33, v38, v39
	v_cvt_pk_bf16_f32 v34, v34, v35
	v_cvt_pk_bf16_f32 v35, v40, v41
	global_store_dwordx4 v[48:49], v[32:35], off offset:256
	s_nop 1
	v_lshl_add_u64 v[32:33], v[144:145], 0, s[2:3]
	s_mov_b32 s2, 0xa0000
	v_add_co_u32_e32 v38, vcc, s2, v144
	s_mov_b64 s[2:3], 0xb0000
	s_nop 0
	v_addc_co_u32_e32 v39, vcc, 0, v145, vcc
	s_waitcnt vmcnt(15)
	s_nop 1
	v_mov_b32_e32 v34, v210
	v_mov_b32_e32 v35, v211
	v_mov_b32_e32 v36, v212
	v_mov_b32_e32 v37, v213
	s_waitcnt lgkmcnt(0)
	v_lshlrev_b32_e32 v40, 16, v34
	v_and_b32_e32 v41, 0xffff0000, v34
	v_lshlrev_b32_e32 v34, 16, v35
	v_and_b32_e32 v35, 0xffff0000, v35
	v_lshlrev_b32_e32 v42, 16, v36
	v_and_b32_e32 v43, 0xffff0000, v36
	v_lshlrev_b32_e32 v36, 16, v37
	v_and_b32_e32 v37, 0xffff0000, v37
	v_pk_add_f32 v[30:31], v[30:31], v[34:35]
	v_pk_add_f32 v[28:29], v[28:29], v[40:41]
	v_pk_add_f32 v[34:35], v[26:27], v[36:37]
	v_pk_add_f32 v[26:27], v[24:25], v[42:43]
	v_cvt_pk_bf16_f32 v24, v28, v29
	v_cvt_pk_bf16_f32 v25, v30, v31
	v_cvt_pk_bf16_f32 v26, v26, v27
	v_cvt_pk_bf16_f32 v27, v34, v35
	global_store_dwordx4 v[38:39], v[24:27], off
	s_waitcnt vmcnt(15)
	s_nop 1
	v_mov_b32_e32 v24, v214
	v_mov_b32_e32 v25, v215
	v_mov_b32_e32 v26, v216
	v_mov_b32_e32 v27, v217
	s_waitcnt lgkmcnt(0)
	v_lshlrev_b32_e32 v28, 16, v24
	v_and_b32_e32 v29, 0xffff0000, v24
	v_lshlrev_b32_e32 v24, 16, v25
	v_and_b32_e32 v25, 0xffff0000, v25
	v_lshlrev_b32_e32 v30, 16, v26
	v_and_b32_e32 v31, 0xffff0000, v26
	v_lshlrev_b32_e32 v26, 16, v27
	v_and_b32_e32 v27, 0xffff0000, v27
	v_pk_add_f32 v[22:23], v[22:23], v[24:25]
	v_pk_add_f32 v[20:21], v[20:21], v[28:29]
	v_pk_add_f32 v[24:25], v[18:19], v[26:27]
	v_pk_add_f32 v[18:19], v[16:17], v[30:31]
	v_cvt_pk_bf16_f32 v16, v20, v21
	v_cvt_pk_bf16_f32 v17, v22, v23
	v_cvt_pk_bf16_f32 v18, v18, v19
	v_cvt_pk_bf16_f32 v19, v24, v25
	global_store_dwordx4 v[32:33], v[16:19], off offset:256
	s_nop 1
	v_lshl_add_u64 v[16:17], v[144:145], 0, s[2:3]
	s_mov_b32 s2, 0xb0000
	v_add_co_u32_e32 v22, vcc, s2, v144
	s_mov_b32 s2, s46
	s_nop 0
	v_addc_co_u32_e32 v23, vcc, 0, v145, vcc
	s_waitcnt vmcnt(15)
	s_nop 1
	v_mov_b32_e32 v18, v248
	v_mov_b32_e32 v19, v249
	v_mov_b32_e32 v20, v250
	v_mov_b32_e32 v21, v251
	s_and_b64 vcc, exec, s[40:41]
	s_waitcnt lgkmcnt(0)
	v_lshlrev_b32_e32 v24, 16, v18
	v_and_b32_e32 v25, 0xffff0000, v18
	v_lshlrev_b32_e32 v18, 16, v19
	v_and_b32_e32 v19, 0xffff0000, v19
	v_lshlrev_b32_e32 v26, 16, v20
	v_and_b32_e32 v27, 0xffff0000, v20
	v_lshlrev_b32_e32 v20, 16, v21
	v_and_b32_e32 v21, 0xffff0000, v21
	v_pk_add_f32 v[14:15], v[14:15], v[18:19]
	v_pk_add_f32 v[12:13], v[12:13], v[24:25]
	v_pk_add_f32 v[18:19], v[10:11], v[20:21]
	v_pk_add_f32 v[10:11], v[8:9], v[26:27]
	v_cvt_pk_bf16_f32 v8, v12, v13
	v_cvt_pk_bf16_f32 v9, v14, v15
	v_cvt_pk_bf16_f32 v10, v10, v11
	v_cvt_pk_bf16_f32 v11, v18, v19
	global_store_dwordx4 v[22:23], v[8:11], off
	s_waitcnt vmcnt(15)
	s_nop 1
	v_mov_b32_e32 v8, v252
	v_mov_b32_e32 v9, v253
	v_mov_b32_e32 v10, v254
	v_mov_b32_e32 v11, v255
	s_waitcnt lgkmcnt(0)
	v_lshlrev_b32_e32 v12, 16, v8
	v_and_b32_e32 v13, 0xffff0000, v8
	v_lshlrev_b32_e32 v8, 16, v9
	v_and_b32_e32 v9, 0xffff0000, v9
	v_lshlrev_b32_e32 v14, 16, v10
	v_and_b32_e32 v15, 0xffff0000, v10
	v_lshlrev_b32_e32 v10, 16, v11
	v_and_b32_e32 v11, 0xffff0000, v11
	v_pk_add_f32 v[6:7], v[6:7], v[8:9]
	v_pk_add_f32 v[4:5], v[4:5], v[12:13]
	v_pk_add_f32 v[8:9], v[2:3], v[10:11]
	v_pk_add_f32 v[2:3], v[0:1], v[14:15]
	v_cvt_pk_bf16_f32 v0, v4, v5
	v_cvt_pk_bf16_f32 v1, v6, v7
	v_cvt_pk_bf16_f32 v2, v2, v3
	v_cvt_pk_bf16_f32 v3, v8, v9
	global_store_dwordx4 v[16:17], v[0:3], off offset:256
	s_cbranch_vccz .LBB1_922
	s_waitcnt vmcnt(0)
	s_cmpk_gt_u32 s17, 0xff
	s_cbranch_scc1 .LBB1_929
	s_barrier

;     DI const char* a(const Unit& u) const { return (const char*)(A + (size_t)u.pm * BM * lda); }
;     DI const char* a(const Unit& u) const { return (const char*)(A + (size_t)u.pm * BM * 2048 + (u.pn >> 1) * 512); }
;     DI const char* a(const Unit& u) const { return (const char*)((u.pn < 12 ? A1 : A2) + (size_t)u.pm * BM * 512); }
; #define PG8_STAGE(bufoff, gbase, voff) do { _Pragma("unroll") for (int _i = 0; _i < 2; ++_i) \
;         __builtin_amdgcn_global_load_lds((const unsigned*)((const char*)(gbase) + (voff)[_i]), (LAS unsigned*)(lds + (bufoff) + ldsw + _i * 8192), 16, 0, 0); } while (0)
; #define PG8_LDA(dst, b, h) do { _Pragma("unroll") for (int m = 0; m < 4; ++m) _Pragma("unroll") for (int k = 0; k < 2; ++k) dst[m][k] = *(const LAS bf16x8*)(lds + PG8_SA(b, h) + aoff + m * 2048 + k * 1024); } while (0)
; template <class Map, class Epi>
; DI void gemm_phase(LAS unsigned char* lds, const Map& MP, const Epi& E, const int nM, const int nN, const int K, const int lda, const int ldb) {
;     ...
;         const bool has_next = sched_next(ui + 1, nM, nN, G, cblk, nxt);
;         const char* nA = has_next ? MP.a(nxt) : cA; const char* nB = has_next ? MP.b(nxt) : cB;
;         for (int t = 0; t < nt; t += 2) {
;             const bool last = (t == nt - 2);
;             const char* a1 = cA + (size_t)(t + 1) * kstep;
;             const char* a2 = last ? nA : cA + (size_t)(t + 2) * kstep; const char* b2 = last ? nB : cB + (size_t)(t + 2) * kstep;
;             const char* a3 = a2 + kstep; const char* b3 = b2 + kstep;
;             PG8_LDB(B0, 0, 0); PG8_SCHED; PG8_LDA(At, 0, 0); PG8_STAGE(PG8_SA(1, 1), a1 + hstepA, voffA);
;             PG8_WAIT_L(8); PG8_BAR; PG8_WAIT_L(0); PG8_MMA(0, 0, At, B0); PG8_BAR; PG8_SCHED;
;             PG8_LDB(B1, 0, 1); PG8_STAGE(PG8_SB(0, 0), b2, voffB);
;             PG8_BAR; PG8_WAIT_L(0); PG8_MMA(0, 1, At, B1); PG8_BAR;
;             PG8_LDA(At, 0, 1); PG8_STAGE(PG8_SA(0, 0), a2, voffA);
;             PG8_BAR; PG8_WAIT_L(0); PG8_MMA(1, 0, At, B0); PG8_BAR; PG8_SCHED;
;     ...
; #pragma unroll
;         for (int a = 0; a < 2; ++a)
; #pragma unroll
;             for (int b = 0; b < 2; ++b)
; #pragma unroll
;                 for (int m = 0; m < 4; ++m)
; #pragma unroll
;                     for (int n = 0; n < 2; ++n) acc[a][b][m][n] = (f32x4){0.f, 0.f, 0.f, 0.f};
;         cur = nxt; cA = nA; cB = nB; ++ui;
.LBB1_1068:
	s_ashr_i32 s23, s22, 31
	v_cmp_lt_i64_e32 vcc, s[26:27], v[180:181]
	s_lshl_b64 s[26:27], s[22:23], 20
	s_add_u32 s28, s34, s26
	s_addc_u32 s29, s35, s27
	s_and_b64 s[26:27], vcc, exec
	s_cselect_b32 s23, s29, s25
	s_cselect_b32 s58, s28, s24
	s_ashr_i32 s21, s20, 31
	s_lshl_b64 s[26:27], s[20:21], 20
	s_add_u32 s26, s36, s26
	s_addc_u32 s27, s37, s27
	s_and_b64 s[42:43], vcc, exec
	s_cselect_b32 s21, s27, s47
	s_cselect_b32 s59, s26, s46
	s_add_u32 vcc_lo, s46, 0x100
	s_addc_u32 vcc_hi, s47, 0
	s_add_u32 s42, s24, 0x80080
	v_mov_b32_e32 v0, 0
	s_addc_u32 s43, s25, 0
	s_mov_b32 s3, -2
	v_mov_b32_e32 v1, 0
	v_mov_b64_e32 v[2:3], 0
	v_mov_b64_e32 v[4:5], 0
	v_mov_b64_e32 v[6:7], 0
	v_mov_b64_e32 v[8:9], 0
	v_mov_b64_e32 v[10:11], 0
	v_mov_b64_e32 v[12:13], 0
	v_mov_b64_e32 v[14:15], 0
	v_mov_b64_e32 v[16:17], 0
	v_mov_b64_e32 v[18:19], 0
	v_mov_b64_e32 v[20:21], 0
	v_mov_b64_e32 v[22:23], 0
	v_mov_b64_e32 v[24:25], 0
	v_mov_b64_e32 v[26:27], 0
	v_mov_b64_e32 v[28:29], 0
	v_mov_b64_e32 v[30:31], 0
	v_mov_b64_e32 v[32:33], 0
	v_mov_b64_e32 v[34:35], 0
	v_mov_b64_e32 v[36:37], 0
	v_mov_b64_e32 v[38:39], 0
	v_mov_b64_e32 v[40:41], 0
	v_mov_b64_e32 v[42:43], 0
	v_mov_b64_e32 v[44:45], 0
	v_mov_b64_e32 v[46:47], 0
	v_mov_b64_e32 v[48:49], 0
	v_mov_b64_e32 v[50:51], 0
	v_mov_b64_e32 v[52:53], 0
	v_mov_b64_e32 v[54:55], 0
	v_mov_b64_e32 v[56:57], 0
	v_mov_b64_e32 v[58:59], 0
	v_mov_b64_e32 v[60:61], 0
	v_mov_b64_e32 v[62:63], 0
	v_mov_b64_e32 v[64:65], 0
	v_mov_b64_e32 v[66:67], 0
	v_mov_b64_e32 v[68:69], 0
	v_mov_b64_e32 v[70:71], 0
	v_mov_b64_e32 v[72:73], 0
	v_mov_b64_e32 v[74:75], 0
	v_mov_b64_e32 v[76:77], 0
	v_mov_b64_e32 v[78:79], 0
	v_mov_b64_e32 v[104:105], 0
	v_mov_b64_e32 v[106:107], 0
	v_mov_b64_e32 v[116:117], 0
	v_mov_b64_e32 v[118:119], 0
	v_mov_b64_e32 v[120:121], 0
	v_mov_b64_e32 v[122:123], 0
	v_mov_b64_e32 v[124:125], 0
	v_mov_b64_e32 v[126:127], 0
	v_mov_b64_e32 v[128:129], 0
	v_mov_b64_e32 v[130:131], 0
	v_mov_b64_e32 v[132:133], 0
	v_mov_b64_e32 v[134:135], 0
	v_mov_b64_e32 v[136:137], 0
	v_mov_b64_e32 v[138:139], 0
	v_mov_b64_e32 v[140:141], 0
	v_mov_b64_e32 v[142:143], 0
	v_mov_b64_e32 v[144:145], 0
	v_mov_b64_e32 v[146:147], 0
	v_mov_b64_e32 v[148:149], 0
	v_mov_b64_e32 v[150:151], 0
	v_mov_b64_e32 v[152:153], 0
	v_mov_b64_e32 v[154:155], 0
	v_mov_b64_e32 v[156:157], 0
	v_mov_b64_e32 v[158:159], 0
	ds_read_b128 v[80:83], v189
	ds_read_b128 v[84:87], v189 offset:1024
	ds_read_b128 v[88:91], v189 offset:2048
	ds_read_b128 v[92:95], v189 offset:3072
	s_add_u32 s24, s42, 0xfff80080
	s_addc_u32 s25, s43, -1
	s_cmp_eq_u32 s3, 28
	s_cselect_b32 s47, s23, s25
	s_cselect_b32 s46, s58, s24
	s_cselect_b32 s25, s21, vcc_hi
	s_cselect_b32 s24, s59, vcc_lo
.LBB1_1069:
	s_add_i32 m0, s38, 0xc000
	ds_read_b128 v[96:99], v190
	ds_read_b128 v[100:103], v190 offset:1024
	ds_read_b128 v[108:111], v190 offset:2048
	ds_read_b128 v[112:115], v190 offset:3072
	ds_read_b128 v[160:163], v190 offset:4096
	ds_read_b128 v[164:167], v190 offset:5120
	ds_read_b128 v[198:201], v190 offset:6144
	ds_read_b128 v[202:205], v190 offset:7168
	global_load_lds_dwordx4 v178, s[42:43]
	s_add_i32 m0, s38, 0xe000
	s_nop 0
	global_load_lds_dwordx4 v176, s[42:43]
	s_waitcnt lgkmcnt(8)
	s_setprio 1
	s_barrier
	s_waitcnt lgkmcnt(7)
	v_mfma_f32_16x16x32_bf16 v[148:151], v[80:83], v[96:99], v[148:151]
	v_mfma_f32_16x16x32_bf16 v[144:147], v[88:91], v[96:99], v[144:147]
	s_waitcnt lgkmcnt(5)
	v_mfma_f32_16x16x32_bf16 v[136:139], v[80:83], v[108:111], v[136:139]
	v_mfma_f32_16x16x32_bf16 v[128:131], v[88:91], v[108:111], v[128:131]
	s_waitcnt lgkmcnt(3)
	v_mfma_f32_16x16x32_bf16 v[120:123], v[80:83], v[160:163], v[120:123]
	v_mfma_f32_16x16x32_bf16 v[104:107], v[88:91], v[160:163], v[104:107]
	s_waitcnt lgkmcnt(1)
	v_mfma_f32_16x16x32_bf16 v[76:79], v[80:83], v[198:201], v[76:79]
	v_mfma_f32_16x16x32_bf16 v[72:75], v[88:91], v[198:201], v[72:75]
	v_mfma_f32_16x16x32_bf16 v[148:151], v[84:87], v[100:103], v[148:151]
	s_add_i32 s68, s31, s66
	v_mfma_f32_16x16x32_bf16 v[144:147], v[92:95], v[100:103], v[144:147]
	v_lshl_add_u64 v[184:185], s[24:25], 0, v[172:173]
	v_mfma_f32_16x16x32_bf16 v[136:139], v[84:87], v[112:115], v[136:139]
	v_lshl_add_u64 v[194:195], s[24:25], 0, v[168:169]
	v_mfma_f32_16x16x32_bf16 v[128:131], v[92:95], v[112:115], v[128:131]
	v_mfma_f32_16x16x32_bf16 v[120:123], v[84:87], v[164:167], v[120:123]
	v_mfma_f32_16x16x32_bf16 v[104:107], v[92:95], v[164:167], v[104:107]
	s_waitcnt lgkmcnt(0)
	v_mfma_f32_16x16x32_bf16 v[76:79], v[84:87], v[202:205], v[76:79]
	v_mfma_f32_16x16x32_bf16 v[72:75], v[92:95], v[202:205], v[72:75]
	s_barrier
	s_setprio 0
	s_mov_b32 m0, s68
	ds_read_b128 v[206:209], v191
	ds_read_b128 v[210:213], v191 offset:1024
	ds_read_b128 v[214:217], v191 offset:2048
	ds_read_b128 v[218:221], v191 offset:3072
	global_load_lds_dwordx4 v[184:185], off
	s_add_i32 m0, s68, 0x2000
	s_nop 0
	global_load_lds_dwordx4 v[194:195], off
	s_setprio 1
	s_barrier
	s_waitcnt lgkmcnt(3)
	v_mfma_f32_16x16x32_bf16 v[156:159], v[206:209], v[96:99], v[156:159]
	s_waitcnt lgkmcnt(1)
	v_mfma_f32_16x16x32_bf16 v[96:99], v[214:217], v[96:99], v[152:155]
	v_mfma_f32_16x16x32_bf16 v[156:159], v[210:213], v[100:103], v[156:159]
	s_waitcnt lgkmcnt(0)
	v_mfma_f32_16x16x32_bf16 v[96:99], v[218:221], v[100:103], v[96:99]
	v_mfma_f32_16x16x32_bf16 v[100:103], v[206:209], v[108:111], v[140:143]
	v_mfma_f32_16x16x32_bf16 v[108:111], v[214:217], v[108:111], v[132:135]
	v_mfma_f32_16x16x32_bf16 v[116:119], v[214:217], v[160:163], v[116:119]
	v_mfma_f32_16x16x32_bf16 v[68:71], v[206:209], v[198:201], v[68:71]
	v_mfma_f32_16x16x32_bf16 v[64:67], v[214:217], v[198:201], v[64:67]
	v_lshl_add_u64 v[234:235], s[46:47], 0, v[170:171]
	s_mov_b32 m0, s38
	v_mfma_f32_16x16x32_bf16 v[100:103], v[210:213], v[112:115], v[100:103]
	v_lshl_add_u64 v[226:227], s[46:47], 0, v[174:175]
	v_mfma_f32_16x16x32_bf16 v[108:111], v[218:221], v[112:115], v[108:111]
	v_mfma_f32_16x16x32_bf16 v[112:115], v[206:209], v[160:163], v[124:127]
	v_mfma_f32_16x16x32_bf16 v[116:119], v[218:221], v[164:167], v[116:119]
	v_mfma_f32_16x16x32_bf16 v[68:71], v[210:213], v[202:205], v[68:71]
	v_mfma_f32_16x16x32_bf16 v[64:67], v[218:221], v[202:205], v[64:67]
	v_mfma_f32_16x16x32_bf16 v[112:115], v[210:213], v[164:167], v[112:115]
	s_barrier
; #define PG8_STAGE(bufoff, gbase, voff) do { _Pragma("unroll") for (int _i = 0; _i < 2; ++_i) \
;         __builtin_amdgcn_global_load_lds((const unsigned*)((const char*)(gbase) + (voff)[_i]), (LAS unsigned*)(lds + (bufoff) + ldsw + _i * 8192), 16, 0, 0); } while (0)
; #define PG8_LDA(dst, b, h) do { _Pragma("unroll") for (int m = 0; m < 4; ++m) _Pragma("unroll") for (int k = 0; k < 2; ++k) dst[m][k] = *(const LAS bf16x8*)(lds + PG8_SA(b, h) + aoff + m * 2048 + k * 1024); } while (0)
; #define PG8_LDB(dst, b, h) do { _Pragma("unroll") for (int n = 0; n < 2; ++n) _Pragma("unroll") for (int k = 0; k < 2; ++k) dst[n][k] = *(const LAS bf16x8*)(lds + PG8_SB(b, h) + boff + n * 2048 + k * 1024); } while (0)
; #define PG8_MMA(ai, bj, At, Bt) do { __builtin_amdgcn_s_setprio(1); _Pragma("unroll") for (int m = 0; m < 4; ++m) _Pragma("unroll") for (int n = 0; n < 2; ++n) _Pragma("unroll") for (int k = 0; k < 2; ++k) \
;         acc[ai][bj][m][n] = __builtin_amdgcn_mfma_f32_16x16x32_bf16(Bt[n][k], At[m][k], acc[ai][bj][m][n], 0, 0, 0); __builtin_amdgcn_s_setprio(0); } while (0)
; #define PG8_WAIT_V(n) asm volatile("s_waitcnt vmcnt(" #n ")" ::: "memory")
; #define PG8_WAIT_L(n) asm volatile("s_waitcnt lgkmcnt(" #n ")" ::: "memory")
; #define PG8_BAR __builtin_amdgcn_s_barrier()
; #define PG8_SCHED __builtin_amdgcn_sched_barrier(0)
; template <class Map, class Epi>
; DI void gemm_phase(LAS unsigned char* lds, const Map& MP, const Epi& E, const int nM, const int nN, const int K, const int lda, const int ldb) {
;     ...
;             PG8_BAR; PG8_WAIT_L(0); PG8_MMA(1, 0, At, B0); PG8_BAR; PG8_SCHED;
;             PG8_STAGE(PG8_SB(0, 1), b2 + hstepB, voffB);
;             PG8_WAIT_V(6); PG8_BAR; PG8_MMA(1, 1, At, B1); PG8_BAR;
;             PG8_LDB(B0, 1, 0); PG8_SCHED; PG8_LDA(At, 1, 0); PG8_STAGE(PG8_SA(0, 1), a2 + hstepA, voffA);
;             PG8_WAIT_L(8); PG8_BAR; PG8_WAIT_L(0); PG8_MMA(0, 0, At, B0); PG8_BAR; PG8_SCHED;
;             PG8_LDB(B1, 1, 1); PG8_STAGE(PG8_SB(1, 0), b3, voffB);
;             PG8_BAR; PG8_WAIT_L(0); PG8_MMA(0, 1, At, B1); PG8_BAR;
;             PG8_LDA(At, 1, 1); PG8_STAGE(PG8_SA(1, 0), a3, voffA);
;             PG8_BAR; PG8_WAIT_L(0); PG8_MMA(1, 0, At, B0); PG8_BAR; PG8_SCHED;
	s_setprio 0
	ds_read_b128 v[124:127], v190 offset:16384
	ds_read_b128 v[132:135], v190 offset:17408
	ds_read_b128 v[140:143], v190 offset:18432
	ds_read_b128 v[152:155], v190 offset:19456
	ds_read_b128 v[160:163], v190 offset:20480
	ds_read_b128 v[164:167], v190 offset:21504
	ds_read_b128 v[198:201], v190 offset:22528
	ds_read_b128 v[202:205], v190 offset:23552
	global_load_lds_dwordx4 v[226:227], off
	s_mov_b32 m0, s39
	s_nop 0
	global_load_lds_dwordx4 v[234:235], off
	s_waitcnt vmcnt(10)
	s_setprio 1
	s_barrier
	s_waitcnt lgkmcnt(7)
	v_mfma_f32_16x16x32_bf16 v[60:63], v[80:83], v[124:127], v[60:63]
	v_mfma_f32_16x16x32_bf16 v[48:51], v[88:91], v[124:127], v[48:51]
	s_waitcnt lgkmcnt(5)
	v_mfma_f32_16x16x32_bf16 v[40:43], v[80:83], v[140:143], v[40:43]
	v_mfma_f32_16x16x32_bf16 v[32:35], v[88:91], v[140:143], v[32:35]
	s_waitcnt lgkmcnt(3)
	v_mfma_f32_16x16x32_bf16 v[24:27], v[80:83], v[160:163], v[24:27]
	v_mfma_f32_16x16x32_bf16 v[16:19], v[88:91], v[160:163], v[16:19]
	s_waitcnt lgkmcnt(1)
	v_mfma_f32_16x16x32_bf16 v[12:15], v[80:83], v[198:201], v[12:15]
	v_mfma_f32_16x16x32_bf16 v[8:11], v[88:91], v[198:201], v[8:11]
	v_mfma_f32_16x16x32_bf16 v[60:63], v[84:87], v[132:135], v[60:63]
	s_add_u32 s68, s24, 0x80000
	s_addc_u32 s69, s25, 0
	v_mfma_f32_16x16x32_bf16 v[48:51], v[92:95], v[132:135], v[48:51]
	s_add_i32 s70, s2, s66
	v_mfma_f32_16x16x32_bf16 v[40:43], v[84:87], v[152:155], v[40:43]
	v_mfma_f32_16x16x32_bf16 v[32:35], v[92:95], v[152:155], v[32:35]
	v_mfma_f32_16x16x32_bf16 v[24:27], v[84:87], v[164:167], v[24:27]
	v_mfma_f32_16x16x32_bf16 v[16:19], v[92:95], v[164:167], v[16:19]
	s_waitcnt lgkmcnt(0)
	v_mfma_f32_16x16x32_bf16 v[12:15], v[84:87], v[202:205], v[12:15]
	v_mfma_f32_16x16x32_bf16 v[8:11], v[92:95], v[202:205], v[8:11]
	s_barrier
	s_setprio 0
	s_mov_b32 m0, s70
	s_nop 0
	global_load_lds_dwordx4 v172, s[68:69]
	s_add_i32 m0, s70, 0x2000
	s_nop 0
	global_load_lds_dwordx4 v168, s[68:69]
	s_waitcnt vmcnt(6)
	s_setprio 1
	s_barrier
	v_mfma_f32_16x16x32_bf16 v[56:59], v[206:209], v[124:127], v[56:59]
	v_mfma_f32_16x16x32_bf16 v[52:55], v[214:217], v[124:127], v[52:55]
	s_add_i32 s68, 0, 0x18000
	v_add_u32_e32 v92, s68, v188
	ds_read_b128 v[80:83], v92
	v_mfma_f32_16x16x32_bf16 v[44:47], v[206:209], v[140:143], v[44:47]
	v_mfma_f32_16x16x32_bf16 v[36:39], v[214:217], v[140:143], v[36:39]
	ds_read_b128 v[84:87], v92 offset:1024
	v_mfma_f32_16x16x32_bf16 v[28:31], v[206:209], v[160:163], v[28:31]
	v_mfma_f32_16x16x32_bf16 v[20:23], v[214:217], v[160:163], v[20:23]
	ds_read_b128 v[88:91], v92 offset:2048
	v_mfma_f32_16x16x32_bf16 v[4:7], v[206:209], v[198:201], v[4:7]
	v_mfma_f32_16x16x32_bf16 v[0:3], v[214:217], v[198:201], v[0:3]
	ds_read_b128 v[92:95], v92 offset:3072
	v_mfma_f32_16x16x32_bf16 v[56:59], v[210:213], v[132:135], v[56:59]
	s_add_u32 s46, s46, 0x80000
	s_addc_u32 s47, s47, 0
	v_mfma_f32_16x16x32_bf16 v[52:55], v[218:221], v[132:135], v[52:55]
	v_mfma_f32_16x16x32_bf16 v[44:47], v[210:213], v[152:155], v[44:47]
	v_mfma_f32_16x16x32_bf16 v[36:39], v[218:221], v[152:155], v[36:39]
	v_mfma_f32_16x16x32_bf16 v[28:31], v[210:213], v[164:167], v[28:31]
	v_mfma_f32_16x16x32_bf16 v[20:23], v[218:221], v[164:167], v[20:23]
	v_mfma_f32_16x16x32_bf16 v[4:7], v[210:213], v[202:205], v[4:7]
	v_mfma_f32_16x16x32_bf16 v[0:3], v[218:221], v[202:205], v[0:3]
	s_barrier
	s_setprio 0
	s_mov_b32 m0, s56
	ds_read_b128 v[124:127], v190 offset:32768
	ds_read_b128 v[132:135], v190 offset:33792
	ds_read_b128 v[160:163], v190 offset:34816
	ds_read_b128 v[164:167], v190 offset:35840
	ds_read_b128 v[198:201], v190 offset:36864
	ds_read_b128 v[202:205], v190 offset:37888
	ds_read_b128 v[206:209], v190 offset:38912
	ds_read_b128 v[210:213], v190 offset:39936
	global_load_lds_dwordx4 v174, s[46:47]
	s_mov_b32 m0, s57
	s_nop 0
	global_load_lds_dwordx4 v170, s[46:47]
	s_waitcnt lgkmcnt(8)
	s_setprio 1
	s_barrier
	s_waitcnt lgkmcnt(7)
	v_mfma_f32_16x16x32_bf16 v[140:143], v[80:83], v[124:127], v[148:151]
	s_waitcnt lgkmcnt(6)
	v_mfma_f32_16x16x32_bf16 v[148:151], v[84:87], v[132:135], v[140:143]
	v_mfma_f32_16x16x32_bf16 v[140:143], v[88:91], v[124:127], v[144:147]
	s_waitcnt lgkmcnt(5)
	v_mfma_f32_16x16x32_bf16 v[136:139], v[80:83], v[160:163], v[136:139]
	v_mfma_f32_16x16x32_bf16 v[128:131], v[88:91], v[160:163], v[128:131]
	s_waitcnt lgkmcnt(3)
	v_mfma_f32_16x16x32_bf16 v[120:123], v[80:83], v[198:201], v[120:123]
	v_mfma_f32_16x16x32_bf16 v[104:107], v[88:91], v[198:201], v[104:107]
	s_waitcnt lgkmcnt(1)
	v_mfma_f32_16x16x32_bf16 v[76:79], v[80:83], v[206:209], v[76:79]
	v_mfma_f32_16x16x32_bf16 v[72:75], v[88:91], v[206:209], v[72:75]
	s_add_i32 s46, 0, 0x1c000
	v_mfma_f32_16x16x32_bf16 v[144:147], v[92:95], v[132:135], v[140:143]
	v_add_u32_e32 v140, s46, v188
	v_mfma_f32_16x16x32_bf16 v[136:139], v[84:87], v[164:167], v[136:139]
	s_add_i32 s47, s68, s66
	v_mfma_f32_16x16x32_bf16 v[128:131], v[92:95], v[164:167], v[128:131]
	v_mfma_f32_16x16x32_bf16 v[120:123], v[84:87], v[202:205], v[120:123]
	v_mfma_f32_16x16x32_bf16 v[104:107], v[92:95], v[202:205], v[104:107]
	s_waitcnt lgkmcnt(0)
	v_mfma_f32_16x16x32_bf16 v[76:79], v[84:87], v[210:213], v[76:79]
	v_mfma_f32_16x16x32_bf16 v[72:75], v[92:95], v[210:213], v[72:75]
	s_barrier
	s_setprio 0
	ds_read_b128 v[214:217], v140
	ds_read_b128 v[218:221], v140 offset:1024
	ds_read_b128 v[222:225], v140 offset:2048
	ds_read_b128 v[230:233], v140 offset:3072
	v_lshl_add_u64 v[140:141], v[184:185], 0, s[14:15]
	s_mov_b32 m0, s47
	s_nop 0
	global_load_lds_dwordx4 v[140:141], off
	v_lshl_add_u64 v[140:141], v[194:195], 0, s[14:15]
	s_add_i32 m0, s47, 0x2000
	s_nop 0
	global_load_lds_dwordx4 v[140:141], off
	s_setprio 1
	s_barrier
; #define PG8_STAGE(bufoff, gbase, voff) do { _Pragma("unroll") for (int _i = 0; _i < 2; ++_i) \
;         __builtin_amdgcn_global_load_lds((const unsigned*)((const char*)(gbase) + (voff)[_i]), (LAS unsigned*)(lds + (bufoff) + ldsw + _i * 8192), 16, 0, 0); } while (0)
; #define PG8_LDA(dst, b, h) do { _Pragma("unroll") for (int m = 0; m < 4; ++m) _Pragma("unroll") for (int k = 0; k < 2; ++k) dst[m][k] = *(const LAS bf16x8*)(lds + PG8_SA(b, h) + aoff + m * 2048 + k * 1024); } while (0)
; #define PG8_MMA(ai, bj, At, Bt) do { __builtin_amdgcn_s_setprio(1); _Pragma("unroll") for (int m = 0; m < 4; ++m) _Pragma("unroll") for (int n = 0; n < 2; ++n) _Pragma("unroll") for (int k = 0; k < 2; ++k) \
;         acc[ai][bj][m][n] = __builtin_amdgcn_mfma_f32_16x16x32_bf16(Bt[n][k], At[m][k], acc[ai][bj][m][n], 0, 0, 0); __builtin_amdgcn_s_setprio(0); } while (0)
; #define PG8_WAIT_V(n) asm volatile("s_waitcnt vmcnt(" #n ")" ::: "memory")
; #define PG8_WAIT_L(n) asm volatile("s_waitcnt lgkmcnt(" #n ")" ::: "memory")
; #define PG8_BAR __builtin_amdgcn_s_barrier()
; #define PG8_SCHED __builtin_amdgcn_sched_barrier(0)
; template <class Map, class Epi>
; DI void gemm_phase(LAS unsigned char* lds, const Map& MP, const Epi& E, const int nM, const int nN, const int K, const int lda, const int ldb) {
;     ...
;             const bool last = (t == nt - 2);
;             const char* a1 = cA + (size_t)(t + 1) * kstep;
;             const char* a2 = last ? nA : cA + (size_t)(t + 2) * kstep; const char* b2 = last ? nB : cB + (size_t)(t + 2) * kstep;
;     ...
;             PG8_LDA(At, 1, 1); PG8_STAGE(PG8_SA(1, 0), a3, voffA);
;             PG8_BAR; PG8_WAIT_L(0); PG8_MMA(1, 0, At, B0); PG8_BAR; PG8_SCHED;
;             PG8_STAGE(PG8_SB(1, 1), b3 + hstepB, voffB);
;             PG8_WAIT_V(6); PG8_BAR; PG8_MMA(1, 1, At, B1); PG8_BAR;
	s_waitcnt lgkmcnt(1)
	v_mfma_f32_16x16x32_bf16 v[96:99], v[222:225], v[124:127], v[96:99]
	v_mfma_f32_16x16x32_bf16 v[140:143], v[214:217], v[124:127], v[156:159]
	s_waitcnt lgkmcnt(0)
	v_mfma_f32_16x16x32_bf16 v[152:155], v[230:233], v[132:135], v[96:99]
	v_mfma_f32_16x16x32_bf16 v[96:99], v[214:217], v[160:163], v[100:103]
	v_mfma_f32_16x16x32_bf16 v[156:159], v[218:221], v[132:135], v[140:143]
	v_mfma_f32_16x16x32_bf16 v[140:143], v[218:221], v[164:167], v[96:99]
	v_mfma_f32_16x16x32_bf16 v[96:99], v[222:225], v[160:163], v[108:111]
	v_mfma_f32_16x16x32_bf16 v[132:135], v[230:233], v[164:167], v[96:99]
	v_mfma_f32_16x16x32_bf16 v[96:99], v[214:217], v[198:201], v[112:115]
	s_mov_b32 m0, s63
	v_mfma_f32_16x16x32_bf16 v[124:127], v[218:221], v[202:205], v[96:99]
	v_lshl_add_u64 v[184:185], v[226:227], 0, s[14:15]
	v_mfma_f32_16x16x32_bf16 v[96:99], v[222:225], v[198:201], v[116:119]
	v_mfma_f32_16x16x32_bf16 v[68:71], v[214:217], v[206:209], v[68:71]
	v_mfma_f32_16x16x32_bf16 v[64:67], v[222:225], v[206:209], v[64:67]
	v_mfma_f32_16x16x32_bf16 v[116:119], v[230:233], v[202:205], v[96:99]
	v_mfma_f32_16x16x32_bf16 v[68:71], v[218:221], v[210:213], v[68:71]
	v_mfma_f32_16x16x32_bf16 v[64:67], v[230:233], v[210:213], v[64:67]
	s_barrier
	s_setprio 0
	ds_read_b128 v[96:99], v190 offset:49152
	ds_read_b128 v[100:103], v190 offset:50176
	ds_read_b128 v[108:111], v190 offset:51200
	ds_read_b128 v[112:115], v190 offset:52224
	ds_read_b128 v[160:163], v190 offset:53248
	ds_read_b128 v[164:167], v190 offset:54272
	ds_read_b128 v[198:201], v190 offset:55296
	ds_read_b128 v[202:205], v190 offset:56320
	global_load_lds_dwordx4 v[184:185], off
	v_lshl_add_u64 v[184:185], v[234:235], 0, s[14:15]
	s_mov_b32 m0, s4
	s_nop 0
	global_load_lds_dwordx4 v[184:185], off
	s_waitcnt vmcnt(10)
	s_setprio 1
	s_barrier
	s_waitcnt lgkmcnt(7)
	v_mfma_f32_16x16x32_bf16 v[60:63], v[80:83], v[96:99], v[60:63]
	v_mfma_f32_16x16x32_bf16 v[48:51], v[88:91], v[96:99], v[48:51]
	s_waitcnt lgkmcnt(5)
	v_mfma_f32_16x16x32_bf16 v[40:43], v[80:83], v[108:111], v[40:43]
	v_mfma_f32_16x16x32_bf16 v[32:35], v[88:91], v[108:111], v[32:35]
	s_waitcnt lgkmcnt(3)
	v_mfma_f32_16x16x32_bf16 v[24:27], v[80:83], v[160:163], v[24:27]
	v_mfma_f32_16x16x32_bf16 v[16:19], v[88:91], v[160:163], v[16:19]
	s_waitcnt lgkmcnt(1)
	v_mfma_f32_16x16x32_bf16 v[12:15], v[80:83], v[198:201], v[12:15]
	v_mfma_f32_16x16x32_bf16 v[8:11], v[88:91], v[198:201], v[8:11]
	v_mfma_f32_16x16x32_bf16 v[60:63], v[84:87], v[100:103], v[60:63]
	s_add_u32 s24, s24, 0x80080
	s_addc_u32 s25, s25, 0
	v_mfma_f32_16x16x32_bf16 v[48:51], v[92:95], v[100:103], v[48:51]
	s_add_i32 s46, s46, s66
	v_mfma_f32_16x16x32_bf16 v[40:43], v[84:87], v[112:115], v[40:43]
	v_mfma_f32_16x16x32_bf16 v[32:35], v[92:95], v[112:115], v[32:35]
	v_mfma_f32_16x16x32_bf16 v[24:27], v[84:87], v[164:167], v[24:27]
	v_mfma_f32_16x16x32_bf16 v[16:19], v[92:95], v[164:167], v[16:19]
	s_waitcnt lgkmcnt(0)
	v_mfma_f32_16x16x32_bf16 v[12:15], v[84:87], v[202:205], v[12:15]
	v_mfma_f32_16x16x32_bf16 v[8:11], v[92:95], v[202:205], v[8:11]
	s_barrier
	s_setprio 0
	s_mov_b32 m0, s46
	s_nop 0
	global_load_lds_dwordx4 v172, s[24:25]
	s_add_i32 m0, s46, 0x2000
	s_nop 0
	global_load_lds_dwordx4 v168, s[24:25]
	s_waitcnt vmcnt(6)
	s_setprio 1
	s_barrier
	v_mfma_f32_16x16x32_bf16 v[56:59], v[214:217], v[96:99], v[56:59]
	v_mfma_f32_16x16x32_bf16 v[52:55], v[222:225], v[96:99], v[52:55]
	ds_read_b128 v[80:83], v189
	v_mfma_f32_16x16x32_bf16 v[44:47], v[214:217], v[108:111], v[44:47]
	v_mfma_f32_16x16x32_bf16 v[36:39], v[222:225], v[108:111], v[36:39]
	ds_read_b128 v[84:87], v189 offset:1024
	v_mfma_f32_16x16x32_bf16 v[28:31], v[214:217], v[160:163], v[28:31]
	v_mfma_f32_16x16x32_bf16 v[20:23], v[222:225], v[160:163], v[20:23]
	ds_read_b128 v[88:91], v189 offset:2048
	v_mfma_f32_16x16x32_bf16 v[4:7], v[214:217], v[198:201], v[4:7]
	v_mfma_f32_16x16x32_bf16 v[0:3], v[222:225], v[198:201], v[0:3]
	ds_read_b128 v[92:95], v189 offset:3072
	v_mfma_f32_16x16x32_bf16 v[56:59], v[218:221], v[100:103], v[56:59]
	s_add_i32 s3, s3, 2
	v_mfma_f32_16x16x32_bf16 v[52:55], v[230:233], v[100:103], v[52:55]
	s_add_u32 vcc_lo, vcc_lo, 0x100
	s_addc_u32 vcc_hi, vcc_hi, 0
	v_mfma_f32_16x16x32_bf16 v[44:47], v[218:221], v[112:115], v[44:47]
	s_add_u32 s42, s42, 0x100
	s_addc_u32 s43, s43, 0
	v_mfma_f32_16x16x32_bf16 v[36:39], v[230:233], v[112:115], v[36:39]
	s_add_u32 s24, s42, 0xfff80080
	s_addc_u32 s25, s43, -1
	s_cmp_eq_u32 s3, 28
	s_cselect_b32 s47, s23, s25
	s_cselect_b32 s46, s58, s24
	s_cselect_b32 s25, s21, vcc_hi
	s_cselect_b32 s24, s59, vcc_lo
	s_cmp_gt_u32 s3, 29
	v_mfma_f32_16x16x32_bf16 v[28:31], v[218:221], v[164:167], v[28:31]
	v_mfma_f32_16x16x32_bf16 v[20:23], v[230:233], v[164:167], v[20:23]
	v_mfma_f32_16x16x32_bf16 v[4:7], v[218:221], v[202:205], v[4:7]
	v_mfma_f32_16x16x32_bf16 v[0:3], v[230:233], v[202:205], v[0:3]
	s_barrier
	s_setprio 0
	s_cbranch_scc0 .LBB1_1069
; DI float silu_mul(float g, float v) { return g * v * __builtin_amdgcn_rcpf(1.0f + __builtin_amdgcn_exp2f(-LOG2E * g)); }
;     DI void operator()(const f32x4 (&acc)[2][2][4][2], const Unit& u, int wr, int wc, int fr, int fq) const {
;         const int row0 = u.pm * BM + wr * 64 + fr, ch0 = u.pn * 128 + wc * 32 + 8 * fq;
;         f32x4 w0[2], w1[2], w2[2], bb[2];
; #pragma unroll
;         for (int n = 0; n < 2; ++n) { w0[n] = *(const f32x4*)(cw + ch0 + 4 * n); w1[n] = *(const f32x4*)(cw + DFF + ch0 + 4 * n); w2[n] = *(const f32x4*)(cw + 2 * DFF + ch0 + 4 * n); bb[n] = *(const f32x4*)(cb + ch0 + 4 * n); }
; #pragma unroll
;         for (int ai = 0; ai < 2; ++ai)
; #pragma unroll
;             for (int m = 0; m < 4; ++m) {
;                 const bool efirst = (m == 0) && (fr == 0), elast = (m == 3) && (fr == 15);
;                 const int row = row0 + ai * HALF + m * 16;
;                 f32x4 gc[2];
; #pragma unroll
;                 for (int n = 0; n < 2; ++n) {
;                     const f32x4 g = acc[ai][0][m][n];
;                     const f32x4 gprev = acc[ai][0][m > 0 ? m - 1 : 0][n], gnext = acc[ai][0][m < 3 ? m + 1 : 3][n];
;                     f32x4 up, dn;
; #pragma unroll
;                     for (int e = 0; e < 4; ++e) {
;                         const float pu = (m > 0 && fr == 15) ? gprev[e] : g[e];
;                         const float pd = (m < 3 && fr == 0) ? gnext[e] : g[e];
;                         up[e] = dpp_ror1(pu); dn[e] = dpp_ror15(pd);
;                     }
;                     if (efirst) up = (f32x4){0.f, 0.f, 0.f, 0.f};
;                     if (elast) dn = (f32x4){0.f, 0.f, 0.f, 0.f};
;                     gc[n] = w0[n] * up + w1[n] * g + w2[n] * dn + bb[n];
;                 }
;                 if (efirst || elast) {
;                     const size_t eo = (size_t)((row >> 6) * 2 + (elast ? 1 : 0)) * DFF + ch0;
; #pragma unroll
;                     for (int n = 0; n < 2; ++n) { *(f32x4*)(EP + eo + 4 * n) = gc[n]; *(f32x4*)(ER + eo + 4 * n) = acc[ai][0][m][n]; *(f32x4*)(EV + eo + 4 * n) = acc[ai][1][m][n]; }
;                 } else {
;                     const f32x4 v0 = acc[ai][1][m][0], v1 = acc[ai][1][m][1];
;                     u32x4 o;
;                     o[0] = pack2(silu_mul(gc[0][0], v0[0]), silu_mul(gc[0][1], v0[1])); o[1] = pack2(silu_mul(gc[0][2], v0[2]), silu_mul(gc[0][3], v0[3]));
	s_waitcnt lgkmcnt(0)
	s_lshl_b32 s21, s45, 7
	v_mov_b32_e32 v194, v186
	v_mov_b32_e32 v80, v187
	s_or_b32 s21, s21, s62
	v_lshl_add_u32 v184, v80, 3, s21
	v_ashrrev_i32_e32 v185, 31, v184
	v_lshlrev_b64 v[80:81], 2, v[184:185]
	v_lshl_add_u64 v[84:85], s[6:7], 0, v[80:81]
	v_lshl_add_u64 v[88:89], s[16:17], 0, v[80:81]
	v_lshl_add_u64 v[92:93], s[18:19], 0, v[80:81]
	v_lshl_add_u64 v[112:113], s[52:53], 0, v[80:81]
	global_load_dwordx4 v[80:83], v[84:85], off offset:16
	global_load_dwordx4 v[96:99], v[84:85], off
	s_nop 0
	global_load_dwordx4 v[84:87], v[88:89], off offset:16
	global_load_dwordx4 v[100:103], v[88:89], off
	s_nop 0
	global_load_dwordx4 v[88:91], v[92:93], off offset:16
	global_load_dwordx4 v[108:111], v[92:93], off
	s_nop 0
	global_load_dwordx4 v[92:95], v[112:113], off offset:16
	s_nop 0
	global_load_dwordx4 v[112:115], v[112:113], off
	v_cmp_eq_u32_e32 vcc, 0, v194
	s_nop 0
	s_nop 0
	v_cndmask_b32_e32 v161, v148, v136, vcc
	v_cndmask_b32_e32 v162, v149, v137, vcc
	v_cndmask_b32_e32 v163, v150, v138, vcc
	v_mov_b32_dpp v160, v161 row_ror:15 row_mask:0xf bank_mask:0xf
	s_nop 0
	s_nop 0
	v_mov_b32_dpp v161, v162 row_ror:15 row_mask:0xf bank_mask:0xf
	v_mov_b32_dpp v164, v150 row_ror:1 row_mask:0xf bank_mask:0xf
	v_cndmask_b32_e32 v165, v151, v139, vcc
	v_mov_b32_dpp v162, v163 row_ror:15 row_mask:0xf bank_mask:0xf
	v_mov_b32_dpp v195, v151 row_ror:1 row_mask:0xf bank_mask:0xf
	v_mov_b32_dpp v166, v148 row_ror:1 row_mask:0xf bank_mask:0xf
	v_mov_b32_dpp v167, v149 row_ror:1 row_mask:0xf bank_mask:0xf
	v_mov_b32_dpp v163, v165 row_ror:15 row_mask:0xf bank_mask:0xf
	v_cndmask_b32_e64 v165, v195, 0, vcc
	v_cndmask_b32_e64 v164, v164, 0, vcc
	v_cndmask_b32_e64 v167, v167, 0, vcc
	v_cndmask_b32_e64 v166, v166, 0, vcc
	s_nop 0
	s_nop 0
	v_mov_b32_dpp v195, v144 row_ror:1 row_mask:0xf bank_mask:0xf
	v_mov_b32_dpp v196, v145 row_ror:1 row_mask:0xf bank_mask:0xf
	v_mov_b32_dpp v198, v146 row_ror:1 row_mask:0xf bank_mask:0xf
	v_cndmask_b32_e32 v199, v147, v131, vcc
	v_mov_b32_dpp v200, v147 row_ror:1 row_mask:0xf bank_mask:0xf
	v_cndmask_b32_e64 v198, v198, 0, vcc
	v_cndmask_b32_e64 v201, v196, 0, vcc
	s_lshl_b32 s3, s44, 8
	s_add_i32 s3, s3, s49
	v_add_u32_e32 v193, s3, v194
	v_cmp_ne_u32_e64 s[46:47], 0, v194
	s_waitcnt vmcnt(0)
	v_pk_mul_f32 v[164:165], v[98:99], v[164:165]
	v_pk_mul_f32 v[166:167], v[96:97], v[166:167]
	v_pk_fma_f32 v[164:165], v[150:151], v[102:103], v[164:165]
	v_pk_fma_f32 v[166:167], v[148:149], v[100:101], v[166:167]
	v_pk_fma_f32 v[162:163], v[110:111], v[162:163], v[164:165]
	v_cndmask_b32_e32 v165, v144, v128, vcc
	v_pk_fma_f32 v[160:161], v[108:109], v[160:161], v[166:167]
	v_cndmask_b32_e32 v166, v145, v129, vcc
	v_mov_b32_dpp v164, v165 row_ror:15 row_mask:0xf bank_mask:0xf
	v_cndmask_b32_e32 v167, v146, v130, vcc
	v_pk_add_f32 v[162:163], v[114:115], v[162:163]
	v_mov_b32_dpp v165, v166 row_ror:15 row_mask:0xf bank_mask:0xf
	v_pk_add_f32 v[160:161], v[112:113], v[160:161]
	s_nop 0
	v_mov_b32_dpp v166, v167 row_ror:15 row_mask:0xf bank_mask:0xf
	s_nop 1
	v_mov_b32_dpp v167, v199 row_ror:15 row_mask:0xf bank_mask:0xf
	v_cndmask_b32_e64 v199, v200, 0, vcc
	v_cndmask_b32_e64 v200, v195, 0, vcc
	v_pk_mul_f32 v[200:201], v[80:81], v[200:201]
	v_pk_mul_f32 v[198:199], v[82:83], v[198:199]
	v_pk_fma_f32 v[200:201], v[144:145], v[84:85], v[200:201]
	v_pk_fma_f32 v[198:199], v[146:147], v[86:87], v[198:199]
	v_pk_fma_f32 v[164:165], v[88:89], v[164:165], v[200:201]
	v_pk_fma_f32 v[166:167], v[90:91], v[166:167], v[198:199]
	v_pk_add_f32 v[164:165], v[92:93], v[164:165]
	v_pk_add_f32 v[166:167], v[94:95], v[166:167]
	s_and_saveexec_b64 s[24:25], s[46:47]
	s_xor_b64 s[24:25], exec, s[24:25]
	s_cbranch_execz .LBB1_1072
	v_mul_f32_e32 v195, 0xbfb8aa3b, v160
	v_exp_f32_e32 v195, v195
	v_mul_f32_e32 v196, 0xbfb8aa3b, v161
	v_exp_f32_e32 v196, v196
	v_pk_mul_f32 v[160:161], v[156:157], v[160:161]
	v_add_f32_e32 v195, 1.0, v195
	v_rcp_f32_e32 v198, v195
	v_add_f32_e32 v196, 1.0, v196
	v_mul_f32_e32 v195, 0xbfb8aa3b, v162
	v_rcp_f32_e32 v199, v196
	v_exp_f32_e32 v195, v195
	v_mul_f32_e32 v196, 0xbfb8aa3b, v163
	v_exp_f32_e32 v196, v196
	v_pk_mul_f32 v[160:161], v[160:161], v[198:199]
	v_add_f32_e32 v195, 1.0, v195
	v_rcp_f32_e32 v200, v195
	v_add_f32_e32 v195, 1.0, v196
	v_rcp_f32_e32 v201, v195
	v_cvt_pk_bf16_f32 v160, v160, v161
	v_mul_f32_e32 v161, 0xbfb8aa3b, v164
	v_exp_f32_e32 v195, v161
	v_mul_f32_e32 v161, 0xbfb8aa3b, v165
	v_exp_f32_e32 v196, v161
	v_pk_mul_f32 v[162:163], v[158:159], v[162:163]
	v_pk_mul_f32 v[164:165], v[152:153], v[164:165]
	v_pk_mul_f32 v[162:163], v[162:163], v[200:201]
	s_nop 0
	v_cvt_pk_bf16_f32 v161, v162, v163
	v_add_f32_e32 v162, 1.0, v195
	v_mul_f32_e32 v195, 0xbfb8aa3b, v166
	v_add_f32_e32 v163, 1.0, v196
	v_exp_f32_e32 v195, v195
	v_mul_f32_e32 v196, 0xbfb8aa3b, v167
	v_exp_f32_e32 v196, v196
	v_rcp_f32_e32 v162, v162
	v_add_f32_e32 v195, 1.0, v195
	v_rcp_f32_e32 v198, v195
	v_add_f32_e32 v195, 1.0, v196
	v_rcp_f32_e32 v163, v163
	v_rcp_f32_e32 v199, v195
	v_pk_mul_f32 v[166:167], v[154:155], v[166:167]
	v_pk_mul_f32 v[162:163], v[164:165], v[162:163]
	v_pk_mul_f32 v[164:165], v[166:167], v[198:199]
	v_cvt_pk_bf16_f32 v162, v162, v163
	v_cvt_pk_bf16_f32 v163, v164, v165
	v_mov_b64_e32 v[164:165], s[54:55]
	v_mad_i64_i32 v[164:165], s[42:43], v193, s60, v[164:165]
	v_lshl_add_u64 v[164:165], v[184:185], 1, v[164:165]
	global_store_dwordx4 v[164:165], v[160:163], off

;     DI const char* a(const Unit& u) const { return (const char*)(A + (size_t)u.pm * BM * lda); }
;     DI const char* a(const Unit& u) const { return (const char*)(A + (size_t)u.pm * BM * 2048 + (u.pn >> 1) * 512); }
;     DI const char* a(const Unit& u) const { return (const char*)((u.pn < 12 ? A1 : A2) + (size_t)u.pm * BM * 512); }
; #define PG8_STAGE(bufoff, gbase, voff) do { _Pragma("unroll") for (int _i = 0; _i < 2; ++_i) \
;         __builtin_amdgcn_global_load_lds((const unsigned*)((const char*)(gbase) + (voff)[_i]), (LAS unsigned*)(lds + (bufoff) + ldsw + _i * 8192), 16, 0, 0); } while (0)
; #define PG8_LDA(dst, b, h) do { _Pragma("unroll") for (int m = 0; m < 4; ++m) _Pragma("unroll") for (int k = 0; k < 2; ++k) dst[m][k] = *(const LAS bf16x8*)(lds + PG8_SA(b, h) + aoff + m * 2048 + k * 1024); } while (0)
; template <class Map, class Epi>
; DI void gemm_phase(LAS unsigned char* lds, const Map& MP, const Epi& E, const int nM, const int nN, const int K, const int lda, const int ldb) {
;     ...
;         const bool has_next = sched_next(ui + 1, nM, nN, G, cblk, nxt);
;         const char* nA = has_next ? MP.a(nxt) : cA; const char* nB = has_next ? MP.b(nxt) : cB;
;         for (int t = 0; t < nt; t += 2) {
;             const bool last = (t == nt - 2);
;             const char* a1 = cA + (size_t)(t + 1) * kstep;
;             const char* a2 = last ? nA : cA + (size_t)(t + 2) * kstep; const char* b2 = last ? nB : cB + (size_t)(t + 2) * kstep;
;             const char* a3 = a2 + kstep; const char* b3 = b2 + kstep;
;             PG8_LDB(B0, 0, 0); PG8_SCHED; PG8_LDA(At, 0, 0); PG8_STAGE(PG8_SA(1, 1), a1 + hstepA, voffA);
;             PG8_WAIT_L(8); PG8_BAR; PG8_WAIT_L(0); PG8_MMA(0, 0, At, B0); PG8_BAR; PG8_SCHED;
;             PG8_LDB(B1, 0, 1); PG8_STAGE(PG8_SB(0, 0), b2, voffB);
;             PG8_BAR; PG8_WAIT_L(0); PG8_MMA(0, 1, At, B1); PG8_BAR;
;             PG8_LDA(At, 0, 1); PG8_STAGE(PG8_SA(0, 0), a2, voffA);
;             PG8_BAR; PG8_WAIT_L(0); PG8_MMA(1, 0, At, B0); PG8_BAR; PG8_SCHED;
;     ...
; #pragma unroll
;         for (int a = 0; a < 2; ++a)
; #pragma unroll
;             for (int b = 0; b < 2; ++b)
; #pragma unroll
;                 for (int m = 0; m < 4; ++m)
; #pragma unroll
;                     for (int n = 0; n < 2; ++n) acc[a][b][m][n] = (f32x4){0.f, 0.f, 0.f, 0.f};
;         cur = nxt; cA = nA; cB = nB; ++ui;
.LBB1_1381:
	s_ashr_i32 s15, s14, 31
	v_cmp_lt_i64_e32 vcc, s[16:17], v[140:141]
	s_lshl_b64 s[16:17], s[14:15], 20
	s_add_u32 s16, s5, s16
	s_addc_u32 s17, s26, s17
	s_and_b64 s[18:19], vcc, exec
	s_cselect_b32 s15, s17, s23
	s_cselect_b32 s48, s16, s22
	s_ashr_i32 s13, s12, 31
	s_lshl_b64 s[18:19], s[12:13], 20
	s_add_u32 s18, s27, s18
	s_addc_u32 s19, s28, s19
	s_and_b64 s[24:25], vcc, exec
	s_cselect_b32 s13, s19, s21
	s_cselect_b32 s49, s18, s20
	s_add_u32 s52, s20, 0x100
	s_addc_u32 s53, s21, 0
	s_add_u32 s20, s22, 0x80080
	v_mov_b32_e32 v0, 0
	s_addc_u32 s21, s23, 0
	s_mov_b32 s3, -2
	v_mov_b32_e32 v1, 0
	v_mov_b64_e32 v[2:3], 0
	v_mov_b64_e32 v[4:5], 0
	v_mov_b64_e32 v[6:7], 0
	v_mov_b64_e32 v[8:9], 0
	v_mov_b64_e32 v[10:11], 0
	v_mov_b64_e32 v[12:13], 0
	v_mov_b64_e32 v[14:15], 0
	v_mov_b64_e32 v[16:17], 0
	v_mov_b64_e32 v[18:19], 0
	v_mov_b64_e32 v[20:21], 0
	v_mov_b64_e32 v[22:23], 0
	v_mov_b64_e32 v[24:25], 0
	v_mov_b64_e32 v[26:27], 0
	v_mov_b64_e32 v[28:29], 0
	v_mov_b64_e32 v[30:31], 0
	v_mov_b64_e32 v[32:33], 0
	v_mov_b64_e32 v[34:35], 0
	v_mov_b64_e32 v[36:37], 0
	v_mov_b64_e32 v[38:39], 0
	v_mov_b64_e32 v[40:41], 0
	v_mov_b64_e32 v[42:43], 0
	v_mov_b64_e32 v[44:45], 0
	v_mov_b64_e32 v[46:47], 0
	v_mov_b64_e32 v[48:49], 0
	v_mov_b64_e32 v[50:51], 0
	v_mov_b64_e32 v[52:53], 0
	v_mov_b64_e32 v[54:55], 0
	v_mov_b64_e32 v[56:57], 0
	v_mov_b64_e32 v[58:59], 0
	v_mov_b64_e32 v[60:61], 0
	v_mov_b64_e32 v[62:63], 0
	v_mov_b64_e32 v[64:65], 0
	v_mov_b64_e32 v[66:67], 0
	v_mov_b64_e32 v[68:69], 0
	v_mov_b64_e32 v[70:71], 0
	v_mov_b64_e32 v[72:73], 0
	v_mov_b64_e32 v[74:75], 0
	v_mov_b64_e32 v[76:77], 0
	v_mov_b64_e32 v[78:79], 0
	v_mov_b64_e32 v[80:81], 0
	v_mov_b64_e32 v[82:83], 0
	v_mov_b64_e32 v[84:85], 0
	v_mov_b64_e32 v[86:87], 0
	v_mov_b64_e32 v[88:89], 0
	v_mov_b64_e32 v[90:91], 0
	v_mov_b64_e32 v[92:93], 0
	v_mov_b64_e32 v[94:95], 0
	v_mov_b64_e32 v[96:97], 0
	v_mov_b64_e32 v[98:99], 0
	v_mov_b64_e32 v[100:101], 0
	v_mov_b64_e32 v[102:103], 0
	v_mov_b64_e32 v[104:105], 0
	v_mov_b64_e32 v[106:107], 0
	v_mov_b64_e32 v[108:109], 0
	v_mov_b64_e32 v[110:111], 0
	v_mov_b64_e32 v[112:113], 0
	v_mov_b64_e32 v[114:115], 0
	v_mov_b64_e32 v[116:117], 0
	v_mov_b64_e32 v[118:119], 0
	v_mov_b64_e32 v[120:121], 0
	v_mov_b64_e32 v[122:123], 0
	v_mov_b64_e32 v[124:125], 0
	v_mov_b64_e32 v[126:127], 0
	ds_read_b128 v[150:153], v147
	ds_read_b128 v[154:157], v147 offset:1024
	ds_read_b128 v[158:161], v147 offset:2048
	ds_read_b128 v[162:165], v147 offset:3072
	s_add_u32 s22, s20, 0xfff80080
	s_addc_u32 s23, s21, -1
	s_cmp_eq_u32 s3, 28
	s_cselect_b32 s25, s15, s23
	s_cselect_b32 s24, s48, s22
	s_cselect_b32 s23, s13, s53
	s_cselect_b32 s22, s49, s52
.LBB1_1382:
	s_add_i32 m0, s31, 0xc000
	ds_read_b128 v[166:169], v148
	ds_read_b128 v[170:173], v148 offset:1024
	ds_read_b128 v[174:177], v148 offset:2048
	ds_read_b128 v[178:181], v148 offset:3072
	ds_read_b128 v[182:185], v148 offset:4096
	ds_read_b128 v[186:189], v148 offset:5120
	ds_read_b128 v[190:193], v148 offset:6144
	ds_read_b128 v[198:201], v148 offset:7168
	global_load_lds_dwordx4 v138, s[20:21]
	s_add_i32 m0, s31, 0xe000
	s_nop 0
	global_load_lds_dwordx4 v136, s[20:21]
	s_waitcnt lgkmcnt(8)
	s_setprio 1
	s_barrier
	s_waitcnt lgkmcnt(7)
	v_mfma_f32_16x16x32_bf16 v[124:127], v[150:153], v[166:169], v[124:127]
	v_mfma_f32_16x16x32_bf16 v[120:123], v[158:161], v[166:169], v[120:123]
	s_waitcnt lgkmcnt(5)
	v_mfma_f32_16x16x32_bf16 v[116:119], v[150:153], v[174:177], v[116:119]
	v_mfma_f32_16x16x32_bf16 v[112:115], v[158:161], v[174:177], v[112:115]
	s_waitcnt lgkmcnt(3)
	v_mfma_f32_16x16x32_bf16 v[100:103], v[150:153], v[182:185], v[100:103]
	v_mfma_f32_16x16x32_bf16 v[96:99], v[158:161], v[182:185], v[96:99]
	s_waitcnt lgkmcnt(1)
	v_mfma_f32_16x16x32_bf16 v[84:87], v[150:153], v[190:193], v[84:87]
	v_mfma_f32_16x16x32_bf16 v[80:83], v[158:161], v[190:193], v[80:83]
	v_mfma_f32_16x16x32_bf16 v[124:127], v[154:157], v[170:173], v[124:127]
	s_add_i32 s54, s44, s29
	v_mfma_f32_16x16x32_bf16 v[120:123], v[162:165], v[170:173], v[120:123]
	v_lshl_add_u64 v[194:195], s[22:23], 0, v[132:133]
	v_mfma_f32_16x16x32_bf16 v[116:119], v[154:157], v[178:181], v[116:119]
	v_lshl_add_u64 v[218:219], s[22:23], 0, v[128:129]
	v_mfma_f32_16x16x32_bf16 v[112:115], v[162:165], v[178:181], v[112:115]
	v_mfma_f32_16x16x32_bf16 v[100:103], v[154:157], v[186:189], v[100:103]
	v_mfma_f32_16x16x32_bf16 v[96:99], v[162:165], v[186:189], v[96:99]
	s_waitcnt lgkmcnt(0)
	v_mfma_f32_16x16x32_bf16 v[84:87], v[154:157], v[198:201], v[84:87]
	v_mfma_f32_16x16x32_bf16 v[80:83], v[162:165], v[198:201], v[80:83]
	s_barrier
	s_setprio 0
	s_mov_b32 m0, s54
	ds_read_b128 v[202:205], v149
	ds_read_b128 v[206:209], v149 offset:1024
	ds_read_b128 v[210:213], v149 offset:2048
	ds_read_b128 v[214:217], v149 offset:3072
	global_load_lds_dwordx4 v[194:195], off
	s_add_i32 m0, s54, 0x2000
	s_nop 0
	global_load_lds_dwordx4 v[218:219], off
	s_setprio 1
	s_barrier
	s_waitcnt lgkmcnt(3)
	v_mfma_f32_16x16x32_bf16 v[108:111], v[202:205], v[166:169], v[108:111]
	s_waitcnt lgkmcnt(1)
	v_mfma_f32_16x16x32_bf16 v[104:107], v[210:213], v[166:169], v[104:107]
	v_mfma_f32_16x16x32_bf16 v[92:95], v[202:205], v[174:177], v[92:95]
	v_mfma_f32_16x16x32_bf16 v[88:91], v[210:213], v[174:177], v[88:91]
	v_mfma_f32_16x16x32_bf16 v[76:79], v[202:205], v[182:185], v[76:79]
	v_mfma_f32_16x16x32_bf16 v[72:75], v[210:213], v[182:185], v[72:75]
	v_mfma_f32_16x16x32_bf16 v[68:71], v[202:205], v[190:193], v[68:71]
	v_mfma_f32_16x16x32_bf16 v[64:67], v[210:213], v[190:193], v[64:67]
	v_mfma_f32_16x16x32_bf16 v[108:111], v[206:209], v[170:173], v[108:111]
	v_lshl_add_u64 v[222:223], s[24:25], 0, v[130:131]
	s_mov_b32 m0, s31
	s_waitcnt lgkmcnt(0)
	v_mfma_f32_16x16x32_bf16 v[104:107], v[214:217], v[170:173], v[104:107]
	v_lshl_add_u64 v[220:221], s[24:25], 0, v[134:135]
	v_mfma_f32_16x16x32_bf16 v[92:95], v[206:209], v[178:181], v[92:95]
	v_mfma_f32_16x16x32_bf16 v[88:91], v[214:217], v[178:181], v[88:91]
	v_mfma_f32_16x16x32_bf16 v[76:79], v[206:209], v[186:189], v[76:79]
	v_mfma_f32_16x16x32_bf16 v[72:75], v[214:217], v[186:189], v[72:75]
	v_mfma_f32_16x16x32_bf16 v[68:71], v[206:209], v[198:201], v[68:71]
	v_mfma_f32_16x16x32_bf16 v[64:67], v[214:217], v[198:201], v[64:67]
	s_barrier
; #define PG8_STAGE(bufoff, gbase, voff) do { _Pragma("unroll") for (int _i = 0; _i < 2; ++_i) \
;         __builtin_amdgcn_global_load_lds((const unsigned*)((const char*)(gbase) + (voff)[_i]), (LAS unsigned*)(lds + (bufoff) + ldsw + _i * 8192), 16, 0, 0); } while (0)
; #define PG8_LDA(dst, b, h) do { _Pragma("unroll") for (int m = 0; m < 4; ++m) _Pragma("unroll") for (int k = 0; k < 2; ++k) dst[m][k] = *(const LAS bf16x8*)(lds + PG8_SA(b, h) + aoff + m * 2048 + k * 1024); } while (0)
; #define PG8_LDB(dst, b, h) do { _Pragma("unroll") for (int n = 0; n < 2; ++n) _Pragma("unroll") for (int k = 0; k < 2; ++k) dst[n][k] = *(const LAS bf16x8*)(lds + PG8_SB(b, h) + boff + n * 2048 + k * 1024); } while (0)
; #define PG8_MMA(ai, bj, At, Bt) do { __builtin_amdgcn_s_setprio(1); _Pragma("unroll") for (int m = 0; m < 4; ++m) _Pragma("unroll") for (int n = 0; n < 2; ++n) _Pragma("unroll") for (int k = 0; k < 2; ++k) \
;         acc[ai][bj][m][n] = __builtin_amdgcn_mfma_f32_16x16x32_bf16(Bt[n][k], At[m][k], acc[ai][bj][m][n], 0, 0, 0); __builtin_amdgcn_s_setprio(0); } while (0)
; #define PG8_WAIT_V(n) asm volatile("s_waitcnt vmcnt(" #n ")" ::: "memory")
; #define PG8_WAIT_L(n) asm volatile("s_waitcnt lgkmcnt(" #n ")" ::: "memory")
; #define PG8_BAR __builtin_amdgcn_s_barrier()
; #define PG8_SCHED __builtin_amdgcn_sched_barrier(0)
; template <class Map, class Epi>
; DI void gemm_phase(LAS unsigned char* lds, const Map& MP, const Epi& E, const int nM, const int nN, const int K, const int lda, const int ldb) {
;     ...
;             PG8_BAR; PG8_WAIT_L(0); PG8_MMA(1, 0, At, B0); PG8_BAR; PG8_SCHED;
;             PG8_STAGE(PG8_SB(0, 1), b2 + hstepB, voffB);
;             PG8_WAIT_V(6); PG8_BAR; PG8_MMA(1, 1, At, B1); PG8_BAR;
;             PG8_LDB(B0, 1, 0); PG8_SCHED; PG8_LDA(At, 1, 0); PG8_STAGE(PG8_SA(0, 1), a2 + hstepA, voffA);
;             PG8_WAIT_L(8); PG8_BAR; PG8_WAIT_L(0); PG8_MMA(0, 0, At, B0); PG8_BAR; PG8_SCHED;
;             PG8_LDB(B1, 1, 1); PG8_STAGE(PG8_SB(1, 0), b3, voffB);
;             PG8_BAR; PG8_WAIT_L(0); PG8_MMA(0, 1, At, B1); PG8_BAR;
;             PG8_LDA(At, 1, 1); PG8_STAGE(PG8_SA(1, 0), a3, voffA);
;             PG8_BAR; PG8_WAIT_L(0); PG8_MMA(1, 0, At, B0); PG8_BAR; PG8_SCHED;
	s_setprio 0
	ds_read_b128 v[166:169], v148 offset:16384
	ds_read_b128 v[170:173], v148 offset:17408
	ds_read_b128 v[174:177], v148 offset:18432
	ds_read_b128 v[178:181], v148 offset:19456
	ds_read_b128 v[182:185], v148 offset:20480
	ds_read_b128 v[186:189], v148 offset:21504
	ds_read_b128 v[190:193], v148 offset:22528
	ds_read_b128 v[198:201], v148 offset:23552
	global_load_lds_dwordx4 v[220:221], off
	s_mov_b32 m0, s11
	s_nop 0
	global_load_lds_dwordx4 v[222:223], off
	s_waitcnt vmcnt(10)
	s_setprio 1
	s_barrier
	s_waitcnt lgkmcnt(7)
	v_mfma_f32_16x16x32_bf16 v[60:63], v[150:153], v[166:169], v[60:63]
	v_mfma_f32_16x16x32_bf16 v[56:59], v[158:161], v[166:169], v[56:59]
	s_waitcnt lgkmcnt(5)
	v_mfma_f32_16x16x32_bf16 v[52:55], v[150:153], v[174:177], v[52:55]
	v_mfma_f32_16x16x32_bf16 v[48:51], v[158:161], v[174:177], v[48:51]
	s_waitcnt lgkmcnt(3)
	v_mfma_f32_16x16x32_bf16 v[36:39], v[150:153], v[182:185], v[36:39]
	v_mfma_f32_16x16x32_bf16 v[32:35], v[158:161], v[182:185], v[32:35]
	s_waitcnt lgkmcnt(1)
	v_mfma_f32_16x16x32_bf16 v[20:23], v[150:153], v[190:193], v[20:23]
	v_mfma_f32_16x16x32_bf16 v[16:19], v[158:161], v[190:193], v[16:19]
	v_mfma_f32_16x16x32_bf16 v[60:63], v[154:157], v[170:173], v[60:63]
	s_add_u32 s54, s22, 0x80000
	s_addc_u32 s55, s23, 0
	v_mfma_f32_16x16x32_bf16 v[56:59], v[162:165], v[170:173], v[56:59]
	s_add_i32 s56, s45, s29
	v_mfma_f32_16x16x32_bf16 v[52:55], v[154:157], v[178:181], v[52:55]
	v_mfma_f32_16x16x32_bf16 v[48:51], v[162:165], v[178:181], v[48:51]
	v_mfma_f32_16x16x32_bf16 v[36:39], v[154:157], v[186:189], v[36:39]
	v_mfma_f32_16x16x32_bf16 v[32:35], v[162:165], v[186:189], v[32:35]
	s_waitcnt lgkmcnt(0)
	v_mfma_f32_16x16x32_bf16 v[20:23], v[154:157], v[198:201], v[20:23]
	v_mfma_f32_16x16x32_bf16 v[16:19], v[162:165], v[198:201], v[16:19]
	s_barrier
	s_setprio 0
	s_mov_b32 m0, s56
	s_nop 0
	global_load_lds_dwordx4 v132, s[54:55]
	s_add_i32 m0, s56, 0x2000
	s_nop 0
	global_load_lds_dwordx4 v128, s[54:55]
	s_waitcnt vmcnt(6)
	s_setprio 1
	s_barrier
	v_mfma_f32_16x16x32_bf16 v[44:47], v[202:205], v[166:169], v[44:47]
	v_mfma_f32_16x16x32_bf16 v[40:43], v[210:213], v[166:169], v[40:43]
	s_add_i32 s54, 0, 0x18000
	v_add_u32_e32 v162, s54, v146
	ds_read_b128 v[150:153], v162
	v_mfma_f32_16x16x32_bf16 v[28:31], v[202:205], v[174:177], v[28:31]
	v_mfma_f32_16x16x32_bf16 v[24:27], v[210:213], v[174:177], v[24:27]
	ds_read_b128 v[154:157], v162 offset:1024
	v_mfma_f32_16x16x32_bf16 v[12:15], v[202:205], v[182:185], v[12:15]
	v_mfma_f32_16x16x32_bf16 v[8:11], v[210:213], v[182:185], v[8:11]
	ds_read_b128 v[158:161], v162 offset:2048
	v_mfma_f32_16x16x32_bf16 v[4:7], v[202:205], v[190:193], v[4:7]
	v_mfma_f32_16x16x32_bf16 v[0:3], v[210:213], v[190:193], v[0:3]
	ds_read_b128 v[162:165], v162 offset:3072
	v_mfma_f32_16x16x32_bf16 v[44:47], v[206:209], v[170:173], v[44:47]
	s_add_u32 s24, s24, 0x80000
	s_addc_u32 s25, s25, 0
	v_mfma_f32_16x16x32_bf16 v[40:43], v[214:217], v[170:173], v[40:43]
	v_mfma_f32_16x16x32_bf16 v[28:31], v[206:209], v[178:181], v[28:31]
	v_mfma_f32_16x16x32_bf16 v[24:27], v[214:217], v[178:181], v[24:27]
	v_mfma_f32_16x16x32_bf16 v[12:15], v[206:209], v[186:189], v[12:15]
	v_mfma_f32_16x16x32_bf16 v[8:11], v[214:217], v[186:189], v[8:11]
	v_mfma_f32_16x16x32_bf16 v[4:7], v[206:209], v[198:201], v[4:7]
	v_mfma_f32_16x16x32_bf16 v[0:3], v[214:217], v[198:201], v[0:3]
	s_barrier
	s_setprio 0
	s_mov_b32 m0, s34
	ds_read_b128 v[166:169], v148 offset:32768
	ds_read_b128 v[170:173], v148 offset:33792
	ds_read_b128 v[174:177], v148 offset:34816
	ds_read_b128 v[178:181], v148 offset:35840
	ds_read_b128 v[182:185], v148 offset:36864
	ds_read_b128 v[186:189], v148 offset:37888
	ds_read_b128 v[190:193], v148 offset:38912
	ds_read_b128 v[198:201], v148 offset:39936
	global_load_lds_dwordx4 v134, s[24:25]
	s_mov_b32 m0, s35
	s_nop 0
	global_load_lds_dwordx4 v130, s[24:25]
	s_waitcnt lgkmcnt(8)
	s_setprio 1
	s_barrier
	s_waitcnt lgkmcnt(7)
	v_mfma_f32_16x16x32_bf16 v[124:127], v[150:153], v[166:169], v[124:127]
	v_mfma_f32_16x16x32_bf16 v[120:123], v[158:161], v[166:169], v[120:123]
	s_waitcnt lgkmcnt(5)
	v_mfma_f32_16x16x32_bf16 v[116:119], v[150:153], v[174:177], v[116:119]
	v_mfma_f32_16x16x32_bf16 v[112:115], v[158:161], v[174:177], v[112:115]
	s_waitcnt lgkmcnt(3)
	v_mfma_f32_16x16x32_bf16 v[100:103], v[150:153], v[182:185], v[100:103]
	v_mfma_f32_16x16x32_bf16 v[96:99], v[158:161], v[182:185], v[96:99]
	s_waitcnt lgkmcnt(1)
	v_mfma_f32_16x16x32_bf16 v[84:87], v[150:153], v[190:193], v[84:87]
	v_mfma_f32_16x16x32_bf16 v[80:83], v[158:161], v[190:193], v[80:83]
	v_mfma_f32_16x16x32_bf16 v[124:127], v[154:157], v[170:173], v[124:127]
	s_add_i32 s24, 0, 0x1c000
	v_mfma_f32_16x16x32_bf16 v[120:123], v[162:165], v[170:173], v[120:123]
	s_add_i32 s25, s54, s29
	v_mfma_f32_16x16x32_bf16 v[116:119], v[154:157], v[178:181], v[116:119]
	v_add_u32_e32 v196, s24, v146
	v_mfma_f32_16x16x32_bf16 v[112:115], v[162:165], v[178:181], v[112:115]
	v_lshl_add_u64 v[194:195], v[194:195], 0, s[8:9]
	v_mfma_f32_16x16x32_bf16 v[100:103], v[154:157], v[186:189], v[100:103]
	v_mfma_f32_16x16x32_bf16 v[96:99], v[162:165], v[186:189], v[96:99]
	s_waitcnt lgkmcnt(0)
	v_mfma_f32_16x16x32_bf16 v[84:87], v[154:157], v[198:201], v[84:87]
	v_mfma_f32_16x16x32_bf16 v[80:83], v[162:165], v[198:201], v[80:83]
	s_barrier
	s_setprio 0
	s_mov_b32 m0, s25
	ds_read_b128 v[202:205], v196
	ds_read_b128 v[206:209], v196 offset:1024
	ds_read_b128 v[210:213], v196 offset:2048
	ds_read_b128 v[214:217], v196 offset:3072
	global_load_lds_dwordx4 v[194:195], off
	v_lshl_add_u64 v[194:195], v[218:219], 0, s[8:9]
	s_add_i32 m0, s25, 0x2000
	s_nop 0
	global_load_lds_dwordx4 v[194:195], off
	s_setprio 1
	s_barrier
; #define PG8_STAGE(bufoff, gbase, voff) do { _Pragma("unroll") for (int _i = 0; _i < 2; ++_i) \
;         __builtin_amdgcn_global_load_lds((const unsigned*)((const char*)(gbase) + (voff)[_i]), (LAS unsigned*)(lds + (bufoff) + ldsw + _i * 8192), 16, 0, 0); } while (0)
; #define PG8_LDA(dst, b, h) do { _Pragma("unroll") for (int m = 0; m < 4; ++m) _Pragma("unroll") for (int k = 0; k < 2; ++k) dst[m][k] = *(const LAS bf16x8*)(lds + PG8_SA(b, h) + aoff + m * 2048 + k * 1024); } while (0)
; #define PG8_MMA(ai, bj, At, Bt) do { __builtin_amdgcn_s_setprio(1); _Pragma("unroll") for (int m = 0; m < 4; ++m) _Pragma("unroll") for (int n = 0; n < 2; ++n) _Pragma("unroll") for (int k = 0; k < 2; ++k) \
;         acc[ai][bj][m][n] = __builtin_amdgcn_mfma_f32_16x16x32_bf16(Bt[n][k], At[m][k], acc[ai][bj][m][n], 0, 0, 0); __builtin_amdgcn_s_setprio(0); } while (0)
; #define PG8_WAIT_V(n) asm volatile("s_waitcnt vmcnt(" #n ")" ::: "memory")
; #define PG8_WAIT_L(n) asm volatile("s_waitcnt lgkmcnt(" #n ")" ::: "memory")
; #define PG8_BAR __builtin_amdgcn_s_barrier()
; #define PG8_SCHED __builtin_amdgcn_sched_barrier(0)
; template <class Map, class Epi>
; DI void gemm_phase(LAS unsigned char* lds, const Map& MP, const Epi& E, const int nM, const int nN, const int K, const int lda, const int ldb) {
;     ...
;             const bool last = (t == nt - 2);
;             const char* a1 = cA + (size_t)(t + 1) * kstep;
;             const char* a2 = last ? nA : cA + (size_t)(t + 2) * kstep; const char* b2 = last ? nB : cB + (size_t)(t + 2) * kstep;
;     ...
;             PG8_LDA(At, 1, 1); PG8_STAGE(PG8_SA(1, 0), a3, voffA);
;             PG8_BAR; PG8_WAIT_L(0); PG8_MMA(1, 0, At, B0); PG8_BAR; PG8_SCHED;
;             PG8_STAGE(PG8_SB(1, 1), b3 + hstepB, voffB);
;             PG8_WAIT_V(6); PG8_BAR; PG8_MMA(1, 1, At, B1); PG8_BAR;
	s_waitcnt lgkmcnt(3)
	v_mfma_f32_16x16x32_bf16 v[108:111], v[202:205], v[166:169], v[108:111]
	s_waitcnt lgkmcnt(1)
	v_mfma_f32_16x16x32_bf16 v[104:107], v[210:213], v[166:169], v[104:107]
	v_mfma_f32_16x16x32_bf16 v[92:95], v[202:205], v[174:177], v[92:95]
	v_mfma_f32_16x16x32_bf16 v[88:91], v[210:213], v[174:177], v[88:91]
	v_mfma_f32_16x16x32_bf16 v[76:79], v[202:205], v[182:185], v[76:79]
	v_mfma_f32_16x16x32_bf16 v[72:75], v[210:213], v[182:185], v[72:75]
	v_mfma_f32_16x16x32_bf16 v[68:71], v[202:205], v[190:193], v[68:71]
	v_mfma_f32_16x16x32_bf16 v[64:67], v[210:213], v[190:193], v[64:67]
	v_mfma_f32_16x16x32_bf16 v[108:111], v[206:209], v[170:173], v[108:111]
	s_mov_b32 m0, s39
	s_waitcnt lgkmcnt(0)
	v_mfma_f32_16x16x32_bf16 v[104:107], v[214:217], v[170:173], v[104:107]
	v_lshl_add_u64 v[194:195], v[220:221], 0, s[8:9]
	v_mfma_f32_16x16x32_bf16 v[92:95], v[206:209], v[178:181], v[92:95]
	v_mfma_f32_16x16x32_bf16 v[88:91], v[214:217], v[178:181], v[88:91]
	v_mfma_f32_16x16x32_bf16 v[76:79], v[206:209], v[186:189], v[76:79]
	v_mfma_f32_16x16x32_bf16 v[72:75], v[214:217], v[186:189], v[72:75]
	v_mfma_f32_16x16x32_bf16 v[68:71], v[206:209], v[198:201], v[68:71]
	v_mfma_f32_16x16x32_bf16 v[64:67], v[214:217], v[198:201], v[64:67]
	s_barrier
	s_setprio 0
	ds_read_b128 v[166:169], v148 offset:49152
	ds_read_b128 v[170:173], v148 offset:50176
	ds_read_b128 v[174:177], v148 offset:51200
	ds_read_b128 v[178:181], v148 offset:52224
	ds_read_b128 v[182:185], v148 offset:53248
	ds_read_b128 v[186:189], v148 offset:54272
	ds_read_b128 v[190:193], v148 offset:55296
	ds_read_b128 v[198:201], v148 offset:56320
	global_load_lds_dwordx4 v[194:195], off
	v_lshl_add_u64 v[194:195], v[222:223], 0, s[8:9]
	s_mov_b32 m0, s42
	s_nop 0
	global_load_lds_dwordx4 v[194:195], off
	s_waitcnt vmcnt(10)
	s_setprio 1
	s_barrier
	s_waitcnt lgkmcnt(7)
	v_mfma_f32_16x16x32_bf16 v[60:63], v[150:153], v[166:169], v[60:63]
	v_mfma_f32_16x16x32_bf16 v[56:59], v[158:161], v[166:169], v[56:59]
	s_waitcnt lgkmcnt(5)
	v_mfma_f32_16x16x32_bf16 v[52:55], v[150:153], v[174:177], v[52:55]
	v_mfma_f32_16x16x32_bf16 v[48:51], v[158:161], v[174:177], v[48:51]
	s_waitcnt lgkmcnt(3)
	v_mfma_f32_16x16x32_bf16 v[36:39], v[150:153], v[182:185], v[36:39]
	v_mfma_f32_16x16x32_bf16 v[32:35], v[158:161], v[182:185], v[32:35]
	s_waitcnt lgkmcnt(1)
	v_mfma_f32_16x16x32_bf16 v[20:23], v[150:153], v[190:193], v[20:23]
	v_mfma_f32_16x16x32_bf16 v[16:19], v[158:161], v[190:193], v[16:19]
	v_mfma_f32_16x16x32_bf16 v[60:63], v[154:157], v[170:173], v[60:63]
	s_add_u32 s22, s22, 0x80080
	s_addc_u32 s23, s23, 0
	v_mfma_f32_16x16x32_bf16 v[56:59], v[162:165], v[170:173], v[56:59]
	s_add_i32 s24, s24, s29
	v_mfma_f32_16x16x32_bf16 v[52:55], v[154:157], v[178:181], v[52:55]
	v_mfma_f32_16x16x32_bf16 v[48:51], v[162:165], v[178:181], v[48:51]
	v_mfma_f32_16x16x32_bf16 v[36:39], v[154:157], v[186:189], v[36:39]
	v_mfma_f32_16x16x32_bf16 v[32:35], v[162:165], v[186:189], v[32:35]
	s_waitcnt lgkmcnt(0)
	v_mfma_f32_16x16x32_bf16 v[20:23], v[154:157], v[198:201], v[20:23]
	v_mfma_f32_16x16x32_bf16 v[16:19], v[162:165], v[198:201], v[16:19]
	s_barrier
	s_setprio 0
	s_mov_b32 m0, s24
	s_nop 0
	global_load_lds_dwordx4 v132, s[22:23]
	s_add_i32 m0, s24, 0x2000
	s_nop 0
	global_load_lds_dwordx4 v128, s[22:23]
	s_waitcnt vmcnt(6)
	s_setprio 1
	s_barrier
	v_mfma_f32_16x16x32_bf16 v[44:47], v[202:205], v[166:169], v[44:47]
	v_mfma_f32_16x16x32_bf16 v[40:43], v[210:213], v[166:169], v[40:43]
	ds_read_b128 v[150:153], v147
	v_mfma_f32_16x16x32_bf16 v[28:31], v[202:205], v[174:177], v[28:31]
	v_mfma_f32_16x16x32_bf16 v[24:27], v[210:213], v[174:177], v[24:27]
	ds_read_b128 v[154:157], v147 offset:1024
	v_mfma_f32_16x16x32_bf16 v[12:15], v[202:205], v[182:185], v[12:15]
	v_mfma_f32_16x16x32_bf16 v[8:11], v[210:213], v[182:185], v[8:11]
	ds_read_b128 v[158:161], v147 offset:2048
	v_mfma_f32_16x16x32_bf16 v[4:7], v[202:205], v[190:193], v[4:7]
	v_mfma_f32_16x16x32_bf16 v[0:3], v[210:213], v[190:193], v[0:3]
	ds_read_b128 v[162:165], v147 offset:3072
	v_mfma_f32_16x16x32_bf16 v[44:47], v[206:209], v[170:173], v[44:47]
	s_add_i32 s3, s3, 2
	v_mfma_f32_16x16x32_bf16 v[40:43], v[214:217], v[170:173], v[40:43]
	s_add_u32 s52, s52, 0x100
	s_addc_u32 s53, s53, 0
	v_mfma_f32_16x16x32_bf16 v[28:31], v[206:209], v[178:181], v[28:31]
	s_add_u32 s20, s20, 0x100
	s_addc_u32 s21, s21, 0
	v_mfma_f32_16x16x32_bf16 v[24:27], v[214:217], v[178:181], v[24:27]
	s_add_u32 s22, s20, 0xfff80080
	s_addc_u32 s23, s21, -1
	s_cmp_eq_u32 s3, 28
	s_cselect_b32 s25, s15, s23
	s_cselect_b32 s24, s48, s22
	s_cselect_b32 s23, s13, s53
	s_cselect_b32 s22, s49, s52
	s_cmp_gt_u32 s3, 29
	v_mfma_f32_16x16x32_bf16 v[12:15], v[206:209], v[186:189], v[12:15]
	v_mfma_f32_16x16x32_bf16 v[8:11], v[214:217], v[186:189], v[8:11]
	v_mfma_f32_16x16x32_bf16 v[4:7], v[206:209], v[198:201], v[4:7]
	v_mfma_f32_16x16x32_bf16 v[0:3], v[214:217], v[198:201], v[0:3]
	s_barrier
; DI unsigned pack2(float a, float b) { f32x2 v = {a, b}; hwbf16x2 r = __builtin_convertvector(v, hwbf16x2); return __builtin_bit_cast(unsigned, r); }
;     DI void operator()(const f32x4 (&acc)[2][2][4][2], const Unit& u, int wr, int wc, int fr, int fq) const {
;         bf16_t* O = O1; int ldc = ldc1, pn = u.pn; if (pn >= split) { O = O2; ldc = ldc2; pn -= split; }
;         const int row0 = u.pm * BM + wr * 64 + fr, col0 = pn * BM + wc * 32 + 8 * fq;
; #pragma unroll
;         for (int ai = 0; ai < 2; ++ai)
; #pragma unroll
;             for (int m = 0; m < 4; ++m) { bf16_t* rowp = O + (size_t)(row0 + ai * HALF + m * 16) * ldc + col0;
; #pragma unroll
;                 for (int bj = 0; bj < 2; ++bj) { const f32x4 v0 = acc[ai][bj][m][0], v1 = acc[ai][bj][m][1];
;                     u32x4 o; o[0] = pack2(v0[0], v0[1]); o[1] = pack2(v0[2], v0[3]); o[2] = pack2(v1[0], v1[1]); o[3] = pack2(v1[2], v1[3]);
;                     *(u32x4*)(rowp + bj * HALF) = o; } }
;     }
	s_setprio 0
	s_cbranch_scc0 .LBB1_1382
	s_waitcnt lgkmcnt(0)
	s_lshl_b32 s3, s10, 8
	v_mov_b32_e32 v150, v144
	v_mov_b32_e32 v151, v145
	s_add_i32 s3, s3, s37
	v_cvt_pk_bf16_f32 v68, v68, v69
	v_add_u32_e32 v154, s3, v150
	s_lshl_b32 s3, s47, 8
	s_or_b32 s3, s3, s38
	v_lshl_add_u32 v150, v151, 3, s3
	v_ashrrev_i32_e32 v151, 31, v150
	v_lshl_add_u64 v[150:151], v[150:151], 1, s[6:7]
	v_cvt_pk_bf16_f32 v69, v70, v71
	v_cvt_pk_bf16_f32 v70, v64, v65
	v_add_u32_e32 v64, 0x80, v154
	v_mad_i64_i32 v[152:153], s[20:21], v154, s46, v[150:151]
	v_cvt_pk_bf16_f32 v108, v108, v109
	v_cvt_pk_bf16_f32 v109, v110, v111
	v_cvt_pk_bf16_f32 v110, v104, v105
	v_cvt_pk_bf16_f32 v111, v106, v107
	v_add_u32_e32 v104, 16, v154
	v_mad_i64_i32 v[64:65], s[20:21], v64, s46, v[150:151]
	v_cvt_pk_bf16_f32 v44, v44, v45
	v_cvt_pk_bf16_f32 v45, v46, v47
	v_cvt_pk_bf16_f32 v46, v40, v41
	v_cvt_pk_bf16_f32 v47, v42, v43
	v_add_u32_e32 v40, 0x90, v154
	global_store_dwordx4 v[152:153], v[108:111], off offset:256
	v_cvt_pk_bf16_f32 v92, v92, v93
	v_cvt_pk_bf16_f32 v93, v94, v95
	v_mad_i64_i32 v[108:109], s[20:21], v104, s46, v[150:151]
	v_cvt_pk_bf16_f32 v94, v88, v89
	v_cvt_pk_bf16_f32 v95, v90, v91
	v_add_u32_e32 v88, 32, v154
	global_store_dwordx4 v[64:65], v[44:47], off offset:256
	v_cvt_pk_bf16_f32 v28, v28, v29
	v_cvt_pk_bf16_f32 v29, v30, v31
	v_mad_i64_i32 v[44:45], s[20:21], v40, s46, v[150:151]
	v_cvt_pk_bf16_f32 v30, v24, v25
	v_cvt_pk_bf16_f32 v31, v26, v27
	v_add_u32_e32 v24, 0xa0, v154
	global_store_dwordx4 v[108:109], v[92:95], off offset:256
	v_cvt_pk_bf16_f32 v76, v76, v77
	v_cvt_pk_bf16_f32 v77, v78, v79
	v_mad_i64_i32 v[92:93], s[20:21], v88, s46, v[150:151]
	v_cvt_pk_bf16_f32 v78, v72, v73
	v_cvt_pk_bf16_f32 v79, v74, v75
	v_add_u32_e32 v72, 48, v154
	global_store_dwordx4 v[44:45], v[28:31], off offset:256
	v_cvt_pk_bf16_f32 v12, v12, v13
	v_cvt_pk_bf16_f32 v13, v14, v15
	v_mad_i64_i32 v[28:29], s[20:21], v24, s46, v[150:151]
	v_cvt_pk_bf16_f32 v14, v8, v9
	v_cvt_pk_bf16_f32 v15, v10, v11
	v_add_u32_e32 v8, 0xb0, v154
	global_store_dwordx4 v[92:93], v[76:79], off offset:256
	global_store_dwordx4 v[28:29], v[12:15], off offset:256
	v_cvt_pk_bf16_f32 v124, v124, v125
	v_mad_i64_i32 v[76:77], s[20:21], v72, s46, v[150:151]
	v_mad_i64_i32 v[12:13], s[20:21], v8, s46, v[150:151]
	v_cvt_pk_bf16_f32 v125, v126, v127
	v_cvt_pk_bf16_f32 v126, v120, v121
	v_cvt_pk_bf16_f32 v127, v122, v123
	v_cvt_pk_bf16_f32 v104, v116, v117
	v_cvt_pk_bf16_f32 v105, v118, v119
	v_cvt_pk_bf16_f32 v106, v112, v113
	v_cvt_pk_bf16_f32 v107, v114, v115
	v_cvt_pk_bf16_f32 v88, v100, v101
	v_cvt_pk_bf16_f32 v89, v102, v103
	v_cvt_pk_bf16_f32 v90, v96, v97
	v_cvt_pk_bf16_f32 v91, v98, v99
	v_cvt_pk_bf16_f32 v72, v84, v85
	v_cvt_pk_bf16_f32 v73, v86, v87
	v_cvt_pk_bf16_f32 v74, v80, v81
	v_cvt_pk_bf16_f32 v75, v82, v83
	v_cvt_pk_bf16_f32 v71, v66, v67
	v_cvt_pk_bf16_f32 v60, v60, v61
	v_cvt_pk_bf16_f32 v61, v62, v63
	v_cvt_pk_bf16_f32 v62, v56, v57
	v_cvt_pk_bf16_f32 v63, v58, v59
	v_cvt_pk_bf16_f32 v40, v52, v53
	v_cvt_pk_bf16_f32 v41, v54, v55
	v_cvt_pk_bf16_f32 v42, v48, v49
	v_cvt_pk_bf16_f32 v43, v50, v51
	v_cvt_pk_bf16_f32 v24, v36, v37
	v_cvt_pk_bf16_f32 v25, v38, v39
	v_cvt_pk_bf16_f32 v26, v32, v33
	v_cvt_pk_bf16_f32 v27, v34, v35
	v_cvt_pk_bf16_f32 v8, v20, v21
	v_cvt_pk_bf16_f32 v9, v22, v23
	v_cvt_pk_bf16_f32 v10, v16, v17
	v_cvt_pk_bf16_f32 v11, v18, v19
	v_cvt_pk_bf16_f32 v4, v4, v5
	v_cvt_pk_bf16_f32 v5, v6, v7
	v_cvt_pk_bf16_f32 v6, v0, v1
	v_cvt_pk_bf16_f32 v7, v2, v3
	s_and_b64 vcc, exec, s[40:41]
	s_mov_b32 s47, s12
	s_mov_b32 s10, s14
	s_mov_b64 s[20:21], s[18:19]
	s_mov_b64 s[22:23], s[16:17]
	global_store_dwordx4 v[152:153], v[124:127], off
	global_store_dwordx4 v[108:109], v[104:107], off
	global_store_dwordx4 v[92:93], v[88:91], off
	global_store_dwordx4 v[76:77], v[72:75], off
	global_store_dwordx4 v[76:77], v[68:71], off offset:256
	global_store_dwordx4 v[64:65], v[60:63], off
	global_store_dwordx4 v[44:45], v[40:43], off
	global_store_dwordx4 v[28:29], v[24:27], off
	global_store_dwordx4 v[12:13], v[8:11], off
	global_store_dwordx4 v[12:13], v[4:7], off offset:256
	s_cbranch_vccz .LBB1_1379
	s_waitcnt vmcnt(0)
	s_cmpk_gt_u32 s4, 0xff
	s_cbranch_scc1 .LBB1_1386
	s_barrier

;     DI const char* a(const Unit& u) const { return (const char*)(A + (size_t)u.pm * BM * lda); }
;     DI const char* a(const Unit& u) const { return (const char*)(A + (size_t)u.pm * BM * 2048 + (u.pn >> 1) * 512); }
; #define PG8_STAGE(bufoff, gbase, voff) do { _Pragma("unroll") for (int _i = 0; _i < 2; ++_i) \
;         __builtin_amdgcn_global_load_lds((const unsigned*)((const char*)(gbase) + (voff)[_i]), (LAS unsigned*)(lds + (bufoff) + ldsw + _i * 8192), 16, 0, 0); } while (0)
; #define PG8_LDA(dst, b, h) do { _Pragma("unroll") for (int m = 0; m < 4; ++m) _Pragma("unroll") for (int k = 0; k < 2; ++k) dst[m][k] = *(const LAS bf16x8*)(lds + PG8_SA(b, h) + aoff + m * 2048 + k * 1024); } while (0)
; #define PG8_LDB(dst, b, h) do { _Pragma("unroll") for (int n = 0; n < 2; ++n) _Pragma("unroll") for (int k = 0; k < 2; ++k) dst[n][k] = *(const LAS bf16x8*)(lds + PG8_SB(b, h) + boff + n * 2048 + k * 1024); } while (0)
; #define PG8_WAIT_L(n) asm volatile("s_waitcnt lgkmcnt(" #n ")" ::: "memory")
; #define PG8_BAR __builtin_amdgcn_s_barrier()
;     DI const char* a(const Unit& u) const { return (const char*)((u.pn < 12 ? A1 : A2) + (size_t)u.pm * BM * 512); }
; template <class Map, class Epi>
; DI void gemm_phase(LAS unsigned char* lds, const Map& MP, const Epi& E, const int nM, const int nN, const int K, const int lda, const int ldb) {
;     ...
;         const bool has_next = sched_next(ui + 1, nM, nN, G, cblk, nxt);
;         const char* nA = has_next ? MP.a(nxt) : cA; const char* nB = has_next ? MP.b(nxt) : cB;
;         for (int t = 0; t < nt; t += 2) {
;             const bool last = (t == nt - 2);
;             const char* a1 = cA + (size_t)(t + 1) * kstep;
;             const char* a2 = last ? nA : cA + (size_t)(t + 2) * kstep; const char* b2 = last ? nB : cB + (size_t)(t + 2) * kstep;
;             const char* a3 = a2 + kstep; const char* b3 = b2 + kstep;
;             PG8_LDB(B0, 0, 0); PG8_SCHED; PG8_LDA(At, 0, 0); PG8_STAGE(PG8_SA(1, 1), a1 + hstepA, voffA);
;             PG8_WAIT_L(8); PG8_BAR; PG8_WAIT_L(0); PG8_MMA(0, 0, At, B0); PG8_BAR; PG8_SCHED;
;             PG8_LDB(B1, 0, 1); PG8_STAGE(PG8_SB(0, 0), b2, voffB);
;             PG8_BAR; PG8_WAIT_L(0); PG8_MMA(0, 1, At, B1); PG8_BAR;
;             PG8_LDA(At, 0, 1); PG8_STAGE(PG8_SA(0, 0), a2, voffA);
;             PG8_BAR; PG8_WAIT_L(0); PG8_MMA(1, 0, At, B0); PG8_BAR; PG8_SCHED;
.LBB1_1528:
	s_add_i32 s3, s49, -12
	s_cmp_lt_i32 s49, 12
	s_cselect_b32 s53, s27, s29
	s_cselect_b32 s54, s28, s30
	s_ashr_i32 s13, s49, 31
	s_cmp_lt_i32 s49, 12
	s_cselect_b32 s22, s24, s26
	s_cselect_b32 s23, s5, s25
	s_cselect_b32 s17, s13, 0
	s_cselect_b32 s16, s49, s3
	s_ashr_i32 s13, s12, 31
	v_cmp_lt_i64_e32 vcc, s[14:15], v[140:141]
	s_lshl_b64 s[14:15], s[12:13], 18
	s_add_u32 s14, s23, s14
	s_addc_u32 s15, s22, s15
	s_and_b64 s[22:23], vcc, exec
	s_cselect_b32 s13, s15, s21
	s_cselect_b32 s52, s14, s20
	s_lshl_b64 s[16:17], s[16:17], 18
	s_add_u32 s16, s53, s16
	s_addc_u32 s17, s54, s17
	s_and_b64 s[22:23], vcc, exec
	s_cselect_b32 s53, s17, s19
	s_cselect_b32 s54, s16, s18
	s_add_u32 s55, s18, 0x100
	s_addc_u32 s56, s19, 0
	s_add_u32 s18, s20, 0x20080
	v_mov_b32_e32 v0, 0
	s_addc_u32 s19, s21, 0
	s_mov_b32 s3, -2
	v_mov_b32_e32 v1, 0
	v_mov_b64_e32 v[2:3], 0
	v_mov_b64_e32 v[4:5], 0
	v_mov_b64_e32 v[6:7], 0
	v_mov_b64_e32 v[8:9], 0
	v_mov_b64_e32 v[10:11], 0
	v_mov_b64_e32 v[12:13], 0
	v_mov_b64_e32 v[14:15], 0
	v_mov_b64_e32 v[16:17], 0
	v_mov_b64_e32 v[18:19], 0
	v_mov_b64_e32 v[20:21], 0
	v_mov_b64_e32 v[22:23], 0
	v_mov_b64_e32 v[24:25], 0
	v_mov_b64_e32 v[26:27], 0
	v_mov_b64_e32 v[28:29], 0
	v_mov_b64_e32 v[30:31], 0
	v_mov_b64_e32 v[32:33], 0
	v_mov_b64_e32 v[34:35], 0
	v_mov_b64_e32 v[36:37], 0
	v_mov_b64_e32 v[38:39], 0
	v_mov_b64_e32 v[40:41], 0
	v_mov_b64_e32 v[42:43], 0
	v_mov_b64_e32 v[44:45], 0
	v_mov_b64_e32 v[46:47], 0
	v_mov_b64_e32 v[48:49], 0
	v_mov_b64_e32 v[50:51], 0
	v_mov_b64_e32 v[52:53], 0
	v_mov_b64_e32 v[54:55], 0
	v_mov_b64_e32 v[56:57], 0
	v_mov_b64_e32 v[58:59], 0
	v_mov_b64_e32 v[60:61], 0
	v_mov_b64_e32 v[62:63], 0
	v_mov_b64_e32 v[64:65], 0
	v_mov_b64_e32 v[66:67], 0
	v_mov_b64_e32 v[68:69], 0
	v_mov_b64_e32 v[70:71], 0
	v_mov_b64_e32 v[72:73], 0
	v_mov_b64_e32 v[74:75], 0
	v_mov_b64_e32 v[76:77], 0
	v_mov_b64_e32 v[78:79], 0
	v_mov_b64_e32 v[80:81], 0
	v_mov_b64_e32 v[82:83], 0
	v_mov_b64_e32 v[84:85], 0
	v_mov_b64_e32 v[86:87], 0
	v_mov_b64_e32 v[88:89], 0
	v_mov_b64_e32 v[90:91], 0
	v_mov_b64_e32 v[92:93], 0
	v_mov_b64_e32 v[94:95], 0
	v_mov_b64_e32 v[96:97], 0
	v_mov_b64_e32 v[98:99], 0
	v_mov_b64_e32 v[100:101], 0
	v_mov_b64_e32 v[102:103], 0
	v_mov_b64_e32 v[104:105], 0
	v_mov_b64_e32 v[106:107], 0
	v_mov_b64_e32 v[108:109], 0
	v_mov_b64_e32 v[110:111], 0
	v_mov_b64_e32 v[112:113], 0
	v_mov_b64_e32 v[114:115], 0
	v_mov_b64_e32 v[116:117], 0
	v_mov_b64_e32 v[118:119], 0
	v_mov_b64_e32 v[120:121], 0
	v_mov_b64_e32 v[122:123], 0
	v_mov_b64_e32 v[124:125], 0
	v_mov_b64_e32 v[126:127], 0
	ds_read_b128 v[150:153], v147
	ds_read_b128 v[154:157], v147 offset:1024
	ds_read_b128 v[158:161], v147 offset:2048
	ds_read_b128 v[162:165], v147 offset:3072
	s_add_u32 s20, s18, 0xfffe0080
	s_addc_u32 s21, s19, -1
	s_cmp_eq_u32 s3, 4
	s_cselect_b32 s23, s13, s21
	s_cselect_b32 s22, s52, s20
	s_cselect_b32 s21, s53, s56
	s_cselect_b32 s20, s54, s55
.LBB1_1529:
	s_add_i32 m0, s11, 0xc000
	ds_read_b128 v[166:169], v148
	ds_read_b128 v[170:173], v148 offset:1024
	ds_read_b128 v[174:177], v148 offset:2048
	ds_read_b128 v[178:181], v148 offset:3072
	ds_read_b128 v[182:185], v148 offset:4096
	ds_read_b128 v[186:189], v148 offset:5120
	ds_read_b128 v[190:193], v148 offset:6144
	ds_read_b128 v[198:201], v148 offset:7168
	global_load_lds_dwordx4 v138, s[18:19]
	s_add_i32 m0, s11, 0xe000
	s_nop 0
	global_load_lds_dwordx4 v136, s[18:19]
	s_waitcnt lgkmcnt(8)
	s_setprio 1
	s_barrier
	s_waitcnt lgkmcnt(7)
	v_mfma_f32_16x16x32_bf16 v[124:127], v[150:153], v[166:169], v[124:127]
	v_mfma_f32_16x16x32_bf16 v[120:123], v[158:161], v[166:169], v[120:123]
	s_waitcnt lgkmcnt(5)
	v_mfma_f32_16x16x32_bf16 v[116:119], v[150:153], v[174:177], v[116:119]
	v_mfma_f32_16x16x32_bf16 v[112:115], v[158:161], v[174:177], v[112:115]
	s_waitcnt lgkmcnt(3)
	v_mfma_f32_16x16x32_bf16 v[100:103], v[150:153], v[182:185], v[100:103]
	v_mfma_f32_16x16x32_bf16 v[96:99], v[158:161], v[182:185], v[96:99]
	s_waitcnt lgkmcnt(1)
	v_mfma_f32_16x16x32_bf16 v[84:87], v[150:153], v[190:193], v[84:87]
	v_mfma_f32_16x16x32_bf16 v[80:83], v[158:161], v[190:193], v[80:83]
	v_mfma_f32_16x16x32_bf16 v[124:127], v[154:157], v[170:173], v[124:127]
	s_add_i32 s57, s47, s31
	v_mfma_f32_16x16x32_bf16 v[120:123], v[162:165], v[170:173], v[120:123]
	v_lshl_add_u64 v[194:195], s[20:21], 0, v[132:133]
	v_mfma_f32_16x16x32_bf16 v[116:119], v[154:157], v[178:181], v[116:119]
	v_lshl_add_u64 v[218:219], s[20:21], 0, v[128:129]
	v_mfma_f32_16x16x32_bf16 v[112:115], v[162:165], v[178:181], v[112:115]
	v_mfma_f32_16x16x32_bf16 v[100:103], v[154:157], v[186:189], v[100:103]
	v_mfma_f32_16x16x32_bf16 v[96:99], v[162:165], v[186:189], v[96:99]
	s_waitcnt lgkmcnt(0)
	v_mfma_f32_16x16x32_bf16 v[84:87], v[154:157], v[198:201], v[84:87]
	v_mfma_f32_16x16x32_bf16 v[80:83], v[162:165], v[198:201], v[80:83]
	s_barrier
	s_setprio 0
	s_mov_b32 m0, s57
	ds_read_b128 v[202:205], v149
	ds_read_b128 v[206:209], v149 offset:1024
	ds_read_b128 v[210:213], v149 offset:2048
	ds_read_b128 v[214:217], v149 offset:3072
	global_load_lds_dwordx4 v[194:195], off
	s_add_i32 m0, s57, 0x2000
	s_nop 0
	global_load_lds_dwordx4 v[218:219], off
	s_setprio 1
	s_barrier
; #define PG8_STAGE(bufoff, gbase, voff) do { _Pragma("unroll") for (int _i = 0; _i < 2; ++_i) \
;         __builtin_amdgcn_global_load_lds((const unsigned*)((const char*)(gbase) + (voff)[_i]), (LAS unsigned*)(lds + (bufoff) + ldsw + _i * 8192), 16, 0, 0); } while (0)
; #define PG8_LDA(dst, b, h) do { _Pragma("unroll") for (int m = 0; m < 4; ++m) _Pragma("unroll") for (int k = 0; k < 2; ++k) dst[m][k] = *(const LAS bf16x8*)(lds + PG8_SA(b, h) + aoff + m * 2048 + k * 1024); } while (0)
; #define PG8_LDB(dst, b, h) do { _Pragma("unroll") for (int n = 0; n < 2; ++n) _Pragma("unroll") for (int k = 0; k < 2; ++k) dst[n][k] = *(const LAS bf16x8*)(lds + PG8_SB(b, h) + boff + n * 2048 + k * 1024); } while (0)
; #define PG8_MMA(ai, bj, At, Bt) do { __builtin_amdgcn_s_setprio(1); _Pragma("unroll") for (int m = 0; m < 4; ++m) _Pragma("unroll") for (int n = 0; n < 2; ++n) _Pragma("unroll") for (int k = 0; k < 2; ++k) \
;         acc[ai][bj][m][n] = __builtin_amdgcn_mfma_f32_16x16x32_bf16(Bt[n][k], At[m][k], acc[ai][bj][m][n], 0, 0, 0); __builtin_amdgcn_s_setprio(0); } while (0)
; #define PG8_WAIT_V(n) asm volatile("s_waitcnt vmcnt(" #n ")" ::: "memory")
; #define PG8_WAIT_L(n) asm volatile("s_waitcnt lgkmcnt(" #n ")" ::: "memory")
; #define PG8_BAR __builtin_amdgcn_s_barrier()
; #define PG8_SCHED __builtin_amdgcn_sched_barrier(0)
; template <class Map, class Epi>
; DI void gemm_phase(LAS unsigned char* lds, const Map& MP, const Epi& E, const int nM, const int nN, const int K, const int lda, const int ldb) {
;     ...
;             PG8_WAIT_L(8); PG8_BAR; PG8_WAIT_L(0); PG8_MMA(0, 0, At, B0); PG8_BAR; PG8_SCHED;
;             PG8_LDB(B1, 0, 1); PG8_STAGE(PG8_SB(0, 0), b2, voffB);
;             PG8_BAR; PG8_WAIT_L(0); PG8_MMA(0, 1, At, B1); PG8_BAR;
;             PG8_LDA(At, 0, 1); PG8_STAGE(PG8_SA(0, 0), a2, voffA);
;             PG8_BAR; PG8_WAIT_L(0); PG8_MMA(1, 0, At, B0); PG8_BAR; PG8_SCHED;
;             PG8_STAGE(PG8_SB(0, 1), b2 + hstepB, voffB);
;             PG8_WAIT_V(6); PG8_BAR; PG8_MMA(1, 1, At, B1); PG8_BAR;
;             PG8_LDB(B0, 1, 0); PG8_SCHED; PG8_LDA(At, 1, 0); PG8_STAGE(PG8_SA(0, 1), a2 + hstepA, voffA);
;             PG8_WAIT_L(8); PG8_BAR; PG8_WAIT_L(0); PG8_MMA(0, 0, At, B0); PG8_BAR; PG8_SCHED;
;             PG8_LDB(B1, 1, 1); PG8_STAGE(PG8_SB(1, 0), b3, voffB);
	s_waitcnt lgkmcnt(3)
	v_mfma_f32_16x16x32_bf16 v[108:111], v[202:205], v[166:169], v[108:111]
	s_waitcnt lgkmcnt(1)
	v_mfma_f32_16x16x32_bf16 v[104:107], v[210:213], v[166:169], v[104:107]
	v_mfma_f32_16x16x32_bf16 v[92:95], v[202:205], v[174:177], v[92:95]
	v_mfma_f32_16x16x32_bf16 v[88:91], v[210:213], v[174:177], v[88:91]
	v_mfma_f32_16x16x32_bf16 v[76:79], v[202:205], v[182:185], v[76:79]
	v_mfma_f32_16x16x32_bf16 v[72:75], v[210:213], v[182:185], v[72:75]
	v_mfma_f32_16x16x32_bf16 v[68:71], v[202:205], v[190:193], v[68:71]
	v_mfma_f32_16x16x32_bf16 v[64:67], v[210:213], v[190:193], v[64:67]
	v_mfma_f32_16x16x32_bf16 v[108:111], v[206:209], v[170:173], v[108:111]
	v_lshl_add_u64 v[222:223], s[22:23], 0, v[130:131]
	s_mov_b32 m0, s11
	s_waitcnt lgkmcnt(0)
	v_mfma_f32_16x16x32_bf16 v[104:107], v[214:217], v[170:173], v[104:107]
	v_lshl_add_u64 v[220:221], s[22:23], 0, v[134:135]
	v_mfma_f32_16x16x32_bf16 v[92:95], v[206:209], v[178:181], v[92:95]
	v_mfma_f32_16x16x32_bf16 v[88:91], v[214:217], v[178:181], v[88:91]
	v_mfma_f32_16x16x32_bf16 v[76:79], v[206:209], v[186:189], v[76:79]
	v_mfma_f32_16x16x32_bf16 v[72:75], v[214:217], v[186:189], v[72:75]
	v_mfma_f32_16x16x32_bf16 v[68:71], v[206:209], v[198:201], v[68:71]
	v_mfma_f32_16x16x32_bf16 v[64:67], v[214:217], v[198:201], v[64:67]
	s_barrier
	s_setprio 0
	ds_read_b128 v[166:169], v148 offset:16384
	ds_read_b128 v[170:173], v148 offset:17408
	ds_read_b128 v[174:177], v148 offset:18432
	ds_read_b128 v[178:181], v148 offset:19456
	ds_read_b128 v[182:185], v148 offset:20480
	ds_read_b128 v[186:189], v148 offset:21504
	ds_read_b128 v[190:193], v148 offset:22528
	ds_read_b128 v[198:201], v148 offset:23552
	global_load_lds_dwordx4 v[220:221], off
	s_mov_b32 m0, s35
	s_nop 0
	global_load_lds_dwordx4 v[222:223], off
	s_waitcnt vmcnt(10)
	s_setprio 1
	s_barrier
	s_waitcnt lgkmcnt(7)
	v_mfma_f32_16x16x32_bf16 v[60:63], v[150:153], v[166:169], v[60:63]
	v_mfma_f32_16x16x32_bf16 v[56:59], v[158:161], v[166:169], v[56:59]
	s_waitcnt lgkmcnt(5)
	v_mfma_f32_16x16x32_bf16 v[52:55], v[150:153], v[174:177], v[52:55]
	v_mfma_f32_16x16x32_bf16 v[48:51], v[158:161], v[174:177], v[48:51]
	s_waitcnt lgkmcnt(3)
	v_mfma_f32_16x16x32_bf16 v[36:39], v[150:153], v[182:185], v[36:39]
	v_mfma_f32_16x16x32_bf16 v[32:35], v[158:161], v[182:185], v[32:35]
	s_waitcnt lgkmcnt(1)
	v_mfma_f32_16x16x32_bf16 v[20:23], v[150:153], v[190:193], v[20:23]
	v_mfma_f32_16x16x32_bf16 v[16:19], v[158:161], v[190:193], v[16:19]
	v_mfma_f32_16x16x32_bf16 v[60:63], v[154:157], v[170:173], v[60:63]
	s_add_u32 s58, s20, 0x20000
	s_addc_u32 s59, s21, 0
	v_mfma_f32_16x16x32_bf16 v[56:59], v[162:165], v[170:173], v[56:59]
	s_add_i32 s57, s48, s31
	v_mfma_f32_16x16x32_bf16 v[52:55], v[154:157], v[178:181], v[52:55]
	v_mfma_f32_16x16x32_bf16 v[48:51], v[162:165], v[178:181], v[48:51]
	v_mfma_f32_16x16x32_bf16 v[36:39], v[154:157], v[186:189], v[36:39]
	v_mfma_f32_16x16x32_bf16 v[32:35], v[162:165], v[186:189], v[32:35]
	s_waitcnt lgkmcnt(0)
	v_mfma_f32_16x16x32_bf16 v[20:23], v[154:157], v[198:201], v[20:23]
	v_mfma_f32_16x16x32_bf16 v[16:19], v[162:165], v[198:201], v[16:19]
	s_barrier
	s_setprio 0
	s_mov_b32 m0, s57
	s_nop 0
	global_load_lds_dwordx4 v132, s[58:59]
	s_add_i32 m0, s57, 0x2000
	s_nop 0
	global_load_lds_dwordx4 v128, s[58:59]
	s_waitcnt vmcnt(6)
	s_setprio 1
	s_barrier
	v_mfma_f32_16x16x32_bf16 v[44:47], v[202:205], v[166:169], v[44:47]
	v_mfma_f32_16x16x32_bf16 v[40:43], v[210:213], v[166:169], v[40:43]
	s_add_i32 s57, 0, 0x18000
	v_add_u32_e32 v162, s57, v146
	ds_read_b128 v[150:153], v162
	v_mfma_f32_16x16x32_bf16 v[28:31], v[202:205], v[174:177], v[28:31]
	v_mfma_f32_16x16x32_bf16 v[24:27], v[210:213], v[174:177], v[24:27]
	ds_read_b128 v[154:157], v162 offset:1024
	v_mfma_f32_16x16x32_bf16 v[12:15], v[202:205], v[182:185], v[12:15]
	v_mfma_f32_16x16x32_bf16 v[8:11], v[210:213], v[182:185], v[8:11]
	ds_read_b128 v[158:161], v162 offset:2048
	v_mfma_f32_16x16x32_bf16 v[4:7], v[202:205], v[190:193], v[4:7]
	v_mfma_f32_16x16x32_bf16 v[0:3], v[210:213], v[190:193], v[0:3]
	ds_read_b128 v[162:165], v162 offset:3072
	v_mfma_f32_16x16x32_bf16 v[44:47], v[206:209], v[170:173], v[44:47]
	s_add_u32 s22, s22, 0x20000
	s_addc_u32 s23, s23, 0
	v_mfma_f32_16x16x32_bf16 v[40:43], v[214:217], v[170:173], v[40:43]
	v_mfma_f32_16x16x32_bf16 v[28:31], v[206:209], v[178:181], v[28:31]
	v_mfma_f32_16x16x32_bf16 v[24:27], v[214:217], v[178:181], v[24:27]
	v_mfma_f32_16x16x32_bf16 v[12:15], v[206:209], v[186:189], v[12:15]
	v_mfma_f32_16x16x32_bf16 v[8:11], v[214:217], v[186:189], v[8:11]
	v_mfma_f32_16x16x32_bf16 v[4:7], v[206:209], v[198:201], v[4:7]
	v_mfma_f32_16x16x32_bf16 v[0:3], v[214:217], v[198:201], v[0:3]
	s_barrier
	s_setprio 0
	s_mov_b32 m0, s36
	ds_read_b128 v[166:169], v148 offset:32768
	ds_read_b128 v[170:173], v148 offset:33792
	ds_read_b128 v[174:177], v148 offset:34816
	ds_read_b128 v[178:181], v148 offset:35840
	ds_read_b128 v[182:185], v148 offset:36864
	ds_read_b128 v[186:189], v148 offset:37888
	ds_read_b128 v[190:193], v148 offset:38912
	ds_read_b128 v[198:201], v148 offset:39936
	global_load_lds_dwordx4 v134, s[22:23]
	s_mov_b32 m0, s37
	s_nop 0
	global_load_lds_dwordx4 v130, s[22:23]
	s_waitcnt lgkmcnt(8)
	s_setprio 1
	s_barrier
; #define PG8_STAGE(bufoff, gbase, voff) do { _Pragma("unroll") for (int _i = 0; _i < 2; ++_i) \
;         __builtin_amdgcn_global_load_lds((const unsigned*)((const char*)(gbase) + (voff)[_i]), (LAS unsigned*)(lds + (bufoff) + ldsw + _i * 8192), 16, 0, 0); } while (0)
; #define PG8_LDA(dst, b, h) do { _Pragma("unroll") for (int m = 0; m < 4; ++m) _Pragma("unroll") for (int k = 0; k < 2; ++k) dst[m][k] = *(const LAS bf16x8*)(lds + PG8_SA(b, h) + aoff + m * 2048 + k * 1024); } while (0)
; #define PG8_LDB(dst, b, h) do { _Pragma("unroll") for (int n = 0; n < 2; ++n) _Pragma("unroll") for (int k = 0; k < 2; ++k) dst[n][k] = *(const LAS bf16x8*)(lds + PG8_SB(b, h) + boff + n * 2048 + k * 1024); } while (0)
; #define PG8_MMA(ai, bj, At, Bt) do { __builtin_amdgcn_s_setprio(1); _Pragma("unroll") for (int m = 0; m < 4; ++m) _Pragma("unroll") for (int n = 0; n < 2; ++n) _Pragma("unroll") for (int k = 0; k < 2; ++k) \
;         acc[ai][bj][m][n] = __builtin_amdgcn_mfma_f32_16x16x32_bf16(Bt[n][k], At[m][k], acc[ai][bj][m][n], 0, 0, 0); __builtin_amdgcn_s_setprio(0); } while (0)
; #define PG8_WAIT_V(n) asm volatile("s_waitcnt vmcnt(" #n ")" ::: "memory")
; #define PG8_WAIT_L(n) asm volatile("s_waitcnt lgkmcnt(" #n ")" ::: "memory")
; #define PG8_BAR __builtin_amdgcn_s_barrier()
; #define PG8_SCHED __builtin_amdgcn_sched_barrier(0)
; template <class Map, class Epi>
; DI void gemm_phase(LAS unsigned char* lds, const Map& MP, const Epi& E, const int nM, const int nN, const int K, const int lda, const int ldb) {
;     ...
;             PG8_WAIT_L(8); PG8_BAR; PG8_WAIT_L(0); PG8_MMA(0, 0, At, B0); PG8_BAR; PG8_SCHED;
;             PG8_LDB(B1, 1, 1); PG8_STAGE(PG8_SB(1, 0), b3, voffB);
;             PG8_BAR; PG8_WAIT_L(0); PG8_MMA(0, 1, At, B1); PG8_BAR;
;             PG8_LDA(At, 1, 1); PG8_STAGE(PG8_SA(1, 0), a3, voffA);
;             PG8_BAR; PG8_WAIT_L(0); PG8_MMA(1, 0, At, B0); PG8_BAR; PG8_SCHED;
;             PG8_STAGE(PG8_SB(1, 1), b3 + hstepB, voffB);
;             PG8_WAIT_V(6); PG8_BAR; PG8_MMA(1, 1, At, B1); PG8_BAR;
	s_waitcnt lgkmcnt(7)
	v_mfma_f32_16x16x32_bf16 v[124:127], v[150:153], v[166:169], v[124:127]
	v_mfma_f32_16x16x32_bf16 v[120:123], v[158:161], v[166:169], v[120:123]
	s_waitcnt lgkmcnt(5)
	v_mfma_f32_16x16x32_bf16 v[116:119], v[150:153], v[174:177], v[116:119]
	v_mfma_f32_16x16x32_bf16 v[112:115], v[158:161], v[174:177], v[112:115]
	s_waitcnt lgkmcnt(3)
	v_mfma_f32_16x16x32_bf16 v[100:103], v[150:153], v[182:185], v[100:103]
	v_mfma_f32_16x16x32_bf16 v[96:99], v[158:161], v[182:185], v[96:99]
	s_waitcnt lgkmcnt(1)
	v_mfma_f32_16x16x32_bf16 v[84:87], v[150:153], v[190:193], v[84:87]
	v_mfma_f32_16x16x32_bf16 v[80:83], v[158:161], v[190:193], v[80:83]
	v_mfma_f32_16x16x32_bf16 v[124:127], v[154:157], v[170:173], v[124:127]
	s_add_i32 s22, 0, 0x1c000
	v_mfma_f32_16x16x32_bf16 v[120:123], v[162:165], v[170:173], v[120:123]
	s_add_i32 s23, s57, s31
	v_mfma_f32_16x16x32_bf16 v[116:119], v[154:157], v[178:181], v[116:119]
	v_add_u32_e32 v196, s22, v146
	v_mfma_f32_16x16x32_bf16 v[112:115], v[162:165], v[178:181], v[112:115]
	v_lshl_add_u64 v[194:195], v[194:195], 0, s[8:9]
	v_mfma_f32_16x16x32_bf16 v[100:103], v[154:157], v[186:189], v[100:103]
	v_mfma_f32_16x16x32_bf16 v[96:99], v[162:165], v[186:189], v[96:99]
	s_waitcnt lgkmcnt(0)
	v_mfma_f32_16x16x32_bf16 v[84:87], v[154:157], v[198:201], v[84:87]
	v_mfma_f32_16x16x32_bf16 v[80:83], v[162:165], v[198:201], v[80:83]
	s_barrier
	s_setprio 0
	s_mov_b32 m0, s23
	ds_read_b128 v[202:205], v196
	ds_read_b128 v[206:209], v196 offset:1024
	ds_read_b128 v[210:213], v196 offset:2048
	ds_read_b128 v[214:217], v196 offset:3072
	global_load_lds_dwordx4 v[194:195], off
	v_lshl_add_u64 v[194:195], v[218:219], 0, s[8:9]
	s_add_i32 m0, s23, 0x2000
	s_nop 0
	global_load_lds_dwordx4 v[194:195], off
	s_setprio 1
	s_barrier
	s_waitcnt lgkmcnt(3)
	v_mfma_f32_16x16x32_bf16 v[108:111], v[202:205], v[166:169], v[108:111]
	s_waitcnt lgkmcnt(1)
	v_mfma_f32_16x16x32_bf16 v[104:107], v[210:213], v[166:169], v[104:107]
	v_mfma_f32_16x16x32_bf16 v[92:95], v[202:205], v[174:177], v[92:95]
	v_mfma_f32_16x16x32_bf16 v[88:91], v[210:213], v[174:177], v[88:91]
	v_mfma_f32_16x16x32_bf16 v[76:79], v[202:205], v[182:185], v[76:79]
	v_mfma_f32_16x16x32_bf16 v[72:75], v[210:213], v[182:185], v[72:75]
	v_mfma_f32_16x16x32_bf16 v[68:71], v[202:205], v[190:193], v[68:71]
	v_mfma_f32_16x16x32_bf16 v[64:67], v[210:213], v[190:193], v[64:67]
	v_mfma_f32_16x16x32_bf16 v[108:111], v[206:209], v[170:173], v[108:111]
	s_mov_b32 m0, s43
	s_waitcnt lgkmcnt(0)
	v_mfma_f32_16x16x32_bf16 v[104:107], v[214:217], v[170:173], v[104:107]
	v_lshl_add_u64 v[194:195], v[220:221], 0, s[8:9]
	v_mfma_f32_16x16x32_bf16 v[92:95], v[206:209], v[178:181], v[92:95]
	v_mfma_f32_16x16x32_bf16 v[88:91], v[214:217], v[178:181], v[88:91]
	v_mfma_f32_16x16x32_bf16 v[76:79], v[206:209], v[186:189], v[76:79]
	v_mfma_f32_16x16x32_bf16 v[72:75], v[214:217], v[186:189], v[72:75]
	v_mfma_f32_16x16x32_bf16 v[68:71], v[206:209], v[198:201], v[68:71]
	v_mfma_f32_16x16x32_bf16 v[64:67], v[214:217], v[198:201], v[64:67]
	s_barrier
	s_setprio 0
	ds_read_b128 v[166:169], v148 offset:49152
	ds_read_b128 v[170:173], v148 offset:50176
	ds_read_b128 v[174:177], v148 offset:51200
	ds_read_b128 v[178:181], v148 offset:52224
	ds_read_b128 v[182:185], v148 offset:53248
	ds_read_b128 v[186:189], v148 offset:54272
	ds_read_b128 v[190:193], v148 offset:55296
	ds_read_b128 v[198:201], v148 offset:56320
	global_load_lds_dwordx4 v[194:195], off
	v_lshl_add_u64 v[194:195], v[222:223], 0, s[8:9]
	s_mov_b32 m0, s44
	s_nop 0
	global_load_lds_dwordx4 v[194:195], off
	s_waitcnt vmcnt(10)
	s_setprio 1
	s_barrier
	s_waitcnt lgkmcnt(7)
	v_mfma_f32_16x16x32_bf16 v[60:63], v[150:153], v[166:169], v[60:63]
	v_mfma_f32_16x16x32_bf16 v[56:59], v[158:161], v[166:169], v[56:59]
	s_waitcnt lgkmcnt(5)
	v_mfma_f32_16x16x32_bf16 v[52:55], v[150:153], v[174:177], v[52:55]
	v_mfma_f32_16x16x32_bf16 v[48:51], v[158:161], v[174:177], v[48:51]
	s_waitcnt lgkmcnt(3)
	v_mfma_f32_16x16x32_bf16 v[36:39], v[150:153], v[182:185], v[36:39]
	v_mfma_f32_16x16x32_bf16 v[32:35], v[158:161], v[182:185], v[32:35]
	s_waitcnt lgkmcnt(1)
	v_mfma_f32_16x16x32_bf16 v[20:23], v[150:153], v[190:193], v[20:23]
	v_mfma_f32_16x16x32_bf16 v[16:19], v[158:161], v[190:193], v[16:19]
	v_mfma_f32_16x16x32_bf16 v[60:63], v[154:157], v[170:173], v[60:63]
	s_add_u32 s20, s20, 0x20080
	s_addc_u32 s21, s21, 0
	v_mfma_f32_16x16x32_bf16 v[56:59], v[162:165], v[170:173], v[56:59]
	s_add_i32 s22, s22, s31
	v_mfma_f32_16x16x32_bf16 v[52:55], v[154:157], v[178:181], v[52:55]
	v_mfma_f32_16x16x32_bf16 v[48:51], v[162:165], v[178:181], v[48:51]
	v_mfma_f32_16x16x32_bf16 v[36:39], v[154:157], v[186:189], v[36:39]
	v_mfma_f32_16x16x32_bf16 v[32:35], v[162:165], v[186:189], v[32:35]
	s_waitcnt lgkmcnt(0)
	v_mfma_f32_16x16x32_bf16 v[20:23], v[154:157], v[198:201], v[20:23]
	v_mfma_f32_16x16x32_bf16 v[16:19], v[162:165], v[198:201], v[16:19]
	s_barrier
	s_setprio 0
	s_mov_b32 m0, s22
	s_nop 0
	global_load_lds_dwordx4 v132, s[20:21]
	s_add_i32 m0, s22, 0x2000
	s_nop 0
	global_load_lds_dwordx4 v128, s[20:21]
	s_waitcnt vmcnt(6)
	s_setprio 1
	s_barrier
; DI unsigned pack2(float a, float b) { f32x2 v = {a, b}; hwbf16x2 r = __builtin_convertvector(v, hwbf16x2); return __builtin_bit_cast(unsigned, r); }
;     DI void operator()(const f32x4 (&acc)[2][2][4][2], const Unit& u, int wr, int wc, int fr, int fq) const {
;         bf16_t* O = O1; int ldc = ldc1, pn = u.pn; if (pn >= split) { O = O2; ldc = ldc2; pn -= split; }
;         const int row0 = u.pm * BM + wr * 64 + fr, col0 = pn * BM + wc * 32 + 8 * fq;
; #pragma unroll
;         for (int ai = 0; ai < 2; ++ai)
; #pragma unroll
;             for (int m = 0; m < 4; ++m) { bf16_t* rowp = O + (size_t)(row0 + ai * HALF + m * 16) * ldc + col0;
; #pragma unroll
;                 for (int bj = 0; bj < 2; ++bj) { const f32x4 v0 = acc[ai][bj][m][0], v1 = acc[ai][bj][m][1];
;                     u32x4 o; o[0] = pack2(v0[0], v0[1]); o[1] = pack2(v0[2], v0[3]); o[2] = pack2(v1[0], v1[1]); o[3] = pack2(v1[2], v1[3]);
;                     *(u32x4*)(rowp + bj * HALF) = o; } }
;     }
; template <class Map, class Epi>
; DI void gemm_phase(LAS unsigned char* lds, const Map& MP, const Epi& E, const int nM, const int nN, const int K, const int lda, const int ldb) {
;     ...
;             const bool last = (t == nt - 2);
;             const char* a1 = cA + (size_t)(t + 1) * kstep;
;             const char* a2 = last ? nA : cA + (size_t)(t + 2) * kstep; const char* b2 = last ? nB : cB + (size_t)(t + 2) * kstep;
	v_mfma_f32_16x16x32_bf16 v[44:47], v[202:205], v[166:169], v[44:47]
	v_mfma_f32_16x16x32_bf16 v[40:43], v[210:213], v[166:169], v[40:43]
	ds_read_b128 v[150:153], v147
	v_mfma_f32_16x16x32_bf16 v[28:31], v[202:205], v[174:177], v[28:31]
	v_mfma_f32_16x16x32_bf16 v[24:27], v[210:213], v[174:177], v[24:27]
	ds_read_b128 v[154:157], v147 offset:1024
	v_mfma_f32_16x16x32_bf16 v[12:15], v[202:205], v[182:185], v[12:15]
	v_mfma_f32_16x16x32_bf16 v[8:11], v[210:213], v[182:185], v[8:11]
	ds_read_b128 v[158:161], v147 offset:2048
	v_mfma_f32_16x16x32_bf16 v[4:7], v[202:205], v[190:193], v[4:7]
	v_mfma_f32_16x16x32_bf16 v[0:3], v[210:213], v[190:193], v[0:3]
	ds_read_b128 v[162:165], v147 offset:3072
	v_mfma_f32_16x16x32_bf16 v[44:47], v[206:209], v[170:173], v[44:47]
	s_add_i32 s3, s3, 2
	v_mfma_f32_16x16x32_bf16 v[40:43], v[214:217], v[170:173], v[40:43]
	s_add_u32 s55, s55, 0x100
	s_addc_u32 s56, s56, 0
	v_mfma_f32_16x16x32_bf16 v[28:31], v[206:209], v[178:181], v[28:31]
	s_add_u32 s18, s18, 0x100
	s_addc_u32 s19, s19, 0
	v_mfma_f32_16x16x32_bf16 v[24:27], v[214:217], v[178:181], v[24:27]
	s_add_u32 s20, s18, 0xfffe0080
	s_addc_u32 s21, s19, -1
	s_cmp_eq_u32 s3, 4
	s_cselect_b32 s23, s13, s21
	s_cselect_b32 s22, s52, s20
	s_cselect_b32 s21, s53, s56
	s_cselect_b32 s20, s54, s55
	s_cmp_gt_u32 s3, 5
	v_mfma_f32_16x16x32_bf16 v[12:15], v[206:209], v[186:189], v[12:15]
	v_mfma_f32_16x16x32_bf16 v[8:11], v[214:217], v[186:189], v[8:11]
	v_mfma_f32_16x16x32_bf16 v[4:7], v[206:209], v[198:201], v[4:7]
	v_mfma_f32_16x16x32_bf16 v[0:3], v[214:217], v[198:201], v[0:3]
	s_barrier
	s_setprio 0
	s_cbranch_scc0 .LBB1_1529
	s_waitcnt lgkmcnt(0)
	s_cmp_lt_i32 s45, 12
	s_cselect_b32 s3, 0, -12
	s_mov_b32 s13, 0x1e510000
	s_movk_i32 s18, 0xc00
	s_cselect_b32 s13, s13, 0x2a510000
	s_cselect_b32 s20, s18, 0x1000
	s_add_i32 s3, s3, s45
	s_add_u32 s18, s6, s13
	v_mov_b32_e32 v150, v144
	v_mov_b32_e32 v151, v145
	s_addc_u32 s19, s7, 0
	s_lshl_b32 s10, s10, 8
	s_lshl_b32 s3, s3, 8
	s_add_i32 s10, s10, s39
	s_or_b32 s3, s3, s42
	v_add_u32_e32 v154, s10, v150
	v_lshl_add_u32 v150, v151, 3, s3
	v_ashrrev_i32_e32 v151, 31, v150
	v_lshl_add_u64 v[150:151], v[150:151], 1, s[18:19]
	v_mad_i64_i32 v[152:153], s[18:19], s20, v154, 0
	v_cvt_pk_bf16_f32 v108, v108, v109
	v_cvt_pk_bf16_f32 v109, v110, v111
	v_cvt_pk_bf16_f32 v110, v104, v105
	v_add_u32_e32 v104, 16, v154
	v_lshl_add_u64 v[152:153], v[152:153], 1, v[150:151]
	v_cvt_pk_bf16_f32 v111, v106, v107
	v_mad_i64_i32 v[104:105], s[18:19], s20, v104, 0
	v_cvt_pk_bf16_f32 v92, v92, v93
	v_cvt_pk_bf16_f32 v93, v94, v95
	v_cvt_pk_bf16_f32 v94, v88, v89
	v_add_u32_e32 v88, 32, v154
	v_cvt_pk_bf16_f32 v124, v124, v125
	v_cvt_pk_bf16_f32 v125, v126, v127
	v_cvt_pk_bf16_f32 v126, v120, v121
	v_cvt_pk_bf16_f32 v127, v122, v123
	global_store_dwordx4 v[152:153], v[108:111], off offset:256
	v_cvt_pk_bf16_f32 v95, v90, v91
	v_mad_i64_i32 v[88:89], s[18:19], s20, v88, 0
	v_lshl_add_u64 v[108:109], v[104:105], 1, v[150:151]
	v_cvt_pk_bf16_f32 v76, v76, v77
	v_cvt_pk_bf16_f32 v77, v78, v79
	v_cvt_pk_bf16_f32 v78, v72, v73
	v_add_u32_e32 v72, 48, v154
	v_cvt_pk_bf16_f32 v68, v68, v69
	v_cvt_pk_bf16_f32 v69, v70, v71
	v_cvt_pk_bf16_f32 v70, v64, v65
	v_add_u32_e32 v64, 0x80, v154
	global_store_dwordx4 v[152:153], v[124:127], off
	v_cvt_pk_bf16_f32 v104, v116, v117
	v_cvt_pk_bf16_f32 v105, v118, v119
	v_cvt_pk_bf16_f32 v106, v112, v113
	v_cvt_pk_bf16_f32 v107, v114, v115
	global_store_dwordx4 v[108:109], v[92:95], off offset:256
	v_cvt_pk_bf16_f32 v79, v74, v75
	v_mad_i64_i32 v[72:73], s[18:19], s20, v72, 0
	v_lshl_add_u64 v[92:93], v[88:89], 1, v[150:151]
	v_mad_i64_i32 v[64:65], s[18:19], s20, v64, 0
	v_cvt_pk_bf16_f32 v44, v44, v45
	v_cvt_pk_bf16_f32 v45, v46, v47
	v_cvt_pk_bf16_f32 v46, v40, v41
	v_add_u32_e32 v40, 0x90, v154
	global_store_dwordx4 v[108:109], v[104:107], off
	v_cvt_pk_bf16_f32 v88, v100, v101
	v_cvt_pk_bf16_f32 v89, v102, v103
	v_cvt_pk_bf16_f32 v90, v96, v97
	v_cvt_pk_bf16_f32 v91, v98, v99
	global_store_dwordx4 v[92:93], v[76:79], off offset:256
	v_cvt_pk_bf16_f32 v74, v80, v81
	v_cvt_pk_bf16_f32 v75, v82, v83
	v_lshl_add_u64 v[76:77], v[72:73], 1, v[150:151]
	v_cvt_pk_bf16_f32 v72, v84, v85
	v_cvt_pk_bf16_f32 v73, v86, v87
	v_cvt_pk_bf16_f32 v71, v66, v67
	v_lshl_add_u64 v[64:65], v[64:65], 1, v[150:151]
	v_cvt_pk_bf16_f32 v47, v42, v43
	v_mad_i64_i32 v[40:41], s[18:19], s20, v40, 0
	v_cvt_pk_bf16_f32 v28, v28, v29
	v_cvt_pk_bf16_f32 v29, v30, v31
	v_cvt_pk_bf16_f32 v30, v24, v25
	v_add_u32_e32 v24, 0xa0, v154
	global_store_dwordx4 v[92:93], v[88:91], off
	global_store_dwordx4 v[76:77], v[72:75], off
	global_store_dwordx4 v[76:77], v[68:71], off offset:256
	v_cvt_pk_bf16_f32 v60, v60, v61
	v_cvt_pk_bf16_f32 v61, v62, v63
	v_cvt_pk_bf16_f32 v62, v56, v57
	v_cvt_pk_bf16_f32 v63, v58, v59
	global_store_dwordx4 v[64:65], v[44:47], off offset:256
	v_cvt_pk_bf16_f32 v31, v26, v27
	v_mad_i64_i32 v[24:25], s[18:19], s20, v24, 0
	v_lshl_add_u64 v[44:45], v[40:41], 1, v[150:151]
	v_cvt_pk_bf16_f32 v12, v12, v13
	v_cvt_pk_bf16_f32 v13, v14, v15
	v_cvt_pk_bf16_f32 v14, v8, v9
	v_add_u32_e32 v8, 0xb0, v154
	global_store_dwordx4 v[64:65], v[60:63], off
	v_cvt_pk_bf16_f32 v40, v52, v53
	v_cvt_pk_bf16_f32 v41, v54, v55
	v_cvt_pk_bf16_f32 v42, v48, v49
	v_cvt_pk_bf16_f32 v43, v50, v51
	global_store_dwordx4 v[44:45], v[28:31], off offset:256
	v_cvt_pk_bf16_f32 v15, v10, v11
	v_mad_i64_i32 v[8:9], s[18:19], s20, v8, 0
	v_lshl_add_u64 v[28:29], v[24:25], 1, v[150:151]
	global_store_dwordx4 v[44:45], v[40:43], off
	v_cvt_pk_bf16_f32 v24, v36, v37
	v_cvt_pk_bf16_f32 v25, v38, v39
	v_cvt_pk_bf16_f32 v26, v32, v33
	v_cvt_pk_bf16_f32 v27, v34, v35
	global_store_dwordx4 v[28:29], v[12:15], off offset:256
	v_cvt_pk_bf16_f32 v10, v16, v17
	v_cvt_pk_bf16_f32 v11, v18, v19
	v_lshl_add_u64 v[12:13], v[8:9], 1, v[150:151]
	v_cvt_pk_bf16_f32 v8, v20, v21
	v_cvt_pk_bf16_f32 v9, v22, v23
	v_cvt_pk_bf16_f32 v4, v4, v5
	v_cvt_pk_bf16_f32 v5, v6, v7
	v_cvt_pk_bf16_f32 v6, v0, v1
	v_cvt_pk_bf16_f32 v7, v2, v3
	s_and_b64 vcc, exec, s[40:41]
	s_mov_b32 s45, s49
	s_mov_b32 s10, s12
	s_mov_b64 s[18:19], s[16:17]
	s_mov_b64 s[20:21], s[14:15]
	global_store_dwordx4 v[28:29], v[24:27], off
	global_store_dwordx4 v[12:13], v[8:11], off
	global_store_dwordx4 v[12:13], v[4:7], off offset:256
	s_cbranch_vccz .LBB1_1526
	s_waitcnt vmcnt(0)
	s_cmpk_gt_u32 s4, 0xff
	s_cbranch_scc1 .LBB1_1533
	s_barrier

;     DI const char* a(const Unit& u) const { return (const char*)(A + (size_t)u.pm * BM * lda); }
;     DI const char* a(const Unit& u) const { return (const char*)(A + (size_t)u.pm * BM * 2048 + (u.pn >> 1) * 512); }
;     DI const char* a(const Unit& u) const { return (const char*)((u.pn < 12 ? A1 : A2) + (size_t)u.pm * BM * 512); }
; #define PG8_STAGE(bufoff, gbase, voff) do { _Pragma("unroll") for (int _i = 0; _i < 2; ++_i) \
;         __builtin_amdgcn_global_load_lds((const unsigned*)((const char*)(gbase) + (voff)[_i]), (LAS unsigned*)(lds + (bufoff) + ldsw + _i * 8192), 16, 0, 0); } while (0)
; #define PG8_LDA(dst, b, h) do { _Pragma("unroll") for (int m = 0; m < 4; ++m) _Pragma("unroll") for (int k = 0; k < 2; ++k) dst[m][k] = *(const LAS bf16x8*)(lds + PG8_SA(b, h) + aoff + m * 2048 + k * 1024); } while (0)
; template <class Map, class Epi>
; DI void gemm_phase(LAS unsigned char* lds, const Map& MP, const Epi& E, const int nM, const int nN, const int K, const int lda, const int ldb) {
;     ...
;         const bool has_next = sched_next(ui + 1, nM, nN, G, cblk, nxt);
;         const char* nA = has_next ? MP.a(nxt) : cA; const char* nB = has_next ? MP.b(nxt) : cB;
;         for (int t = 0; t < nt; t += 2) {
;             const bool last = (t == nt - 2);
;             const char* a1 = cA + (size_t)(t + 1) * kstep;
;             const char* a2 = last ? nA : cA + (size_t)(t + 2) * kstep; const char* b2 = last ? nB : cB + (size_t)(t + 2) * kstep;
;             const char* a3 = a2 + kstep; const char* b3 = b2 + kstep;
;             PG8_LDB(B0, 0, 0); PG8_SCHED; PG8_LDA(At, 0, 0); PG8_STAGE(PG8_SA(1, 1), a1 + hstepA, voffA);
;             PG8_WAIT_L(8); PG8_BAR; PG8_WAIT_L(0); PG8_MMA(0, 0, At, B0); PG8_BAR; PG8_SCHED;
;             PG8_LDB(B1, 0, 1); PG8_STAGE(PG8_SB(0, 0), b2, voffB);
;             PG8_BAR; PG8_WAIT_L(0); PG8_MMA(0, 1, At, B1); PG8_BAR;
;             PG8_LDA(At, 0, 1); PG8_STAGE(PG8_SA(0, 0), a2, voffA);
;             PG8_BAR; PG8_WAIT_L(0); PG8_MMA(1, 0, At, B0); PG8_BAR; PG8_SCHED;
;     ...
; #pragma unroll
;         for (int a = 0; a < 2; ++a)
; #pragma unroll
;             for (int b = 0; b < 2; ++b)
; #pragma unroll
;                 for (int m = 0; m < 4; ++m)
; #pragma unroll
;                     for (int n = 0; n < 2; ++n) acc[a][b][m][n] = (f32x4){0.f, 0.f, 0.f, 0.f};
;         cur = nxt; cA = nA; cB = nB; ++ui;
.LBB1_1763:
	s_ashr_i32 s47, s46, 31
	v_cmp_lt_i64_e32 vcc, s[6:7], v[140:141]
	s_lshl_b64 s[6:7], s[46:47], 20
	s_add_u32 s52, s18, s6
	s_addc_u32 s53, s19, s7
	s_and_b64 s[6:7], vcc, exec
	s_cselect_b32 s37, s53, s13
	s_cselect_b32 s38, s52, s12
	s_ashr_i32 s45, s44, 31
	s_lshl_b64 s[6:7], s[44:45], 20
	s_add_u32 s6, s20, s6
	s_addc_u32 s7, s21, s7
	s_and_b64 s[14:15], vcc, exec
	s_cselect_b32 s39, s7, s11
	s_cselect_b32 s45, s6, s10
	s_add_u32 s47, s10, 0x100
	s_addc_u32 s48, s11, 0
	s_add_u32 s10, s12, 0x80080
	v_mov_b32_e32 v0, 0
	s_addc_u32 s11, s13, 0
	s_mov_b32 s3, -2
	v_mov_b32_e32 v1, 0
	v_mov_b64_e32 v[2:3], 0
	v_mov_b64_e32 v[4:5], 0
	v_mov_b64_e32 v[6:7], 0
	v_mov_b64_e32 v[8:9], 0
	v_mov_b64_e32 v[10:11], 0
	v_mov_b64_e32 v[12:13], 0
	v_mov_b64_e32 v[14:15], 0
	v_mov_b64_e32 v[16:17], 0
	v_mov_b64_e32 v[18:19], 0
	v_mov_b64_e32 v[20:21], 0
	v_mov_b64_e32 v[22:23], 0
	v_mov_b64_e32 v[24:25], 0
	v_mov_b64_e32 v[26:27], 0
	v_mov_b64_e32 v[28:29], 0
	v_mov_b64_e32 v[30:31], 0
	v_mov_b64_e32 v[32:33], 0
	v_mov_b64_e32 v[34:35], 0
	v_mov_b64_e32 v[36:37], 0
	v_mov_b64_e32 v[38:39], 0
	v_mov_b64_e32 v[40:41], 0
	v_mov_b64_e32 v[42:43], 0
	v_mov_b64_e32 v[44:45], 0
	v_mov_b64_e32 v[46:47], 0
	v_mov_b64_e32 v[48:49], 0
	v_mov_b64_e32 v[50:51], 0
	v_mov_b64_e32 v[52:53], 0
	v_mov_b64_e32 v[54:55], 0
	v_mov_b64_e32 v[56:57], 0
	v_mov_b64_e32 v[58:59], 0
	v_mov_b64_e32 v[60:61], 0
	v_mov_b64_e32 v[62:63], 0
	v_mov_b64_e32 v[64:65], 0
	v_mov_b64_e32 v[66:67], 0
	v_mov_b64_e32 v[68:69], 0
	v_mov_b64_e32 v[70:71], 0
	v_mov_b64_e32 v[72:73], 0
	v_mov_b64_e32 v[74:75], 0
	v_mov_b64_e32 v[76:77], 0
	v_mov_b64_e32 v[78:79], 0
	v_mov_b64_e32 v[80:81], 0
	v_mov_b64_e32 v[82:83], 0
	v_mov_b64_e32 v[84:85], 0
	v_mov_b64_e32 v[86:87], 0
	v_mov_b64_e32 v[88:89], 0
	v_mov_b64_e32 v[90:91], 0
	v_mov_b64_e32 v[92:93], 0
	v_mov_b64_e32 v[94:95], 0
	v_mov_b64_e32 v[96:97], 0
	v_mov_b64_e32 v[98:99], 0
	v_mov_b64_e32 v[100:101], 0
	v_mov_b64_e32 v[102:103], 0
	v_mov_b64_e32 v[104:105], 0
	v_mov_b64_e32 v[106:107], 0
	v_mov_b64_e32 v[108:109], 0
	v_mov_b64_e32 v[110:111], 0
	v_mov_b64_e32 v[112:113], 0
	v_mov_b64_e32 v[114:115], 0
	v_mov_b64_e32 v[116:117], 0
	v_mov_b64_e32 v[118:119], 0
	v_mov_b64_e32 v[120:121], 0
	v_mov_b64_e32 v[122:123], 0
	v_mov_b64_e32 v[124:125], 0
	v_mov_b64_e32 v[126:127], 0
	ds_read_b128 v[152:155], v149
	ds_read_b128 v[156:159], v149 offset:1024
	ds_read_b128 v[160:163], v149 offset:2048
	ds_read_b128 v[164:167], v149 offset:3072
	s_add_u32 s12, s10, 0xfff80080
	s_addc_u32 s13, s11, -1
	s_cmp_eq_u32 s3, 28
	s_cselect_b32 s15, s37, s13
	s_cselect_b32 s14, s38, s12
	s_cselect_b32 s13, s39, s48
	s_cselect_b32 s12, s45, s47
.LBB1_1764:
	s_add_i32 m0, s24, 0xc000
	ds_read_b128 v[168:171], v150
	ds_read_b128 v[172:175], v150 offset:1024
	ds_read_b128 v[176:179], v150 offset:2048
	ds_read_b128 v[180:183], v150 offset:3072
	ds_read_b128 v[184:187], v150 offset:4096
	ds_read_b128 v[188:191], v150 offset:5120
	ds_read_b128 v[192:195], v150 offset:6144
	ds_read_b128 v[198:201], v150 offset:7168
	global_load_lds_dwordx4 v138, s[10:11]
	s_add_i32 m0, s24, 0xe000
	s_nop 0
	global_load_lds_dwordx4 v136, s[10:11]
	s_waitcnt lgkmcnt(8)
	s_setprio 1
	s_barrier
	s_waitcnt lgkmcnt(7)
	v_mfma_f32_16x16x32_bf16 v[124:127], v[152:155], v[168:171], v[124:127]
	v_mfma_f32_16x16x32_bf16 v[120:123], v[160:163], v[168:171], v[120:123]
	s_waitcnt lgkmcnt(5)
	v_mfma_f32_16x16x32_bf16 v[108:111], v[152:155], v[176:179], v[108:111]
	v_mfma_f32_16x16x32_bf16 v[104:107], v[160:163], v[176:179], v[104:107]
	s_waitcnt lgkmcnt(3)
	v_mfma_f32_16x16x32_bf16 v[92:95], v[152:155], v[184:187], v[92:95]
	v_mfma_f32_16x16x32_bf16 v[88:91], v[160:163], v[184:187], v[88:91]
	s_waitcnt lgkmcnt(1)
	v_mfma_f32_16x16x32_bf16 v[76:79], v[152:155], v[192:195], v[76:79]
	v_mfma_f32_16x16x32_bf16 v[72:75], v[160:163], v[192:195], v[72:75]
	v_mfma_f32_16x16x32_bf16 v[124:127], v[156:159], v[172:175], v[124:127]
	s_add_i32 s49, s35, s22
	v_mfma_f32_16x16x32_bf16 v[120:123], v[164:167], v[172:175], v[120:123]
	v_lshl_add_u64 v[144:145], s[12:13], 0, v[132:133]
	v_mfma_f32_16x16x32_bf16 v[108:111], v[156:159], v[180:183], v[108:111]
	v_lshl_add_u64 v[218:219], s[12:13], 0, v[128:129]
	v_mfma_f32_16x16x32_bf16 v[104:107], v[164:167], v[180:183], v[104:107]
	v_mfma_f32_16x16x32_bf16 v[92:95], v[156:159], v[188:191], v[92:95]
	v_mfma_f32_16x16x32_bf16 v[88:91], v[164:167], v[188:191], v[88:91]
	s_waitcnt lgkmcnt(0)
	v_mfma_f32_16x16x32_bf16 v[76:79], v[156:159], v[198:201], v[76:79]
	v_mfma_f32_16x16x32_bf16 v[72:75], v[164:167], v[198:201], v[72:75]
	s_barrier
	s_setprio 0
	s_mov_b32 m0, s49
	ds_read_b128 v[202:205], v151
	ds_read_b128 v[206:209], v151 offset:1024
	ds_read_b128 v[210:213], v151 offset:2048
	ds_read_b128 v[214:217], v151 offset:3072
	global_load_lds_dwordx4 v[144:145], off
	s_add_i32 m0, s49, 0x2000
	s_nop 0
	global_load_lds_dwordx4 v[218:219], off
	s_setprio 1
	s_barrier
	s_waitcnt lgkmcnt(3)
	v_mfma_f32_16x16x32_bf16 v[116:119], v[202:205], v[168:171], v[116:119]
	s_waitcnt lgkmcnt(1)
	v_mfma_f32_16x16x32_bf16 v[112:115], v[210:213], v[168:171], v[112:115]
	v_mfma_f32_16x16x32_bf16 v[100:103], v[202:205], v[176:179], v[100:103]
	v_mfma_f32_16x16x32_bf16 v[96:99], v[210:213], v[176:179], v[96:99]
	v_mfma_f32_16x16x32_bf16 v[84:87], v[202:205], v[184:187], v[84:87]
	v_mfma_f32_16x16x32_bf16 v[80:83], v[210:213], v[184:187], v[80:83]
	v_mfma_f32_16x16x32_bf16 v[68:71], v[202:205], v[192:195], v[68:71]
	v_mfma_f32_16x16x32_bf16 v[64:67], v[210:213], v[192:195], v[64:67]
	v_mfma_f32_16x16x32_bf16 v[116:119], v[206:209], v[172:175], v[116:119]
	v_lshl_add_u64 v[222:223], s[14:15], 0, v[130:131]
	s_mov_b32 m0, s24
	s_waitcnt lgkmcnt(0)
	v_mfma_f32_16x16x32_bf16 v[112:115], v[214:217], v[172:175], v[112:115]
	v_lshl_add_u64 v[220:221], s[14:15], 0, v[134:135]
	v_mfma_f32_16x16x32_bf16 v[100:103], v[206:209], v[180:183], v[100:103]
	v_mfma_f32_16x16x32_bf16 v[96:99], v[214:217], v[180:183], v[96:99]
	v_mfma_f32_16x16x32_bf16 v[84:87], v[206:209], v[188:191], v[84:87]
	v_mfma_f32_16x16x32_bf16 v[80:83], v[214:217], v[188:191], v[80:83]
	v_mfma_f32_16x16x32_bf16 v[68:71], v[206:209], v[198:201], v[68:71]
	v_mfma_f32_16x16x32_bf16 v[64:67], v[214:217], v[198:201], v[64:67]
	s_barrier
; #define PG8_STAGE(bufoff, gbase, voff) do { _Pragma("unroll") for (int _i = 0; _i < 2; ++_i) \
;         __builtin_amdgcn_global_load_lds((const unsigned*)((const char*)(gbase) + (voff)[_i]), (LAS unsigned*)(lds + (bufoff) + ldsw + _i * 8192), 16, 0, 0); } while (0)
; #define PG8_LDA(dst, b, h) do { _Pragma("unroll") for (int m = 0; m < 4; ++m) _Pragma("unroll") for (int k = 0; k < 2; ++k) dst[m][k] = *(const LAS bf16x8*)(lds + PG8_SA(b, h) + aoff + m * 2048 + k * 1024); } while (0)
; #define PG8_LDB(dst, b, h) do { _Pragma("unroll") for (int n = 0; n < 2; ++n) _Pragma("unroll") for (int k = 0; k < 2; ++k) dst[n][k] = *(const LAS bf16x8*)(lds + PG8_SB(b, h) + boff + n * 2048 + k * 1024); } while (0)
; #define PG8_MMA(ai, bj, At, Bt) do { __builtin_amdgcn_s_setprio(1); _Pragma("unroll") for (int m = 0; m < 4; ++m) _Pragma("unroll") for (int n = 0; n < 2; ++n) _Pragma("unroll") for (int k = 0; k < 2; ++k) \
;         acc[ai][bj][m][n] = __builtin_amdgcn_mfma_f32_16x16x32_bf16(Bt[n][k], At[m][k], acc[ai][bj][m][n], 0, 0, 0); __builtin_amdgcn_s_setprio(0); } while (0)
; #define PG8_WAIT_V(n) asm volatile("s_waitcnt vmcnt(" #n ")" ::: "memory")
; #define PG8_WAIT_L(n) asm volatile("s_waitcnt lgkmcnt(" #n ")" ::: "memory")
; #define PG8_BAR __builtin_amdgcn_s_barrier()
; #define PG8_SCHED __builtin_amdgcn_sched_barrier(0)
; template <class Map, class Epi>
; DI void gemm_phase(LAS unsigned char* lds, const Map& MP, const Epi& E, const int nM, const int nN, const int K, const int lda, const int ldb) {
;     ...
;             PG8_BAR; PG8_WAIT_L(0); PG8_MMA(1, 0, At, B0); PG8_BAR; PG8_SCHED;
;             PG8_STAGE(PG8_SB(0, 1), b2 + hstepB, voffB);
;             PG8_WAIT_V(6); PG8_BAR; PG8_MMA(1, 1, At, B1); PG8_BAR;
;             PG8_LDB(B0, 1, 0); PG8_SCHED; PG8_LDA(At, 1, 0); PG8_STAGE(PG8_SA(0, 1), a2 + hstepA, voffA);
;             PG8_WAIT_L(8); PG8_BAR; PG8_WAIT_L(0); PG8_MMA(0, 0, At, B0); PG8_BAR; PG8_SCHED;
;             PG8_LDB(B1, 1, 1); PG8_STAGE(PG8_SB(1, 0), b3, voffB);
;             PG8_BAR; PG8_WAIT_L(0); PG8_MMA(0, 1, At, B1); PG8_BAR;
;             PG8_LDA(At, 1, 1); PG8_STAGE(PG8_SA(1, 0), a3, voffA);
;             PG8_BAR; PG8_WAIT_L(0); PG8_MMA(1, 0, At, B0); PG8_BAR; PG8_SCHED;
	s_setprio 0
	ds_read_b128 v[168:171], v150 offset:16384
	ds_read_b128 v[172:175], v150 offset:17408
	ds_read_b128 v[176:179], v150 offset:18432
	ds_read_b128 v[180:183], v150 offset:19456
	ds_read_b128 v[184:187], v150 offset:20480
	ds_read_b128 v[188:191], v150 offset:21504
	ds_read_b128 v[192:195], v150 offset:22528
	ds_read_b128 v[198:201], v150 offset:23552
	global_load_lds_dwordx4 v[220:221], off
	s_mov_b32 m0, s9
	s_nop 0
	global_load_lds_dwordx4 v[222:223], off
	s_waitcnt vmcnt(10)
	s_setprio 1
	s_barrier
	s_waitcnt lgkmcnt(7)
	v_mfma_f32_16x16x32_bf16 v[60:63], v[152:155], v[168:171], v[60:63]
	v_mfma_f32_16x16x32_bf16 v[56:59], v[160:163], v[168:171], v[56:59]
	s_waitcnt lgkmcnt(5)
	v_mfma_f32_16x16x32_bf16 v[44:47], v[152:155], v[176:179], v[44:47]
	v_mfma_f32_16x16x32_bf16 v[40:43], v[160:163], v[176:179], v[40:43]
	s_waitcnt lgkmcnt(3)
	v_mfma_f32_16x16x32_bf16 v[28:31], v[152:155], v[184:187], v[28:31]
	v_mfma_f32_16x16x32_bf16 v[24:27], v[160:163], v[184:187], v[24:27]
	s_waitcnt lgkmcnt(1)
	v_mfma_f32_16x16x32_bf16 v[12:15], v[152:155], v[192:195], v[12:15]
	v_mfma_f32_16x16x32_bf16 v[8:11], v[160:163], v[192:195], v[8:11]
	v_mfma_f32_16x16x32_bf16 v[60:63], v[156:159], v[172:175], v[60:63]
	s_add_u32 s54, s12, 0x80000
	s_addc_u32 s55, s13, 0
	v_mfma_f32_16x16x32_bf16 v[56:59], v[164:167], v[172:175], v[56:59]
	s_add_i32 s49, s36, s22
	v_mfma_f32_16x16x32_bf16 v[44:47], v[156:159], v[180:183], v[44:47]
	v_mfma_f32_16x16x32_bf16 v[40:43], v[164:167], v[180:183], v[40:43]
	v_mfma_f32_16x16x32_bf16 v[28:31], v[156:159], v[188:191], v[28:31]
	v_mfma_f32_16x16x32_bf16 v[24:27], v[164:167], v[188:191], v[24:27]
	s_waitcnt lgkmcnt(0)
	v_mfma_f32_16x16x32_bf16 v[12:15], v[156:159], v[198:201], v[12:15]
	v_mfma_f32_16x16x32_bf16 v[8:11], v[164:167], v[198:201], v[8:11]
	s_barrier
	s_setprio 0
	s_mov_b32 m0, s49
	s_nop 0
	global_load_lds_dwordx4 v132, s[54:55]
	s_add_i32 m0, s49, 0x2000
	s_nop 0
	global_load_lds_dwordx4 v128, s[54:55]
	s_waitcnt vmcnt(6)
	s_setprio 1
	s_barrier
	v_mfma_f32_16x16x32_bf16 v[52:55], v[202:205], v[168:171], v[52:55]
	v_mfma_f32_16x16x32_bf16 v[48:51], v[210:213], v[168:171], v[48:51]
	s_add_i32 s49, 0, 0x18000
	v_add_u32_e32 v164, s49, v148
	ds_read_b128 v[152:155], v164
	v_mfma_f32_16x16x32_bf16 v[36:39], v[202:205], v[176:179], v[36:39]
	v_mfma_f32_16x16x32_bf16 v[32:35], v[210:213], v[176:179], v[32:35]
	ds_read_b128 v[156:159], v164 offset:1024
	v_mfma_f32_16x16x32_bf16 v[20:23], v[202:205], v[184:187], v[20:23]
	v_mfma_f32_16x16x32_bf16 v[16:19], v[210:213], v[184:187], v[16:19]
	ds_read_b128 v[160:163], v164 offset:2048
	v_mfma_f32_16x16x32_bf16 v[4:7], v[202:205], v[192:195], v[4:7]
	v_mfma_f32_16x16x32_bf16 v[0:3], v[210:213], v[192:195], v[0:3]
	ds_read_b128 v[164:167], v164 offset:3072
	v_mfma_f32_16x16x32_bf16 v[52:55], v[206:209], v[172:175], v[52:55]
	s_add_u32 s14, s14, 0x80000
	s_addc_u32 s15, s15, 0
	v_mfma_f32_16x16x32_bf16 v[48:51], v[214:217], v[172:175], v[48:51]
	v_mfma_f32_16x16x32_bf16 v[36:39], v[206:209], v[180:183], v[36:39]
	v_mfma_f32_16x16x32_bf16 v[32:35], v[214:217], v[180:183], v[32:35]
	v_mfma_f32_16x16x32_bf16 v[20:23], v[206:209], v[188:191], v[20:23]
	v_mfma_f32_16x16x32_bf16 v[16:19], v[214:217], v[188:191], v[16:19]
	v_mfma_f32_16x16x32_bf16 v[4:7], v[206:209], v[198:201], v[4:7]
	v_mfma_f32_16x16x32_bf16 v[0:3], v[214:217], v[198:201], v[0:3]
	s_barrier
	s_setprio 0
	s_mov_b32 m0, s25
	ds_read_b128 v[168:171], v150 offset:32768
	ds_read_b128 v[172:175], v150 offset:33792
	ds_read_b128 v[176:179], v150 offset:34816
	ds_read_b128 v[180:183], v150 offset:35840
	ds_read_b128 v[184:187], v150 offset:36864
	ds_read_b128 v[188:191], v150 offset:37888
	ds_read_b128 v[192:195], v150 offset:38912
	ds_read_b128 v[198:201], v150 offset:39936
	global_load_lds_dwordx4 v134, s[14:15]
	s_mov_b32 m0, s26
	s_nop 0
	global_load_lds_dwordx4 v130, s[14:15]
	s_waitcnt lgkmcnt(8)
	s_setprio 1
	s_barrier
	s_waitcnt lgkmcnt(7)
	v_mfma_f32_16x16x32_bf16 v[124:127], v[152:155], v[168:171], v[124:127]
	v_mfma_f32_16x16x32_bf16 v[120:123], v[160:163], v[168:171], v[120:123]
	s_waitcnt lgkmcnt(5)
	v_mfma_f32_16x16x32_bf16 v[108:111], v[152:155], v[176:179], v[108:111]
	v_mfma_f32_16x16x32_bf16 v[104:107], v[160:163], v[176:179], v[104:107]
	s_waitcnt lgkmcnt(3)
	v_mfma_f32_16x16x32_bf16 v[92:95], v[152:155], v[184:187], v[92:95]
	v_mfma_f32_16x16x32_bf16 v[88:91], v[160:163], v[184:187], v[88:91]
	s_waitcnt lgkmcnt(1)
	v_mfma_f32_16x16x32_bf16 v[76:79], v[152:155], v[192:195], v[76:79]
	v_mfma_f32_16x16x32_bf16 v[72:75], v[160:163], v[192:195], v[72:75]
	v_mfma_f32_16x16x32_bf16 v[124:127], v[156:159], v[172:175], v[124:127]
	s_add_i32 s14, 0, 0x1c000
	v_mfma_f32_16x16x32_bf16 v[120:123], v[164:167], v[172:175], v[120:123]
	s_add_i32 s15, s49, s22
	v_mfma_f32_16x16x32_bf16 v[108:111], v[156:159], v[180:183], v[108:111]
	v_add_u32_e32 v196, s14, v148
	v_mfma_f32_16x16x32_bf16 v[104:107], v[164:167], v[180:183], v[104:107]
	v_lshl_add_u64 v[144:145], v[144:145], 0, s[42:43]
	v_mfma_f32_16x16x32_bf16 v[92:95], v[156:159], v[188:191], v[92:95]
	v_mfma_f32_16x16x32_bf16 v[88:91], v[164:167], v[188:191], v[88:91]
	s_waitcnt lgkmcnt(0)
	v_mfma_f32_16x16x32_bf16 v[76:79], v[156:159], v[198:201], v[76:79]
	v_mfma_f32_16x16x32_bf16 v[72:75], v[164:167], v[198:201], v[72:75]
	s_barrier
	s_setprio 0
	s_mov_b32 m0, s15
	ds_read_b128 v[202:205], v196
	ds_read_b128 v[206:209], v196 offset:1024
	ds_read_b128 v[210:213], v196 offset:2048
	ds_read_b128 v[214:217], v196 offset:3072
	global_load_lds_dwordx4 v[144:145], off
	v_lshl_add_u64 v[144:145], v[218:219], 0, s[42:43]
	s_add_i32 m0, s15, 0x2000
	s_nop 0
	global_load_lds_dwordx4 v[144:145], off
	s_setprio 1
	s_barrier
; #define PG8_STAGE(bufoff, gbase, voff) do { _Pragma("unroll") for (int _i = 0; _i < 2; ++_i) \
;         __builtin_amdgcn_global_load_lds((const unsigned*)((const char*)(gbase) + (voff)[_i]), (LAS unsigned*)(lds + (bufoff) + ldsw + _i * 8192), 16, 0, 0); } while (0)
; #define PG8_LDA(dst, b, h) do { _Pragma("unroll") for (int m = 0; m < 4; ++m) _Pragma("unroll") for (int k = 0; k < 2; ++k) dst[m][k] = *(const LAS bf16x8*)(lds + PG8_SA(b, h) + aoff + m * 2048 + k * 1024); } while (0)
; #define PG8_MMA(ai, bj, At, Bt) do { __builtin_amdgcn_s_setprio(1); _Pragma("unroll") for (int m = 0; m < 4; ++m) _Pragma("unroll") for (int n = 0; n < 2; ++n) _Pragma("unroll") for (int k = 0; k < 2; ++k) \
;         acc[ai][bj][m][n] = __builtin_amdgcn_mfma_f32_16x16x32_bf16(Bt[n][k], At[m][k], acc[ai][bj][m][n], 0, 0, 0); __builtin_amdgcn_s_setprio(0); } while (0)
; #define PG8_WAIT_V(n) asm volatile("s_waitcnt vmcnt(" #n ")" ::: "memory")
; #define PG8_WAIT_L(n) asm volatile("s_waitcnt lgkmcnt(" #n ")" ::: "memory")
; #define PG8_BAR __builtin_amdgcn_s_barrier()
; #define PG8_SCHED __builtin_amdgcn_sched_barrier(0)
; template <class Map, class Epi>
; DI void gemm_phase(LAS unsigned char* lds, const Map& MP, const Epi& E, const int nM, const int nN, const int K, const int lda, const int ldb) {
;     ...
;             const bool last = (t == nt - 2);
;             const char* a1 = cA + (size_t)(t + 1) * kstep;
;             const char* a2 = last ? nA : cA + (size_t)(t + 2) * kstep; const char* b2 = last ? nB : cB + (size_t)(t + 2) * kstep;
;     ...
;             PG8_LDA(At, 1, 1); PG8_STAGE(PG8_SA(1, 0), a3, voffA);
;             PG8_BAR; PG8_WAIT_L(0); PG8_MMA(1, 0, At, B0); PG8_BAR; PG8_SCHED;
;             PG8_STAGE(PG8_SB(1, 1), b3 + hstepB, voffB);
;             PG8_WAIT_V(6); PG8_BAR; PG8_MMA(1, 1, At, B1); PG8_BAR;
	s_waitcnt lgkmcnt(3)
	v_mfma_f32_16x16x32_bf16 v[116:119], v[202:205], v[168:171], v[116:119]
	s_waitcnt lgkmcnt(1)
	v_mfma_f32_16x16x32_bf16 v[112:115], v[210:213], v[168:171], v[112:115]
	v_mfma_f32_16x16x32_bf16 v[100:103], v[202:205], v[176:179], v[100:103]
	v_mfma_f32_16x16x32_bf16 v[96:99], v[210:213], v[176:179], v[96:99]
	v_mfma_f32_16x16x32_bf16 v[84:87], v[202:205], v[184:187], v[84:87]
	v_mfma_f32_16x16x32_bf16 v[80:83], v[210:213], v[184:187], v[80:83]
	v_mfma_f32_16x16x32_bf16 v[68:71], v[202:205], v[192:195], v[68:71]
	v_mfma_f32_16x16x32_bf16 v[64:67], v[210:213], v[192:195], v[64:67]
	v_mfma_f32_16x16x32_bf16 v[116:119], v[206:209], v[172:175], v[116:119]
	s_mov_b32 m0, s30
	s_waitcnt lgkmcnt(0)
	v_mfma_f32_16x16x32_bf16 v[112:115], v[214:217], v[172:175], v[112:115]
	v_lshl_add_u64 v[144:145], v[220:221], 0, s[42:43]
	v_mfma_f32_16x16x32_bf16 v[100:103], v[206:209], v[180:183], v[100:103]
	v_mfma_f32_16x16x32_bf16 v[96:99], v[214:217], v[180:183], v[96:99]
	v_mfma_f32_16x16x32_bf16 v[84:87], v[206:209], v[188:191], v[84:87]
	v_mfma_f32_16x16x32_bf16 v[80:83], v[214:217], v[188:191], v[80:83]
	v_mfma_f32_16x16x32_bf16 v[68:71], v[206:209], v[198:201], v[68:71]
	v_mfma_f32_16x16x32_bf16 v[64:67], v[214:217], v[198:201], v[64:67]
	s_barrier
	s_setprio 0
	ds_read_b128 v[168:171], v150 offset:49152
	ds_read_b128 v[172:175], v150 offset:50176
	ds_read_b128 v[176:179], v150 offset:51200
	ds_read_b128 v[180:183], v150 offset:52224
	ds_read_b128 v[184:187], v150 offset:53248
	ds_read_b128 v[188:191], v150 offset:54272
	ds_read_b128 v[192:195], v150 offset:55296
	ds_read_b128 v[198:201], v150 offset:56320
	global_load_lds_dwordx4 v[144:145], off
	v_lshl_add_u64 v[144:145], v[222:223], 0, s[42:43]
	s_mov_b32 m0, s31
	s_nop 0
	global_load_lds_dwordx4 v[144:145], off
	s_waitcnt vmcnt(10)
	s_setprio 1
	s_barrier
	s_waitcnt lgkmcnt(7)
	v_mfma_f32_16x16x32_bf16 v[60:63], v[152:155], v[168:171], v[60:63]
	v_mfma_f32_16x16x32_bf16 v[56:59], v[160:163], v[168:171], v[56:59]
	s_waitcnt lgkmcnt(5)
	v_mfma_f32_16x16x32_bf16 v[44:47], v[152:155], v[176:179], v[44:47]
	v_mfma_f32_16x16x32_bf16 v[40:43], v[160:163], v[176:179], v[40:43]
	s_waitcnt lgkmcnt(3)
	v_mfma_f32_16x16x32_bf16 v[28:31], v[152:155], v[184:187], v[28:31]
	v_mfma_f32_16x16x32_bf16 v[24:27], v[160:163], v[184:187], v[24:27]
	s_waitcnt lgkmcnt(1)
	v_mfma_f32_16x16x32_bf16 v[12:15], v[152:155], v[192:195], v[12:15]
	v_mfma_f32_16x16x32_bf16 v[8:11], v[160:163], v[192:195], v[8:11]
	v_mfma_f32_16x16x32_bf16 v[60:63], v[156:159], v[172:175], v[60:63]
	s_add_u32 s12, s12, 0x80080
	s_addc_u32 s13, s13, 0
	v_mfma_f32_16x16x32_bf16 v[56:59], v[164:167], v[172:175], v[56:59]
	s_add_i32 s14, s14, s22
	v_mfma_f32_16x16x32_bf16 v[44:47], v[156:159], v[180:183], v[44:47]
	v_mfma_f32_16x16x32_bf16 v[40:43], v[164:167], v[180:183], v[40:43]
	v_mfma_f32_16x16x32_bf16 v[28:31], v[156:159], v[188:191], v[28:31]
	v_mfma_f32_16x16x32_bf16 v[24:27], v[164:167], v[188:191], v[24:27]
	s_waitcnt lgkmcnt(0)
	v_mfma_f32_16x16x32_bf16 v[12:15], v[156:159], v[198:201], v[12:15]
	v_mfma_f32_16x16x32_bf16 v[8:11], v[164:167], v[198:201], v[8:11]
	s_barrier
	s_setprio 0
	s_mov_b32 m0, s14
	s_nop 0
	global_load_lds_dwordx4 v132, s[12:13]
	s_add_i32 m0, s14, 0x2000
	s_nop 0
	global_load_lds_dwordx4 v128, s[12:13]
	s_waitcnt vmcnt(6)
	s_setprio 1
	s_barrier
	v_mfma_f32_16x16x32_bf16 v[52:55], v[202:205], v[168:171], v[52:55]
	v_mfma_f32_16x16x32_bf16 v[48:51], v[210:213], v[168:171], v[48:51]
	ds_read_b128 v[152:155], v149
	v_mfma_f32_16x16x32_bf16 v[36:39], v[202:205], v[176:179], v[36:39]
	v_mfma_f32_16x16x32_bf16 v[32:35], v[210:213], v[176:179], v[32:35]
	ds_read_b128 v[156:159], v149 offset:1024
	v_mfma_f32_16x16x32_bf16 v[20:23], v[202:205], v[184:187], v[20:23]
	v_mfma_f32_16x16x32_bf16 v[16:19], v[210:213], v[184:187], v[16:19]
	ds_read_b128 v[160:163], v149 offset:2048
	v_mfma_f32_16x16x32_bf16 v[4:7], v[202:205], v[192:195], v[4:7]
	v_mfma_f32_16x16x32_bf16 v[0:3], v[210:213], v[192:195], v[0:3]
	ds_read_b128 v[164:167], v149 offset:3072
	v_mfma_f32_16x16x32_bf16 v[52:55], v[206:209], v[172:175], v[52:55]
	s_add_i32 s3, s3, 2
	v_mfma_f32_16x16x32_bf16 v[48:51], v[214:217], v[172:175], v[48:51]
	s_add_u32 s47, s47, 0x100
	s_addc_u32 s48, s48, 0
	v_mfma_f32_16x16x32_bf16 v[36:39], v[206:209], v[180:183], v[36:39]
	s_add_u32 s10, s10, 0x100
	s_addc_u32 s11, s11, 0
	v_mfma_f32_16x16x32_bf16 v[32:35], v[214:217], v[180:183], v[32:35]
	s_add_u32 s12, s10, 0xfff80080
	s_addc_u32 s13, s11, -1
	s_cmp_eq_u32 s3, 28
	s_cselect_b32 s15, s37, s13
	s_cselect_b32 s14, s38, s12
	s_cselect_b32 s13, s39, s48
	s_cselect_b32 s12, s45, s47
	s_cmp_gt_u32 s3, 29
	v_mfma_f32_16x16x32_bf16 v[20:23], v[206:209], v[188:191], v[20:23]
	v_mfma_f32_16x16x32_bf16 v[16:19], v[214:217], v[188:191], v[16:19]
	v_mfma_f32_16x16x32_bf16 v[4:7], v[206:209], v[198:201], v[4:7]
	v_mfma_f32_16x16x32_bf16 v[0:3], v[214:217], v[198:201], v[0:3]
	s_barrier
	s_setprio 0
	s_cbranch_scc0 .LBB1_1764
; DI unsigned pack2(float a, float b) { f32x2 v = {a, b}; hwbf16x2 r = __builtin_convertvector(v, hwbf16x2); return __builtin_bit_cast(unsigned, r); }
; DI float bflo(unsigned w) { return __uint_as_float(w << 16); }
; DI float bfhi(unsigned w) { return __uint_as_float(w & 0xffff0000u); }
;     DI void operator()(const f32x4 (&acc)[2][2][4][2], const Unit& u, int wr, int wc, int fr, int fq) const {
;     ...
;         for (int ai = 0; ai < 2; ++ai)
; #pragma unroll
;             for (int m = 0; m < 4; ++m) { const size_t ro = (size_t)(row0 + ai * HALF + m * 16) * D + col0;
; #pragma unroll
;                 for (int bj = 0; bj < 2; ++bj) {
;                     f32x4 x0, x1;
;                     if constexpr (IB) { const u32x4 w = *(const u32x4*)((const bf16_t*)Xin + ro + bj * HALF);
;                         x0 = (f32x4){bflo(w[0]), bfhi(w[0]), bflo(w[1]), bfhi(w[1])}; x1 = (f32x4){bflo(w[2]), bfhi(w[2]), bflo(w[3]), bfhi(w[3])}; }
;                     else { x0 = *(const f32x4*)((const float*)Xin + ro + bj * HALF); x1 = *(const f32x4*)((const float*)Xin + ro + bj * HALF + 4); }
;                     x0 += acc[ai][bj][m][0] * sc[bj][0]; x1 += acc[ai][bj][m][1] * sc[bj][1];
;                     if constexpr (OB) { u32x4 o; o[0] = pack2(x0[0], x0[1]); o[1] = pack2(x0[2], x0[3]); o[2] = pack2(x1[0], x1[1]); o[3] = pack2(x1[2], x1[3]);
;                         *(u32x4*)((bf16_t*)Xout + ro + bj * HALF) = o; }
;                     else { *(f32x4*)((float*)Xout + ro + bj * HALF) = x0; *(f32x4*)((float*)Xout + ro + bj * HALF + 4) = x1; } } }
	s_waitcnt lgkmcnt(0)
	v_mov_b32_e32 v152, v147
	v_mov_b32_e32 v144, v146
	s_lshl_b32 s2, s2, 8
	s_or_b32 s2, s2, s29
	v_lshl_add_u32 v144, v144, 3, s2
	s_lshl_b32 s2, s8, 8
	s_add_i32 s2, s2, s28
	v_add_u32_e32 v152, s2, v152
	v_ashrrev_i32_e32 v153, 31, v152
	v_lshlrev_b64 v[152:153], 12, v[152:153]
	v_ashrrev_i32_e32 v145, 31, v144
	v_lshl_add_u64 v[152:153], s[4:5], 0, v[152:153]
	v_lshl_add_u64 v[144:145], v[144:145], 1, v[152:153]
	global_load_dwordx4 v[160:163], v[144:145], off
	global_load_dwordx4 v[164:167], v[144:145], off offset:256
	s_mov_b64 s[98:99], 0x10000
	v_lshl_add_u64 v[154:155], v[144:145], 0, s[98:99]
	global_load_dwordx4 v[168:171], v[154:155], off
	global_load_dwordx4 v[172:175], v[154:155], off offset:256
	s_mov_b64 s[98:99], 0x20000
	v_lshl_add_u64 v[154:155], v[144:145], 0, s[98:99]
	global_load_dwordx4 v[176:179], v[154:155], off
	global_load_dwordx4 v[180:183], v[154:155], off offset:256
	s_mov_b64 s[98:99], 0x30000
	v_lshl_add_u64 v[154:155], v[144:145], 0, s[98:99]
	global_load_dwordx4 v[184:187], v[154:155], off
	global_load_dwordx4 v[188:191], v[154:155], off offset:256
	s_mov_b64 s[98:99], 0x80000
	v_lshl_add_u64 v[154:155], v[144:145], 0, s[98:99]
	global_load_dwordx4 v[192:195], v[154:155], off
	global_load_dwordx4 v[198:201], v[154:155], off offset:256
	s_mov_b64 s[98:99], 0x90000
	v_lshl_add_u64 v[154:155], v[144:145], 0, s[98:99]
	global_load_dwordx4 v[202:205], v[154:155], off
	global_load_dwordx4 v[206:209], v[154:155], off offset:256
	s_mov_b64 s[98:99], 0xa0000
	v_lshl_add_u64 v[154:155], v[144:145], 0, s[98:99]
	global_load_dwordx4 v[210:213], v[154:155], off
	global_load_dwordx4 v[214:217], v[154:155], off offset:256
	s_mov_b64 s[98:99], 0xb0000
	v_lshl_add_u64 v[154:155], v[144:145], 0, s[98:99]
	global_load_dwordx4 v[248:251], v[154:155], off
	global_load_dwordx4 v[252:255], v[154:155], off offset:256
	s_waitcnt vmcnt(15)
	s_nop 1
	v_mov_b32_e32 v152, v160
	v_mov_b32_e32 v153, v161
	v_mov_b32_e32 v154, v162
	v_mov_b32_e32 v155, v163
	s_mov_b64 s[2:3], 0x10000
	s_mov_b32 s8, s46
	s_mov_b64 s[10:11], s[6:7]
	s_mov_b64 s[12:13], s[52:53]
	s_waitcnt lgkmcnt(0)
	v_lshlrev_b32_e32 v156, 16, v152
	v_and_b32_e32 v157, 0xffff0000, v152
	v_lshlrev_b32_e32 v152, 16, v153
	v_and_b32_e32 v153, 0xffff0000, v153
	v_lshlrev_b32_e32 v158, 16, v154
	v_and_b32_e32 v159, 0xffff0000, v154
	v_lshlrev_b32_e32 v154, 16, v155
	v_and_b32_e32 v155, 0xffff0000, v155
	v_pk_add_f32 v[126:127], v[126:127], v[152:153]
	v_pk_add_f32 v[124:125], v[124:125], v[156:157]
	v_pk_add_f32 v[152:153], v[122:123], v[154:155]
	v_pk_add_f32 v[122:123], v[120:121], v[158:159]
	v_cvt_pk_bf16_f32 v120, v124, v125
	v_cvt_pk_bf16_f32 v121, v126, v127
	v_cvt_pk_bf16_f32 v122, v122, v123
	v_cvt_pk_bf16_f32 v123, v152, v153
	global_store_dwordx4 v[144:145], v[120:123], off
	s_waitcnt vmcnt(15)
	s_nop 1
	v_mov_b32_e32 v120, v164
	v_mov_b32_e32 v121, v165
	v_mov_b32_e32 v122, v166
	v_mov_b32_e32 v123, v167
	s_waitcnt lgkmcnt(0)
	v_lshlrev_b32_e32 v124, 16, v120
	v_and_b32_e32 v125, 0xffff0000, v120
	v_lshlrev_b32_e32 v120, 16, v121
	v_and_b32_e32 v121, 0xffff0000, v121
	v_lshlrev_b32_e32 v126, 16, v122
	v_and_b32_e32 v127, 0xffff0000, v122
	v_lshlrev_b32_e32 v122, 16, v123
	v_and_b32_e32 v123, 0xffff0000, v123
	v_pk_add_f32 v[116:117], v[116:117], v[124:125]
	v_pk_add_f32 v[118:119], v[118:119], v[120:121]
	v_pk_add_f32 v[120:121], v[114:115], v[122:123]
	v_pk_add_f32 v[114:115], v[112:113], v[126:127]
	v_cvt_pk_bf16_f32 v112, v116, v117
	v_lshl_add_u64 v[116:117], v[144:145], 0, s[2:3]
	s_mov_b32 s2, 0x10000
	v_cvt_pk_bf16_f32 v113, v118, v119
	v_add_co_u32_e32 v118, vcc, s2, v144
	v_cvt_pk_bf16_f32 v114, v114, v115
	v_cvt_pk_bf16_f32 v115, v120, v121
	v_addc_co_u32_e32 v119, vcc, 0, v145, vcc
	global_store_dwordx4 v[144:145], v[112:115], off offset:256
	s_waitcnt vmcnt(15)
	s_nop 1
	v_mov_b32_e32 v112, v168
	v_mov_b32_e32 v113, v169
	v_mov_b32_e32 v114, v170
	v_mov_b32_e32 v115, v171
	s_mov_b64 s[2:3], 0x20000
	s_waitcnt lgkmcnt(0)
	v_lshlrev_b32_e32 v120, 16, v112
	v_and_b32_e32 v121, 0xffff0000, v112
	v_lshlrev_b32_e32 v112, 16, v113
	v_and_b32_e32 v113, 0xffff0000, v113
	v_lshlrev_b32_e32 v122, 16, v114
	v_and_b32_e32 v123, 0xffff0000, v114
	v_lshlrev_b32_e32 v114, 16, v115
	v_and_b32_e32 v115, 0xffff0000, v115
	v_pk_add_f32 v[110:111], v[110:111], v[112:113]
	v_pk_add_f32 v[108:109], v[108:109], v[120:121]
	v_pk_add_f32 v[112:113], v[106:107], v[114:115]
	v_pk_add_f32 v[106:107], v[104:105], v[122:123]
	v_cvt_pk_bf16_f32 v104, v108, v109
	v_cvt_pk_bf16_f32 v105, v110, v111
	v_cvt_pk_bf16_f32 v106, v106, v107
	v_cvt_pk_bf16_f32 v107, v112, v113
	global_store_dwordx4 v[118:119], v[104:107], off
	s_waitcnt vmcnt(15)
	s_nop 1
	v_mov_b32_e32 v104, v172
	v_mov_b32_e32 v105, v173
	v_mov_b32_e32 v106, v174
	v_mov_b32_e32 v107, v175
	s_waitcnt lgkmcnt(0)
	v_lshlrev_b32_e32 v108, 16, v104
	v_and_b32_e32 v109, 0xffff0000, v104
	v_lshlrev_b32_e32 v104, 16, v105
	v_and_b32_e32 v105, 0xffff0000, v105
	v_lshlrev_b32_e32 v110, 16, v106
	v_and_b32_e32 v111, 0xffff0000, v106
	v_lshlrev_b32_e32 v106, 16, v107
	v_and_b32_e32 v107, 0xffff0000, v107
	v_pk_add_f32 v[100:101], v[100:101], v[108:109]
	v_pk_add_f32 v[102:103], v[102:103], v[104:105]
	v_pk_add_f32 v[104:105], v[98:99], v[106:107]
	v_pk_add_f32 v[98:99], v[96:97], v[110:111]
	v_cvt_pk_bf16_f32 v96, v100, v101
	v_lshl_add_u64 v[100:101], v[144:145], 0, s[2:3]
	s_mov_b32 s2, 0x20000
	v_cvt_pk_bf16_f32 v97, v102, v103
	v_add_co_u32_e32 v102, vcc, s2, v144
	v_cvt_pk_bf16_f32 v98, v98, v99
	v_cvt_pk_bf16_f32 v99, v104, v105
	v_addc_co_u32_e32 v103, vcc, 0, v145, vcc
	global_store_dwordx4 v[116:117], v[96:99], off offset:256
	s_waitcnt vmcnt(15)
; DI unsigned pack2(float a, float b) { f32x2 v = {a, b}; hwbf16x2 r = __builtin_convertvector(v, hwbf16x2); return __builtin_bit_cast(unsigned, r); }
; DI float bflo(unsigned w) { return __uint_as_float(w << 16); }
; DI float bfhi(unsigned w) { return __uint_as_float(w & 0xffff0000u); }
;     DI void operator()(const f32x4 (&acc)[2][2][4][2], const Unit& u, int wr, int wc, int fr, int fq) const {
;     ...
;         for (int ai = 0; ai < 2; ++ai)
; #pragma unroll
;             for (int m = 0; m < 4; ++m) { const size_t ro = (size_t)(row0 + ai * HALF + m * 16) * D + col0;
; #pragma unroll
;                 for (int bj = 0; bj < 2; ++bj) {
;                     f32x4 x0, x1;
;                     if constexpr (IB) { const u32x4 w = *(const u32x4*)((const bf16_t*)Xin + ro + bj * HALF);
;                         x0 = (f32x4){bflo(w[0]), bfhi(w[0]), bflo(w[1]), bfhi(w[1])}; x1 = (f32x4){bflo(w[2]), bfhi(w[2]), bflo(w[3]), bfhi(w[3])}; }
;                     else { x0 = *(const f32x4*)((const float*)Xin + ro + bj * HALF); x1 = *(const f32x4*)((const float*)Xin + ro + bj * HALF + 4); }
;                     x0 += acc[ai][bj][m][0] * sc[bj][0]; x1 += acc[ai][bj][m][1] * sc[bj][1];
;                     if constexpr (OB) { u32x4 o; o[0] = pack2(x0[0], x0[1]); o[1] = pack2(x0[2], x0[3]); o[2] = pack2(x1[0], x1[1]); o[3] = pack2(x1[2], x1[3]);
;                         *(u32x4*)((bf16_t*)Xout + ro + bj * HALF) = o; }
;                     else { *(f32x4*)((float*)Xout + ro + bj * HALF) = x0; *(f32x4*)((float*)Xout + ro + bj * HALF + 4) = x1; } } }
	s_nop 1
	v_mov_b32_e32 v96, v176
	v_mov_b32_e32 v97, v177
	v_mov_b32_e32 v98, v178
	v_mov_b32_e32 v99, v179
	s_mov_b64 s[2:3], 0x30000
	s_waitcnt lgkmcnt(0)
	v_lshlrev_b32_e32 v104, 16, v96
	v_and_b32_e32 v105, 0xffff0000, v96
	v_lshlrev_b32_e32 v96, 16, v97
	v_and_b32_e32 v97, 0xffff0000, v97
	v_lshlrev_b32_e32 v106, 16, v98
	v_and_b32_e32 v107, 0xffff0000, v98
	v_lshlrev_b32_e32 v98, 16, v99
	v_and_b32_e32 v99, 0xffff0000, v99
	v_pk_add_f32 v[94:95], v[94:95], v[96:97]
	v_pk_add_f32 v[92:93], v[92:93], v[104:105]
	v_pk_add_f32 v[96:97], v[90:91], v[98:99]
	v_pk_add_f32 v[90:91], v[88:89], v[106:107]
	v_cvt_pk_bf16_f32 v88, v92, v93
	v_cvt_pk_bf16_f32 v89, v94, v95
	v_cvt_pk_bf16_f32 v90, v90, v91
	v_cvt_pk_bf16_f32 v91, v96, v97
	global_store_dwordx4 v[102:103], v[88:91], off
	s_waitcnt vmcnt(15)
	s_nop 1
	v_mov_b32_e32 v88, v180
	v_mov_b32_e32 v89, v181
	v_mov_b32_e32 v90, v182
	v_mov_b32_e32 v91, v183
	s_waitcnt lgkmcnt(0)
	v_lshlrev_b32_e32 v92, 16, v88
	v_and_b32_e32 v93, 0xffff0000, v88
	v_lshlrev_b32_e32 v88, 16, v89
	v_and_b32_e32 v89, 0xffff0000, v89
	v_lshlrev_b32_e32 v94, 16, v90
	v_and_b32_e32 v95, 0xffff0000, v90
	v_lshlrev_b32_e32 v90, 16, v91
	v_and_b32_e32 v91, 0xffff0000, v91
	v_pk_add_f32 v[86:87], v[86:87], v[88:89]
	v_pk_add_f32 v[84:85], v[84:85], v[92:93]
	v_pk_add_f32 v[88:89], v[82:83], v[90:91]
	v_pk_add_f32 v[82:83], v[80:81], v[94:95]
	v_cvt_pk_bf16_f32 v80, v84, v85
	v_cvt_pk_bf16_f32 v81, v86, v87
	v_cvt_pk_bf16_f32 v82, v82, v83
	v_cvt_pk_bf16_f32 v83, v88, v89
	global_store_dwordx4 v[100:101], v[80:83], off offset:256
	s_nop 1
	v_lshl_add_u64 v[80:81], v[144:145], 0, s[2:3]
	s_mov_b32 s2, 0x30000
	v_add_co_u32_e32 v86, vcc, s2, v144
	s_mov_b64 s[2:3], 0x80000
	s_nop 0
	v_addc_co_u32_e32 v87, vcc, 0, v145, vcc
	s_waitcnt vmcnt(15)
	s_nop 1
	v_mov_b32_e32 v82, v184
	v_mov_b32_e32 v83, v185
	v_mov_b32_e32 v84, v186
	v_mov_b32_e32 v85, v187
	s_waitcnt lgkmcnt(0)
	v_lshlrev_b32_e32 v88, 16, v82
	v_and_b32_e32 v89, 0xffff0000, v82
	v_lshlrev_b32_e32 v82, 16, v83
	v_and_b32_e32 v83, 0xffff0000, v83
	v_lshlrev_b32_e32 v90, 16, v84
	v_and_b32_e32 v91, 0xffff0000, v84
	v_lshlrev_b32_e32 v84, 16, v85
	v_and_b32_e32 v85, 0xffff0000, v85
	v_pk_add_f32 v[78:79], v[78:79], v[82:83]
	v_pk_add_f32 v[76:77], v[76:77], v[88:89]
	v_pk_add_f32 v[82:83], v[74:75], v[84:85]
	v_pk_add_f32 v[74:75], v[72:73], v[90:91]
	v_cvt_pk_bf16_f32 v72, v76, v77
	v_cvt_pk_bf16_f32 v73, v78, v79
	v_cvt_pk_bf16_f32 v74, v74, v75
	v_cvt_pk_bf16_f32 v75, v82, v83
	global_store_dwordx4 v[86:87], v[72:75], off
	s_waitcnt vmcnt(15)
	s_nop 1
	v_mov_b32_e32 v72, v188
	v_mov_b32_e32 v73, v189
	v_mov_b32_e32 v74, v190
	v_mov_b32_e32 v75, v191
	s_waitcnt lgkmcnt(0)
	v_lshlrev_b32_e32 v76, 16, v72
	v_and_b32_e32 v77, 0xffff0000, v72
	v_lshlrev_b32_e32 v72, 16, v73
	v_and_b32_e32 v73, 0xffff0000, v73
	v_lshlrev_b32_e32 v78, 16, v74
	v_and_b32_e32 v79, 0xffff0000, v74
	v_lshlrev_b32_e32 v74, 16, v75
	v_and_b32_e32 v75, 0xffff0000, v75
	v_pk_add_f32 v[70:71], v[70:71], v[72:73]
	v_pk_add_f32 v[68:69], v[68:69], v[76:77]
	v_pk_add_f32 v[72:73], v[66:67], v[74:75]
	v_pk_add_f32 v[66:67], v[64:65], v[78:79]
	v_cvt_pk_bf16_f32 v64, v68, v69
	v_cvt_pk_bf16_f32 v65, v70, v71
	v_cvt_pk_bf16_f32 v66, v66, v67
	v_cvt_pk_bf16_f32 v67, v72, v73
	global_store_dwordx4 v[80:81], v[64:67], off offset:256
	s_nop 1
	v_lshl_add_u64 v[64:65], v[144:145], 0, s[2:3]
	s_mov_b32 s2, 0x80000
	v_add_co_u32_e32 v70, vcc, s2, v144
	s_mov_b64 s[2:3], 0x90000
	s_nop 0
	v_addc_co_u32_e32 v71, vcc, 0, v145, vcc
	s_waitcnt vmcnt(15)
	s_nop 1
	v_mov_b32_e32 v66, v192
	v_mov_b32_e32 v67, v193
	v_mov_b32_e32 v68, v194
	v_mov_b32_e32 v69, v195
	s_waitcnt lgkmcnt(0)
	v_lshlrev_b32_e32 v72, 16, v66
	v_and_b32_e32 v73, 0xffff0000, v66
	v_lshlrev_b32_e32 v66, 16, v67
	v_and_b32_e32 v67, 0xffff0000, v67
	v_lshlrev_b32_e32 v74, 16, v68
	v_and_b32_e32 v75, 0xffff0000, v68
	v_lshlrev_b32_e32 v68, 16, v69
	v_and_b32_e32 v69, 0xffff0000, v69
	v_pk_add_f32 v[62:63], v[62:63], v[66:67]
	v_pk_add_f32 v[60:61], v[60:61], v[72:73]
	v_pk_add_f32 v[66:67], v[58:59], v[68:69]
	v_pk_add_f32 v[58:59], v[56:57], v[74:75]
	v_cvt_pk_bf16_f32 v56, v60, v61
	v_cvt_pk_bf16_f32 v57, v62, v63
	v_cvt_pk_bf16_f32 v58, v58, v59
	v_cvt_pk_bf16_f32 v59, v66, v67
	global_store_dwordx4 v[70:71], v[56:59], off
	s_waitcnt vmcnt(15)
	s_nop 1
	v_mov_b32_e32 v56, v198
	v_mov_b32_e32 v57, v199
	v_mov_b32_e32 v58, v200
	v_mov_b32_e32 v59, v201
	s_waitcnt lgkmcnt(0)
	v_lshlrev_b32_e32 v60, 16, v56
	v_and_b32_e32 v61, 0xffff0000, v56
	v_lshlrev_b32_e32 v56, 16, v57
	v_and_b32_e32 v57, 0xffff0000, v57
	v_lshlrev_b32_e32 v62, 16, v58
	v_and_b32_e32 v63, 0xffff0000, v58
	v_lshlrev_b32_e32 v58, 16, v59
	v_and_b32_e32 v59, 0xffff0000, v59
	v_pk_add_f32 v[54:55], v[54:55], v[56:57]
	v_pk_add_f32 v[52:53], v[52:53], v[60:61]
	v_pk_add_f32 v[56:57], v[50:51], v[58:59]
	v_pk_add_f32 v[50:51], v[48:49], v[62:63]
	v_cvt_pk_bf16_f32 v48, v52, v53
	v_cvt_pk_bf16_f32 v49, v54, v55
	v_cvt_pk_bf16_f32 v50, v50, v51
	v_cvt_pk_bf16_f32 v51, v56, v57
	global_store_dwordx4 v[64:65], v[48:51], off offset:256
	s_nop 1
	v_lshl_add_u64 v[48:49], v[144:145], 0, s[2:3]
	s_mov_b32 s2, 0x90000
	v_add_co_u32_e32 v54, vcc, s2, v144
	s_mov_b64 s[2:3], 0xa0000
	s_nop 0
	v_addc_co_u32_e32 v55, vcc, 0, v145, vcc
	s_waitcnt vmcnt(15)
; DI unsigned pack2(float a, float b) { f32x2 v = {a, b}; hwbf16x2 r = __builtin_convertvector(v, hwbf16x2); return __builtin_bit_cast(unsigned, r); }
; DI float bflo(unsigned w) { return __uint_as_float(w << 16); }
; DI float bfhi(unsigned w) { return __uint_as_float(w & 0xffff0000u); }
;     DI const char* a(const Unit& u) const { return (const char*)(A + (size_t)u.pm * BM * lda); }
;     DI const char* a(const Unit& u) const { return (const char*)(A + (size_t)u.pm * BM * 2048 + (u.pn >> 1) * 512); }
;     DI void operator()(const f32x4 (&acc)[2][2][4][2], const Unit& u, int wr, int wc, int fr, int fq) const {
;     ...
;         for (int ai = 0; ai < 2; ++ai)
; #pragma unroll
;             for (int m = 0; m < 4; ++m) { const size_t ro = (size_t)(row0 + ai * HALF + m * 16) * D + col0;
; #pragma unroll
;                 for (int bj = 0; bj < 2; ++bj) {
;                     f32x4 x0, x1;
;                     if constexpr (IB) { const u32x4 w = *(const u32x4*)((const bf16_t*)Xin + ro + bj * HALF);
;                         x0 = (f32x4){bflo(w[0]), bfhi(w[0]), bflo(w[1]), bfhi(w[1])}; x1 = (f32x4){bflo(w[2]), bfhi(w[2]), bflo(w[3]), bfhi(w[3])}; }
;                     else { x0 = *(const f32x4*)((const float*)Xin + ro + bj * HALF); x1 = *(const f32x4*)((const float*)Xin + ro + bj * HALF + 4); }
;                     x0 += acc[ai][bj][m][0] * sc[bj][0]; x1 += acc[ai][bj][m][1] * sc[bj][1];
;                     if constexpr (OB) { u32x4 o; o[0] = pack2(x0[0], x0[1]); o[1] = pack2(x0[2], x0[3]); o[2] = pack2(x1[0], x1[1]); o[3] = pack2(x1[2], x1[3]);
;                         *(u32x4*)((bf16_t*)Xout + ro + bj * HALF) = o; }
;                     else { *(f32x4*)((float*)Xout + ro + bj * HALF) = x0; *(f32x4*)((float*)Xout + ro + bj * HALF + 4) = x1; } } }
; template <class Map, class Epi>
; DI void gemm_phase(LAS unsigned char* lds, const Map& MP, const Epi& E, const int nM, const int nN, const int K, const int lda, const int ldb) {
;     ...
;         if (!has_next) break;
; #pragma unroll
;         for (int a = 0; a < 2; ++a)
; #pragma unroll
;             for (int b = 0; b < 2; ++b)
; #pragma unroll
;                 for (int m = 0; m < 4; ++m)
; #pragma unroll
;                     for (int n = 0; n < 2; ++n) acc[a][b][m][n] = (f32x4){0.f, 0.f, 0.f, 0.f};
;         cur = nxt; cA = nA; cB = nB; ++ui;
;     }
;     PG8_WAIT_V(0);
;     if (wr == 0) PG8_BAR;
;     PG8_BAR;
	s_nop 1
	v_mov_b32_e32 v50, v202
	v_mov_b32_e32 v51, v203
	v_mov_b32_e32 v52, v204
	v_mov_b32_e32 v53, v205
	s_waitcnt lgkmcnt(0)
	v_lshlrev_b32_e32 v56, 16, v50
	v_and_b32_e32 v57, 0xffff0000, v50
	v_lshlrev_b32_e32 v50, 16, v51
	v_and_b32_e32 v51, 0xffff0000, v51
	v_lshlrev_b32_e32 v58, 16, v52
	v_and_b32_e32 v59, 0xffff0000, v52
	v_lshlrev_b32_e32 v52, 16, v53
	v_and_b32_e32 v53, 0xffff0000, v53
	v_pk_add_f32 v[46:47], v[46:47], v[50:51]
	v_pk_add_f32 v[44:45], v[44:45], v[56:57]
	v_pk_add_f32 v[50:51], v[42:43], v[52:53]
	v_pk_add_f32 v[42:43], v[40:41], v[58:59]
	v_cvt_pk_bf16_f32 v40, v44, v45
	v_cvt_pk_bf16_f32 v41, v46, v47
	v_cvt_pk_bf16_f32 v42, v42, v43
	v_cvt_pk_bf16_f32 v43, v50, v51
	global_store_dwordx4 v[54:55], v[40:43], off
	s_waitcnt vmcnt(15)
	s_nop 1
	v_mov_b32_e32 v40, v206
	v_mov_b32_e32 v41, v207
	v_mov_b32_e32 v42, v208
	v_mov_b32_e32 v43, v209
	s_waitcnt lgkmcnt(0)
	v_lshlrev_b32_e32 v44, 16, v40
	v_and_b32_e32 v45, 0xffff0000, v40
	v_lshlrev_b32_e32 v40, 16, v41
	v_and_b32_e32 v41, 0xffff0000, v41
	v_lshlrev_b32_e32 v46, 16, v42
	v_and_b32_e32 v47, 0xffff0000, v42
	v_lshlrev_b32_e32 v42, 16, v43
	v_and_b32_e32 v43, 0xffff0000, v43
	v_pk_add_f32 v[38:39], v[38:39], v[40:41]
	v_pk_add_f32 v[36:37], v[36:37], v[44:45]
	v_pk_add_f32 v[40:41], v[34:35], v[42:43]
	v_pk_add_f32 v[34:35], v[32:33], v[46:47]
	v_cvt_pk_bf16_f32 v32, v36, v37
	v_cvt_pk_bf16_f32 v33, v38, v39
	v_cvt_pk_bf16_f32 v34, v34, v35
	v_cvt_pk_bf16_f32 v35, v40, v41
	global_store_dwordx4 v[48:49], v[32:35], off offset:256
	s_nop 1
	v_lshl_add_u64 v[32:33], v[144:145], 0, s[2:3]
	s_mov_b32 s2, 0xa0000
	v_add_co_u32_e32 v38, vcc, s2, v144
	s_mov_b64 s[2:3], 0xb0000
	s_nop 0
	v_addc_co_u32_e32 v39, vcc, 0, v145, vcc
	s_waitcnt vmcnt(15)
	s_nop 1
	v_mov_b32_e32 v34, v210
	v_mov_b32_e32 v35, v211
	v_mov_b32_e32 v36, v212
	v_mov_b32_e32 v37, v213
	s_waitcnt lgkmcnt(0)
	v_lshlrev_b32_e32 v40, 16, v34
	v_and_b32_e32 v41, 0xffff0000, v34
	v_lshlrev_b32_e32 v34, 16, v35
	v_and_b32_e32 v35, 0xffff0000, v35
	v_lshlrev_b32_e32 v42, 16, v36
	v_and_b32_e32 v43, 0xffff0000, v36
	v_lshlrev_b32_e32 v36, 16, v37
	v_and_b32_e32 v37, 0xffff0000, v37
	v_pk_add_f32 v[30:31], v[30:31], v[34:35]
	v_pk_add_f32 v[28:29], v[28:29], v[40:41]
	v_pk_add_f32 v[34:35], v[26:27], v[36:37]
	v_pk_add_f32 v[26:27], v[24:25], v[42:43]
	v_cvt_pk_bf16_f32 v24, v28, v29
	v_cvt_pk_bf16_f32 v25, v30, v31
	v_cvt_pk_bf16_f32 v26, v26, v27
	v_cvt_pk_bf16_f32 v27, v34, v35
	global_store_dwordx4 v[38:39], v[24:27], off
	s_waitcnt vmcnt(15)
	s_nop 1
	v_mov_b32_e32 v24, v214
	v_mov_b32_e32 v25, v215
	v_mov_b32_e32 v26, v216
	v_mov_b32_e32 v27, v217
	s_waitcnt lgkmcnt(0)
	v_lshlrev_b32_e32 v28, 16, v24
	v_and_b32_e32 v29, 0xffff0000, v24
	v_lshlrev_b32_e32 v24, 16, v25
	v_and_b32_e32 v25, 0xffff0000, v25
	v_lshlrev_b32_e32 v30, 16, v26
	v_and_b32_e32 v31, 0xffff0000, v26
	v_lshlrev_b32_e32 v26, 16, v27
	v_and_b32_e32 v27, 0xffff0000, v27
	v_pk_add_f32 v[22:23], v[22:23], v[24:25]
	v_pk_add_f32 v[20:21], v[20:21], v[28:29]
	v_pk_add_f32 v[24:25], v[18:19], v[26:27]
	v_pk_add_f32 v[18:19], v[16:17], v[30:31]
	v_cvt_pk_bf16_f32 v16, v20, v21
	v_cvt_pk_bf16_f32 v17, v22, v23
	v_cvt_pk_bf16_f32 v18, v18, v19
	v_cvt_pk_bf16_f32 v19, v24, v25
	global_store_dwordx4 v[32:33], v[16:19], off offset:256
	s_nop 1
	v_lshl_add_u64 v[16:17], v[144:145], 0, s[2:3]
	s_mov_b32 s2, 0xb0000
	v_add_co_u32_e32 v22, vcc, s2, v144
	s_mov_b32 s2, s44
	s_nop 0
	v_addc_co_u32_e32 v23, vcc, 0, v145, vcc
	s_waitcnt vmcnt(15)
	s_nop 1
	v_mov_b32_e32 v18, v248
	v_mov_b32_e32 v19, v249
	v_mov_b32_e32 v20, v250
	v_mov_b32_e32 v21, v251
	s_and_b64 vcc, exec, s[40:41]
	s_waitcnt lgkmcnt(0)
	v_lshlrev_b32_e32 v24, 16, v18
	v_and_b32_e32 v25, 0xffff0000, v18
	v_lshlrev_b32_e32 v18, 16, v19
	v_and_b32_e32 v19, 0xffff0000, v19
	v_lshlrev_b32_e32 v26, 16, v20
	v_and_b32_e32 v27, 0xffff0000, v20
	v_lshlrev_b32_e32 v20, 16, v21
	v_and_b32_e32 v21, 0xffff0000, v21
	v_pk_add_f32 v[14:15], v[14:15], v[18:19]
	v_pk_add_f32 v[12:13], v[12:13], v[24:25]
	v_pk_add_f32 v[18:19], v[10:11], v[20:21]
	v_pk_add_f32 v[10:11], v[8:9], v[26:27]
	v_cvt_pk_bf16_f32 v8, v12, v13
	v_cvt_pk_bf16_f32 v9, v14, v15
	v_cvt_pk_bf16_f32 v10, v10, v11
	v_cvt_pk_bf16_f32 v11, v18, v19
	global_store_dwordx4 v[22:23], v[8:11], off
	s_waitcnt vmcnt(15)
	s_nop 1
	v_mov_b32_e32 v8, v252
	v_mov_b32_e32 v9, v253
	v_mov_b32_e32 v10, v254
	v_mov_b32_e32 v11, v255
	s_waitcnt lgkmcnt(0)
	v_lshlrev_b32_e32 v12, 16, v8
	v_and_b32_e32 v13, 0xffff0000, v8
	v_lshlrev_b32_e32 v8, 16, v9
	v_and_b32_e32 v9, 0xffff0000, v9
	v_lshlrev_b32_e32 v14, 16, v10
	v_and_b32_e32 v15, 0xffff0000, v10
	v_lshlrev_b32_e32 v10, 16, v11
	v_and_b32_e32 v11, 0xffff0000, v11
	v_pk_add_f32 v[6:7], v[6:7], v[8:9]
	v_pk_add_f32 v[4:5], v[4:5], v[12:13]
	v_pk_add_f32 v[8:9], v[2:3], v[10:11]
	v_pk_add_f32 v[2:3], v[0:1], v[14:15]
	v_cvt_pk_bf16_f32 v0, v4, v5
	v_cvt_pk_bf16_f32 v1, v6, v7
	v_cvt_pk_bf16_f32 v2, v2, v3
	v_cvt_pk_bf16_f32 v3, v8, v9
	global_store_dwordx4 v[16:17], v[0:3], off offset:256
	s_cbranch_vccz .LBB1_1761
	s_waitcnt vmcnt(0)
	s_cmpk_gt_u32 s17, 0xff
	s_cbranch_scc1 .LBB1_1768
	s_barrier

;     DI const char* a(const Unit& u) const { return (const char*)(A + (size_t)u.pm * BM * lda); }
;     DI const char* a(const Unit& u) const { return (const char*)(A + (size_t)u.pm * BM * 2048 + (u.pn >> 1) * 512); }
;     DI const char* a(const Unit& u) const { return (const char*)((u.pn < 12 ? A1 : A2) + (size_t)u.pm * BM * 512); }
; #define PG8_STAGE(bufoff, gbase, voff) do { _Pragma("unroll") for (int _i = 0; _i < 2; ++_i) \
;         __builtin_amdgcn_global_load_lds((const unsigned*)((const char*)(gbase) + (voff)[_i]), (LAS unsigned*)(lds + (bufoff) + ldsw + _i * 8192), 16, 0, 0); } while (0)
; #define PG8_LDA(dst, b, h) do { _Pragma("unroll") for (int m = 0; m < 4; ++m) _Pragma("unroll") for (int k = 0; k < 2; ++k) dst[m][k] = *(const LAS bf16x8*)(lds + PG8_SA(b, h) + aoff + m * 2048 + k * 1024); } while (0)
; #define PG8_WAIT_L(n) asm volatile("s_waitcnt lgkmcnt(" #n ")" ::: "memory")
; #define PG8_BAR __builtin_amdgcn_s_barrier()
; #define PG8_SCHED __builtin_amdgcn_sched_barrier(0)
; template <class Map, class Epi>
; DI void gemm_phase(LAS unsigned char* lds, const Map& MP, const Epi& E, const int nM, const int nN, const int K, const int lda, const int ldb) {
;     ...
;         const bool has_next = sched_next(ui + 1, nM, nN, G, cblk, nxt);
;         const char* nA = has_next ? MP.a(nxt) : cA; const char* nB = has_next ? MP.b(nxt) : cB;
;         for (int t = 0; t < nt; t += 2) {
;             const bool last = (t == nt - 2);
;             const char* a1 = cA + (size_t)(t + 1) * kstep;
;             const char* a2 = last ? nA : cA + (size_t)(t + 2) * kstep; const char* b2 = last ? nB : cB + (size_t)(t + 2) * kstep;
;             const char* a3 = a2 + kstep; const char* b3 = b2 + kstep;
;             PG8_LDB(B0, 0, 0); PG8_SCHED; PG8_LDA(At, 0, 0); PG8_STAGE(PG8_SA(1, 1), a1 + hstepA, voffA);
;             PG8_WAIT_L(8); PG8_BAR; PG8_WAIT_L(0); PG8_MMA(0, 0, At, B0); PG8_BAR; PG8_SCHED;
;             PG8_LDB(B1, 0, 1); PG8_STAGE(PG8_SB(0, 0), b2, voffB);
;             PG8_BAR; PG8_WAIT_L(0); PG8_MMA(0, 1, At, B1); PG8_BAR;
;     ...
; #pragma unroll
;         for (int a = 0; a < 2; ++a)
; #pragma unroll
;             for (int b = 0; b < 2; ++b)
; #pragma unroll
;                 for (int m = 0; m < 4; ++m)
; #pragma unroll
;                     for (int n = 0; n < 2; ++n) acc[a][b][m][n] = (f32x4){0.f, 0.f, 0.f, 0.f};
;         cur = nxt; cA = nA; cB = nB; ++ui;
.LBB1_1907:
	s_ashr_i32 s23, s22, 31
	v_cmp_lt_i64_e32 vcc, s[24:25], v[180:181]
	s_lshl_b64 s[24:25], s[22:23], 20
	s_add_u32 s24, s34, s24
	s_addc_u32 s25, s35, s25
	s_and_b64 s[26:27], vcc, exec
	s_cselect_b32 s23, s25, s29
	s_cselect_b32 s58, s24, s28
	s_ashr_i32 s21, s20, 31
	s_lshl_b64 s[26:27], s[20:21], 20
	s_add_u32 s26, s36, s26
	s_addc_u32 s27, s37, s27
	s_and_b64 s[42:43], vcc, exec
	s_cselect_b32 s21, s27, s47
	s_cselect_b32 s59, s26, s46
	s_add_u32 vcc_lo, s46, 0x100
	s_addc_u32 vcc_hi, s47, 0
	s_add_u32 s42, s28, 0x80080
	v_mov_b32_e32 v0, 0
	s_addc_u32 s43, s29, 0
	s_mov_b32 s3, -2
	v_mov_b32_e32 v1, 0
	v_mov_b64_e32 v[2:3], 0
	v_mov_b64_e32 v[4:5], 0
	v_mov_b64_e32 v[6:7], 0
	v_mov_b64_e32 v[8:9], 0
	v_mov_b64_e32 v[10:11], 0
	v_mov_b64_e32 v[12:13], 0
	v_mov_b64_e32 v[14:15], 0
	v_mov_b64_e32 v[16:17], 0
	v_mov_b64_e32 v[18:19], 0
	v_mov_b64_e32 v[20:21], 0
	v_mov_b64_e32 v[22:23], 0
	v_mov_b64_e32 v[24:25], 0
	v_mov_b64_e32 v[26:27], 0
	v_mov_b64_e32 v[28:29], 0
	v_mov_b64_e32 v[30:31], 0
	v_mov_b64_e32 v[32:33], 0
	v_mov_b64_e32 v[34:35], 0
	v_mov_b64_e32 v[36:37], 0
	v_mov_b64_e32 v[38:39], 0
	v_mov_b64_e32 v[40:41], 0
	v_mov_b64_e32 v[42:43], 0
	v_mov_b64_e32 v[44:45], 0
	v_mov_b64_e32 v[46:47], 0
	v_mov_b64_e32 v[48:49], 0
	v_mov_b64_e32 v[50:51], 0
	v_mov_b64_e32 v[52:53], 0
	v_mov_b64_e32 v[54:55], 0
	v_mov_b64_e32 v[56:57], 0
	v_mov_b64_e32 v[58:59], 0
	v_mov_b64_e32 v[60:61], 0
	v_mov_b64_e32 v[62:63], 0
	v_mov_b64_e32 v[64:65], 0
	v_mov_b64_e32 v[66:67], 0
	v_mov_b64_e32 v[68:69], 0
	v_mov_b64_e32 v[70:71], 0
	v_mov_b64_e32 v[72:73], 0
	v_mov_b64_e32 v[74:75], 0
	v_mov_b64_e32 v[76:77], 0
	v_mov_b64_e32 v[78:79], 0
	v_mov_b64_e32 v[104:105], 0
	v_mov_b64_e32 v[106:107], 0
	v_mov_b64_e32 v[116:117], 0
	v_mov_b64_e32 v[118:119], 0
	v_mov_b64_e32 v[120:121], 0
	v_mov_b64_e32 v[122:123], 0
	v_mov_b64_e32 v[124:125], 0
	v_mov_b64_e32 v[126:127], 0
	v_mov_b64_e32 v[128:129], 0
	v_mov_b64_e32 v[130:131], 0
	v_mov_b64_e32 v[132:133], 0
	v_mov_b64_e32 v[134:135], 0
	v_mov_b64_e32 v[136:137], 0
	v_mov_b64_e32 v[138:139], 0
	v_mov_b64_e32 v[140:141], 0
	v_mov_b64_e32 v[142:143], 0
	v_mov_b64_e32 v[144:145], 0
	v_mov_b64_e32 v[146:147], 0
	v_mov_b64_e32 v[148:149], 0
	v_mov_b64_e32 v[150:151], 0
	v_mov_b64_e32 v[152:153], 0
	v_mov_b64_e32 v[154:155], 0
	v_mov_b64_e32 v[156:157], 0
	v_mov_b64_e32 v[158:159], 0
	ds_read_b128 v[80:83], v189
	ds_read_b128 v[84:87], v189 offset:1024
	ds_read_b128 v[88:91], v189 offset:2048
	ds_read_b128 v[92:95], v189 offset:3072
	s_add_u32 s28, s42, 0xfff80080
	s_addc_u32 s29, s43, -1
	s_cmp_eq_u32 s3, 28
	s_cselect_b32 s47, s23, s29
	s_cselect_b32 s46, s58, s28
	s_cselect_b32 s29, s21, vcc_hi
	s_cselect_b32 s28, s59, vcc_lo
.LBB1_1908:
	s_add_i32 m0, s38, 0xc000
	ds_read_b128 v[96:99], v190
	ds_read_b128 v[100:103], v190 offset:1024
	ds_read_b128 v[108:111], v190 offset:2048
	ds_read_b128 v[112:115], v190 offset:3072
	ds_read_b128 v[160:163], v190 offset:4096
	ds_read_b128 v[164:167], v190 offset:5120
	ds_read_b128 v[198:201], v190 offset:6144
	ds_read_b128 v[202:205], v190 offset:7168
	global_load_lds_dwordx4 v178, s[42:43]
	s_add_i32 m0, s38, 0xe000
	s_nop 0
	global_load_lds_dwordx4 v176, s[42:43]
	s_waitcnt lgkmcnt(8)
	s_setprio 1
	s_barrier
	s_waitcnt lgkmcnt(7)
	v_mfma_f32_16x16x32_bf16 v[148:151], v[80:83], v[96:99], v[148:151]
	v_mfma_f32_16x16x32_bf16 v[144:147], v[88:91], v[96:99], v[144:147]
	s_waitcnt lgkmcnt(5)
	v_mfma_f32_16x16x32_bf16 v[136:139], v[80:83], v[108:111], v[136:139]
	v_mfma_f32_16x16x32_bf16 v[128:131], v[88:91], v[108:111], v[128:131]
	s_waitcnt lgkmcnt(3)
	v_mfma_f32_16x16x32_bf16 v[120:123], v[80:83], v[160:163], v[120:123]
	v_mfma_f32_16x16x32_bf16 v[104:107], v[88:91], v[160:163], v[104:107]
	s_waitcnt lgkmcnt(1)
	v_mfma_f32_16x16x32_bf16 v[76:79], v[80:83], v[198:201], v[76:79]
	v_mfma_f32_16x16x32_bf16 v[72:75], v[88:91], v[198:201], v[72:75]
	v_mfma_f32_16x16x32_bf16 v[148:151], v[84:87], v[100:103], v[148:151]
	s_add_i32 s68, s2, s54
	v_mfma_f32_16x16x32_bf16 v[144:147], v[92:95], v[100:103], v[144:147]
	v_lshl_add_u64 v[184:185], s[28:29], 0, v[172:173]
	v_mfma_f32_16x16x32_bf16 v[136:139], v[84:87], v[112:115], v[136:139]
	v_lshl_add_u64 v[194:195], s[28:29], 0, v[168:169]
	v_mfma_f32_16x16x32_bf16 v[128:131], v[92:95], v[112:115], v[128:131]
	v_mfma_f32_16x16x32_bf16 v[120:123], v[84:87], v[164:167], v[120:123]
	v_mfma_f32_16x16x32_bf16 v[104:107], v[92:95], v[164:167], v[104:107]
	s_waitcnt lgkmcnt(0)
	v_mfma_f32_16x16x32_bf16 v[76:79], v[84:87], v[202:205], v[76:79]
	v_mfma_f32_16x16x32_bf16 v[72:75], v[92:95], v[202:205], v[72:75]
	s_barrier
	s_setprio 0
	s_mov_b32 m0, s68
	ds_read_b128 v[206:209], v191
	ds_read_b128 v[210:213], v191 offset:1024
	ds_read_b128 v[214:217], v191 offset:2048
	ds_read_b128 v[218:221], v191 offset:3072
	global_load_lds_dwordx4 v[184:185], off
	s_add_i32 m0, s68, 0x2000
	s_nop 0
	global_load_lds_dwordx4 v[194:195], off
	s_setprio 1
	s_barrier
	s_waitcnt lgkmcnt(3)
	v_mfma_f32_16x16x32_bf16 v[156:159], v[206:209], v[96:99], v[156:159]
	s_waitcnt lgkmcnt(1)
	v_mfma_f32_16x16x32_bf16 v[96:99], v[214:217], v[96:99], v[152:155]
	v_mfma_f32_16x16x32_bf16 v[156:159], v[210:213], v[100:103], v[156:159]
	s_waitcnt lgkmcnt(0)
	v_mfma_f32_16x16x32_bf16 v[96:99], v[218:221], v[100:103], v[96:99]
	v_mfma_f32_16x16x32_bf16 v[100:103], v[206:209], v[108:111], v[140:143]
	v_mfma_f32_16x16x32_bf16 v[108:111], v[214:217], v[108:111], v[132:135]
	v_mfma_f32_16x16x32_bf16 v[116:119], v[214:217], v[160:163], v[116:119]
	v_mfma_f32_16x16x32_bf16 v[68:71], v[206:209], v[198:201], v[68:71]
	v_mfma_f32_16x16x32_bf16 v[64:67], v[214:217], v[198:201], v[64:67]
	v_lshl_add_u64 v[234:235], s[46:47], 0, v[170:171]
	s_mov_b32 m0, s38
	v_mfma_f32_16x16x32_bf16 v[100:103], v[210:213], v[112:115], v[100:103]
	v_lshl_add_u64 v[226:227], s[46:47], 0, v[174:175]
	v_mfma_f32_16x16x32_bf16 v[108:111], v[218:221], v[112:115], v[108:111]
	v_mfma_f32_16x16x32_bf16 v[112:115], v[206:209], v[160:163], v[124:127]
	v_mfma_f32_16x16x32_bf16 v[116:119], v[218:221], v[164:167], v[116:119]
	v_mfma_f32_16x16x32_bf16 v[68:71], v[210:213], v[202:205], v[68:71]
	v_mfma_f32_16x16x32_bf16 v[64:67], v[218:221], v[202:205], v[64:67]
	v_mfma_f32_16x16x32_bf16 v[112:115], v[210:213], v[164:167], v[112:115]
	s_barrier
; #define PG8_STAGE(bufoff, gbase, voff) do { _Pragma("unroll") for (int _i = 0; _i < 2; ++_i) \
;         __builtin_amdgcn_global_load_lds((const unsigned*)((const char*)(gbase) + (voff)[_i]), (LAS unsigned*)(lds + (bufoff) + ldsw + _i * 8192), 16, 0, 0); } while (0)
; #define PG8_LDA(dst, b, h) do { _Pragma("unroll") for (int m = 0; m < 4; ++m) _Pragma("unroll") for (int k = 0; k < 2; ++k) dst[m][k] = *(const LAS bf16x8*)(lds + PG8_SA(b, h) + aoff + m * 2048 + k * 1024); } while (0)
; #define PG8_LDB(dst, b, h) do { _Pragma("unroll") for (int n = 0; n < 2; ++n) _Pragma("unroll") for (int k = 0; k < 2; ++k) dst[n][k] = *(const LAS bf16x8*)(lds + PG8_SB(b, h) + boff + n * 2048 + k * 1024); } while (0)
; #define PG8_MMA(ai, bj, At, Bt) do { __builtin_amdgcn_s_setprio(1); _Pragma("unroll") for (int m = 0; m < 4; ++m) _Pragma("unroll") for (int n = 0; n < 2; ++n) _Pragma("unroll") for (int k = 0; k < 2; ++k) \
;         acc[ai][bj][m][n] = __builtin_amdgcn_mfma_f32_16x16x32_bf16(Bt[n][k], At[m][k], acc[ai][bj][m][n], 0, 0, 0); __builtin_amdgcn_s_setprio(0); } while (0)
; #define PG8_WAIT_V(n) asm volatile("s_waitcnt vmcnt(" #n ")" ::: "memory")
; #define PG8_WAIT_L(n) asm volatile("s_waitcnt lgkmcnt(" #n ")" ::: "memory")
; #define PG8_BAR __builtin_amdgcn_s_barrier()
; #define PG8_SCHED __builtin_amdgcn_sched_barrier(0)
; template <class Map, class Epi>
; DI void gemm_phase(LAS unsigned char* lds, const Map& MP, const Epi& E, const int nM, const int nN, const int K, const int lda, const int ldb) {
;     ...
;             PG8_BAR; PG8_WAIT_L(0); PG8_MMA(0, 1, At, B1); PG8_BAR;
;             PG8_LDA(At, 0, 1); PG8_STAGE(PG8_SA(0, 0), a2, voffA);
;             PG8_BAR; PG8_WAIT_L(0); PG8_MMA(1, 0, At, B0); PG8_BAR; PG8_SCHED;
;             PG8_STAGE(PG8_SB(0, 1), b2 + hstepB, voffB);
;             PG8_WAIT_V(6); PG8_BAR; PG8_MMA(1, 1, At, B1); PG8_BAR;
;             PG8_LDB(B0, 1, 0); PG8_SCHED; PG8_LDA(At, 1, 0); PG8_STAGE(PG8_SA(0, 1), a2 + hstepA, voffA);
;             PG8_WAIT_L(8); PG8_BAR; PG8_WAIT_L(0); PG8_MMA(0, 0, At, B0); PG8_BAR; PG8_SCHED;
;             PG8_LDB(B1, 1, 1); PG8_STAGE(PG8_SB(1, 0), b3, voffB);
	s_setprio 0
	ds_read_b128 v[124:127], v190 offset:16384
	ds_read_b128 v[132:135], v190 offset:17408
	ds_read_b128 v[140:143], v190 offset:18432
	ds_read_b128 v[152:155], v190 offset:19456
	ds_read_b128 v[160:163], v190 offset:20480
	ds_read_b128 v[164:167], v190 offset:21504
	ds_read_b128 v[198:201], v190 offset:22528
	ds_read_b128 v[202:205], v190 offset:23552
	global_load_lds_dwordx4 v[226:227], off
	s_mov_b32 m0, s39
	s_nop 0
	global_load_lds_dwordx4 v[234:235], off
	s_waitcnt vmcnt(10)
	s_setprio 1
	s_barrier
	s_waitcnt lgkmcnt(7)
	v_mfma_f32_16x16x32_bf16 v[60:63], v[80:83], v[124:127], v[60:63]
	v_mfma_f32_16x16x32_bf16 v[48:51], v[88:91], v[124:127], v[48:51]
	s_waitcnt lgkmcnt(5)
	v_mfma_f32_16x16x32_bf16 v[40:43], v[80:83], v[140:143], v[40:43]
	v_mfma_f32_16x16x32_bf16 v[32:35], v[88:91], v[140:143], v[32:35]
	s_waitcnt lgkmcnt(3)
	v_mfma_f32_16x16x32_bf16 v[24:27], v[80:83], v[160:163], v[24:27]
	v_mfma_f32_16x16x32_bf16 v[16:19], v[88:91], v[160:163], v[16:19]
	s_waitcnt lgkmcnt(1)
	v_mfma_f32_16x16x32_bf16 v[12:15], v[80:83], v[198:201], v[12:15]
	v_mfma_f32_16x16x32_bf16 v[8:11], v[88:91], v[198:201], v[8:11]
	v_mfma_f32_16x16x32_bf16 v[60:63], v[84:87], v[132:135], v[60:63]
	s_add_u32 s68, s28, 0x80000
	s_addc_u32 s69, s29, 0
	v_mfma_f32_16x16x32_bf16 v[48:51], v[92:95], v[132:135], v[48:51]
	s_add_i32 s70, s31, s54
	v_mfma_f32_16x16x32_bf16 v[40:43], v[84:87], v[152:155], v[40:43]
	v_mfma_f32_16x16x32_bf16 v[32:35], v[92:95], v[152:155], v[32:35]
	v_mfma_f32_16x16x32_bf16 v[24:27], v[84:87], v[164:167], v[24:27]
	v_mfma_f32_16x16x32_bf16 v[16:19], v[92:95], v[164:167], v[16:19]
	s_waitcnt lgkmcnt(0)
	v_mfma_f32_16x16x32_bf16 v[12:15], v[84:87], v[202:205], v[12:15]
	v_mfma_f32_16x16x32_bf16 v[8:11], v[92:95], v[202:205], v[8:11]
	s_barrier
	s_setprio 0
	s_mov_b32 m0, s70
	s_nop 0
	global_load_lds_dwordx4 v172, s[68:69]
	s_add_i32 m0, s70, 0x2000
	s_nop 0
	global_load_lds_dwordx4 v168, s[68:69]
	s_waitcnt vmcnt(6)
	s_setprio 1
	s_barrier
	v_mfma_f32_16x16x32_bf16 v[56:59], v[206:209], v[124:127], v[56:59]
	v_mfma_f32_16x16x32_bf16 v[52:55], v[214:217], v[124:127], v[52:55]
	s_add_i32 s68, 0, 0x18000
	v_add_u32_e32 v92, s68, v188
	ds_read_b128 v[80:83], v92
	v_mfma_f32_16x16x32_bf16 v[44:47], v[206:209], v[140:143], v[44:47]
	v_mfma_f32_16x16x32_bf16 v[36:39], v[214:217], v[140:143], v[36:39]
	ds_read_b128 v[84:87], v92 offset:1024
	v_mfma_f32_16x16x32_bf16 v[28:31], v[206:209], v[160:163], v[28:31]
	v_mfma_f32_16x16x32_bf16 v[20:23], v[214:217], v[160:163], v[20:23]
	ds_read_b128 v[88:91], v92 offset:2048
	v_mfma_f32_16x16x32_bf16 v[4:7], v[206:209], v[198:201], v[4:7]
	v_mfma_f32_16x16x32_bf16 v[0:3], v[214:217], v[198:201], v[0:3]
	ds_read_b128 v[92:95], v92 offset:3072
	v_mfma_f32_16x16x32_bf16 v[56:59], v[210:213], v[132:135], v[56:59]
	s_add_u32 s46, s46, 0x80000
	s_addc_u32 s47, s47, 0
	v_mfma_f32_16x16x32_bf16 v[52:55], v[218:221], v[132:135], v[52:55]
	v_mfma_f32_16x16x32_bf16 v[44:47], v[210:213], v[152:155], v[44:47]
	v_mfma_f32_16x16x32_bf16 v[36:39], v[218:221], v[152:155], v[36:39]
	v_mfma_f32_16x16x32_bf16 v[28:31], v[210:213], v[164:167], v[28:31]
	v_mfma_f32_16x16x32_bf16 v[20:23], v[218:221], v[164:167], v[20:23]
	v_mfma_f32_16x16x32_bf16 v[4:7], v[210:213], v[202:205], v[4:7]
	v_mfma_f32_16x16x32_bf16 v[0:3], v[218:221], v[202:205], v[0:3]
	s_barrier
	s_setprio 0
	s_mov_b32 m0, s56
	ds_read_b128 v[124:127], v190 offset:32768
	ds_read_b128 v[132:135], v190 offset:33792
	ds_read_b128 v[160:163], v190 offset:34816
	ds_read_b128 v[164:167], v190 offset:35840
	ds_read_b128 v[198:201], v190 offset:36864
	ds_read_b128 v[202:205], v190 offset:37888
	ds_read_b128 v[206:209], v190 offset:38912
	ds_read_b128 v[210:213], v190 offset:39936
	global_load_lds_dwordx4 v174, s[46:47]
	s_mov_b32 m0, s57
	s_nop 0
	global_load_lds_dwordx4 v170, s[46:47]
	s_waitcnt lgkmcnt(8)
	s_setprio 1
	s_barrier
	s_waitcnt lgkmcnt(7)
	v_mfma_f32_16x16x32_bf16 v[140:143], v[80:83], v[124:127], v[148:151]
	s_waitcnt lgkmcnt(6)
	v_mfma_f32_16x16x32_bf16 v[148:151], v[84:87], v[132:135], v[140:143]
	v_mfma_f32_16x16x32_bf16 v[140:143], v[88:91], v[124:127], v[144:147]
	s_waitcnt lgkmcnt(5)
	v_mfma_f32_16x16x32_bf16 v[136:139], v[80:83], v[160:163], v[136:139]
	v_mfma_f32_16x16x32_bf16 v[128:131], v[88:91], v[160:163], v[128:131]
	s_waitcnt lgkmcnt(3)
	v_mfma_f32_16x16x32_bf16 v[120:123], v[80:83], v[198:201], v[120:123]
	v_mfma_f32_16x16x32_bf16 v[104:107], v[88:91], v[198:201], v[104:107]
	s_waitcnt lgkmcnt(1)
	v_mfma_f32_16x16x32_bf16 v[76:79], v[80:83], v[206:209], v[76:79]
	v_mfma_f32_16x16x32_bf16 v[72:75], v[88:91], v[206:209], v[72:75]
	s_add_i32 s46, 0, 0x1c000
	v_mfma_f32_16x16x32_bf16 v[144:147], v[92:95], v[132:135], v[140:143]
	v_add_u32_e32 v140, s46, v188
	v_mfma_f32_16x16x32_bf16 v[136:139], v[84:87], v[164:167], v[136:139]
	s_add_i32 s47, s68, s54
	v_mfma_f32_16x16x32_bf16 v[128:131], v[92:95], v[164:167], v[128:131]
	v_mfma_f32_16x16x32_bf16 v[120:123], v[84:87], v[202:205], v[120:123]
	v_mfma_f32_16x16x32_bf16 v[104:107], v[92:95], v[202:205], v[104:107]
	s_waitcnt lgkmcnt(0)
	v_mfma_f32_16x16x32_bf16 v[76:79], v[84:87], v[210:213], v[76:79]
	v_mfma_f32_16x16x32_bf16 v[72:75], v[92:95], v[210:213], v[72:75]
	s_barrier
	s_setprio 0
	ds_read_b128 v[214:217], v140
	ds_read_b128 v[218:221], v140 offset:1024
	ds_read_b128 v[222:225], v140 offset:2048
	ds_read_b128 v[230:233], v140 offset:3072
	v_lshl_add_u64 v[140:141], v[184:185], 0, s[14:15]
	s_mov_b32 m0, s47
	s_nop 0
	global_load_lds_dwordx4 v[140:141], off
	v_lshl_add_u64 v[140:141], v[194:195], 0, s[14:15]
	s_add_i32 m0, s47, 0x2000
	s_nop 0
	global_load_lds_dwordx4 v[140:141], off
	s_setprio 1
	s_barrier
; #define PG8_STAGE(bufoff, gbase, voff) do { _Pragma("unroll") for (int _i = 0; _i < 2; ++_i) \
;         __builtin_amdgcn_global_load_lds((const unsigned*)((const char*)(gbase) + (voff)[_i]), (LAS unsigned*)(lds + (bufoff) + ldsw + _i * 8192), 16, 0, 0); } while (0)
; #define PG8_LDA(dst, b, h) do { _Pragma("unroll") for (int m = 0; m < 4; ++m) _Pragma("unroll") for (int k = 0; k < 2; ++k) dst[m][k] = *(const LAS bf16x8*)(lds + PG8_SA(b, h) + aoff + m * 2048 + k * 1024); } while (0)
; #define PG8_LDB(dst, b, h) do { _Pragma("unroll") for (int n = 0; n < 2; ++n) _Pragma("unroll") for (int k = 0; k < 2; ++k) dst[n][k] = *(const LAS bf16x8*)(lds + PG8_SB(b, h) + boff + n * 2048 + k * 1024); } while (0)
; #define PG8_MMA(ai, bj, At, Bt) do { __builtin_amdgcn_s_setprio(1); _Pragma("unroll") for (int m = 0; m < 4; ++m) _Pragma("unroll") for (int n = 0; n < 2; ++n) _Pragma("unroll") for (int k = 0; k < 2; ++k) \
;         acc[ai][bj][m][n] = __builtin_amdgcn_mfma_f32_16x16x32_bf16(Bt[n][k], At[m][k], acc[ai][bj][m][n], 0, 0, 0); __builtin_amdgcn_s_setprio(0); } while (0)
; #define PG8_WAIT_V(n) asm volatile("s_waitcnt vmcnt(" #n ")" ::: "memory")
; #define PG8_WAIT_L(n) asm volatile("s_waitcnt lgkmcnt(" #n ")" ::: "memory")
; template <class Map, class Epi>
; DI void gemm_phase(LAS unsigned char* lds, const Map& MP, const Epi& E, const int nM, const int nN, const int K, const int lda, const int ldb) {
;     ...
;             const bool last = (t == nt - 2);
;             const char* a1 = cA + (size_t)(t + 1) * kstep;
;             const char* a2 = last ? nA : cA + (size_t)(t + 2) * kstep; const char* b2 = last ? nB : cB + (size_t)(t + 2) * kstep;
;             const char* a3 = a2 + kstep; const char* b3 = b2 + kstep;
;     ...
;             PG8_LDB(B0, 1, 0); PG8_SCHED; PG8_LDA(At, 1, 0); PG8_STAGE(PG8_SA(0, 1), a2 + hstepA, voffA);
;             PG8_WAIT_L(8); PG8_BAR; PG8_WAIT_L(0); PG8_MMA(0, 0, At, B0); PG8_BAR; PG8_SCHED;
;             PG8_LDB(B1, 1, 1); PG8_STAGE(PG8_SB(1, 0), b3, voffB);
;             PG8_BAR; PG8_WAIT_L(0); PG8_MMA(0, 1, At, B1); PG8_BAR;
;             PG8_LDA(At, 1, 1); PG8_STAGE(PG8_SA(1, 0), a3, voffA);
;             PG8_BAR; PG8_WAIT_L(0); PG8_MMA(1, 0, At, B0); PG8_BAR; PG8_SCHED;
;             PG8_STAGE(PG8_SB(1, 1), b3 + hstepB, voffB);
;             PG8_WAIT_V(6); PG8_BAR; PG8_MMA(1, 1, At, B1); PG8_BAR;
	s_waitcnt lgkmcnt(1)
	v_mfma_f32_16x16x32_bf16 v[96:99], v[222:225], v[124:127], v[96:99]
	v_mfma_f32_16x16x32_bf16 v[140:143], v[214:217], v[124:127], v[156:159]
	s_waitcnt lgkmcnt(0)
	v_mfma_f32_16x16x32_bf16 v[152:155], v[230:233], v[132:135], v[96:99]
	v_mfma_f32_16x16x32_bf16 v[96:99], v[214:217], v[160:163], v[100:103]
	v_mfma_f32_16x16x32_bf16 v[156:159], v[218:221], v[132:135], v[140:143]
	v_mfma_f32_16x16x32_bf16 v[140:143], v[218:221], v[164:167], v[96:99]
	v_mfma_f32_16x16x32_bf16 v[96:99], v[222:225], v[160:163], v[108:111]
	v_mfma_f32_16x16x32_bf16 v[132:135], v[230:233], v[164:167], v[96:99]
	v_mfma_f32_16x16x32_bf16 v[96:99], v[214:217], v[198:201], v[112:115]
	s_mov_b32 m0, s63
	v_mfma_f32_16x16x32_bf16 v[124:127], v[218:221], v[202:205], v[96:99]
	v_lshl_add_u64 v[184:185], v[226:227], 0, s[14:15]
	v_mfma_f32_16x16x32_bf16 v[96:99], v[222:225], v[198:201], v[116:119]
	v_mfma_f32_16x16x32_bf16 v[68:71], v[214:217], v[206:209], v[68:71]
	v_mfma_f32_16x16x32_bf16 v[64:67], v[222:225], v[206:209], v[64:67]
	v_mfma_f32_16x16x32_bf16 v[116:119], v[230:233], v[202:205], v[96:99]
	v_mfma_f32_16x16x32_bf16 v[68:71], v[218:221], v[210:213], v[68:71]
	v_mfma_f32_16x16x32_bf16 v[64:67], v[230:233], v[210:213], v[64:67]
	s_barrier
	s_setprio 0
	ds_read_b128 v[96:99], v190 offset:49152
	ds_read_b128 v[100:103], v190 offset:50176
	ds_read_b128 v[108:111], v190 offset:51200
	ds_read_b128 v[112:115], v190 offset:52224
	ds_read_b128 v[160:163], v190 offset:53248
	ds_read_b128 v[164:167], v190 offset:54272
	ds_read_b128 v[198:201], v190 offset:55296
	ds_read_b128 v[202:205], v190 offset:56320
	global_load_lds_dwordx4 v[184:185], off
	v_lshl_add_u64 v[184:185], v[234:235], 0, s[14:15]
	s_mov_b32 m0, s66
	s_nop 0
	global_load_lds_dwordx4 v[184:185], off
	s_waitcnt vmcnt(10)
	s_setprio 1
	s_barrier
	s_waitcnt lgkmcnt(7)
	v_mfma_f32_16x16x32_bf16 v[60:63], v[80:83], v[96:99], v[60:63]
	v_mfma_f32_16x16x32_bf16 v[48:51], v[88:91], v[96:99], v[48:51]
	s_waitcnt lgkmcnt(5)
	v_mfma_f32_16x16x32_bf16 v[40:43], v[80:83], v[108:111], v[40:43]
	v_mfma_f32_16x16x32_bf16 v[32:35], v[88:91], v[108:111], v[32:35]
	s_waitcnt lgkmcnt(3)
	v_mfma_f32_16x16x32_bf16 v[24:27], v[80:83], v[160:163], v[24:27]
	v_mfma_f32_16x16x32_bf16 v[16:19], v[88:91], v[160:163], v[16:19]
	s_waitcnt lgkmcnt(1)
	v_mfma_f32_16x16x32_bf16 v[12:15], v[80:83], v[198:201], v[12:15]
	v_mfma_f32_16x16x32_bf16 v[8:11], v[88:91], v[198:201], v[8:11]
	v_mfma_f32_16x16x32_bf16 v[60:63], v[84:87], v[100:103], v[60:63]
	s_add_u32 s28, s28, 0x80080
	s_addc_u32 s29, s29, 0
	v_mfma_f32_16x16x32_bf16 v[48:51], v[92:95], v[100:103], v[48:51]
	s_add_i32 s46, s46, s54
	v_mfma_f32_16x16x32_bf16 v[40:43], v[84:87], v[112:115], v[40:43]
	v_mfma_f32_16x16x32_bf16 v[32:35], v[92:95], v[112:115], v[32:35]
	v_mfma_f32_16x16x32_bf16 v[24:27], v[84:87], v[164:167], v[24:27]
	v_mfma_f32_16x16x32_bf16 v[16:19], v[92:95], v[164:167], v[16:19]
	s_waitcnt lgkmcnt(0)
	v_mfma_f32_16x16x32_bf16 v[12:15], v[84:87], v[202:205], v[12:15]
	v_mfma_f32_16x16x32_bf16 v[8:11], v[92:95], v[202:205], v[8:11]
	s_barrier
	s_setprio 0
	s_mov_b32 m0, s46
	s_nop 0
	global_load_lds_dwordx4 v172, s[28:29]
	s_add_i32 m0, s46, 0x2000
	s_nop 0
	global_load_lds_dwordx4 v168, s[28:29]
	s_waitcnt vmcnt(6)
	s_setprio 1
	s_barrier
	v_mfma_f32_16x16x32_bf16 v[56:59], v[214:217], v[96:99], v[56:59]
	v_mfma_f32_16x16x32_bf16 v[52:55], v[222:225], v[96:99], v[52:55]
	ds_read_b128 v[80:83], v189
	v_mfma_f32_16x16x32_bf16 v[44:47], v[214:217], v[108:111], v[44:47]
	v_mfma_f32_16x16x32_bf16 v[36:39], v[222:225], v[108:111], v[36:39]
	ds_read_b128 v[84:87], v189 offset:1024
	v_mfma_f32_16x16x32_bf16 v[28:31], v[214:217], v[160:163], v[28:31]
	v_mfma_f32_16x16x32_bf16 v[20:23], v[222:225], v[160:163], v[20:23]
	ds_read_b128 v[88:91], v189 offset:2048
	v_mfma_f32_16x16x32_bf16 v[4:7], v[214:217], v[198:201], v[4:7]
	v_mfma_f32_16x16x32_bf16 v[0:3], v[222:225], v[198:201], v[0:3]
	ds_read_b128 v[92:95], v189 offset:3072
	v_mfma_f32_16x16x32_bf16 v[56:59], v[218:221], v[100:103], v[56:59]
	s_add_i32 s3, s3, 2
	v_mfma_f32_16x16x32_bf16 v[52:55], v[230:233], v[100:103], v[52:55]
	s_add_u32 vcc_lo, vcc_lo, 0x100
	s_addc_u32 vcc_hi, vcc_hi, 0
	v_mfma_f32_16x16x32_bf16 v[44:47], v[218:221], v[112:115], v[44:47]
	s_add_u32 s42, s42, 0x100
	s_addc_u32 s43, s43, 0
	v_mfma_f32_16x16x32_bf16 v[36:39], v[230:233], v[112:115], v[36:39]
	s_add_u32 s28, s42, 0xfff80080
	s_addc_u32 s29, s43, -1
	s_cmp_eq_u32 s3, 28
	s_cselect_b32 s47, s23, s29
	s_cselect_b32 s46, s58, s28
	s_cselect_b32 s29, s21, vcc_hi
	s_cselect_b32 s28, s59, vcc_lo
	s_cmp_gt_u32 s3, 29
	v_mfma_f32_16x16x32_bf16 v[28:31], v[218:221], v[164:167], v[28:31]
	v_mfma_f32_16x16x32_bf16 v[20:23], v[230:233], v[164:167], v[20:23]
	v_mfma_f32_16x16x32_bf16 v[4:7], v[218:221], v[202:205], v[4:7]
	v_mfma_f32_16x16x32_bf16 v[0:3], v[230:233], v[202:205], v[0:3]
	s_barrier
	s_setprio 0
	s_cbranch_scc0 .LBB1_1908
; DI float silu_mul(float g, float v) { return g * v * __builtin_amdgcn_rcpf(1.0f + __builtin_amdgcn_exp2f(-LOG2E * g)); }
;     DI void operator()(const f32x4 (&acc)[2][2][4][2], const Unit& u, int wr, int wc, int fr, int fq) const {
;         const int row0 = u.pm * BM + wr * 64 + fr, ch0 = u.pn * 128 + wc * 32 + 8 * fq;
;         f32x4 w0[2], w1[2], w2[2], bb[2];
; #pragma unroll
;         for (int n = 0; n < 2; ++n) { w0[n] = *(const f32x4*)(cw + ch0 + 4 * n); w1[n] = *(const f32x4*)(cw + DFF + ch0 + 4 * n); w2[n] = *(const f32x4*)(cw + 2 * DFF + ch0 + 4 * n); bb[n] = *(const f32x4*)(cb + ch0 + 4 * n); }
; #pragma unroll
;         for (int ai = 0; ai < 2; ++ai)
; #pragma unroll
;             for (int m = 0; m < 4; ++m) {
;                 const bool efirst = (m == 0) && (fr == 0), elast = (m == 3) && (fr == 15);
;                 const int row = row0 + ai * HALF + m * 16;
;                 f32x4 gc[2];
; #pragma unroll
;                 for (int n = 0; n < 2; ++n) {
;                     const f32x4 g = acc[ai][0][m][n];
;                     const f32x4 gprev = acc[ai][0][m > 0 ? m - 1 : 0][n], gnext = acc[ai][0][m < 3 ? m + 1 : 3][n];
;                     f32x4 up, dn;
; #pragma unroll
;                     for (int e = 0; e < 4; ++e) {
;                         const float pu = (m > 0 && fr == 15) ? gprev[e] : g[e];
;                         const float pd = (m < 3 && fr == 0) ? gnext[e] : g[e];
;                         up[e] = dpp_ror1(pu); dn[e] = dpp_ror15(pd);
;                     }
;                     if (efirst) up = (f32x4){0.f, 0.f, 0.f, 0.f};
;                     if (elast) dn = (f32x4){0.f, 0.f, 0.f, 0.f};
;                     gc[n] = w0[n] * up + w1[n] * g + w2[n] * dn + bb[n];
;                 }
;                 if (efirst || elast) {
;                     const size_t eo = (size_t)((row >> 6) * 2 + (elast ? 1 : 0)) * DFF + ch0;
; #pragma unroll
;                     for (int n = 0; n < 2; ++n) { *(f32x4*)(EP + eo + 4 * n) = gc[n]; *(f32x4*)(ER + eo + 4 * n) = acc[ai][0][m][n]; *(f32x4*)(EV + eo + 4 * n) = acc[ai][1][m][n]; }
;                 } else {
;                     const f32x4 v0 = acc[ai][1][m][0], v1 = acc[ai][1][m][1];
;                     u32x4 o;
;                     o[0] = pack2(silu_mul(gc[0][0], v0[0]), silu_mul(gc[0][1], v0[1])); o[1] = pack2(silu_mul(gc[0][2], v0[2]), silu_mul(gc[0][3], v0[3]));
	s_waitcnt lgkmcnt(0)
	s_lshl_b32 s21, s45, 7
	v_mov_b32_e32 v194, v186
	v_mov_b32_e32 v80, v187
	s_or_b32 s21, s21, s62
	v_lshl_add_u32 v184, v80, 3, s21
	v_ashrrev_i32_e32 v185, 31, v184
	v_lshlrev_b64 v[80:81], 2, v[184:185]
	v_lshl_add_u64 v[84:85], s[4:5], 0, v[80:81]
	v_lshl_add_u64 v[88:89], s[16:17], 0, v[80:81]
	v_lshl_add_u64 v[92:93], s[18:19], 0, v[80:81]
	v_lshl_add_u64 v[112:113], s[6:7], 0, v[80:81]
	global_load_dwordx4 v[80:83], v[84:85], off offset:16
	global_load_dwordx4 v[96:99], v[84:85], off
	s_nop 0
	global_load_dwordx4 v[84:87], v[88:89], off offset:16
	global_load_dwordx4 v[100:103], v[88:89], off
	s_nop 0
	global_load_dwordx4 v[88:91], v[92:93], off offset:16
	global_load_dwordx4 v[108:111], v[92:93], off
	s_nop 0
	global_load_dwordx4 v[92:95], v[112:113], off offset:16
	s_nop 0
	global_load_dwordx4 v[112:115], v[112:113], off
	v_cmp_eq_u32_e32 vcc, 0, v194
	s_nop 0
	s_nop 0
	v_cndmask_b32_e32 v161, v148, v136, vcc
	v_cndmask_b32_e32 v162, v149, v137, vcc
	v_cndmask_b32_e32 v163, v150, v138, vcc
	v_mov_b32_dpp v160, v161 row_ror:15 row_mask:0xf bank_mask:0xf
	s_nop 0
	s_nop 0
	v_mov_b32_dpp v161, v162 row_ror:15 row_mask:0xf bank_mask:0xf
	v_mov_b32_dpp v164, v150 row_ror:1 row_mask:0xf bank_mask:0xf
	v_cndmask_b32_e32 v165, v151, v139, vcc
	v_mov_b32_dpp v162, v163 row_ror:15 row_mask:0xf bank_mask:0xf
	v_mov_b32_dpp v195, v151 row_ror:1 row_mask:0xf bank_mask:0xf
	v_mov_b32_dpp v166, v148 row_ror:1 row_mask:0xf bank_mask:0xf
	v_mov_b32_dpp v167, v149 row_ror:1 row_mask:0xf bank_mask:0xf
	v_mov_b32_dpp v163, v165 row_ror:15 row_mask:0xf bank_mask:0xf
	v_cndmask_b32_e64 v165, v195, 0, vcc
	v_cndmask_b32_e64 v164, v164, 0, vcc
	v_cndmask_b32_e64 v167, v167, 0, vcc
	v_cndmask_b32_e64 v166, v166, 0, vcc
	s_nop 0
	s_nop 0
	v_mov_b32_dpp v195, v144 row_ror:1 row_mask:0xf bank_mask:0xf
	v_mov_b32_dpp v196, v145 row_ror:1 row_mask:0xf bank_mask:0xf
	v_mov_b32_dpp v198, v146 row_ror:1 row_mask:0xf bank_mask:0xf
	v_cndmask_b32_e32 v199, v147, v131, vcc
	v_mov_b32_dpp v200, v147 row_ror:1 row_mask:0xf bank_mask:0xf
	v_cndmask_b32_e64 v198, v198, 0, vcc
	v_cndmask_b32_e64 v201, v196, 0, vcc
	s_lshl_b32 s3, s44, 8
	s_add_i32 s3, s3, s49
	v_add_u32_e32 v193, s3, v194
	v_cmp_ne_u32_e64 s[46:47], 0, v194
	s_waitcnt vmcnt(0)
	v_pk_mul_f32 v[164:165], v[98:99], v[164:165]
	v_pk_mul_f32 v[166:167], v[96:97], v[166:167]
	v_pk_fma_f32 v[164:165], v[150:151], v[102:103], v[164:165]
	v_pk_fma_f32 v[166:167], v[148:149], v[100:101], v[166:167]
	v_pk_fma_f32 v[162:163], v[110:111], v[162:163], v[164:165]
	v_cndmask_b32_e32 v165, v144, v128, vcc
	v_pk_fma_f32 v[160:161], v[108:109], v[160:161], v[166:167]
	v_cndmask_b32_e32 v166, v145, v129, vcc
	v_mov_b32_dpp v164, v165 row_ror:15 row_mask:0xf bank_mask:0xf
	v_cndmask_b32_e32 v167, v146, v130, vcc
	v_pk_add_f32 v[162:163], v[114:115], v[162:163]
	v_mov_b32_dpp v165, v166 row_ror:15 row_mask:0xf bank_mask:0xf
	v_pk_add_f32 v[160:161], v[112:113], v[160:161]
	s_nop 0
	v_mov_b32_dpp v166, v167 row_ror:15 row_mask:0xf bank_mask:0xf
	s_nop 1
	v_mov_b32_dpp v167, v199 row_ror:15 row_mask:0xf bank_mask:0xf
	v_cndmask_b32_e64 v199, v200, 0, vcc
	v_cndmask_b32_e64 v200, v195, 0, vcc
	v_pk_mul_f32 v[200:201], v[80:81], v[200:201]
	v_pk_mul_f32 v[198:199], v[82:83], v[198:199]
	v_pk_fma_f32 v[200:201], v[144:145], v[84:85], v[200:201]
	v_pk_fma_f32 v[198:199], v[146:147], v[86:87], v[198:199]
	v_pk_fma_f32 v[164:165], v[88:89], v[164:165], v[200:201]
	v_pk_fma_f32 v[166:167], v[90:91], v[166:167], v[198:199]
	v_pk_add_f32 v[164:165], v[92:93], v[164:165]
	v_pk_add_f32 v[166:167], v[94:95], v[166:167]
	s_and_saveexec_b64 s[28:29], s[46:47]
	s_xor_b64 s[28:29], exec, s[28:29]
	s_cbranch_execz .LBB1_1911
	v_mul_f32_e32 v195, 0xbfb8aa3b, v160
	v_exp_f32_e32 v195, v195
	v_mul_f32_e32 v196, 0xbfb8aa3b, v161
	v_exp_f32_e32 v196, v196
	v_pk_mul_f32 v[160:161], v[156:157], v[160:161]
	v_add_f32_e32 v195, 1.0, v195
	v_rcp_f32_e32 v198, v195
	v_add_f32_e32 v196, 1.0, v196
	v_mul_f32_e32 v195, 0xbfb8aa3b, v162
	v_rcp_f32_e32 v199, v196
	v_exp_f32_e32 v195, v195
	v_mul_f32_e32 v196, 0xbfb8aa3b, v163
	v_exp_f32_e32 v196, v196
	v_pk_mul_f32 v[160:161], v[160:161], v[198:199]
	v_add_f32_e32 v195, 1.0, v195
	v_rcp_f32_e32 v200, v195
	v_add_f32_e32 v195, 1.0, v196
	v_rcp_f32_e32 v201, v195
	v_cvt_pk_bf16_f32 v160, v160, v161
	v_mul_f32_e32 v161, 0xbfb8aa3b, v164
	v_exp_f32_e32 v195, v161
	v_mul_f32_e32 v161, 0xbfb8aa3b, v165
	v_exp_f32_e32 v196, v161
	v_pk_mul_f32 v[162:163], v[158:159], v[162:163]
	v_pk_mul_f32 v[164:165], v[152:153], v[164:165]
	v_pk_mul_f32 v[162:163], v[162:163], v[200:201]
	s_nop 0
	v_cvt_pk_bf16_f32 v161, v162, v163
	v_add_f32_e32 v162, 1.0, v195
	v_mul_f32_e32 v195, 0xbfb8aa3b, v166
	v_add_f32_e32 v163, 1.0, v196
	v_exp_f32_e32 v195, v195
	v_mul_f32_e32 v196, 0xbfb8aa3b, v167
	v_exp_f32_e32 v196, v196
	v_rcp_f32_e32 v162, v162
	v_add_f32_e32 v195, 1.0, v195
	v_rcp_f32_e32 v198, v195
	v_add_f32_e32 v195, 1.0, v196
	v_rcp_f32_e32 v163, v163
	v_rcp_f32_e32 v199, v195
	v_pk_mul_f32 v[166:167], v[154:155], v[166:167]
	v_pk_mul_f32 v[162:163], v[164:165], v[162:163]
	v_pk_mul_f32 v[164:165], v[166:167], v[198:199]
	v_cvt_pk_bf16_f32 v162, v162, v163
	v_cvt_pk_bf16_f32 v163, v164, v165
	v_mov_b64_e32 v[164:165], s[52:53]
	v_mad_i64_i32 v[164:165], s[42:43], v193, s60, v[164:165]
	v_lshl_add_u64 v[164:165], v[184:185], 1, v[164:165]
	global_store_dwordx4 v[164:165], v[160:163], off

;     DI const char* a(const Unit& u) const { return (const char*)(A + (size_t)u.pm * BM * lda); }
;     DI const char* a(const Unit& u) const { return (const char*)(A + (size_t)u.pm * BM * 2048 + (u.pn >> 1) * 512); }
;     DI const char* a(const Unit& u) const { return (const char*)((u.pn < 12 ? A1 : A2) + (size_t)u.pm * BM * 512); }
; #define PG8_STAGE(bufoff, gbase, voff) do { _Pragma("unroll") for (int _i = 0; _i < 2; ++_i) \
;         __builtin_amdgcn_global_load_lds((const unsigned*)((const char*)(gbase) + (voff)[_i]), (LAS unsigned*)(lds + (bufoff) + ldsw + _i * 8192), 16, 0, 0); } while (0)
; #define PG8_LDA(dst, b, h) do { _Pragma("unroll") for (int m = 0; m < 4; ++m) _Pragma("unroll") for (int k = 0; k < 2; ++k) dst[m][k] = *(const LAS bf16x8*)(lds + PG8_SA(b, h) + aoff + m * 2048 + k * 1024); } while (0)
; #define PG8_WAIT_L(n) asm volatile("s_waitcnt lgkmcnt(" #n ")" ::: "memory")
; #define PG8_BAR __builtin_amdgcn_s_barrier()
; #define PG8_SCHED __builtin_amdgcn_sched_barrier(0)
; template <class Map, class Epi>
; DI void gemm_phase(LAS unsigned char* lds, const Map& MP, const Epi& E, const int nM, const int nN, const int K, const int lda, const int ldb) {
;     ...
;         const bool has_next = sched_next(ui + 1, nM, nN, G, cblk, nxt);
;         const char* nA = has_next ? MP.a(nxt) : cA; const char* nB = has_next ? MP.b(nxt) : cB;
;         for (int t = 0; t < nt; t += 2) {
;             const bool last = (t == nt - 2);
;             const char* a1 = cA + (size_t)(t + 1) * kstep;
;             const char* a2 = last ? nA : cA + (size_t)(t + 2) * kstep; const char* b2 = last ? nB : cB + (size_t)(t + 2) * kstep;
;             const char* a3 = a2 + kstep; const char* b3 = b2 + kstep;
;             PG8_LDB(B0, 0, 0); PG8_SCHED; PG8_LDA(At, 0, 0); PG8_STAGE(PG8_SA(1, 1), a1 + hstepA, voffA);
;             PG8_WAIT_L(8); PG8_BAR; PG8_WAIT_L(0); PG8_MMA(0, 0, At, B0); PG8_BAR; PG8_SCHED;
;             PG8_LDB(B1, 0, 1); PG8_STAGE(PG8_SB(0, 0), b2, voffB);
;             PG8_BAR; PG8_WAIT_L(0); PG8_MMA(0, 1, At, B1); PG8_BAR;
;     ...
; #pragma unroll
;         for (int a = 0; a < 2; ++a)
; #pragma unroll
;             for (int b = 0; b < 2; ++b)
; #pragma unroll
;                 for (int m = 0; m < 4; ++m)
; #pragma unroll
;                     for (int n = 0; n < 2; ++n) acc[a][b][m][n] = (f32x4){0.f, 0.f, 0.f, 0.f};
;         cur = nxt; cA = nA; cB = nB; ++ui;
.LBB1_2338:
	s_ashr_i32 s53, s52, 31
	v_cmp_lt_i64_e32 vcc, s[6:7], v[156:157]
	s_lshl_b64 s[6:7], s[52:53], 20
	s_add_u32 s3, s18, s6
	s_addc_u32 s14, s19, s7
	s_lshl_b32 s6, s37, 8
	s_and_b32 s6, s6, 0xfffffe00
	s_ashr_i32 s7, s6, 31
	s_lshl_b64 s[6:7], s[6:7], 1
	s_add_u32 s6, s3, s6
	s_addc_u32 s7, s14, s7
	s_and_b64 s[14:15], vcc, exec
	s_cselect_b32 s38, s7, s13
	s_cselect_b32 s39, s6, s12
	s_ashr_i32 s14, s37, 1
	s_ashr_i32 s15, s14, 31
	s_lshl_b64 s[14:15], s[14:15], 19
	s_add_u32 s3, s20, s14
	s_addc_u32 s14, s21, s15
	s_lshl_b32 s15, s37, 18
	s_and_b32 s15, s15, 0x40000
	s_add_u32 s54, s3, s15
	s_addc_u32 s55, s14, 0
	s_and_b64 s[14:15], vcc, exec
	s_cselect_b32 s48, s55, s11
	s_cselect_b32 s49, s54, s10
	s_add_u32 s53, s10, 0x100
	s_addc_u32 s56, s11, 0
	s_add_u32 s10, s12, 0x80080
	v_mov_b32_e32 v0, 0
	s_addc_u32 s11, s13, 0
	s_mov_b32 s3, -2
	v_mov_b32_e32 v1, 0
	v_mov_b64_e32 v[2:3], 0
	v_mov_b64_e32 v[4:5], 0
	v_mov_b64_e32 v[6:7], 0
	v_mov_b64_e32 v[8:9], 0
	v_mov_b64_e32 v[10:11], 0
	v_mov_b64_e32 v[12:13], 0
	v_mov_b64_e32 v[14:15], 0
	v_mov_b64_e32 v[16:17], 0
	v_mov_b64_e32 v[18:19], 0
	v_mov_b64_e32 v[20:21], 0
	v_mov_b64_e32 v[22:23], 0
	v_mov_b64_e32 v[24:25], 0
	v_mov_b64_e32 v[26:27], 0
	v_mov_b64_e32 v[28:29], 0
	v_mov_b64_e32 v[30:31], 0
	v_mov_b64_e32 v[32:33], 0
	v_mov_b64_e32 v[34:35], 0
	v_mov_b64_e32 v[36:37], 0
	v_mov_b64_e32 v[38:39], 0
	v_mov_b64_e32 v[48:49], 0
	v_mov_b64_e32 v[50:51], 0
	v_mov_b64_e32 v[52:53], 0
	v_mov_b64_e32 v[54:55], 0
	v_mov_b64_e32 v[64:65], 0
	v_mov_b64_e32 v[66:67], 0
	v_mov_b64_e32 v[68:69], 0
	v_mov_b64_e32 v[70:71], 0
	v_mov_b64_e32 v[72:73], 0
	v_mov_b64_e32 v[74:75], 0
	v_mov_b64_e32 v[76:77], 0
	v_mov_b64_e32 v[78:79], 0
	v_mov_b64_e32 v[80:81], 0
	v_mov_b64_e32 v[82:83], 0
	v_mov_b64_e32 v[84:85], 0
	v_mov_b64_e32 v[86:87], 0
	v_mov_b64_e32 v[88:89], 0
	v_mov_b64_e32 v[90:91], 0
	v_mov_b64_e32 v[92:93], 0
	v_mov_b64_e32 v[94:95], 0
	v_mov_b64_e32 v[96:97], 0
	v_mov_b64_e32 v[98:99], 0
	v_mov_b64_e32 v[100:101], 0
	v_mov_b64_e32 v[102:103], 0
	v_mov_b64_e32 v[104:105], 0
	v_mov_b64_e32 v[106:107], 0
	v_mov_b64_e32 v[108:109], 0
	v_mov_b64_e32 v[110:111], 0
	v_mov_b64_e32 v[112:113], 0
	v_mov_b64_e32 v[114:115], 0
	v_mov_b64_e32 v[116:117], 0
	v_mov_b64_e32 v[118:119], 0
	v_mov_b64_e32 v[120:121], 0
	v_mov_b64_e32 v[122:123], 0
	v_mov_b64_e32 v[124:125], 0
	v_mov_b64_e32 v[126:127], 0
	v_mov_b64_e32 v[128:129], 0
	v_mov_b64_e32 v[130:131], 0
	v_mov_b64_e32 v[132:133], 0
	v_mov_b64_e32 v[134:135], 0
	v_mov_b64_e32 v[136:137], 0
	v_mov_b64_e32 v[138:139], 0
	v_mov_b64_e32 v[140:141], 0
	v_mov_b64_e32 v[142:143], 0
	ds_read_b128 v[40:43], v165
	ds_read_b128 v[44:47], v165 offset:1024
	ds_read_b128 v[56:59], v165 offset:2048
	ds_read_b128 v[60:63], v165 offset:3072
	s_add_u32 s12, s10, 0xfff80080
	s_addc_u32 s13, s11, -1
	s_cmp_eq_u32 s3, 4
	s_cselect_b32 s15, s38, s13
	s_cselect_b32 s14, s39, s12
	s_cselect_b32 s13, s48, s56
	s_cselect_b32 s12, s49, s53
.LBB1_2339:
	s_add_i32 m0, s9, 0xc000
	ds_read_b128 v[168:171], v166
	ds_read_b128 v[172:175], v166 offset:1024
	ds_read_b128 v[176:179], v166 offset:2048
	ds_read_b128 v[180:183], v166 offset:3072
	ds_read_b128 v[184:187], v166 offset:4096
	ds_read_b128 v[188:191], v166 offset:5120
	ds_read_b128 v[192:195], v166 offset:6144
	ds_read_b128 v[198:201], v166 offset:7168
	global_load_lds_dwordx4 v154, s[10:11]
	s_add_i32 m0, s9, 0xe000
	s_nop 0
	global_load_lds_dwordx4 v152, s[10:11]
	s_waitcnt lgkmcnt(8)
	s_setprio 1
	s_barrier
	s_waitcnt lgkmcnt(7)
	v_mfma_f32_16x16x32_bf16 v[140:143], v[40:43], v[168:171], v[140:143]
	v_mfma_f32_16x16x32_bf16 v[136:139], v[56:59], v[168:171], v[136:139]
	s_waitcnt lgkmcnt(5)
	v_mfma_f32_16x16x32_bf16 v[124:127], v[40:43], v[176:179], v[124:127]
	v_mfma_f32_16x16x32_bf16 v[120:123], v[56:59], v[176:179], v[120:123]
	s_waitcnt lgkmcnt(3)
	v_mfma_f32_16x16x32_bf16 v[108:111], v[40:43], v[184:187], v[108:111]
	v_mfma_f32_16x16x32_bf16 v[104:107], v[56:59], v[184:187], v[104:107]
	s_waitcnt lgkmcnt(1)
	v_mfma_f32_16x16x32_bf16 v[92:95], v[40:43], v[192:195], v[92:95]
	v_mfma_f32_16x16x32_bf16 v[88:91], v[56:59], v[192:195], v[88:91]
	v_mfma_f32_16x16x32_bf16 v[140:143], v[44:47], v[172:175], v[140:143]
	s_add_i32 s57, s35, s22
	v_mfma_f32_16x16x32_bf16 v[136:139], v[60:63], v[172:175], v[136:139]
	v_lshl_add_u64 v[160:161], s[12:13], 0, v[148:149]
	v_mfma_f32_16x16x32_bf16 v[124:127], v[44:47], v[180:183], v[124:127]
	v_lshl_add_u64 v[218:219], s[12:13], 0, v[144:145]
	v_mfma_f32_16x16x32_bf16 v[120:123], v[60:63], v[180:183], v[120:123]
	v_mfma_f32_16x16x32_bf16 v[108:111], v[44:47], v[188:191], v[108:111]
	v_mfma_f32_16x16x32_bf16 v[104:107], v[60:63], v[188:191], v[104:107]
	s_waitcnt lgkmcnt(0)
	v_mfma_f32_16x16x32_bf16 v[92:95], v[44:47], v[198:201], v[92:95]
	v_mfma_f32_16x16x32_bf16 v[88:91], v[60:63], v[198:201], v[88:91]
	s_barrier
	s_setprio 0
	s_mov_b32 m0, s57
	ds_read_b128 v[202:205], v167
	ds_read_b128 v[206:209], v167 offset:1024
	ds_read_b128 v[210:213], v167 offset:2048
	ds_read_b128 v[214:217], v167 offset:3072
	global_load_lds_dwordx4 v[160:161], off
	s_add_i32 m0, s57, 0x2000
	s_nop 0
	global_load_lds_dwordx4 v[218:219], off
	s_setprio 1
	s_barrier
; #define PG8_STAGE(bufoff, gbase, voff) do { _Pragma("unroll") for (int _i = 0; _i < 2; ++_i) \
;         __builtin_amdgcn_global_load_lds((const unsigned*)((const char*)(gbase) + (voff)[_i]), (LAS unsigned*)(lds + (bufoff) + ldsw + _i * 8192), 16, 0, 0); } while (0)
; #define PG8_LDA(dst, b, h) do { _Pragma("unroll") for (int m = 0; m < 4; ++m) _Pragma("unroll") for (int k = 0; k < 2; ++k) dst[m][k] = *(const LAS bf16x8*)(lds + PG8_SA(b, h) + aoff + m * 2048 + k * 1024); } while (0)
; #define PG8_LDB(dst, b, h) do { _Pragma("unroll") for (int n = 0; n < 2; ++n) _Pragma("unroll") for (int k = 0; k < 2; ++k) dst[n][k] = *(const LAS bf16x8*)(lds + PG8_SB(b, h) + boff + n * 2048 + k * 1024); } while (0)
; #define PG8_MMA(ai, bj, At, Bt) do { __builtin_amdgcn_s_setprio(1); _Pragma("unroll") for (int m = 0; m < 4; ++m) _Pragma("unroll") for (int n = 0; n < 2; ++n) _Pragma("unroll") for (int k = 0; k < 2; ++k) \
;         acc[ai][bj][m][n] = __builtin_amdgcn_mfma_f32_16x16x32_bf16(Bt[n][k], At[m][k], acc[ai][bj][m][n], 0, 0, 0); __builtin_amdgcn_s_setprio(0); } while (0)
; #define PG8_WAIT_V(n) asm volatile("s_waitcnt vmcnt(" #n ")" ::: "memory")
; #define PG8_WAIT_L(n) asm volatile("s_waitcnt lgkmcnt(" #n ")" ::: "memory")
; #define PG8_BAR __builtin_amdgcn_s_barrier()
; #define PG8_SCHED __builtin_amdgcn_sched_barrier(0)
; template <class Map, class Epi>
; DI void gemm_phase(LAS unsigned char* lds, const Map& MP, const Epi& E, const int nM, const int nN, const int K, const int lda, const int ldb) {
;     ...
;             PG8_BAR; PG8_WAIT_L(0); PG8_MMA(0, 1, At, B1); PG8_BAR;
;             PG8_LDA(At, 0, 1); PG8_STAGE(PG8_SA(0, 0), a2, voffA);
;             PG8_BAR; PG8_WAIT_L(0); PG8_MMA(1, 0, At, B0); PG8_BAR; PG8_SCHED;
;             PG8_STAGE(PG8_SB(0, 1), b2 + hstepB, voffB);
;             PG8_WAIT_V(6); PG8_BAR; PG8_MMA(1, 1, At, B1); PG8_BAR;
;             PG8_LDB(B0, 1, 0); PG8_SCHED; PG8_LDA(At, 1, 0); PG8_STAGE(PG8_SA(0, 1), a2 + hstepA, voffA);
;             PG8_WAIT_L(8); PG8_BAR; PG8_WAIT_L(0); PG8_MMA(0, 0, At, B0); PG8_BAR; PG8_SCHED;
	s_waitcnt lgkmcnt(3)
	v_mfma_f32_16x16x32_bf16 v[132:135], v[202:205], v[168:171], v[132:135]
	s_waitcnt lgkmcnt(1)
	v_mfma_f32_16x16x32_bf16 v[128:131], v[210:213], v[168:171], v[128:131]
	v_mfma_f32_16x16x32_bf16 v[116:119], v[202:205], v[176:179], v[116:119]
	v_mfma_f32_16x16x32_bf16 v[112:115], v[210:213], v[176:179], v[112:115]
	v_mfma_f32_16x16x32_bf16 v[100:103], v[202:205], v[184:187], v[100:103]
	v_mfma_f32_16x16x32_bf16 v[96:99], v[210:213], v[184:187], v[96:99]
	v_mfma_f32_16x16x32_bf16 v[84:87], v[202:205], v[192:195], v[84:87]
	v_mfma_f32_16x16x32_bf16 v[80:83], v[210:213], v[192:195], v[80:83]
	v_mfma_f32_16x16x32_bf16 v[132:135], v[206:209], v[172:175], v[132:135]
	v_lshl_add_u64 v[222:223], s[14:15], 0, v[146:147]
	s_mov_b32 m0, s9
	s_waitcnt lgkmcnt(0)
	v_mfma_f32_16x16x32_bf16 v[128:131], v[214:217], v[172:175], v[128:131]
	v_lshl_add_u64 v[220:221], s[14:15], 0, v[150:151]
	v_mfma_f32_16x16x32_bf16 v[116:119], v[206:209], v[180:183], v[116:119]
	v_mfma_f32_16x16x32_bf16 v[112:115], v[214:217], v[180:183], v[112:115]
	v_mfma_f32_16x16x32_bf16 v[100:103], v[206:209], v[188:191], v[100:103]
	v_mfma_f32_16x16x32_bf16 v[96:99], v[214:217], v[188:191], v[96:99]
	v_mfma_f32_16x16x32_bf16 v[84:87], v[206:209], v[198:201], v[84:87]
	v_mfma_f32_16x16x32_bf16 v[80:83], v[214:217], v[198:201], v[80:83]
	s_barrier
	s_setprio 0
	ds_read_b128 v[168:171], v166 offset:16384
	ds_read_b128 v[172:175], v166 offset:17408
	ds_read_b128 v[176:179], v166 offset:18432
	ds_read_b128 v[180:183], v166 offset:19456
	ds_read_b128 v[184:187], v166 offset:20480
	ds_read_b128 v[188:191], v166 offset:21504
	ds_read_b128 v[192:195], v166 offset:22528
	ds_read_b128 v[198:201], v166 offset:23552
	global_load_lds_dwordx4 v[220:221], off
	s_mov_b32 m0, s24
	s_nop 0
	global_load_lds_dwordx4 v[222:223], off
	s_waitcnt vmcnt(10)
	s_setprio 1
	s_barrier
	s_waitcnt lgkmcnt(7)
	v_mfma_f32_16x16x32_bf16 v[76:79], v[40:43], v[168:171], v[76:79]
	v_mfma_f32_16x16x32_bf16 v[72:75], v[56:59], v[168:171], v[72:75]
	s_waitcnt lgkmcnt(5)
	v_mfma_f32_16x16x32_bf16 v[52:55], v[40:43], v[176:179], v[52:55]
	v_mfma_f32_16x16x32_bf16 v[48:51], v[56:59], v[176:179], v[48:51]
	s_waitcnt lgkmcnt(3)
	v_mfma_f32_16x16x32_bf16 v[28:31], v[40:43], v[184:187], v[28:31]
	v_mfma_f32_16x16x32_bf16 v[24:27], v[56:59], v[184:187], v[24:27]
	s_waitcnt lgkmcnt(1)
	v_mfma_f32_16x16x32_bf16 v[12:15], v[40:43], v[192:195], v[12:15]
	v_mfma_f32_16x16x32_bf16 v[8:11], v[56:59], v[192:195], v[8:11]
	v_mfma_f32_16x16x32_bf16 v[76:79], v[44:47], v[172:175], v[76:79]
	s_add_u32 s58, s12, 0x20000
	s_addc_u32 s59, s13, 0
	v_mfma_f32_16x16x32_bf16 v[72:75], v[60:63], v[172:175], v[72:75]
	s_add_i32 s57, s36, s22
	v_mfma_f32_16x16x32_bf16 v[52:55], v[44:47], v[180:183], v[52:55]
	v_mfma_f32_16x16x32_bf16 v[48:51], v[60:63], v[180:183], v[48:51]
	v_mfma_f32_16x16x32_bf16 v[28:31], v[44:47], v[188:191], v[28:31]
	v_mfma_f32_16x16x32_bf16 v[24:27], v[60:63], v[188:191], v[24:27]
	s_waitcnt lgkmcnt(0)
	v_mfma_f32_16x16x32_bf16 v[12:15], v[44:47], v[198:201], v[12:15]
	v_mfma_f32_16x16x32_bf16 v[8:11], v[60:63], v[198:201], v[8:11]
	s_barrier
	s_setprio 0
	s_mov_b32 m0, s57
	s_nop 0
	global_load_lds_dwordx4 v148, s[58:59]
	s_add_i32 m0, s57, 0x2000
	s_nop 0
	global_load_lds_dwordx4 v144, s[58:59]
	s_waitcnt vmcnt(6)
	s_setprio 1
	s_barrier
	v_mfma_f32_16x16x32_bf16 v[36:39], v[202:205], v[176:179], v[36:39]
	v_mfma_f32_16x16x32_bf16 v[32:35], v[210:213], v[176:179], v[32:35]
	v_mfma_f32_16x16x32_bf16 v[20:23], v[202:205], v[184:187], v[20:23]
	v_mfma_f32_16x16x32_bf16 v[16:19], v[210:213], v[184:187], v[16:19]
	v_mfma_f32_16x16x32_bf16 v[4:7], v[202:205], v[192:195], v[4:7]
	v_mfma_f32_16x16x32_bf16 v[0:3], v[210:213], v[192:195], v[0:3]
	v_mfma_f32_16x16x32_bf16 v[40:43], v[202:205], v[168:171], v[68:71]
	s_add_i32 s57, 0, 0x18000
	v_add_u32_e32 v68, s57, v164
	ds_read_b128 v[56:59], v68
	ds_read_b128 v[60:63], v68 offset:1024
	v_mfma_f32_16x16x32_bf16 v[44:47], v[210:213], v[168:171], v[64:67]
	ds_read_b128 v[64:67], v68 offset:2048
	ds_read_b128 v[68:71], v68 offset:3072
	v_mfma_f32_16x16x32_bf16 v[36:39], v[206:209], v[180:183], v[36:39]
	s_add_u32 s14, s14, 0x80000
	s_addc_u32 s15, s15, 0
	v_mfma_f32_16x16x32_bf16 v[32:35], v[214:217], v[180:183], v[32:35]
	v_mfma_f32_16x16x32_bf16 v[20:23], v[206:209], v[188:191], v[20:23]
	v_mfma_f32_16x16x32_bf16 v[16:19], v[214:217], v[188:191], v[16:19]
	v_mfma_f32_16x16x32_bf16 v[4:7], v[206:209], v[198:201], v[4:7]
	v_mfma_f32_16x16x32_bf16 v[0:3], v[214:217], v[198:201], v[0:3]
	v_mfma_f32_16x16x32_bf16 v[40:43], v[206:209], v[172:175], v[40:43]
	v_mfma_f32_16x16x32_bf16 v[44:47], v[214:217], v[172:175], v[44:47]
	s_barrier
	s_setprio 0
	s_mov_b32 m0, s25
	ds_read_b128 v[168:171], v166 offset:32768
	ds_read_b128 v[172:175], v166 offset:33792
	ds_read_b128 v[176:179], v166 offset:34816
	ds_read_b128 v[180:183], v166 offset:35840
	ds_read_b128 v[184:187], v166 offset:36864
	ds_read_b128 v[188:191], v166 offset:37888
	ds_read_b128 v[192:195], v166 offset:38912
	ds_read_b128 v[198:201], v166 offset:39936
	global_load_lds_dwordx4 v150, s[14:15]
	s_mov_b32 m0, s26
	s_nop 0
	global_load_lds_dwordx4 v146, s[14:15]
	s_waitcnt lgkmcnt(8)
	s_setprio 1
	s_barrier
; #define PG8_STAGE(bufoff, gbase, voff) do { _Pragma("unroll") for (int _i = 0; _i < 2; ++_i) \
;         __builtin_amdgcn_global_load_lds((const unsigned*)((const char*)(gbase) + (voff)[_i]), (LAS unsigned*)(lds + (bufoff) + ldsw + _i * 8192), 16, 0, 0); } while (0)
; #define PG8_LDA(dst, b, h) do { _Pragma("unroll") for (int m = 0; m < 4; ++m) _Pragma("unroll") for (int k = 0; k < 2; ++k) dst[m][k] = *(const LAS bf16x8*)(lds + PG8_SA(b, h) + aoff + m * 2048 + k * 1024); } while (0)
; #define PG8_LDB(dst, b, h) do { _Pragma("unroll") for (int n = 0; n < 2; ++n) _Pragma("unroll") for (int k = 0; k < 2; ++k) dst[n][k] = *(const LAS bf16x8*)(lds + PG8_SB(b, h) + boff + n * 2048 + k * 1024); } while (0)
; #define PG8_MMA(ai, bj, At, Bt) do { __builtin_amdgcn_s_setprio(1); _Pragma("unroll") for (int m = 0; m < 4; ++m) _Pragma("unroll") for (int n = 0; n < 2; ++n) _Pragma("unroll") for (int k = 0; k < 2; ++k) \
;         acc[ai][bj][m][n] = __builtin_amdgcn_mfma_f32_16x16x32_bf16(Bt[n][k], At[m][k], acc[ai][bj][m][n], 0, 0, 0); __builtin_amdgcn_s_setprio(0); } while (0)
; #define PG8_WAIT_L(n) asm volatile("s_waitcnt lgkmcnt(" #n ")" ::: "memory")
; #define PG8_BAR __builtin_amdgcn_s_barrier()
; #define PG8_SCHED __builtin_amdgcn_sched_barrier(0)
; template <class Map, class Epi>
; DI void gemm_phase(LAS unsigned char* lds, const Map& MP, const Epi& E, const int nM, const int nN, const int K, const int lda, const int ldb) {
;     ...
;             PG8_WAIT_L(8); PG8_BAR; PG8_WAIT_L(0); PG8_MMA(0, 0, At, B0); PG8_BAR; PG8_SCHED;
;             PG8_LDB(B1, 1, 1); PG8_STAGE(PG8_SB(1, 0), b3, voffB);
;             PG8_BAR; PG8_WAIT_L(0); PG8_MMA(0, 1, At, B1); PG8_BAR;
;             PG8_LDA(At, 1, 1); PG8_STAGE(PG8_SA(1, 0), a3, voffA);
;             PG8_BAR; PG8_WAIT_L(0); PG8_MMA(1, 0, At, B0); PG8_BAR; PG8_SCHED;
;             PG8_STAGE(PG8_SB(1, 1), b3 + hstepB, voffB);
	s_waitcnt lgkmcnt(7)
	v_mfma_f32_16x16x32_bf16 v[140:143], v[56:59], v[168:171], v[140:143]
	v_mfma_f32_16x16x32_bf16 v[136:139], v[64:67], v[168:171], v[136:139]
	s_waitcnt lgkmcnt(5)
	v_mfma_f32_16x16x32_bf16 v[124:127], v[56:59], v[176:179], v[124:127]
	v_mfma_f32_16x16x32_bf16 v[120:123], v[64:67], v[176:179], v[120:123]
	s_waitcnt lgkmcnt(3)
	v_mfma_f32_16x16x32_bf16 v[108:111], v[56:59], v[184:187], v[108:111]
	v_mfma_f32_16x16x32_bf16 v[104:107], v[64:67], v[184:187], v[104:107]
	s_waitcnt lgkmcnt(1)
	v_mfma_f32_16x16x32_bf16 v[92:95], v[56:59], v[192:195], v[92:95]
	v_mfma_f32_16x16x32_bf16 v[88:91], v[64:67], v[192:195], v[88:91]
	v_mfma_f32_16x16x32_bf16 v[140:143], v[60:63], v[172:175], v[140:143]
	s_add_i32 s14, 0, 0x1c000
	v_mfma_f32_16x16x32_bf16 v[136:139], v[68:71], v[172:175], v[136:139]
	s_add_i32 s15, s57, s22
	v_mfma_f32_16x16x32_bf16 v[124:127], v[60:63], v[180:183], v[124:127]
	v_add_u32_e32 v196, s14, v164
	v_mfma_f32_16x16x32_bf16 v[120:123], v[68:71], v[180:183], v[120:123]
	v_lshl_add_u64 v[160:161], v[160:161], 0, s[46:47]
	v_mfma_f32_16x16x32_bf16 v[108:111], v[60:63], v[188:191], v[108:111]
	v_mfma_f32_16x16x32_bf16 v[104:107], v[68:71], v[188:191], v[104:107]
	s_waitcnt lgkmcnt(0)
	v_mfma_f32_16x16x32_bf16 v[92:95], v[60:63], v[198:201], v[92:95]
	v_mfma_f32_16x16x32_bf16 v[88:91], v[68:71], v[198:201], v[88:91]
	s_barrier
	s_setprio 0
	s_mov_b32 m0, s15
	ds_read_b128 v[202:205], v196
	ds_read_b128 v[206:209], v196 offset:1024
	ds_read_b128 v[210:213], v196 offset:2048
	ds_read_b128 v[214:217], v196 offset:3072
	global_load_lds_dwordx4 v[160:161], off
	v_lshl_add_u64 v[160:161], v[218:219], 0, s[46:47]
	s_add_i32 m0, s15, 0x2000
	s_nop 0
	global_load_lds_dwordx4 v[160:161], off
	s_setprio 1
	s_barrier
	s_waitcnt lgkmcnt(3)
	v_mfma_f32_16x16x32_bf16 v[132:135], v[202:205], v[168:171], v[132:135]
	s_waitcnt lgkmcnt(1)
	v_mfma_f32_16x16x32_bf16 v[128:131], v[210:213], v[168:171], v[128:131]
	v_mfma_f32_16x16x32_bf16 v[116:119], v[202:205], v[176:179], v[116:119]
	v_mfma_f32_16x16x32_bf16 v[112:115], v[210:213], v[176:179], v[112:115]
	v_mfma_f32_16x16x32_bf16 v[100:103], v[202:205], v[184:187], v[100:103]
	v_mfma_f32_16x16x32_bf16 v[96:99], v[210:213], v[184:187], v[96:99]
	v_mfma_f32_16x16x32_bf16 v[84:87], v[202:205], v[192:195], v[84:87]
	v_mfma_f32_16x16x32_bf16 v[80:83], v[210:213], v[192:195], v[80:83]
	v_mfma_f32_16x16x32_bf16 v[132:135], v[206:209], v[172:175], v[132:135]
	s_mov_b32 m0, s30
	s_waitcnt lgkmcnt(0)
	v_mfma_f32_16x16x32_bf16 v[128:131], v[214:217], v[172:175], v[128:131]
	v_lshl_add_u64 v[160:161], v[220:221], 0, s[46:47]
	v_mfma_f32_16x16x32_bf16 v[116:119], v[206:209], v[180:183], v[116:119]
	v_mfma_f32_16x16x32_bf16 v[112:115], v[214:217], v[180:183], v[112:115]
	v_mfma_f32_16x16x32_bf16 v[100:103], v[206:209], v[188:191], v[100:103]
	v_mfma_f32_16x16x32_bf16 v[96:99], v[214:217], v[188:191], v[96:99]
	v_mfma_f32_16x16x32_bf16 v[84:87], v[206:209], v[198:201], v[84:87]
	v_mfma_f32_16x16x32_bf16 v[80:83], v[214:217], v[198:201], v[80:83]
	s_barrier
	s_setprio 0
	ds_read_b128 v[168:171], v166 offset:49152
	ds_read_b128 v[172:175], v166 offset:50176
	ds_read_b128 v[176:179], v166 offset:51200
	ds_read_b128 v[180:183], v166 offset:52224
	ds_read_b128 v[184:187], v166 offset:53248
	ds_read_b128 v[188:191], v166 offset:54272
	ds_read_b128 v[192:195], v166 offset:55296
	ds_read_b128 v[198:201], v166 offset:56320
	global_load_lds_dwordx4 v[160:161], off
	v_lshl_add_u64 v[160:161], v[222:223], 0, s[46:47]
	s_mov_b32 m0, s31
	s_nop 0
	global_load_lds_dwordx4 v[160:161], off
	s_waitcnt vmcnt(10)
	s_setprio 1
	s_barrier
	s_waitcnt lgkmcnt(7)
	v_mfma_f32_16x16x32_bf16 v[76:79], v[56:59], v[168:171], v[76:79]
	v_mfma_f32_16x16x32_bf16 v[72:75], v[64:67], v[168:171], v[72:75]
	s_waitcnt lgkmcnt(5)
	v_mfma_f32_16x16x32_bf16 v[52:55], v[56:59], v[176:179], v[52:55]
	v_mfma_f32_16x16x32_bf16 v[48:51], v[64:67], v[176:179], v[48:51]
	s_waitcnt lgkmcnt(3)
	v_mfma_f32_16x16x32_bf16 v[28:31], v[56:59], v[184:187], v[28:31]
	v_mfma_f32_16x16x32_bf16 v[24:27], v[64:67], v[184:187], v[24:27]
	s_waitcnt lgkmcnt(1)
	v_mfma_f32_16x16x32_bf16 v[12:15], v[56:59], v[192:195], v[12:15]
	v_mfma_f32_16x16x32_bf16 v[8:11], v[64:67], v[192:195], v[8:11]
	v_mfma_f32_16x16x32_bf16 v[76:79], v[60:63], v[172:175], v[76:79]
	s_add_u32 s12, s12, 0x20080
	s_addc_u32 s13, s13, 0
	v_mfma_f32_16x16x32_bf16 v[72:75], v[68:71], v[172:175], v[72:75]
	s_add_i32 s14, s14, s22
	v_mfma_f32_16x16x32_bf16 v[52:55], v[60:63], v[180:183], v[52:55]
	v_mfma_f32_16x16x32_bf16 v[48:51], v[68:71], v[180:183], v[48:51]
	v_mfma_f32_16x16x32_bf16 v[28:31], v[60:63], v[188:191], v[28:31]
	v_mfma_f32_16x16x32_bf16 v[24:27], v[68:71], v[188:191], v[24:27]
	s_waitcnt lgkmcnt(0)
	v_mfma_f32_16x16x32_bf16 v[12:15], v[60:63], v[198:201], v[12:15]
	v_mfma_f32_16x16x32_bf16 v[8:11], v[68:71], v[198:201], v[8:11]
	s_barrier
	s_setprio 0
	s_mov_b32 m0, s14
	s_nop 0
	global_load_lds_dwordx4 v148, s[12:13]
	s_add_i32 m0, s14, 0x2000
	s_nop 0
	global_load_lds_dwordx4 v144, s[12:13]
	s_waitcnt vmcnt(6)
	s_setprio 1
	s_barrier
; DI unsigned pack2(float a, float b) { f32x2 v = {a, b}; hwbf16x2 r = __builtin_convertvector(v, hwbf16x2); return __builtin_bit_cast(unsigned, r); }
; DI float bflo(unsigned w) { return __uint_as_float(w << 16); }
; DI float bfhi(unsigned w) { return __uint_as_float(w & 0xffff0000u); }
; #define PG8_WAIT_V(n) asm volatile("s_waitcnt vmcnt(" #n ")" ::: "memory")
;     DI void operator()(const f32x4 (&acc)[2][2][4][2], const Unit& u, int wr, int wc, int fr, int fq) const {
;         const int row0 = u.pm * BM + wr * 64 + fr, col0 = u.pn * BM + wc * 32 + 8 * fq;
;         f32x4 sc[2][2];
; #pragma unroll
;         for (int bj = 0; bj < 2; ++bj)
; #pragma unroll
;             for (int n = 0; n < 2; ++n) sc[bj][n] = scale ? *(const f32x4*)(scale + col0 + bj * HALF + 4 * n) : (f32x4){1.f, 1.f, 1.f, 1.f};
; #pragma unroll
;         for (int ai = 0; ai < 2; ++ai)
; #pragma unroll
;             for (int m = 0; m < 4; ++m) { const size_t ro = (size_t)(row0 + ai * HALF + m * 16) * D + col0;
; #pragma unroll
;                 for (int bj = 0; bj < 2; ++bj) {
;                     f32x4 x0, x1;
;                     if constexpr (IB) { const u32x4 w = *(const u32x4*)((const bf16_t*)Xin + ro + bj * HALF);
;                         x0 = (f32x4){bflo(w[0]), bfhi(w[0]), bflo(w[1]), bfhi(w[1])}; x1 = (f32x4){bflo(w[2]), bfhi(w[2]), bflo(w[3]), bfhi(w[3])}; }
;                     else { x0 = *(const f32x4*)((const float*)Xin + ro + bj * HALF); x1 = *(const f32x4*)((const float*)Xin + ro + bj * HALF + 4); }
;                     x0 += acc[ai][bj][m][0] * sc[bj][0]; x1 += acc[ai][bj][m][1] * sc[bj][1];
;                     if constexpr (OB) { u32x4 o; o[0] = pack2(x0[0], x0[1]); o[1] = pack2(x0[2], x0[3]); o[2] = pack2(x1[0], x1[1]); o[3] = pack2(x1[2], x1[3]);
;                         *(u32x4*)((bf16_t*)Xout + ro + bj * HALF) = o; }
;                     else { *(f32x4*)((float*)Xout + ro + bj * HALF) = x0; *(f32x4*)((float*)Xout + ro + bj * HALF + 4) = x1; } } }
; template <class Map, class Epi>
; DI void gemm_phase(LAS unsigned char* lds, const Map& MP, const Epi& E, const int nM, const int nN, const int K, const int lda, const int ldb) {
;     ...
;             PG8_BAR; PG8_WAIT_L(0); PG8_MMA(1, 0, At, B0); PG8_BAR; PG8_SCHED;
;             PG8_STAGE(PG8_SB(1, 1), b3 + hstepB, voffB);
;             PG8_WAIT_V(6); PG8_BAR; PG8_MMA(1, 1, At, B1); PG8_BAR;
;         }
	v_mfma_f32_16x16x32_bf16 v[40:43], v[202:205], v[168:171], v[40:43]
	v_mfma_f32_16x16x32_bf16 v[68:71], v[206:209], v[172:175], v[40:43]
	v_mfma_f32_16x16x32_bf16 v[40:43], v[210:213], v[168:171], v[44:47]
	v_mfma_f32_16x16x32_bf16 v[36:39], v[202:205], v[176:179], v[36:39]
	v_mfma_f32_16x16x32_bf16 v[32:35], v[210:213], v[176:179], v[32:35]
	v_mfma_f32_16x16x32_bf16 v[20:23], v[202:205], v[184:187], v[20:23]
	v_mfma_f32_16x16x32_bf16 v[16:19], v[210:213], v[184:187], v[16:19]
	v_mfma_f32_16x16x32_bf16 v[4:7], v[202:205], v[192:195], v[4:7]
	v_mfma_f32_16x16x32_bf16 v[0:3], v[210:213], v[192:195], v[0:3]
	s_add_i32 s3, s3, 2
	v_mfma_f32_16x16x32_bf16 v[64:67], v[214:217], v[172:175], v[40:43]
	s_add_u32 s53, s53, 0x100
	s_addc_u32 s56, s56, 0
	ds_read_b128 v[40:43], v165
	ds_read_b128 v[44:47], v165 offset:1024
	ds_read_b128 v[56:59], v165 offset:2048
	ds_read_b128 v[60:63], v165 offset:3072
	v_mfma_f32_16x16x32_bf16 v[36:39], v[206:209], v[180:183], v[36:39]
	s_add_u32 s10, s10, 0x100
	s_addc_u32 s11, s11, 0
	v_mfma_f32_16x16x32_bf16 v[32:35], v[214:217], v[180:183], v[32:35]
	s_add_u32 s12, s10, 0xfff80080
	s_addc_u32 s13, s11, -1
	s_cmp_eq_u32 s3, 4
	s_cselect_b32 s15, s38, s13
	s_cselect_b32 s14, s39, s12
	s_cselect_b32 s13, s48, s56
	s_cselect_b32 s12, s49, s53
	s_cmp_gt_u32 s3, 5
	v_mfma_f32_16x16x32_bf16 v[20:23], v[206:209], v[188:191], v[20:23]
	v_mfma_f32_16x16x32_bf16 v[16:19], v[214:217], v[188:191], v[16:19]
	v_mfma_f32_16x16x32_bf16 v[4:7], v[206:209], v[198:201], v[4:7]
	v_mfma_f32_16x16x32_bf16 v[0:3], v[214:217], v[198:201], v[0:3]
	s_barrier
	s_setprio 0
	s_cbranch_scc0 .LBB1_2339
	s_waitcnt lgkmcnt(0)
	s_lshl_b32 s2, s2, 8
	v_mov_b32_e32 v40, v163
	v_mov_b32_e32 v168, v162
	s_or_b32 s2, s2, s29
	s_and_b64 vcc, exec, s[40:41]
	v_lshl_add_u32 v160, v40, 3, s2
	s_lshl_b32 s2, s8, 8
	s_add_i32 s2, s2, s28
	v_add_u32_e32 v168, s2, v168
	v_ashrrev_i32_e32 v169, 31, v168
	v_ashrrev_i32_e32 v161, 31, v160
	v_lshlrev_b64 v[168:169], 11, v[168:169]
	v_lshl_add_u64 v[44:45], v[160:161], 2, s[44:45]
	v_lshl_add_u64 v[160:161], v[168:169], 0, v[160:161]
	v_lshlrev_b64 v[160:161], 1, v[160:161]
	v_lshl_add_u64 v[172:173], s[4:5], 0, v[160:161]
	global_load_dwordx4 v[56:59], v[44:45], off offset:16
	global_load_dwordx4 v[60:63], v[44:45], off
	global_load_dwordx4 v[40:43], v[44:45], off offset:528
	s_nop 0
	global_load_dwordx4 v[44:47], v[44:45], off offset:512
	s_mov_b64 s[2:3], 0x10000
	global_load_dwordx4 v[178:181], v[172:173], off
	global_load_dwordx4 v[182:185], v[172:173], off offset:256
	s_mov_b64 s[98:99], 0x10000
	v_lshl_add_u64 v[170:171], v[172:173], 0, s[98:99]
	global_load_dwordx4 v[186:189], v[170:171], off
	global_load_dwordx4 v[190:193], v[170:171], off offset:256
	s_mov_b64 s[98:99], 0x20000
	v_lshl_add_u64 v[170:171], v[172:173], 0, s[98:99]
	global_load_dwordx4 v[198:201], v[170:171], off
	global_load_dwordx4 v[202:205], v[170:171], off offset:256
	s_mov_b64 s[98:99], 0x30000
	v_lshl_add_u64 v[170:171], v[172:173], 0, s[98:99]
	global_load_dwordx4 v[206:209], v[170:171], off
	global_load_dwordx4 v[210:213], v[170:171], off offset:256
	s_mov_b64 s[98:99], 0x80000
	v_lshl_add_u64 v[170:171], v[172:173], 0, s[98:99]
	global_load_dwordx4 v[214:217], v[170:171], off
	global_load_dwordx4 v[248:251], v[170:171], off offset:256
	s_mov_b64 s[98:99], 0x90000
	v_lshl_add_u64 v[170:171], v[172:173], 0, s[98:99]
	global_load_dwordx4 v[252:255], v[170:171], off
	s_waitcnt vmcnt(10)
	s_nop 1
	v_mov_b32_e32 v168, v178
	v_mov_b32_e32 v169, v179
	v_mov_b32_e32 v170, v180
	v_mov_b32_e32 v171, v181
	s_mov_b32 s8, s52
	s_mov_b64 s[10:11], s[54:55]
	s_mov_b64 s[12:13], s[6:7]
	s_waitcnt lgkmcnt(0)
	v_lshlrev_b32_e32 v174, 16, v168
	v_and_b32_e32 v175, 0xffff0000, v168
	v_lshlrev_b32_e32 v168, 16, v169
	v_and_b32_e32 v169, 0xffff0000, v169
	v_lshlrev_b32_e32 v176, 16, v170
	v_and_b32_e32 v177, 0xffff0000, v170
	v_lshlrev_b32_e32 v170, 16, v171
	v_and_b32_e32 v171, 0xffff0000, v171
	v_pk_fma_f32 v[142:143], v[142:143], v[62:63], v[168:169]
	v_pk_fma_f32 v[140:141], v[140:141], v[60:61], v[174:175]
	v_pk_fma_f32 v[168:169], v[138:139], v[58:59], v[170:171]
	v_pk_fma_f32 v[138:139], v[136:137], v[56:57], v[176:177]
	v_cvt_pk_bf16_f32 v136, v140, v141
	v_cvt_pk_bf16_f32 v137, v142, v143
	v_cvt_pk_bf16_f32 v138, v138, v139
	v_cvt_pk_bf16_f32 v139, v168, v169
	v_lshl_add_u64 v[140:141], s[42:43], 0, v[160:161]
	global_store_dwordx4 v[140:141], v[136:139], off
	s_waitcnt vmcnt(10)
	s_nop 1
	v_mov_b32_e32 v136, v182
	v_mov_b32_e32 v137, v183
	v_mov_b32_e32 v138, v184
	v_mov_b32_e32 v139, v185
	s_waitcnt lgkmcnt(0)
	v_lshlrev_b32_e32 v142, 16, v136
	v_and_b32_e32 v143, 0xffff0000, v136
	v_lshlrev_b32_e32 v136, 16, v137
	v_and_b32_e32 v137, 0xffff0000, v137
	v_lshlrev_b32_e32 v168, 16, v138
	v_and_b32_e32 v169, 0xffff0000, v138
	v_lshlrev_b32_e32 v138, 16, v139
	v_and_b32_e32 v139, 0xffff0000, v139
	v_pk_fma_f32 v[134:135], v[134:135], v[46:47], v[136:137]
	v_pk_fma_f32 v[132:133], v[132:133], v[44:45], v[142:143]
	v_pk_fma_f32 v[136:137], v[130:131], v[42:43], v[138:139]
	v_pk_fma_f32 v[130:131], v[128:129], v[40:41], v[168:169]
	v_cvt_pk_bf16_f32 v128, v132, v133
	v_cvt_pk_bf16_f32 v129, v134, v135
	v_cvt_pk_bf16_f32 v130, v130, v131
	v_cvt_pk_bf16_f32 v131, v136, v137
	v_lshl_add_u64 v[132:133], v[160:161], 0, s[2:3]
	global_store_dwordx4 v[140:141], v[128:131], off offset:256
	v_lshl_add_u64 v[134:135], s[4:5], 0, v[132:133]
	s_waitcnt vmcnt(10)
	s_nop 1
	v_mov_b32_e32 v128, v186
	v_mov_b32_e32 v129, v187
	v_mov_b32_e32 v130, v188
	v_mov_b32_e32 v131, v189
	s_mov_b64 s[2:3], 0x20000
	s_waitcnt lgkmcnt(0)
; DI unsigned pack2(float a, float b) { f32x2 v = {a, b}; hwbf16x2 r = __builtin_convertvector(v, hwbf16x2); return __builtin_bit_cast(unsigned, r); }
; DI float bflo(unsigned w) { return __uint_as_float(w << 16); }
; DI float bfhi(unsigned w) { return __uint_as_float(w & 0xffff0000u); }
;     DI void operator()(const f32x4 (&acc)[2][2][4][2], const Unit& u, int wr, int wc, int fr, int fq) const {
;     ...
;         for (int ai = 0; ai < 2; ++ai)
; #pragma unroll
;             for (int m = 0; m < 4; ++m) { const size_t ro = (size_t)(row0 + ai * HALF + m * 16) * D + col0;
; #pragma unroll
;                 for (int bj = 0; bj < 2; ++bj) {
;                     f32x4 x0, x1;
;                     if constexpr (IB) { const u32x4 w = *(const u32x4*)((const bf16_t*)Xin + ro + bj * HALF);
;                         x0 = (f32x4){bflo(w[0]), bfhi(w[0]), bflo(w[1]), bfhi(w[1])}; x1 = (f32x4){bflo(w[2]), bfhi(w[2]), bflo(w[3]), bfhi(w[3])}; }
;                     else { x0 = *(const f32x4*)((const float*)Xin + ro + bj * HALF); x1 = *(const f32x4*)((const float*)Xin + ro + bj * HALF + 4); }
;                     x0 += acc[ai][bj][m][0] * sc[bj][0]; x1 += acc[ai][bj][m][1] * sc[bj][1];
;                     if constexpr (OB) { u32x4 o; o[0] = pack2(x0[0], x0[1]); o[1] = pack2(x0[2], x0[3]); o[2] = pack2(x1[0], x1[1]); o[3] = pack2(x1[2], x1[3]);
;                         *(u32x4*)((bf16_t*)Xout + ro + bj * HALF) = o; }
;                     else { *(f32x4*)((float*)Xout + ro + bj * HALF) = x0; *(f32x4*)((float*)Xout + ro + bj * HALF + 4) = x1; } } }
	v_lshlrev_b32_e32 v136, 16, v128
	v_and_b32_e32 v137, 0xffff0000, v128
	v_lshlrev_b32_e32 v128, 16, v129
	v_and_b32_e32 v129, 0xffff0000, v129
	v_lshlrev_b32_e32 v138, 16, v130
	v_and_b32_e32 v139, 0xffff0000, v130
	v_lshlrev_b32_e32 v130, 16, v131
	v_and_b32_e32 v131, 0xffff0000, v131
	v_pk_fma_f32 v[126:127], v[126:127], v[62:63], v[128:129]
	v_pk_fma_f32 v[124:125], v[124:125], v[60:61], v[136:137]
	v_pk_fma_f32 v[128:129], v[122:123], v[58:59], v[130:131]
	v_pk_fma_f32 v[122:123], v[120:121], v[56:57], v[138:139]
	v_cvt_pk_bf16_f32 v120, v124, v125
	v_cvt_pk_bf16_f32 v121, v126, v127
	v_cvt_pk_bf16_f32 v122, v122, v123
	v_cvt_pk_bf16_f32 v123, v128, v129
	v_lshl_add_u64 v[124:125], s[42:43], 0, v[132:133]
	global_store_dwordx4 v[124:125], v[120:123], off
	s_waitcnt vmcnt(10)
	s_nop 1
	v_mov_b32_e32 v120, v190
	v_mov_b32_e32 v121, v191
	v_mov_b32_e32 v122, v192
	v_mov_b32_e32 v123, v193
	s_waitcnt lgkmcnt(0)
	v_lshlrev_b32_e32 v126, 16, v120
	v_and_b32_e32 v127, 0xffff0000, v120
	v_lshlrev_b32_e32 v120, 16, v121
	v_and_b32_e32 v121, 0xffff0000, v121
	v_lshlrev_b32_e32 v128, 16, v122
	v_and_b32_e32 v129, 0xffff0000, v122
	v_lshlrev_b32_e32 v122, 16, v123
	v_and_b32_e32 v123, 0xffff0000, v123
	v_pk_fma_f32 v[118:119], v[118:119], v[46:47], v[120:121]
	v_pk_fma_f32 v[116:117], v[116:117], v[44:45], v[126:127]
	v_pk_fma_f32 v[120:121], v[114:115], v[42:43], v[122:123]
	v_pk_fma_f32 v[114:115], v[112:113], v[40:41], v[128:129]
	v_cvt_pk_bf16_f32 v112, v116, v117
	v_cvt_pk_bf16_f32 v113, v118, v119
	v_cvt_pk_bf16_f32 v114, v114, v115
	v_cvt_pk_bf16_f32 v115, v120, v121
	v_lshl_add_u64 v[116:117], v[160:161], 0, s[2:3]
	global_store_dwordx4 v[124:125], v[112:115], off offset:256
	v_lshl_add_u64 v[118:119], s[4:5], 0, v[116:117]
	s_waitcnt vmcnt(10)
	s_nop 1
	v_mov_b32_e32 v112, v198
	v_mov_b32_e32 v113, v199
	v_mov_b32_e32 v114, v200
	v_mov_b32_e32 v115, v201
	s_mov_b64 s[2:3], 0x30000
	s_waitcnt lgkmcnt(0)
	v_lshlrev_b32_e32 v120, 16, v112
	v_and_b32_e32 v121, 0xffff0000, v112
	v_lshlrev_b32_e32 v112, 16, v113
	v_and_b32_e32 v113, 0xffff0000, v113
	v_lshlrev_b32_e32 v122, 16, v114
	v_and_b32_e32 v123, 0xffff0000, v114
	v_lshlrev_b32_e32 v114, 16, v115
	v_and_b32_e32 v115, 0xffff0000, v115
	v_pk_fma_f32 v[110:111], v[110:111], v[62:63], v[112:113]
	v_pk_fma_f32 v[108:109], v[108:109], v[60:61], v[120:121]
	v_pk_fma_f32 v[112:113], v[106:107], v[58:59], v[114:115]
	v_pk_fma_f32 v[106:107], v[104:105], v[56:57], v[122:123]
	v_cvt_pk_bf16_f32 v104, v108, v109
	v_cvt_pk_bf16_f32 v105, v110, v111
	v_cvt_pk_bf16_f32 v106, v106, v107
	v_cvt_pk_bf16_f32 v107, v112, v113
	v_lshl_add_u64 v[108:109], s[42:43], 0, v[116:117]
	global_store_dwordx4 v[108:109], v[104:107], off
	s_waitcnt vmcnt(10)
	s_nop 1
	v_mov_b32_e32 v104, v202
	v_mov_b32_e32 v105, v203
	v_mov_b32_e32 v106, v204
	v_mov_b32_e32 v107, v205
	s_waitcnt lgkmcnt(0)
	v_lshlrev_b32_e32 v110, 16, v104
	v_and_b32_e32 v111, 0xffff0000, v104
	v_lshlrev_b32_e32 v104, 16, v105
	v_and_b32_e32 v105, 0xffff0000, v105
	v_lshlrev_b32_e32 v112, 16, v106
	v_and_b32_e32 v113, 0xffff0000, v106
	v_lshlrev_b32_e32 v106, 16, v107
	v_and_b32_e32 v107, 0xffff0000, v107
	v_pk_fma_f32 v[102:103], v[102:103], v[46:47], v[104:105]
	v_pk_fma_f32 v[100:101], v[100:101], v[44:45], v[110:111]
	v_pk_fma_f32 v[104:105], v[98:99], v[42:43], v[106:107]
	v_pk_fma_f32 v[98:99], v[96:97], v[40:41], v[112:113]
	v_cvt_pk_bf16_f32 v96, v100, v101
	v_cvt_pk_bf16_f32 v97, v102, v103
	v_cvt_pk_bf16_f32 v98, v98, v99
	v_cvt_pk_bf16_f32 v99, v104, v105
	v_lshl_add_u64 v[100:101], v[160:161], 0, s[2:3]
	global_store_dwordx4 v[108:109], v[96:99], off offset:256
	v_lshl_add_u64 v[102:103], s[4:5], 0, v[100:101]
	s_waitcnt vmcnt(10)
	s_nop 1
	v_mov_b32_e32 v96, v206
	v_mov_b32_e32 v97, v207
	v_mov_b32_e32 v98, v208
	v_mov_b32_e32 v99, v209
	s_mov_b64 s[2:3], 0x80000
	s_waitcnt lgkmcnt(0)
	v_lshlrev_b32_e32 v104, 16, v96
	v_and_b32_e32 v105, 0xffff0000, v96
	v_lshlrev_b32_e32 v96, 16, v97
	v_and_b32_e32 v97, 0xffff0000, v97
	v_lshlrev_b32_e32 v106, 16, v98
	v_and_b32_e32 v107, 0xffff0000, v98
	v_lshlrev_b32_e32 v98, 16, v99
	v_and_b32_e32 v99, 0xffff0000, v99
	v_pk_fma_f32 v[94:95], v[94:95], v[62:63], v[96:97]
	v_pk_fma_f32 v[92:93], v[92:93], v[60:61], v[104:105]
	v_pk_fma_f32 v[96:97], v[90:91], v[58:59], v[98:99]
	v_pk_fma_f32 v[90:91], v[88:89], v[56:57], v[106:107]
	v_cvt_pk_bf16_f32 v88, v92, v93
	v_cvt_pk_bf16_f32 v89, v94, v95
	v_cvt_pk_bf16_f32 v90, v90, v91
	v_cvt_pk_bf16_f32 v91, v96, v97
	v_lshl_add_u64 v[92:93], s[42:43], 0, v[100:101]
	global_store_dwordx4 v[92:93], v[88:91], off
	s_waitcnt vmcnt(10)
	s_nop 1
	v_mov_b32_e32 v88, v210
	v_mov_b32_e32 v89, v211
	v_mov_b32_e32 v90, v212
	v_mov_b32_e32 v91, v213
	s_waitcnt lgkmcnt(0)
	v_lshlrev_b32_e32 v94, 16, v88
	v_and_b32_e32 v95, 0xffff0000, v88
	v_lshlrev_b32_e32 v88, 16, v89
	v_and_b32_e32 v89, 0xffff0000, v89
	v_lshlrev_b32_e32 v96, 16, v90
	v_and_b32_e32 v97, 0xffff0000, v90
	v_lshlrev_b32_e32 v90, 16, v91
	v_and_b32_e32 v91, 0xffff0000, v91
	v_pk_fma_f32 v[86:87], v[86:87], v[46:47], v[88:89]
	v_pk_fma_f32 v[84:85], v[84:85], v[44:45], v[94:95]
	v_pk_fma_f32 v[88:89], v[82:83], v[42:43], v[90:91]
	v_pk_fma_f32 v[82:83], v[80:81], v[40:41], v[96:97]
	v_cvt_pk_bf16_f32 v80, v84, v85
	v_cvt_pk_bf16_f32 v81, v86, v87
	v_cvt_pk_bf16_f32 v82, v82, v83
	v_cvt_pk_bf16_f32 v83, v88, v89
	v_lshl_add_u64 v[84:85], v[160:161], 0, s[2:3]
	global_store_dwordx4 v[92:93], v[80:83], off offset:256
	v_lshl_add_u64 v[86:87], s[4:5], 0, v[84:85]
	s_waitcnt vmcnt(10)
	s_nop 1
	v_mov_b32_e32 v80, v214
	v_mov_b32_e32 v81, v215
	v_mov_b32_e32 v82, v216
	v_mov_b32_e32 v83, v217
	s_mov_b64 s[2:3], 0x90000
	s_waitcnt lgkmcnt(0)
; DI unsigned pack2(float a, float b) { f32x2 v = {a, b}; hwbf16x2 r = __builtin_convertvector(v, hwbf16x2); return __builtin_bit_cast(unsigned, r); }
; DI float bflo(unsigned w) { return __uint_as_float(w << 16); }
; DI float bfhi(unsigned w) { return __uint_as_float(w & 0xffff0000u); }
;     DI const char* a(const Unit& u) const { return (const char*)(A + (size_t)u.pm * BM * lda); }
;     DI const char* a(const Unit& u) const { return (const char*)(A + (size_t)u.pm * BM * 2048 + (u.pn >> 1) * 512); }
;     DI void operator()(const f32x4 (&acc)[2][2][4][2], const Unit& u, int wr, int wc, int fr, int fq) const {
;     ...
;         for (int ai = 0; ai < 2; ++ai)
; #pragma unroll
;             for (int m = 0; m < 4; ++m) { const size_t ro = (size_t)(row0 + ai * HALF + m * 16) * D + col0;
; #pragma unroll
;                 for (int bj = 0; bj < 2; ++bj) {
;                     f32x4 x0, x1;
;                     if constexpr (IB) { const u32x4 w = *(const u32x4*)((const bf16_t*)Xin + ro + bj * HALF);
;                         x0 = (f32x4){bflo(w[0]), bfhi(w[0]), bflo(w[1]), bfhi(w[1])}; x1 = (f32x4){bflo(w[2]), bfhi(w[2]), bflo(w[3]), bfhi(w[3])}; }
;                     else { x0 = *(const f32x4*)((const float*)Xin + ro + bj * HALF); x1 = *(const f32x4*)((const float*)Xin + ro + bj * HALF + 4); }
;                     x0 += acc[ai][bj][m][0] * sc[bj][0]; x1 += acc[ai][bj][m][1] * sc[bj][1];
;                     if constexpr (OB) { u32x4 o; o[0] = pack2(x0[0], x0[1]); o[1] = pack2(x0[2], x0[3]); o[2] = pack2(x1[0], x1[1]); o[3] = pack2(x1[2], x1[3]);
;                         *(u32x4*)((bf16_t*)Xout + ro + bj * HALF) = o; }
;                     else { *(f32x4*)((float*)Xout + ro + bj * HALF) = x0; *(f32x4*)((float*)Xout + ro + bj * HALF + 4) = x1; } } }
; template <class Map, class Epi>
; DI void gemm_phase(LAS unsigned char* lds, const Map& MP, const Epi& E, const int nM, const int nN, const int K, const int lda, const int ldb) {
;     ...
;         if (!has_next) break;
; #pragma unroll
;         for (int a = 0; a < 2; ++a)
; #pragma unroll
;             for (int b = 0; b < 2; ++b)
; #pragma unroll
;                 for (int m = 0; m < 4; ++m)
; #pragma unroll
;                     for (int n = 0; n < 2; ++n) acc[a][b][m][n] = (f32x4){0.f, 0.f, 0.f, 0.f};
;         cur = nxt; cA = nA; cB = nB; ++ui;
;     }
;     PG8_WAIT_V(0);
;     if (wr == 0) PG8_BAR;
;     PG8_BAR;
	v_lshlrev_b32_e32 v88, 16, v80
	v_and_b32_e32 v89, 0xffff0000, v80
	v_lshlrev_b32_e32 v80, 16, v81
	v_and_b32_e32 v81, 0xffff0000, v81
	v_lshlrev_b32_e32 v90, 16, v82
	v_and_b32_e32 v91, 0xffff0000, v82
	v_lshlrev_b32_e32 v82, 16, v83
	v_and_b32_e32 v83, 0xffff0000, v83
	v_pk_fma_f32 v[78:79], v[78:79], v[62:63], v[80:81]
	v_pk_fma_f32 v[76:77], v[76:77], v[60:61], v[88:89]
	v_pk_fma_f32 v[80:81], v[74:75], v[58:59], v[82:83]
	v_pk_fma_f32 v[74:75], v[72:73], v[56:57], v[90:91]
	v_cvt_pk_bf16_f32 v72, v76, v77
	v_cvt_pk_bf16_f32 v73, v78, v79
	v_cvt_pk_bf16_f32 v74, v74, v75
	v_cvt_pk_bf16_f32 v75, v80, v81
	v_lshl_add_u64 v[76:77], s[42:43], 0, v[84:85]
	global_store_dwordx4 v[76:77], v[72:75], off
	s_waitcnt vmcnt(10)
	s_nop 1
	v_mov_b32_e32 v72, v248
	v_mov_b32_e32 v73, v249
	v_mov_b32_e32 v74, v250
	v_mov_b32_e32 v75, v251
	s_waitcnt lgkmcnt(0)
	v_lshlrev_b32_e32 v78, 16, v72
	v_and_b32_e32 v79, 0xffff0000, v72
	v_lshlrev_b32_e32 v72, 16, v73
	v_and_b32_e32 v73, 0xffff0000, v73
	v_lshlrev_b32_e32 v80, 16, v74
	v_and_b32_e32 v81, 0xffff0000, v74
	v_lshlrev_b32_e32 v74, 16, v75
	v_and_b32_e32 v75, 0xffff0000, v75
	v_pk_fma_f32 v[70:71], v[70:71], v[46:47], v[72:73]
	v_pk_fma_f32 v[68:69], v[68:69], v[44:45], v[78:79]
	v_pk_fma_f32 v[72:73], v[66:67], v[42:43], v[74:75]
	v_pk_fma_f32 v[66:67], v[64:65], v[40:41], v[80:81]
	v_cvt_pk_bf16_f32 v64, v68, v69
	v_cvt_pk_bf16_f32 v65, v70, v71
	v_cvt_pk_bf16_f32 v66, v66, v67
	v_cvt_pk_bf16_f32 v67, v72, v73
	v_lshl_add_u64 v[68:69], v[160:161], 0, s[2:3]
	global_store_dwordx4 v[76:77], v[64:67], off offset:256
	v_lshl_add_u64 v[70:71], s[4:5], 0, v[68:69]
	s_waitcnt vmcnt(10)
	s_nop 1
	v_mov_b32_e32 v64, v252
	v_mov_b32_e32 v65, v253
	v_mov_b32_e32 v66, v254
	v_mov_b32_e32 v67, v255
	s_mov_b64 s[2:3], 0xa0000
	s_waitcnt lgkmcnt(0)
	v_lshlrev_b32_e32 v72, 16, v64
	v_and_b32_e32 v73, 0xffff0000, v64
	v_lshlrev_b32_e32 v64, 16, v65
	v_and_b32_e32 v65, 0xffff0000, v65
	v_lshlrev_b32_e32 v74, 16, v66
	v_and_b32_e32 v75, 0xffff0000, v66
	v_lshlrev_b32_e32 v66, 16, v67
	v_and_b32_e32 v67, 0xffff0000, v67
	v_pk_fma_f32 v[54:55], v[54:55], v[62:63], v[64:65]
	v_pk_fma_f32 v[52:53], v[52:53], v[60:61], v[72:73]
	v_pk_fma_f32 v[64:65], v[50:51], v[58:59], v[66:67]
	v_pk_fma_f32 v[50:51], v[48:49], v[56:57], v[74:75]
	v_cvt_pk_bf16_f32 v48, v52, v53
	v_cvt_pk_bf16_f32 v49, v54, v55
	v_cvt_pk_bf16_f32 v50, v50, v51
	v_cvt_pk_bf16_f32 v51, v64, v65
	v_lshl_add_u64 v[52:53], s[42:43], 0, v[68:69]
	global_store_dwordx4 v[52:53], v[48:51], off
	global_load_dwordx4 v[48:51], v[70:71], off offset:256
	s_waitcnt vmcnt(0) lgkmcnt(0)
	v_lshlrev_b32_e32 v54, 16, v48
	v_and_b32_e32 v55, 0xffff0000, v48
	v_lshlrev_b32_e32 v48, 16, v49
	v_and_b32_e32 v49, 0xffff0000, v49
	v_lshlrev_b32_e32 v64, 16, v50
	v_and_b32_e32 v65, 0xffff0000, v50
	v_lshlrev_b32_e32 v50, 16, v51
	v_and_b32_e32 v51, 0xffff0000, v51
	v_pk_fma_f32 v[38:39], v[38:39], v[46:47], v[48:49]
	v_pk_fma_f32 v[36:37], v[36:37], v[44:45], v[54:55]
	v_pk_fma_f32 v[48:49], v[34:35], v[42:43], v[50:51]
	v_pk_fma_f32 v[34:35], v[32:33], v[40:41], v[64:65]
	v_cvt_pk_bf16_f32 v32, v36, v37
	v_cvt_pk_bf16_f32 v33, v38, v39
	v_cvt_pk_bf16_f32 v34, v34, v35
	v_cvt_pk_bf16_f32 v35, v48, v49
	v_lshl_add_u64 v[36:37], v[160:161], 0, s[2:3]
	global_store_dwordx4 v[52:53], v[32:35], off offset:256
	v_lshl_add_u64 v[38:39], s[4:5], 0, v[36:37]
	global_load_dwordx4 v[32:35], v[38:39], off
	s_mov_b64 s[2:3], 0xb0000
	s_waitcnt vmcnt(0) lgkmcnt(0)
	v_lshlrev_b32_e32 v48, 16, v32
	v_and_b32_e32 v49, 0xffff0000, v32
	v_lshlrev_b32_e32 v32, 16, v33
	v_and_b32_e32 v33, 0xffff0000, v33
	v_lshlrev_b32_e32 v50, 16, v34
	v_and_b32_e32 v51, 0xffff0000, v34
	v_lshlrev_b32_e32 v34, 16, v35
	v_and_b32_e32 v35, 0xffff0000, v35
	v_pk_fma_f32 v[30:31], v[30:31], v[62:63], v[32:33]
	v_pk_fma_f32 v[28:29], v[28:29], v[60:61], v[48:49]
	v_pk_fma_f32 v[32:33], v[26:27], v[58:59], v[34:35]
	v_pk_fma_f32 v[26:27], v[24:25], v[56:57], v[50:51]
	v_cvt_pk_bf16_f32 v24, v28, v29
	v_cvt_pk_bf16_f32 v25, v30, v31
	v_cvt_pk_bf16_f32 v26, v26, v27
	v_cvt_pk_bf16_f32 v27, v32, v33
	v_lshl_add_u64 v[28:29], s[42:43], 0, v[36:37]
	global_store_dwordx4 v[28:29], v[24:27], off
	global_load_dwordx4 v[24:27], v[38:39], off offset:256
	s_waitcnt vmcnt(0) lgkmcnt(0)
	v_lshlrev_b32_e32 v30, 16, v24
	v_and_b32_e32 v31, 0xffff0000, v24
	v_lshlrev_b32_e32 v24, 16, v25
	v_and_b32_e32 v25, 0xffff0000, v25
	v_lshlrev_b32_e32 v32, 16, v26
	v_and_b32_e32 v33, 0xffff0000, v26
	v_lshlrev_b32_e32 v26, 16, v27
	v_and_b32_e32 v27, 0xffff0000, v27
	v_pk_fma_f32 v[22:23], v[22:23], v[46:47], v[24:25]
	v_pk_fma_f32 v[20:21], v[20:21], v[44:45], v[30:31]
	v_pk_fma_f32 v[24:25], v[18:19], v[42:43], v[26:27]
	v_pk_fma_f32 v[18:19], v[16:17], v[40:41], v[32:33]
	v_cvt_pk_bf16_f32 v16, v20, v21
	v_cvt_pk_bf16_f32 v17, v22, v23
	v_cvt_pk_bf16_f32 v18, v18, v19
	v_cvt_pk_bf16_f32 v19, v24, v25
	v_lshl_add_u64 v[20:21], v[160:161], 0, s[2:3]
	global_store_dwordx4 v[28:29], v[16:19], off offset:256
	v_lshl_add_u64 v[22:23], s[4:5], 0, v[20:21]
	global_load_dwordx4 v[16:19], v[22:23], off
	s_mov_b32 s2, s37
	s_waitcnt vmcnt(0) lgkmcnt(0)
	v_lshlrev_b32_e32 v24, 16, v16
	v_and_b32_e32 v25, 0xffff0000, v16
	v_lshlrev_b32_e32 v16, 16, v17
	v_and_b32_e32 v17, 0xffff0000, v17
	v_lshlrev_b32_e32 v26, 16, v18
	v_and_b32_e32 v27, 0xffff0000, v18
	v_lshlrev_b32_e32 v18, 16, v19
	v_and_b32_e32 v19, 0xffff0000, v19
	v_pk_fma_f32 v[14:15], v[14:15], v[62:63], v[16:17]
	v_pk_fma_f32 v[12:13], v[12:13], v[60:61], v[24:25]
	v_pk_fma_f32 v[16:17], v[10:11], v[58:59], v[18:19]
	v_pk_fma_f32 v[10:11], v[8:9], v[56:57], v[26:27]
	v_cvt_pk_bf16_f32 v8, v12, v13
	v_cvt_pk_bf16_f32 v9, v14, v15
	v_cvt_pk_bf16_f32 v10, v10, v11
	v_cvt_pk_bf16_f32 v11, v16, v17
	v_lshl_add_u64 v[12:13], s[42:43], 0, v[20:21]
	global_store_dwordx4 v[12:13], v[8:11], off
	global_load_dwordx4 v[8:11], v[22:23], off offset:256
	s_waitcnt vmcnt(0) lgkmcnt(0)
	v_lshlrev_b32_e32 v14, 16, v8
	v_and_b32_e32 v15, 0xffff0000, v8
	v_lshlrev_b32_e32 v8, 16, v9
	v_and_b32_e32 v9, 0xffff0000, v9
	v_lshlrev_b32_e32 v16, 16, v10
	v_and_b32_e32 v17, 0xffff0000, v10
	v_lshlrev_b32_e32 v10, 16, v11
	v_and_b32_e32 v11, 0xffff0000, v11
	v_pk_fma_f32 v[6:7], v[6:7], v[46:47], v[8:9]
	v_pk_fma_f32 v[4:5], v[4:5], v[44:45], v[14:15]
	v_pk_fma_f32 v[8:9], v[2:3], v[42:43], v[10:11]
	v_pk_fma_f32 v[2:3], v[0:1], v[40:41], v[16:17]
	v_cvt_pk_bf16_f32 v0, v4, v5
	v_cvt_pk_bf16_f32 v1, v6, v7
	v_cvt_pk_bf16_f32 v2, v2, v3
	v_cvt_pk_bf16_f32 v3, v8, v9
	global_store_dwordx4 v[12:13], v[0:3], off offset:256
	s_cbranch_vccz .LBB1_2336
	s_waitcnt vmcnt(0)
	s_cmpk_gt_u32 s17, 0xff
	s_cbranch_scc1 .LBB1_2343
	s_barrier

;     DI const char* a(const Unit& u) const { return (const char*)(A + (size_t)u.pm * BM * lda); }
;     DI const char* a(const Unit& u) const { return (const char*)(A + (size_t)u.pm * BM * 2048 + (u.pn >> 1) * 512); }
;     DI const char* a(const Unit& u) const { return (const char*)((u.pn < 12 ? A1 : A2) + (size_t)u.pm * BM * 512); }
; #define PG8_STAGE(bufoff, gbase, voff) do { _Pragma("unroll") for (int _i = 0; _i < 2; ++_i) \
;         __builtin_amdgcn_global_load_lds((const unsigned*)((const char*)(gbase) + (voff)[_i]), (LAS unsigned*)(lds + (bufoff) + ldsw + _i * 8192), 16, 0, 0); } while (0)
; #define PG8_LDA(dst, b, h) do { _Pragma("unroll") for (int m = 0; m < 4; ++m) _Pragma("unroll") for (int k = 0; k < 2; ++k) dst[m][k] = *(const LAS bf16x8*)(lds + PG8_SA(b, h) + aoff + m * 2048 + k * 1024); } while (0)
; #define PG8_WAIT_L(n) asm volatile("s_waitcnt lgkmcnt(" #n ")" ::: "memory")
; #define PG8_BAR __builtin_amdgcn_s_barrier()
; #define PG8_SCHED __builtin_amdgcn_sched_barrier(0)
; template <class Map, class Epi>
; DI void gemm_phase(LAS unsigned char* lds, const Map& MP, const Epi& E, const int nM, const int nN, const int K, const int lda, const int ldb) {
;     ...
;         const bool has_next = sched_next(ui + 1, nM, nN, G, cblk, nxt);
;         const char* nA = has_next ? MP.a(nxt) : cA; const char* nB = has_next ? MP.b(nxt) : cB;
;         for (int t = 0; t < nt; t += 2) {
;             const bool last = (t == nt - 2);
;             const char* a1 = cA + (size_t)(t + 1) * kstep;
;             const char* a2 = last ? nA : cA + (size_t)(t + 2) * kstep; const char* b2 = last ? nB : cB + (size_t)(t + 2) * kstep;
;             const char* a3 = a2 + kstep; const char* b3 = b2 + kstep;
;             PG8_LDB(B0, 0, 0); PG8_SCHED; PG8_LDA(At, 0, 0); PG8_STAGE(PG8_SA(1, 1), a1 + hstepA, voffA);
;             PG8_WAIT_L(8); PG8_BAR; PG8_WAIT_L(0); PG8_MMA(0, 0, At, B0); PG8_BAR; PG8_SCHED;
;             PG8_LDB(B1, 0, 1); PG8_STAGE(PG8_SB(0, 0), b2, voffB);
;             PG8_BAR; PG8_WAIT_L(0); PG8_MMA(0, 1, At, B1); PG8_BAR;
;     ...
; #pragma unroll
;         for (int a = 0; a < 2; ++a)
; #pragma unroll
;             for (int b = 0; b < 2; ++b)
; #pragma unroll
;                 for (int m = 0; m < 4; ++m)
; #pragma unroll
;                     for (int n = 0; n < 2; ++n) acc[a][b][m][n] = (f32x4){0.f, 0.f, 0.f, 0.f};
;         cur = nxt; cA = nA; cB = nB; ++ui;
.LBB1_2482:
	s_ashr_i32 s23, s22, 31
	v_cmp_lt_i64_e32 vcc, s[24:25], v[180:181]
	s_lshl_b64 s[24:25], s[22:23], 20
	s_add_u32 s24, s33, s24
	s_addc_u32 s25, s34, s25
	s_and_b64 s[26:27], vcc, exec
	s_cselect_b32 s23, s25, s29
	s_cselect_b32 s58, s24, s28
	s_ashr_i32 s21, s20, 31
	s_lshl_b64 s[26:27], s[20:21], 20
	s_add_u32 s26, s35, s26
	s_addc_u32 s27, s36, s27
	s_and_b64 s[42:43], vcc, exec
	s_cselect_b32 s21, s27, s47
	s_cselect_b32 s59, s26, s46
	s_add_u32 vcc_lo, s46, 0x100
	s_addc_u32 vcc_hi, s47, 0
	s_add_u32 s42, s28, 0x80080
	v_mov_b32_e32 v0, 0
	s_addc_u32 s43, s29, 0
	s_mov_b32 s3, -2
	v_mov_b32_e32 v1, 0
	v_mov_b64_e32 v[2:3], 0
	v_mov_b64_e32 v[4:5], 0
	v_mov_b64_e32 v[6:7], 0
	v_mov_b64_e32 v[8:9], 0
	v_mov_b64_e32 v[10:11], 0
	v_mov_b64_e32 v[12:13], 0
	v_mov_b64_e32 v[14:15], 0
	v_mov_b64_e32 v[16:17], 0
	v_mov_b64_e32 v[18:19], 0
	v_mov_b64_e32 v[20:21], 0
	v_mov_b64_e32 v[22:23], 0
	v_mov_b64_e32 v[24:25], 0
	v_mov_b64_e32 v[26:27], 0
	v_mov_b64_e32 v[28:29], 0
	v_mov_b64_e32 v[30:31], 0
	v_mov_b64_e32 v[32:33], 0
	v_mov_b64_e32 v[34:35], 0
	v_mov_b64_e32 v[36:37], 0
	v_mov_b64_e32 v[38:39], 0
	v_mov_b64_e32 v[40:41], 0
	v_mov_b64_e32 v[42:43], 0
	v_mov_b64_e32 v[44:45], 0
	v_mov_b64_e32 v[46:47], 0
	v_mov_b64_e32 v[48:49], 0
	v_mov_b64_e32 v[50:51], 0
	v_mov_b64_e32 v[52:53], 0
	v_mov_b64_e32 v[54:55], 0
	v_mov_b64_e32 v[56:57], 0
	v_mov_b64_e32 v[58:59], 0
	v_mov_b64_e32 v[60:61], 0
	v_mov_b64_e32 v[62:63], 0
	v_mov_b64_e32 v[64:65], 0
	v_mov_b64_e32 v[66:67], 0
	v_mov_b64_e32 v[68:69], 0
	v_mov_b64_e32 v[70:71], 0
	v_mov_b64_e32 v[72:73], 0
	v_mov_b64_e32 v[74:75], 0
	v_mov_b64_e32 v[76:77], 0
	v_mov_b64_e32 v[78:79], 0
	v_mov_b64_e32 v[104:105], 0
	v_mov_b64_e32 v[106:107], 0
	v_mov_b64_e32 v[116:117], 0
	v_mov_b64_e32 v[118:119], 0
	v_mov_b64_e32 v[120:121], 0
	v_mov_b64_e32 v[122:123], 0
	v_mov_b64_e32 v[124:125], 0
	v_mov_b64_e32 v[126:127], 0
	v_mov_b64_e32 v[128:129], 0
	v_mov_b64_e32 v[130:131], 0
	v_mov_b64_e32 v[132:133], 0
	v_mov_b64_e32 v[134:135], 0
	v_mov_b64_e32 v[136:137], 0
	v_mov_b64_e32 v[138:139], 0
	v_mov_b64_e32 v[140:141], 0
	v_mov_b64_e32 v[142:143], 0
	v_mov_b64_e32 v[144:145], 0
	v_mov_b64_e32 v[146:147], 0
	v_mov_b64_e32 v[148:149], 0
	v_mov_b64_e32 v[150:151], 0
	v_mov_b64_e32 v[152:153], 0
	v_mov_b64_e32 v[154:155], 0
	v_mov_b64_e32 v[156:157], 0
	v_mov_b64_e32 v[158:159], 0
	ds_read_b128 v[80:83], v189
	ds_read_b128 v[84:87], v189 offset:1024
	ds_read_b128 v[88:91], v189 offset:2048
	ds_read_b128 v[92:95], v189 offset:3072
	s_add_u32 s28, s42, 0xfff80080
	s_addc_u32 s29, s43, -1
	s_cmp_eq_u32 s3, 28
	s_cselect_b32 s47, s23, s29
	s_cselect_b32 s46, s58, s28
	s_cselect_b32 s29, s21, vcc_hi
	s_cselect_b32 s28, s59, vcc_lo
.LBB1_2483:
	s_add_i32 m0, s38, 0xc000
	ds_read_b128 v[96:99], v190
	ds_read_b128 v[100:103], v190 offset:1024
	ds_read_b128 v[108:111], v190 offset:2048
	ds_read_b128 v[112:115], v190 offset:3072
	ds_read_b128 v[160:163], v190 offset:4096
	ds_read_b128 v[164:167], v190 offset:5120
	ds_read_b128 v[198:201], v190 offset:6144
	ds_read_b128 v[202:205], v190 offset:7168
	global_load_lds_dwordx4 v178, s[42:43]
	s_add_i32 m0, s38, 0xe000
	s_nop 0
	global_load_lds_dwordx4 v176, s[42:43]
	s_waitcnt lgkmcnt(8)
	s_setprio 1
	s_barrier
	s_waitcnt lgkmcnt(7)
	v_mfma_f32_16x16x32_bf16 v[148:151], v[80:83], v[96:99], v[148:151]
	v_mfma_f32_16x16x32_bf16 v[144:147], v[88:91], v[96:99], v[144:147]
	s_waitcnt lgkmcnt(5)
	v_mfma_f32_16x16x32_bf16 v[136:139], v[80:83], v[108:111], v[136:139]
	v_mfma_f32_16x16x32_bf16 v[128:131], v[88:91], v[108:111], v[128:131]
	s_waitcnt lgkmcnt(3)
	v_mfma_f32_16x16x32_bf16 v[120:123], v[80:83], v[160:163], v[120:123]
	v_mfma_f32_16x16x32_bf16 v[104:107], v[88:91], v[160:163], v[104:107]
	s_waitcnt lgkmcnt(1)
	v_mfma_f32_16x16x32_bf16 v[76:79], v[80:83], v[198:201], v[76:79]
	v_mfma_f32_16x16x32_bf16 v[72:75], v[88:91], v[198:201], v[72:75]
	v_mfma_f32_16x16x32_bf16 v[148:151], v[84:87], v[100:103], v[148:151]
	s_add_i32 s68, s2, s37
	v_mfma_f32_16x16x32_bf16 v[144:147], v[92:95], v[100:103], v[144:147]
	v_lshl_add_u64 v[184:185], s[28:29], 0, v[172:173]
	v_mfma_f32_16x16x32_bf16 v[136:139], v[84:87], v[112:115], v[136:139]
	v_lshl_add_u64 v[194:195], s[28:29], 0, v[168:169]
	v_mfma_f32_16x16x32_bf16 v[128:131], v[92:95], v[112:115], v[128:131]
	v_mfma_f32_16x16x32_bf16 v[120:123], v[84:87], v[164:167], v[120:123]
	v_mfma_f32_16x16x32_bf16 v[104:107], v[92:95], v[164:167], v[104:107]
	s_waitcnt lgkmcnt(0)
	v_mfma_f32_16x16x32_bf16 v[76:79], v[84:87], v[202:205], v[76:79]
	v_mfma_f32_16x16x32_bf16 v[72:75], v[92:95], v[202:205], v[72:75]
	s_barrier
	s_setprio 0
	s_mov_b32 m0, s68
	ds_read_b128 v[206:209], v191
	ds_read_b128 v[210:213], v191 offset:1024
	ds_read_b128 v[214:217], v191 offset:2048
	ds_read_b128 v[218:221], v191 offset:3072
	global_load_lds_dwordx4 v[184:185], off
	s_add_i32 m0, s68, 0x2000
	s_nop 0
	global_load_lds_dwordx4 v[194:195], off
	s_setprio 1
	s_barrier
	s_waitcnt lgkmcnt(3)
	v_mfma_f32_16x16x32_bf16 v[156:159], v[206:209], v[96:99], v[156:159]
	s_waitcnt lgkmcnt(1)
	v_mfma_f32_16x16x32_bf16 v[96:99], v[214:217], v[96:99], v[152:155]
	v_mfma_f32_16x16x32_bf16 v[156:159], v[210:213], v[100:103], v[156:159]
	s_waitcnt lgkmcnt(0)
	v_mfma_f32_16x16x32_bf16 v[96:99], v[218:221], v[100:103], v[96:99]
	v_mfma_f32_16x16x32_bf16 v[100:103], v[206:209], v[108:111], v[140:143]
	v_mfma_f32_16x16x32_bf16 v[108:111], v[214:217], v[108:111], v[132:135]
	v_mfma_f32_16x16x32_bf16 v[116:119], v[214:217], v[160:163], v[116:119]
	v_mfma_f32_16x16x32_bf16 v[68:71], v[206:209], v[198:201], v[68:71]
	v_mfma_f32_16x16x32_bf16 v[64:67], v[214:217], v[198:201], v[64:67]
	v_lshl_add_u64 v[232:233], s[46:47], 0, v[170:171]
	s_mov_b32 m0, s38
	v_mfma_f32_16x16x32_bf16 v[100:103], v[210:213], v[112:115], v[100:103]
	v_lshl_add_u64 v[230:231], s[46:47], 0, v[174:175]
	v_mfma_f32_16x16x32_bf16 v[108:111], v[218:221], v[112:115], v[108:111]
	v_mfma_f32_16x16x32_bf16 v[112:115], v[206:209], v[160:163], v[124:127]
	v_mfma_f32_16x16x32_bf16 v[116:119], v[218:221], v[164:167], v[116:119]
	v_mfma_f32_16x16x32_bf16 v[68:71], v[210:213], v[202:205], v[68:71]
	v_mfma_f32_16x16x32_bf16 v[64:67], v[218:221], v[202:205], v[64:67]
	v_mfma_f32_16x16x32_bf16 v[112:115], v[210:213], v[164:167], v[112:115]
	s_barrier
; #define PG8_STAGE(bufoff, gbase, voff) do { _Pragma("unroll") for (int _i = 0; _i < 2; ++_i) \
;         __builtin_amdgcn_global_load_lds((const unsigned*)((const char*)(gbase) + (voff)[_i]), (LAS unsigned*)(lds + (bufoff) + ldsw + _i * 8192), 16, 0, 0); } while (0)
; #define PG8_LDA(dst, b, h) do { _Pragma("unroll") for (int m = 0; m < 4; ++m) _Pragma("unroll") for (int k = 0; k < 2; ++k) dst[m][k] = *(const LAS bf16x8*)(lds + PG8_SA(b, h) + aoff + m * 2048 + k * 1024); } while (0)
; #define PG8_LDB(dst, b, h) do { _Pragma("unroll") for (int n = 0; n < 2; ++n) _Pragma("unroll") for (int k = 0; k < 2; ++k) dst[n][k] = *(const LAS bf16x8*)(lds + PG8_SB(b, h) + boff + n * 2048 + k * 1024); } while (0)
; #define PG8_MMA(ai, bj, At, Bt) do { __builtin_amdgcn_s_setprio(1); _Pragma("unroll") for (int m = 0; m < 4; ++m) _Pragma("unroll") for (int n = 0; n < 2; ++n) _Pragma("unroll") for (int k = 0; k < 2; ++k) \
;         acc[ai][bj][m][n] = __builtin_amdgcn_mfma_f32_16x16x32_bf16(Bt[n][k], At[m][k], acc[ai][bj][m][n], 0, 0, 0); __builtin_amdgcn_s_setprio(0); } while (0)
; #define PG8_WAIT_V(n) asm volatile("s_waitcnt vmcnt(" #n ")" ::: "memory")
; #define PG8_WAIT_L(n) asm volatile("s_waitcnt lgkmcnt(" #n ")" ::: "memory")
; #define PG8_BAR __builtin_amdgcn_s_barrier()
; #define PG8_SCHED __builtin_amdgcn_sched_barrier(0)
; template <class Map, class Epi>
; DI void gemm_phase(LAS unsigned char* lds, const Map& MP, const Epi& E, const int nM, const int nN, const int K, const int lda, const int ldb) {
;     ...
;             PG8_BAR; PG8_WAIT_L(0); PG8_MMA(0, 1, At, B1); PG8_BAR;
;             PG8_LDA(At, 0, 1); PG8_STAGE(PG8_SA(0, 0), a2, voffA);
;             PG8_BAR; PG8_WAIT_L(0); PG8_MMA(1, 0, At, B0); PG8_BAR; PG8_SCHED;
;             PG8_STAGE(PG8_SB(0, 1), b2 + hstepB, voffB);
;             PG8_WAIT_V(6); PG8_BAR; PG8_MMA(1, 1, At, B1); PG8_BAR;
;             PG8_LDB(B0, 1, 0); PG8_SCHED; PG8_LDA(At, 1, 0); PG8_STAGE(PG8_SA(0, 1), a2 + hstepA, voffA);
;             PG8_WAIT_L(8); PG8_BAR; PG8_WAIT_L(0); PG8_MMA(0, 0, At, B0); PG8_BAR; PG8_SCHED;
;             PG8_LDB(B1, 1, 1); PG8_STAGE(PG8_SB(1, 0), b3, voffB);
	s_setprio 0
	ds_read_b128 v[124:127], v190 offset:16384
	ds_read_b128 v[132:135], v190 offset:17408
	ds_read_b128 v[140:143], v190 offset:18432
	ds_read_b128 v[152:155], v190 offset:19456
	ds_read_b128 v[160:163], v190 offset:20480
	ds_read_b128 v[164:167], v190 offset:21504
	ds_read_b128 v[198:201], v190 offset:22528
	ds_read_b128 v[202:205], v190 offset:23552
	global_load_lds_dwordx4 v[230:231], off
	s_mov_b32 m0, s39
	s_nop 0
	global_load_lds_dwordx4 v[232:233], off
	s_waitcnt vmcnt(10)
	s_setprio 1
	s_barrier
	s_waitcnt lgkmcnt(7)
	v_mfma_f32_16x16x32_bf16 v[60:63], v[80:83], v[124:127], v[60:63]
	v_mfma_f32_16x16x32_bf16 v[48:51], v[88:91], v[124:127], v[48:51]
	s_waitcnt lgkmcnt(5)
	v_mfma_f32_16x16x32_bf16 v[40:43], v[80:83], v[140:143], v[40:43]
	v_mfma_f32_16x16x32_bf16 v[32:35], v[88:91], v[140:143], v[32:35]
	s_waitcnt lgkmcnt(3)
	v_mfma_f32_16x16x32_bf16 v[24:27], v[80:83], v[160:163], v[24:27]
	v_mfma_f32_16x16x32_bf16 v[16:19], v[88:91], v[160:163], v[16:19]
	s_waitcnt lgkmcnt(1)
	v_mfma_f32_16x16x32_bf16 v[12:15], v[80:83], v[198:201], v[12:15]
	v_mfma_f32_16x16x32_bf16 v[8:11], v[88:91], v[198:201], v[8:11]
	v_mfma_f32_16x16x32_bf16 v[60:63], v[84:87], v[132:135], v[60:63]
	s_add_u32 s68, s28, 0x80000
	s_addc_u32 s69, s29, 0
	v_mfma_f32_16x16x32_bf16 v[48:51], v[92:95], v[132:135], v[48:51]
	s_add_i32 s70, s67, s37
	v_mfma_f32_16x16x32_bf16 v[40:43], v[84:87], v[152:155], v[40:43]
	v_mfma_f32_16x16x32_bf16 v[32:35], v[92:95], v[152:155], v[32:35]
	v_mfma_f32_16x16x32_bf16 v[24:27], v[84:87], v[164:167], v[24:27]
	v_mfma_f32_16x16x32_bf16 v[16:19], v[92:95], v[164:167], v[16:19]
	s_waitcnt lgkmcnt(0)
	v_mfma_f32_16x16x32_bf16 v[12:15], v[84:87], v[202:205], v[12:15]
	v_mfma_f32_16x16x32_bf16 v[8:11], v[92:95], v[202:205], v[8:11]
	s_barrier
	s_setprio 0
	s_mov_b32 m0, s70
	s_nop 0
	global_load_lds_dwordx4 v172, s[68:69]
	s_add_i32 m0, s70, 0x2000
	s_nop 0
	global_load_lds_dwordx4 v168, s[68:69]
	s_waitcnt vmcnt(6)
	s_setprio 1
	s_barrier
	v_mfma_f32_16x16x32_bf16 v[56:59], v[206:209], v[124:127], v[56:59]
	v_mfma_f32_16x16x32_bf16 v[52:55], v[214:217], v[124:127], v[52:55]
	s_add_i32 s68, 0, 0x18000
	v_add_u32_e32 v92, s68, v188
	ds_read_b128 v[80:83], v92
	v_mfma_f32_16x16x32_bf16 v[44:47], v[206:209], v[140:143], v[44:47]
	v_mfma_f32_16x16x32_bf16 v[36:39], v[214:217], v[140:143], v[36:39]
	ds_read_b128 v[84:87], v92 offset:1024
	v_mfma_f32_16x16x32_bf16 v[28:31], v[206:209], v[160:163], v[28:31]
	v_mfma_f32_16x16x32_bf16 v[20:23], v[214:217], v[160:163], v[20:23]
	ds_read_b128 v[88:91], v92 offset:2048
	v_mfma_f32_16x16x32_bf16 v[4:7], v[206:209], v[198:201], v[4:7]
	v_mfma_f32_16x16x32_bf16 v[0:3], v[214:217], v[198:201], v[0:3]
	ds_read_b128 v[92:95], v92 offset:3072
	v_mfma_f32_16x16x32_bf16 v[56:59], v[210:213], v[132:135], v[56:59]
	s_add_u32 s46, s46, 0x80000
	s_addc_u32 s47, s47, 0
	v_mfma_f32_16x16x32_bf16 v[52:55], v[218:221], v[132:135], v[52:55]
	v_mfma_f32_16x16x32_bf16 v[44:47], v[210:213], v[152:155], v[44:47]
	v_mfma_f32_16x16x32_bf16 v[36:39], v[218:221], v[152:155], v[36:39]
	v_mfma_f32_16x16x32_bf16 v[28:31], v[210:213], v[164:167], v[28:31]
	v_mfma_f32_16x16x32_bf16 v[20:23], v[218:221], v[164:167], v[20:23]
	v_mfma_f32_16x16x32_bf16 v[4:7], v[210:213], v[202:205], v[4:7]
	v_mfma_f32_16x16x32_bf16 v[0:3], v[218:221], v[202:205], v[0:3]
	s_barrier
	s_setprio 0
	s_mov_b32 m0, s55
	ds_read_b128 v[124:127], v190 offset:32768
	ds_read_b128 v[132:135], v190 offset:33792
	ds_read_b128 v[160:163], v190 offset:34816
	ds_read_b128 v[164:167], v190 offset:35840
	ds_read_b128 v[198:201], v190 offset:36864
	ds_read_b128 v[202:205], v190 offset:37888
	ds_read_b128 v[206:209], v190 offset:38912
	ds_read_b128 v[210:213], v190 offset:39936
	global_load_lds_dwordx4 v174, s[46:47]
	s_mov_b32 m0, s56
	s_nop 0
	global_load_lds_dwordx4 v170, s[46:47]
	s_waitcnt lgkmcnt(8)
	s_setprio 1
	s_barrier
	s_waitcnt lgkmcnt(7)
	v_mfma_f32_16x16x32_bf16 v[140:143], v[80:83], v[124:127], v[148:151]
	s_waitcnt lgkmcnt(6)
	v_mfma_f32_16x16x32_bf16 v[148:151], v[84:87], v[132:135], v[140:143]
	v_mfma_f32_16x16x32_bf16 v[140:143], v[88:91], v[124:127], v[144:147]
	s_waitcnt lgkmcnt(5)
	v_mfma_f32_16x16x32_bf16 v[136:139], v[80:83], v[160:163], v[136:139]
	v_mfma_f32_16x16x32_bf16 v[128:131], v[88:91], v[160:163], v[128:131]
	s_waitcnt lgkmcnt(3)
	v_mfma_f32_16x16x32_bf16 v[120:123], v[80:83], v[198:201], v[120:123]
	v_mfma_f32_16x16x32_bf16 v[104:107], v[88:91], v[198:201], v[104:107]
	s_waitcnt lgkmcnt(1)
	v_mfma_f32_16x16x32_bf16 v[76:79], v[80:83], v[206:209], v[76:79]
	v_mfma_f32_16x16x32_bf16 v[72:75], v[88:91], v[206:209], v[72:75]
	s_add_i32 s46, 0, 0x1c000
	v_mfma_f32_16x16x32_bf16 v[144:147], v[92:95], v[132:135], v[140:143]
	v_add_u32_e32 v140, s46, v188
	v_mfma_f32_16x16x32_bf16 v[136:139], v[84:87], v[164:167], v[136:139]
	s_add_i32 s47, s68, s37
	v_mfma_f32_16x16x32_bf16 v[128:131], v[92:95], v[164:167], v[128:131]
	v_mfma_f32_16x16x32_bf16 v[120:123], v[84:87], v[202:205], v[120:123]
	v_mfma_f32_16x16x32_bf16 v[104:107], v[92:95], v[202:205], v[104:107]
	s_waitcnt lgkmcnt(0)
	v_mfma_f32_16x16x32_bf16 v[76:79], v[84:87], v[210:213], v[76:79]
	v_mfma_f32_16x16x32_bf16 v[72:75], v[92:95], v[210:213], v[72:75]
	s_barrier
	s_setprio 0
	ds_read_b128 v[214:217], v140
	ds_read_b128 v[218:221], v140 offset:1024
	ds_read_b128 v[222:225], v140 offset:2048
	ds_read_b128 v[226:229], v140 offset:3072
	v_lshl_add_u64 v[140:141], v[184:185], 0, s[14:15]
	s_mov_b32 m0, s47
	s_nop 0
	global_load_lds_dwordx4 v[140:141], off
	v_lshl_add_u64 v[140:141], v[194:195], 0, s[14:15]
	s_add_i32 m0, s47, 0x2000
	s_nop 0
	global_load_lds_dwordx4 v[140:141], off
	s_setprio 1
	s_barrier
; #define PG8_STAGE(bufoff, gbase, voff) do { _Pragma("unroll") for (int _i = 0; _i < 2; ++_i) \
;         __builtin_amdgcn_global_load_lds((const unsigned*)((const char*)(gbase) + (voff)[_i]), (LAS unsigned*)(lds + (bufoff) + ldsw + _i * 8192), 16, 0, 0); } while (0)
; #define PG8_LDA(dst, b, h) do { _Pragma("unroll") for (int m = 0; m < 4; ++m) _Pragma("unroll") for (int k = 0; k < 2; ++k) dst[m][k] = *(const LAS bf16x8*)(lds + PG8_SA(b, h) + aoff + m * 2048 + k * 1024); } while (0)
; #define PG8_LDB(dst, b, h) do { _Pragma("unroll") for (int n = 0; n < 2; ++n) _Pragma("unroll") for (int k = 0; k < 2; ++k) dst[n][k] = *(const LAS bf16x8*)(lds + PG8_SB(b, h) + boff + n * 2048 + k * 1024); } while (0)
; #define PG8_MMA(ai, bj, At, Bt) do { __builtin_amdgcn_s_setprio(1); _Pragma("unroll") for (int m = 0; m < 4; ++m) _Pragma("unroll") for (int n = 0; n < 2; ++n) _Pragma("unroll") for (int k = 0; k < 2; ++k) \
;         acc[ai][bj][m][n] = __builtin_amdgcn_mfma_f32_16x16x32_bf16(Bt[n][k], At[m][k], acc[ai][bj][m][n], 0, 0, 0); __builtin_amdgcn_s_setprio(0); } while (0)
; #define PG8_WAIT_V(n) asm volatile("s_waitcnt vmcnt(" #n ")" ::: "memory")
; #define PG8_WAIT_L(n) asm volatile("s_waitcnt lgkmcnt(" #n ")" ::: "memory")
; template <class Map, class Epi>
; DI void gemm_phase(LAS unsigned char* lds, const Map& MP, const Epi& E, const int nM, const int nN, const int K, const int lda, const int ldb) {
;     ...
;             const bool last = (t == nt - 2);
;             const char* a1 = cA + (size_t)(t + 1) * kstep;
;             const char* a2 = last ? nA : cA + (size_t)(t + 2) * kstep; const char* b2 = last ? nB : cB + (size_t)(t + 2) * kstep;
;             const char* a3 = a2 + kstep; const char* b3 = b2 + kstep;
;     ...
;             PG8_LDB(B0, 1, 0); PG8_SCHED; PG8_LDA(At, 1, 0); PG8_STAGE(PG8_SA(0, 1), a2 + hstepA, voffA);
;             PG8_WAIT_L(8); PG8_BAR; PG8_WAIT_L(0); PG8_MMA(0, 0, At, B0); PG8_BAR; PG8_SCHED;
;             PG8_LDB(B1, 1, 1); PG8_STAGE(PG8_SB(1, 0), b3, voffB);
;             PG8_BAR; PG8_WAIT_L(0); PG8_MMA(0, 1, At, B1); PG8_BAR;
;             PG8_LDA(At, 1, 1); PG8_STAGE(PG8_SA(1, 0), a3, voffA);
;             PG8_BAR; PG8_WAIT_L(0); PG8_MMA(1, 0, At, B0); PG8_BAR; PG8_SCHED;
;             PG8_STAGE(PG8_SB(1, 1), b3 + hstepB, voffB);
;             PG8_WAIT_V(6); PG8_BAR; PG8_MMA(1, 1, At, B1); PG8_BAR;
	s_waitcnt lgkmcnt(1)
	v_mfma_f32_16x16x32_bf16 v[96:99], v[222:225], v[124:127], v[96:99]
	v_mfma_f32_16x16x32_bf16 v[140:143], v[214:217], v[124:127], v[156:159]
	s_waitcnt lgkmcnt(0)
	v_mfma_f32_16x16x32_bf16 v[152:155], v[226:229], v[132:135], v[96:99]
	v_mfma_f32_16x16x32_bf16 v[96:99], v[214:217], v[160:163], v[100:103]
	v_mfma_f32_16x16x32_bf16 v[156:159], v[218:221], v[132:135], v[140:143]
	v_mfma_f32_16x16x32_bf16 v[140:143], v[218:221], v[164:167], v[96:99]
	v_mfma_f32_16x16x32_bf16 v[96:99], v[222:225], v[160:163], v[108:111]
	v_mfma_f32_16x16x32_bf16 v[132:135], v[226:229], v[164:167], v[96:99]
	v_mfma_f32_16x16x32_bf16 v[96:99], v[214:217], v[198:201], v[112:115]
	s_mov_b32 m0, s62
	v_mfma_f32_16x16x32_bf16 v[124:127], v[218:221], v[202:205], v[96:99]
	v_lshl_add_u64 v[184:185], v[230:231], 0, s[14:15]
	v_mfma_f32_16x16x32_bf16 v[96:99], v[222:225], v[198:201], v[116:119]
	v_mfma_f32_16x16x32_bf16 v[68:71], v[214:217], v[206:209], v[68:71]
	v_mfma_f32_16x16x32_bf16 v[64:67], v[222:225], v[206:209], v[64:67]
	v_mfma_f32_16x16x32_bf16 v[116:119], v[226:229], v[202:205], v[96:99]
	v_mfma_f32_16x16x32_bf16 v[68:71], v[218:221], v[210:213], v[68:71]
	v_mfma_f32_16x16x32_bf16 v[64:67], v[226:229], v[210:213], v[64:67]
	s_barrier
	s_setprio 0
	ds_read_b128 v[96:99], v190 offset:49152
	ds_read_b128 v[100:103], v190 offset:50176
	ds_read_b128 v[108:111], v190 offset:51200
	ds_read_b128 v[112:115], v190 offset:52224
	ds_read_b128 v[160:163], v190 offset:53248
	ds_read_b128 v[164:167], v190 offset:54272
	ds_read_b128 v[198:201], v190 offset:55296
	ds_read_b128 v[202:205], v190 offset:56320
	global_load_lds_dwordx4 v[184:185], off
	v_lshl_add_u64 v[184:185], v[232:233], 0, s[14:15]
	s_mov_b32 m0, s63
	s_nop 0
	global_load_lds_dwordx4 v[184:185], off
	s_waitcnt vmcnt(10)
	s_setprio 1
	s_barrier
	s_waitcnt lgkmcnt(7)
	v_mfma_f32_16x16x32_bf16 v[60:63], v[80:83], v[96:99], v[60:63]
	v_mfma_f32_16x16x32_bf16 v[48:51], v[88:91], v[96:99], v[48:51]
	s_waitcnt lgkmcnt(5)
	v_mfma_f32_16x16x32_bf16 v[40:43], v[80:83], v[108:111], v[40:43]
	v_mfma_f32_16x16x32_bf16 v[32:35], v[88:91], v[108:111], v[32:35]
	s_waitcnt lgkmcnt(3)
	v_mfma_f32_16x16x32_bf16 v[24:27], v[80:83], v[160:163], v[24:27]
	v_mfma_f32_16x16x32_bf16 v[16:19], v[88:91], v[160:163], v[16:19]
	s_waitcnt lgkmcnt(1)
	v_mfma_f32_16x16x32_bf16 v[12:15], v[80:83], v[198:201], v[12:15]
	v_mfma_f32_16x16x32_bf16 v[8:11], v[88:91], v[198:201], v[8:11]
	v_mfma_f32_16x16x32_bf16 v[60:63], v[84:87], v[100:103], v[60:63]
	s_add_u32 s28, s28, 0x80080
	s_addc_u32 s29, s29, 0
	v_mfma_f32_16x16x32_bf16 v[48:51], v[92:95], v[100:103], v[48:51]
	s_add_i32 s46, s46, s37
	v_mfma_f32_16x16x32_bf16 v[40:43], v[84:87], v[112:115], v[40:43]
	v_mfma_f32_16x16x32_bf16 v[32:35], v[92:95], v[112:115], v[32:35]
	v_mfma_f32_16x16x32_bf16 v[24:27], v[84:87], v[164:167], v[24:27]
	v_mfma_f32_16x16x32_bf16 v[16:19], v[92:95], v[164:167], v[16:19]
	s_waitcnt lgkmcnt(0)
	v_mfma_f32_16x16x32_bf16 v[12:15], v[84:87], v[202:205], v[12:15]
	v_mfma_f32_16x16x32_bf16 v[8:11], v[92:95], v[202:205], v[8:11]
	s_barrier
	s_setprio 0
	s_mov_b32 m0, s46
	s_nop 0
	global_load_lds_dwordx4 v172, s[28:29]
	s_add_i32 m0, s46, 0x2000
	s_nop 0
	global_load_lds_dwordx4 v168, s[28:29]
	s_waitcnt vmcnt(6)
	s_setprio 1
	s_barrier
	v_mfma_f32_16x16x32_bf16 v[56:59], v[214:217], v[96:99], v[56:59]
	v_mfma_f32_16x16x32_bf16 v[52:55], v[222:225], v[96:99], v[52:55]
	ds_read_b128 v[80:83], v189
	v_mfma_f32_16x16x32_bf16 v[44:47], v[214:217], v[108:111], v[44:47]
	v_mfma_f32_16x16x32_bf16 v[36:39], v[222:225], v[108:111], v[36:39]
	ds_read_b128 v[84:87], v189 offset:1024
	v_mfma_f32_16x16x32_bf16 v[28:31], v[214:217], v[160:163], v[28:31]
	v_mfma_f32_16x16x32_bf16 v[20:23], v[222:225], v[160:163], v[20:23]
	ds_read_b128 v[88:91], v189 offset:2048
	v_mfma_f32_16x16x32_bf16 v[4:7], v[214:217], v[198:201], v[4:7]
	v_mfma_f32_16x16x32_bf16 v[0:3], v[222:225], v[198:201], v[0:3]
	ds_read_b128 v[92:95], v189 offset:3072
	v_mfma_f32_16x16x32_bf16 v[56:59], v[218:221], v[100:103], v[56:59]
	s_add_i32 s3, s3, 2
	v_mfma_f32_16x16x32_bf16 v[52:55], v[226:229], v[100:103], v[52:55]
	s_add_u32 vcc_lo, vcc_lo, 0x100
	s_addc_u32 vcc_hi, vcc_hi, 0
	v_mfma_f32_16x16x32_bf16 v[44:47], v[218:221], v[112:115], v[44:47]
	s_add_u32 s42, s42, 0x100
	s_addc_u32 s43, s43, 0
	v_mfma_f32_16x16x32_bf16 v[36:39], v[226:229], v[112:115], v[36:39]
	s_add_u32 s28, s42, 0xfff80080
	s_addc_u32 s29, s43, -1
	s_cmp_eq_u32 s3, 28
	s_cselect_b32 s47, s23, s29
	s_cselect_b32 s46, s58, s28
	s_cselect_b32 s29, s21, vcc_hi
	s_cselect_b32 s28, s59, vcc_lo
	s_cmp_gt_u32 s3, 29
	v_mfma_f32_16x16x32_bf16 v[28:31], v[218:221], v[164:167], v[28:31]
	v_mfma_f32_16x16x32_bf16 v[20:23], v[226:229], v[164:167], v[20:23]
	v_mfma_f32_16x16x32_bf16 v[4:7], v[218:221], v[202:205], v[4:7]
	v_mfma_f32_16x16x32_bf16 v[0:3], v[226:229], v[202:205], v[0:3]
	s_barrier
	s_setprio 0
	s_cbranch_scc0 .LBB1_2483
; DI float silu_mul(float g, float v) { return g * v * __builtin_amdgcn_rcpf(1.0f + __builtin_amdgcn_exp2f(-LOG2E * g)); }
;     DI void operator()(const f32x4 (&acc)[2][2][4][2], const Unit& u, int wr, int wc, int fr, int fq) const {
;         const int row0 = u.pm * BM + wr * 64 + fr, ch0 = u.pn * 128 + wc * 32 + 8 * fq;
;         f32x4 w0[2], w1[2], w2[2], bb[2];
; #pragma unroll
;         for (int n = 0; n < 2; ++n) { w0[n] = *(const f32x4*)(cw + ch0 + 4 * n); w1[n] = *(const f32x4*)(cw + DFF + ch0 + 4 * n); w2[n] = *(const f32x4*)(cw + 2 * DFF + ch0 + 4 * n); bb[n] = *(const f32x4*)(cb + ch0 + 4 * n); }
; #pragma unroll
;         for (int ai = 0; ai < 2; ++ai)
; #pragma unroll
;             for (int m = 0; m < 4; ++m) {
;                 const bool efirst = (m == 0) && (fr == 0), elast = (m == 3) && (fr == 15);
;                 const int row = row0 + ai * HALF + m * 16;
;                 f32x4 gc[2];
; #pragma unroll
;                 for (int n = 0; n < 2; ++n) {
;                     const f32x4 g = acc[ai][0][m][n];
;                     const f32x4 gprev = acc[ai][0][m > 0 ? m - 1 : 0][n], gnext = acc[ai][0][m < 3 ? m + 1 : 3][n];
;                     f32x4 up, dn;
; #pragma unroll
;                     for (int e = 0; e < 4; ++e) {
;                         const float pu = (m > 0 && fr == 15) ? gprev[e] : g[e];
;                         const float pd = (m < 3 && fr == 0) ? gnext[e] : g[e];
;                         up[e] = dpp_ror1(pu); dn[e] = dpp_ror15(pd);
;                     }
;                     if (efirst) up = (f32x4){0.f, 0.f, 0.f, 0.f};
;                     if (elast) dn = (f32x4){0.f, 0.f, 0.f, 0.f};
;                     gc[n] = w0[n] * up + w1[n] * g + w2[n] * dn + bb[n];
;                 }
;                 if (efirst || elast) {
;                     const size_t eo = (size_t)((row >> 6) * 2 + (elast ? 1 : 0)) * DFF + ch0;
; #pragma unroll
;                     for (int n = 0; n < 2; ++n) { *(f32x4*)(EP + eo + 4 * n) = gc[n]; *(f32x4*)(ER + eo + 4 * n) = acc[ai][0][m][n]; *(f32x4*)(EV + eo + 4 * n) = acc[ai][1][m][n]; }
;                 } else {
;                     const f32x4 v0 = acc[ai][1][m][0], v1 = acc[ai][1][m][1];
;                     u32x4 o;
;                     o[0] = pack2(silu_mul(gc[0][0], v0[0]), silu_mul(gc[0][1], v0[1])); o[1] = pack2(silu_mul(gc[0][2], v0[2]), silu_mul(gc[0][3], v0[3]));
	s_waitcnt lgkmcnt(0)
	s_lshl_b32 s21, s45, 7
	v_mov_b32_e32 v80, v187
	v_mov_b32_e32 v194, v186
	s_or_b32 s21, s21, s57
	v_lshl_add_u32 v184, v80, 3, s21
	v_ashrrev_i32_e32 v185, 31, v184
	v_lshlrev_b64 v[80:81], 2, v[184:185]
	v_lshl_add_u64 v[84:85], s[4:5], 0, v[80:81]
	v_lshl_add_u64 v[88:89], s[16:17], 0, v[80:81]
	v_lshl_add_u64 v[92:93], s[18:19], 0, v[80:81]
	v_lshl_add_u64 v[112:113], s[6:7], 0, v[80:81]
	global_load_dwordx4 v[80:83], v[84:85], off offset:16
	global_load_dwordx4 v[96:99], v[84:85], off
	s_nop 0
	global_load_dwordx4 v[84:87], v[88:89], off offset:16
	global_load_dwordx4 v[100:103], v[88:89], off
	s_nop 0
	global_load_dwordx4 v[88:91], v[92:93], off offset:16
	global_load_dwordx4 v[108:111], v[92:93], off
	s_nop 0
	global_load_dwordx4 v[92:95], v[112:113], off offset:16
	s_nop 0
	global_load_dwordx4 v[112:115], v[112:113], off
	v_cmp_eq_u32_e32 vcc, 0, v194
	s_nop 0
	s_nop 0
	v_cndmask_b32_e32 v161, v148, v136, vcc
	v_cndmask_b32_e32 v162, v149, v137, vcc
	v_cndmask_b32_e32 v163, v150, v138, vcc
	v_mov_b32_dpp v160, v161 row_ror:15 row_mask:0xf bank_mask:0xf
	s_nop 0
	s_nop 0
	v_mov_b32_dpp v161, v162 row_ror:15 row_mask:0xf bank_mask:0xf
	v_mov_b32_dpp v164, v150 row_ror:1 row_mask:0xf bank_mask:0xf
	v_cndmask_b32_e32 v165, v151, v139, vcc
	v_mov_b32_dpp v162, v163 row_ror:15 row_mask:0xf bank_mask:0xf
	v_mov_b32_dpp v195, v151 row_ror:1 row_mask:0xf bank_mask:0xf
	v_mov_b32_dpp v166, v148 row_ror:1 row_mask:0xf bank_mask:0xf
	v_mov_b32_dpp v167, v149 row_ror:1 row_mask:0xf bank_mask:0xf
	v_mov_b32_dpp v163, v165 row_ror:15 row_mask:0xf bank_mask:0xf
	v_cndmask_b32_e64 v165, v195, 0, vcc
	v_cndmask_b32_e64 v164, v164, 0, vcc
	v_cndmask_b32_e64 v167, v167, 0, vcc
	v_cndmask_b32_e64 v166, v166, 0, vcc
	s_nop 0
	s_nop 0
	v_mov_b32_dpp v195, v144 row_ror:1 row_mask:0xf bank_mask:0xf
	v_mov_b32_dpp v196, v145 row_ror:1 row_mask:0xf bank_mask:0xf
	v_mov_b32_dpp v198, v146 row_ror:1 row_mask:0xf bank_mask:0xf
	v_cndmask_b32_e32 v199, v147, v131, vcc
	v_mov_b32_dpp v200, v147 row_ror:1 row_mask:0xf bank_mask:0xf
	v_cndmask_b32_e64 v198, v198, 0, vcc
	v_cndmask_b32_e64 v201, v196, 0, vcc
	s_lshl_b32 s3, s44, 8
	s_add_i32 s3, s3, s49
	v_add_u32_e32 v193, s3, v194
	v_cmp_ne_u32_e64 s[46:47], 0, v194
	s_waitcnt vmcnt(0)
	v_pk_mul_f32 v[164:165], v[98:99], v[164:165]
	v_pk_mul_f32 v[166:167], v[96:97], v[166:167]
	v_pk_fma_f32 v[164:165], v[150:151], v[102:103], v[164:165]
	v_pk_fma_f32 v[166:167], v[148:149], v[100:101], v[166:167]
	v_pk_fma_f32 v[162:163], v[110:111], v[162:163], v[164:165]
	v_cndmask_b32_e32 v165, v144, v128, vcc
	v_pk_fma_f32 v[160:161], v[108:109], v[160:161], v[166:167]
	v_cndmask_b32_e32 v166, v145, v129, vcc
	v_mov_b32_dpp v164, v165 row_ror:15 row_mask:0xf bank_mask:0xf
	v_cndmask_b32_e32 v167, v146, v130, vcc
	v_pk_add_f32 v[162:163], v[114:115], v[162:163]
	v_mov_b32_dpp v165, v166 row_ror:15 row_mask:0xf bank_mask:0xf
	v_pk_add_f32 v[160:161], v[112:113], v[160:161]
	s_nop 0
	v_mov_b32_dpp v166, v167 row_ror:15 row_mask:0xf bank_mask:0xf
	s_nop 1
	v_mov_b32_dpp v167, v199 row_ror:15 row_mask:0xf bank_mask:0xf
	v_cndmask_b32_e64 v199, v200, 0, vcc
	v_cndmask_b32_e64 v200, v195, 0, vcc
	v_pk_mul_f32 v[200:201], v[80:81], v[200:201]
	v_pk_mul_f32 v[198:199], v[82:83], v[198:199]
	v_pk_fma_f32 v[200:201], v[144:145], v[84:85], v[200:201]
	v_pk_fma_f32 v[198:199], v[146:147], v[86:87], v[198:199]
	v_pk_fma_f32 v[164:165], v[88:89], v[164:165], v[200:201]
	v_pk_fma_f32 v[166:167], v[90:91], v[166:167], v[198:199]
	v_pk_add_f32 v[164:165], v[92:93], v[164:165]
	v_pk_add_f32 v[166:167], v[94:95], v[166:167]
	s_and_saveexec_b64 s[28:29], s[46:47]
	s_xor_b64 s[28:29], exec, s[28:29]
	s_cbranch_execz .LBB1_2486
	v_mul_f32_e32 v195, 0xbfb8aa3b, v160
	v_exp_f32_e32 v195, v195
	v_mul_f32_e32 v196, 0xbfb8aa3b, v161
	v_exp_f32_e32 v196, v196
	v_pk_mul_f32 v[160:161], v[156:157], v[160:161]
	v_add_f32_e32 v195, 1.0, v195
	v_rcp_f32_e32 v198, v195
	v_add_f32_e32 v196, 1.0, v196
	v_mul_f32_e32 v195, 0xbfb8aa3b, v162
	v_rcp_f32_e32 v199, v196
	v_exp_f32_e32 v195, v195
	v_mul_f32_e32 v196, 0xbfb8aa3b, v163
	v_exp_f32_e32 v196, v196
	v_pk_mul_f32 v[160:161], v[160:161], v[198:199]
	v_add_f32_e32 v195, 1.0, v195
	v_rcp_f32_e32 v200, v195
	v_add_f32_e32 v195, 1.0, v196
	v_rcp_f32_e32 v201, v195
	v_cvt_pk_bf16_f32 v160, v160, v161
	v_mul_f32_e32 v161, 0xbfb8aa3b, v164
	v_exp_f32_e32 v195, v161
	v_mul_f32_e32 v161, 0xbfb8aa3b, v165
	v_exp_f32_e32 v196, v161
	v_pk_mul_f32 v[162:163], v[158:159], v[162:163]
	v_pk_mul_f32 v[164:165], v[152:153], v[164:165]
	v_pk_mul_f32 v[162:163], v[162:163], v[200:201]
	s_nop 0
	v_cvt_pk_bf16_f32 v161, v162, v163
	v_add_f32_e32 v162, 1.0, v195
	v_mul_f32_e32 v195, 0xbfb8aa3b, v166
	v_add_f32_e32 v163, 1.0, v196
	v_exp_f32_e32 v195, v195
	v_mul_f32_e32 v196, 0xbfb8aa3b, v167
	v_exp_f32_e32 v196, v196
	v_rcp_f32_e32 v162, v162
	v_add_f32_e32 v195, 1.0, v195
	v_rcp_f32_e32 v198, v195
	v_add_f32_e32 v195, 1.0, v196
	v_rcp_f32_e32 v163, v163
	v_rcp_f32_e32 v199, v195
	v_pk_mul_f32 v[166:167], v[154:155], v[166:167]
	v_pk_mul_f32 v[162:163], v[164:165], v[162:163]
	v_pk_mul_f32 v[164:165], v[166:167], v[198:199]
	v_cvt_pk_bf16_f32 v162, v162, v163
	v_cvt_pk_bf16_f32 v163, v164, v165
	v_mov_b64_e32 v[164:165], s[52:53]
	v_mad_i64_i32 v[164:165], s[42:43], v193, s60, v[164:165]
	v_lshl_add_u64 v[164:165], v[184:185], 1, v[164:165]
	global_store_dwordx4 v[164:165], v[160:163], off
